# v044 + GEMM K-loop back-edge rotation: loop-carried SALU (pointer bumps, trip compare) moved before the iteration's last s_barrier
# speedup vs baseline: 1.0001x; 1.0001x over previous
.LBB0_408:
	ds_read_b128 v[34:37], v196
	ds_read_b128 v[38:41], v196 offset:1024
	ds_read_b128 v[42:45], v196 offset:2048
	ds_read_b128 v[46:49], v196 offset:3072
	ds_read_b128 v[146:149], v197
	ds_read_b128 v[150:153], v197 offset:1024
	ds_read_b128 v[184:187], v197 offset:2048
	ds_read_b128 v[188:191], v197 offset:3072
	s_add_i32 s11, s6, 2
	s_add_u32 s12, s4, 0x80
	s_addc_u32 s7, s5, 0
	s_cmp_eq_u32 s27, s6
	s_cselect_b32 s6, s54, s12
	s_cselect_b32 s7, s55, s7
	s_cselect_b32 s13, s61, s9
	s_cselect_b32 s12, s60, s8
	v_lshl_add_u64 v[192:193], s[4:5], 0, v[174:175]
	s_add_i32 m0, s88, 0xc000
	ds_read_b128 v[200:203], v198
	ds_read_b128 v[204:207], v198 offset:1024
	ds_read_b128 v[208:211], v198 offset:2048
	ds_read_b128 v[212:215], v198 offset:3072
	ds_read_b128 v[216:219], v198 offset:4096
	ds_read_b128 v[220:223], v198 offset:5120
	ds_read_b128 v[224:227], v198 offset:6144
	ds_read_b128 v[228:231], v198 offset:7168
	global_load_lds_dwordx4 v[192:193], off
	v_lshl_add_u64 v[192:193], s[4:5], 0, v[176:177]
	s_add_i32 m0, s88, 0xe000
	s_nop 0
	global_load_lds_dwordx4 v[192:193], off
	s_waitcnt vmcnt(8)
	s_waitcnt lgkmcnt(0)
	s_setprio 1
	s_waitcnt lgkmcnt(0)
	v_mfma_f32_16x16x32_bf16 v[142:145], v[34:37], v[200:203], v[142:145]
	v_mfma_f32_16x16x32_bf16 v[138:141], v[42:45], v[200:203], v[138:141]
	s_barrier
	v_mfma_f32_16x16x32_bf16 v[126:129], v[34:37], v[208:211], v[126:129]
	v_mfma_f32_16x16x32_bf16 v[122:125], v[42:45], v[208:211], v[122:125]
	v_mfma_f32_16x16x32_bf16 v[110:113], v[34:37], v[216:219], v[110:113]
	v_mfma_f32_16x16x32_bf16 v[106:109], v[42:45], v[216:219], v[106:109]
	v_mfma_f32_16x16x32_bf16 v[94:97], v[34:37], v[224:227], v[94:97]
	v_mfma_f32_16x16x32_bf16 v[90:93], v[42:45], v[224:227], v[90:93]
	v_mfma_f32_16x16x32_bf16 v[142:145], v[38:41], v[204:207], v[142:145]
	v_mfma_f32_16x16x32_bf16 v[138:141], v[46:49], v[204:207], v[138:141]
	v_mfma_f32_16x16x32_bf16 v[126:129], v[38:41], v[212:215], v[126:129]
	v_mfma_f32_16x16x32_bf16 v[122:125], v[46:49], v[212:215], v[122:125]
	v_mfma_f32_16x16x32_bf16 v[110:113], v[38:41], v[220:223], v[110:113]
	v_mfma_f32_16x16x32_bf16 v[106:109], v[46:49], v[220:223], v[106:109]
	v_mfma_f32_16x16x32_bf16 v[94:97], v[38:41], v[228:231], v[94:97]
	v_mfma_f32_16x16x32_bf16 v[90:93], v[46:49], v[228:231], v[90:93]
	s_setprio 0
	s_setprio 1
	v_mfma_f32_16x16x32_bf16 v[134:137], v[146:149], v[200:203], v[134:137]
	v_mfma_f32_16x16x32_bf16 v[130:133], v[184:187], v[200:203], v[130:133]
	v_mfma_f32_16x16x32_bf16 v[118:121], v[146:149], v[208:211], v[118:121]
	v_mfma_f32_16x16x32_bf16 v[114:117], v[184:187], v[208:211], v[114:117]
	v_mfma_f32_16x16x32_bf16 v[102:105], v[146:149], v[216:219], v[102:105]
	v_mfma_f32_16x16x32_bf16 v[98:101], v[184:187], v[216:219], v[98:101]
	v_mfma_f32_16x16x32_bf16 v[86:89], v[146:149], v[224:227], v[86:89]
	v_mfma_f32_16x16x32_bf16 v[82:85], v[184:187], v[224:227], v[82:85]
	v_mfma_f32_16x16x32_bf16 v[134:137], v[150:153], v[204:207], v[134:137]
	v_mfma_f32_16x16x32_bf16 v[130:133], v[188:191], v[204:207], v[130:133]
	v_mfma_f32_16x16x32_bf16 v[118:121], v[150:153], v[212:215], v[118:121]
	v_mfma_f32_16x16x32_bf16 v[114:117], v[188:191], v[212:215], v[114:117]
	v_mfma_f32_16x16x32_bf16 v[102:105], v[150:153], v[220:223], v[102:105]
	v_mfma_f32_16x16x32_bf16 v[98:101], v[188:191], v[220:223], v[98:101]
	v_mfma_f32_16x16x32_bf16 v[86:89], v[150:153], v[228:231], v[86:89]
	v_mfma_f32_16x16x32_bf16 v[82:85], v[188:191], v[228:231], v[82:85]
	s_setprio 0
	s_barrier
	s_add_i32 s24, s84, s81
	v_lshl_add_u64 v[192:193], s[12:13], 0, v[156:157]
	s_mov_b32 m0, s24
	ds_read_b128 v[200:203], v198 offset:16384
	ds_read_b128 v[204:207], v198 offset:17408
	ds_read_b128 v[208:211], v198 offset:18432
	ds_read_b128 v[212:215], v198 offset:19456
	ds_read_b128 v[216:219], v198 offset:20480
	ds_read_b128 v[220:223], v198 offset:21504
	ds_read_b128 v[224:227], v198 offset:22528
	ds_read_b128 v[228:231], v198 offset:23552
	global_load_lds_dwordx4 v[192:193], off
	s_add_i32 m0, s24, 0x2000
	v_lshl_add_u64 v[232:233], s[12:13], 0, v[160:161]
	s_add_u32 s12, s12, s20
	s_addc_u32 s13, s13, s21
	s_add_i32 s24, s85, s81
	global_load_lds_dwordx4 v[232:233], off
	v_lshl_add_u64 v[234:235], s[12:13], 0, v[156:157]
	s_mov_b32 m0, s24
	v_lshl_add_u64 v[236:237], s[12:13], 0, v[160:161]
	global_load_lds_dwordx4 v[234:235], off
	s_add_i32 m0, s24, 0x2000
	v_lshl_add_u64 v[238:239], s[6:7], 0, v[154:155]
	global_load_lds_dwordx4 v[236:237], off
	s_mov_b32 m0, s88
	v_lshl_add_u64 v[240:241], s[6:7], 0, v[158:159]
	global_load_lds_dwordx4 v[238:239], off
	s_mov_b32 m0, s90
	s_nop 0
	global_load_lds_dwordx4 v[240:241], off
	s_waitcnt vmcnt(8)
	s_waitcnt lgkmcnt(0)
	s_setprio 1
	s_waitcnt lgkmcnt(0)
	v_mfma_f32_16x16x32_bf16 v[78:81], v[34:37], v[200:203], v[78:81]
	v_mfma_f32_16x16x32_bf16 v[74:77], v[42:45], v[200:203], v[74:77]
	s_barrier
	v_mfma_f32_16x16x32_bf16 v[62:65], v[34:37], v[208:211], v[62:65]
	v_mfma_f32_16x16x32_bf16 v[58:61], v[42:45], v[208:211], v[58:61]
	v_mfma_f32_16x16x32_bf16 v[30:33], v[34:37], v[216:219], v[30:33]
	v_mfma_f32_16x16x32_bf16 v[26:29], v[42:45], v[216:219], v[26:29]
	v_mfma_f32_16x16x32_bf16 v[14:17], v[34:37], v[224:227], v[14:17]
	v_mfma_f32_16x16x32_bf16 v[10:13], v[42:45], v[224:227], v[10:13]
	v_mfma_f32_16x16x32_bf16 v[78:81], v[38:41], v[204:207], v[78:81]
	v_mfma_f32_16x16x32_bf16 v[74:77], v[46:49], v[204:207], v[74:77]
	v_mfma_f32_16x16x32_bf16 v[62:65], v[38:41], v[212:215], v[62:65]
	v_mfma_f32_16x16x32_bf16 v[58:61], v[46:49], v[212:215], v[58:61]
	v_mfma_f32_16x16x32_bf16 v[30:33], v[38:41], v[220:223], v[30:33]
	v_mfma_f32_16x16x32_bf16 v[26:29], v[46:49], v[220:223], v[26:29]
	v_mfma_f32_16x16x32_bf16 v[14:17], v[38:41], v[228:231], v[14:17]
	v_mfma_f32_16x16x32_bf16 v[10:13], v[46:49], v[228:231], v[10:13]
	s_setprio 0
	s_setprio 1
	v_mfma_f32_16x16x32_bf16 v[22:25], v[146:149], v[216:219], v[22:25]
	v_mfma_f32_16x16x32_bf16 v[18:21], v[184:187], v[216:219], v[18:21]
	v_mfma_f32_16x16x32_bf16 v[6:9], v[146:149], v[224:227], v[6:9]
	v_mfma_f32_16x16x32_bf16 v[2:5], v[184:187], v[224:227], v[2:5]
	v_mfma_f32_16x16x32_bf16 v[34:37], v[146:149], v[200:203], v[70:73]
	v_mfma_f32_16x16x32_bf16 v[38:41], v[184:187], v[200:203], v[66:69]
	v_mfma_f32_16x16x32_bf16 v[42:45], v[146:149], v[208:211], v[54:57]
	v_mfma_f32_16x16x32_bf16 v[46:49], v[184:187], v[208:211], v[50:53]
	v_mfma_f32_16x16x32_bf16 v[22:25], v[150:153], v[220:223], v[22:25]
	v_mfma_f32_16x16x32_bf16 v[18:21], v[188:191], v[220:223], v[18:21]
	v_mfma_f32_16x16x32_bf16 v[6:9], v[150:153], v[228:231], v[6:9]
	v_mfma_f32_16x16x32_bf16 v[2:5], v[188:191], v[228:231], v[2:5]
	v_mfma_f32_16x16x32_bf16 v[34:37], v[150:153], v[204:207], v[34:37]
	v_mfma_f32_16x16x32_bf16 v[38:41], v[188:191], v[204:207], v[38:41]
	v_mfma_f32_16x16x32_bf16 v[42:45], v[150:153], v[212:215], v[42:45]
	v_mfma_f32_16x16x32_bf16 v[46:49], v[188:191], v[212:215], v[46:49]
	s_setprio 0
	s_barrier
	s_add_i32 s12, 0, 0x18000
	s_add_i32 s13, 0, 0x1c000
	v_add_u32_e32 v70, s12, v194
	v_add_u32_e32 v162, s13, v194
	ds_read_b128 v[50:53], v70
	ds_read_b128 v[54:57], v70 offset:1024
	ds_read_b128 v[66:69], v70 offset:2048
	ds_read_b128 v[70:73], v70 offset:3072
	ds_read_b128 v[146:149], v162
	ds_read_b128 v[150:153], v162 offset:1024
	ds_read_b128 v[184:187], v162 offset:2048
	ds_read_b128 v[188:191], v162 offset:3072
	s_add_u32 s6, s6, s20
	s_addc_u32 s7, s7, s21
	s_mov_b32 m0, s91
	v_lshl_add_u64 v[242:243], s[6:7], 0, v[154:155]
	ds_read_b128 v[200:203], v198 offset:32768
	ds_read_b128 v[204:207], v198 offset:33792
	ds_read_b128 v[208:211], v198 offset:34816
	ds_read_b128 v[212:215], v198 offset:35840
	ds_read_b128 v[216:219], v198 offset:36864
	ds_read_b128 v[220:223], v198 offset:37888
	ds_read_b128 v[224:227], v198 offset:38912
	ds_read_b128 v[228:231], v198 offset:39936
	global_load_lds_dwordx4 v[242:243], off
	v_lshl_add_u64 v[242:243], s[6:7], 0, v[158:159]
	s_mov_b32 m0, s95
	s_nop 0
	global_load_lds_dwordx4 v[242:243], off
	s_waitcnt vmcnt(8)
	s_waitcnt lgkmcnt(0)
	s_setprio 1
	s_waitcnt lgkmcnt(0)
	v_mfma_f32_16x16x32_bf16 v[142:145], v[50:53], v[200:203], v[142:145]
	v_mfma_f32_16x16x32_bf16 v[138:141], v[66:69], v[200:203], v[138:141]
	s_barrier
	v_mfma_f32_16x16x32_bf16 v[126:129], v[50:53], v[208:211], v[126:129]
	v_mfma_f32_16x16x32_bf16 v[122:125], v[66:69], v[208:211], v[122:125]
	v_mfma_f32_16x16x32_bf16 v[110:113], v[50:53], v[216:219], v[110:113]
	v_mfma_f32_16x16x32_bf16 v[106:109], v[66:69], v[216:219], v[106:109]
	v_mfma_f32_16x16x32_bf16 v[94:97], v[50:53], v[224:227], v[94:97]
	v_mfma_f32_16x16x32_bf16 v[90:93], v[66:69], v[224:227], v[90:93]
	v_mfma_f32_16x16x32_bf16 v[142:145], v[54:57], v[204:207], v[142:145]
	v_mfma_f32_16x16x32_bf16 v[138:141], v[70:73], v[204:207], v[138:141]
	v_mfma_f32_16x16x32_bf16 v[126:129], v[54:57], v[212:215], v[126:129]
	v_mfma_f32_16x16x32_bf16 v[122:125], v[70:73], v[212:215], v[122:125]
	v_mfma_f32_16x16x32_bf16 v[110:113], v[54:57], v[220:223], v[110:113]
	v_mfma_f32_16x16x32_bf16 v[106:109], v[70:73], v[220:223], v[106:109]
	v_mfma_f32_16x16x32_bf16 v[94:97], v[54:57], v[228:231], v[94:97]
	v_mfma_f32_16x16x32_bf16 v[90:93], v[70:73], v[228:231], v[90:93]
	s_setprio 0
	s_setprio 1
	v_mfma_f32_16x16x32_bf16 v[134:137], v[146:149], v[200:203], v[134:137]
	v_mfma_f32_16x16x32_bf16 v[130:133], v[184:187], v[200:203], v[130:133]
	v_mfma_f32_16x16x32_bf16 v[118:121], v[146:149], v[208:211], v[118:121]
	v_mfma_f32_16x16x32_bf16 v[114:117], v[184:187], v[208:211], v[114:117]
	v_mfma_f32_16x16x32_bf16 v[102:105], v[146:149], v[216:219], v[102:105]
	v_mfma_f32_16x16x32_bf16 v[98:101], v[184:187], v[216:219], v[98:101]
	v_mfma_f32_16x16x32_bf16 v[86:89], v[146:149], v[224:227], v[86:89]
	v_mfma_f32_16x16x32_bf16 v[82:85], v[184:187], v[224:227], v[82:85]
	v_mfma_f32_16x16x32_bf16 v[134:137], v[150:153], v[204:207], v[134:137]
	v_mfma_f32_16x16x32_bf16 v[130:133], v[188:191], v[204:207], v[130:133]
	v_mfma_f32_16x16x32_bf16 v[118:121], v[150:153], v[212:215], v[118:121]
	v_mfma_f32_16x16x32_bf16 v[114:117], v[188:191], v[212:215], v[114:117]
	v_mfma_f32_16x16x32_bf16 v[102:105], v[150:153], v[220:223], v[102:105]
	v_mfma_f32_16x16x32_bf16 v[98:101], v[188:191], v[220:223], v[98:101]
	v_mfma_f32_16x16x32_bf16 v[86:89], v[150:153], v[228:231], v[86:89]
	v_mfma_f32_16x16x32_bf16 v[82:85], v[188:191], v[228:231], v[82:85]
	s_setprio 0
	s_barrier
	s_add_i32 s6, s12, s81
	v_lshl_add_u64 v[192:193], v[192:193], 0, s[44:45]
	s_mov_b32 m0, s6
	ds_read_b128 v[200:203], v198 offset:49152
	ds_read_b128 v[204:207], v198 offset:50176
	ds_read_b128 v[208:211], v198 offset:51200
	ds_read_b128 v[212:215], v198 offset:52224
	ds_read_b128 v[216:219], v198 offset:53248
	ds_read_b128 v[220:223], v198 offset:54272
	ds_read_b128 v[224:227], v198 offset:55296
	ds_read_b128 v[228:231], v198 offset:56320
	global_load_lds_dwordx4 v[192:193], off
	v_lshl_add_u64 v[192:193], v[232:233], 0, s[44:45]
	s_add_i32 m0, s6, 0x2000
	s_add_i32 s6, s13, s81
	global_load_lds_dwordx4 v[192:193], off
	v_lshl_add_u64 v[192:193], v[234:235], 0, s[44:45]
	s_mov_b32 m0, s6
	s_nop 0
	global_load_lds_dwordx4 v[192:193], off
	v_lshl_add_u64 v[192:193], v[236:237], 0, s[44:45]
	s_add_i32 m0, s6, 0x2000
	s_nop 0
	global_load_lds_dwordx4 v[192:193], off
	v_lshl_add_u64 v[192:193], v[238:239], 0, s[44:45]
	s_mov_b32 m0, s17
	s_nop 0
	global_load_lds_dwordx4 v[192:193], off
	v_lshl_add_u64 v[192:193], v[240:241], 0, s[44:45]
	s_mov_b32 m0, s94
	s_nop 0
	global_load_lds_dwordx4 v[192:193], off
	s_waitcnt vmcnt(8)
	s_waitcnt lgkmcnt(0)
	s_setprio 1
	s_waitcnt lgkmcnt(0)
	v_mfma_f32_16x16x32_bf16 v[78:81], v[50:53], v[200:203], v[78:81]
	v_mfma_f32_16x16x32_bf16 v[74:77], v[66:69], v[200:203], v[74:77]
	s_barrier
	v_mfma_f32_16x16x32_bf16 v[62:65], v[50:53], v[208:211], v[62:65]
	v_mfma_f32_16x16x32_bf16 v[58:61], v[66:69], v[208:211], v[58:61]
	v_mfma_f32_16x16x32_bf16 v[30:33], v[50:53], v[216:219], v[30:33]
	v_mfma_f32_16x16x32_bf16 v[26:29], v[66:69], v[216:219], v[26:29]
	v_mfma_f32_16x16x32_bf16 v[14:17], v[50:53], v[224:227], v[14:17]
	v_mfma_f32_16x16x32_bf16 v[10:13], v[66:69], v[224:227], v[10:13]
	v_mfma_f32_16x16x32_bf16 v[78:81], v[54:57], v[204:207], v[78:81]
	v_mfma_f32_16x16x32_bf16 v[74:77], v[70:73], v[204:207], v[74:77]
	v_mfma_f32_16x16x32_bf16 v[62:65], v[54:57], v[212:215], v[62:65]
	v_mfma_f32_16x16x32_bf16 v[58:61], v[70:73], v[212:215], v[58:61]
	v_mfma_f32_16x16x32_bf16 v[30:33], v[54:57], v[220:223], v[30:33]
	v_mfma_f32_16x16x32_bf16 v[26:29], v[70:73], v[220:223], v[26:29]
	v_mfma_f32_16x16x32_bf16 v[14:17], v[54:57], v[228:231], v[14:17]
	v_mfma_f32_16x16x32_bf16 v[10:13], v[70:73], v[228:231], v[10:13]
	s_setprio 0
	s_setprio 1
	v_mfma_f32_16x16x32_bf16 v[34:37], v[146:149], v[200:203], v[34:37]
	v_mfma_f32_16x16x32_bf16 v[70:73], v[150:153], v[204:207], v[34:37]
	v_mfma_f32_16x16x32_bf16 v[34:37], v[184:187], v[200:203], v[38:41]
	v_mfma_f32_16x16x32_bf16 v[66:69], v[188:191], v[204:207], v[34:37]
	v_mfma_f32_16x16x32_bf16 v[34:37], v[146:149], v[208:211], v[42:45]
	v_mfma_f32_16x16x32_bf16 v[54:57], v[150:153], v[212:215], v[34:37]
	v_mfma_f32_16x16x32_bf16 v[34:37], v[184:187], v[208:211], v[46:49]
	v_mfma_f32_16x16x32_bf16 v[22:25], v[146:149], v[216:219], v[22:25]
	v_mfma_f32_16x16x32_bf16 v[18:21], v[184:187], v[216:219], v[18:21]
	v_mfma_f32_16x16x32_bf16 v[6:9], v[146:149], v[224:227], v[6:9]
	v_mfma_f32_16x16x32_bf16 v[2:5], v[184:187], v[224:227], v[2:5]
	v_mfma_f32_16x16x32_bf16 v[50:53], v[188:191], v[212:215], v[34:37]
	v_mfma_f32_16x16x32_bf16 v[22:25], v[150:153], v[220:223], v[22:25]
	v_mfma_f32_16x16x32_bf16 v[18:21], v[188:191], v[220:223], v[18:21]
	v_mfma_f32_16x16x32_bf16 v[6:9], v[150:153], v[228:231], v[6:9]
	v_mfma_f32_16x16x32_bf16 v[2:5], v[188:191], v[228:231], v[2:5]
	s_setprio 0
	s_add_u32 s4, s4, 0x100
	s_addc_u32 s5, s5, 0
	s_add_u32 s8, s8, 0x100
	s_addc_u32 s9, s9, 0
	s_cmp_ge_i32 s11, s26
	s_mov_b32 s6, s11
	s_barrier
	s_cbranch_scc0 .LBB0_408

.LBB0_895:
	v_add_u32_e32 v158, s84, v227
	v_add_u32_e32 v174, s85, v227
	ds_read_b128 v[146:149], v158
	ds_read_b128 v[150:153], v158 offset:1024
	ds_read_b128 v[154:157], v158 offset:2048
	ds_read_b128 v[158:161], v158 offset:3072
	ds_read_b128 v[162:165], v174
	ds_read_b128 v[166:169], v174 offset:1024
	ds_read_b128 v[170:173], v174 offset:2048
	ds_read_b128 v[174:177], v174 offset:3072
	s_add_i32 s16, s50, 2
	s_add_u32 s17, s46, 0x80
	s_addc_u32 s51, s47, 0
	s_cmp_eq_u32 s81, s50
	s_cselect_b32 s50, s4, s17
	s_cselect_b32 s51, s5, s51
	s_cselect_b32 s55, s45, vcc_hi
	s_cselect_b32 s54, s44, vcc_lo
	v_lshl_add_u64 v[210:211], s[46:47], 0, v[138:139]
	s_add_i32 m0, s63, 0xc000
	ds_read_b128 v[178:181], v229
	ds_read_b128 v[182:185], v229 offset:1024
	ds_read_b128 v[186:189], v229 offset:2048
	ds_read_b128 v[190:193], v229 offset:3072
	ds_read_b128 v[194:197], v229 offset:4096
	ds_read_b128 v[198:201], v229 offset:5120
	ds_read_b128 v[202:205], v229 offset:6144
	ds_read_b128 v[206:209], v229 offset:7168
	global_load_lds_dwordx4 v[210:211], off
	v_lshl_add_u64 v[210:211], s[46:47], 0, v[140:141]
	s_add_i32 m0, s63, 0xe000
	s_nop 0
	global_load_lds_dwordx4 v[210:211], off
	s_waitcnt vmcnt(8)
	s_waitcnt lgkmcnt(0)
	s_setprio 1
	s_waitcnt lgkmcnt(0)
	v_mfma_i32_16x16x64_i8 v[126:129], v[146:149], v[178:181], v[126:129]
	v_mfma_i32_16x16x64_i8 v[122:125], v[154:157], v[178:181], v[122:125]
	s_barrier
	v_mfma_i32_16x16x64_i8 v[118:121], v[146:149], v[186:189], v[118:121]
	v_mfma_i32_16x16x64_i8 v[114:117], v[154:157], v[186:189], v[114:117]
	v_mfma_i32_16x16x64_i8 v[106:109], v[146:149], v[194:197], v[106:109]
	v_mfma_i32_16x16x64_i8 v[98:101], v[154:157], v[194:197], v[98:101]
	v_mfma_i32_16x16x64_i8 v[90:93], v[146:149], v[202:205], v[90:93]
	v_mfma_i32_16x16x64_i8 v[82:85], v[154:157], v[202:205], v[82:85]
	v_mfma_i32_16x16x64_i8 v[126:129], v[150:153], v[182:185], v[126:129]
	v_mfma_i32_16x16x64_i8 v[122:125], v[158:161], v[182:185], v[122:125]
	v_mfma_i32_16x16x64_i8 v[118:121], v[150:153], v[190:193], v[118:121]
	v_mfma_i32_16x16x64_i8 v[114:117], v[158:161], v[190:193], v[114:117]
	v_mfma_i32_16x16x64_i8 v[106:109], v[150:153], v[198:201], v[106:109]
	v_mfma_i32_16x16x64_i8 v[98:101], v[158:161], v[198:201], v[98:101]
	v_mfma_i32_16x16x64_i8 v[90:93], v[150:153], v[206:209], v[90:93]
	v_mfma_i32_16x16x64_i8 v[82:85], v[158:161], v[206:209], v[82:85]
	s_setprio 0
	s_setprio 1
	v_mfma_i32_16x16x64_i8 v[110:113], v[162:165], v[178:181], v[110:113]
	v_mfma_i32_16x16x64_i8 v[102:105], v[170:173], v[178:181], v[102:105]
	v_mfma_i32_16x16x64_i8 v[94:97], v[162:165], v[186:189], v[94:97]
	v_mfma_i32_16x16x64_i8 v[86:89], v[170:173], v[186:189], v[86:89]
	v_mfma_i32_16x16x64_i8 v[78:81], v[162:165], v[194:197], v[78:81]
	v_mfma_i32_16x16x64_i8 v[74:77], v[170:173], v[194:197], v[74:77]
	v_mfma_i32_16x16x64_i8 v[70:73], v[162:165], v[202:205], v[70:73]
	v_mfma_i32_16x16x64_i8 v[66:69], v[170:173], v[202:205], v[66:69]
	v_mfma_i32_16x16x64_i8 v[110:113], v[166:169], v[182:185], v[110:113]
	v_mfma_i32_16x16x64_i8 v[102:105], v[174:177], v[182:185], v[102:105]
	v_mfma_i32_16x16x64_i8 v[94:97], v[166:169], v[190:193], v[94:97]
	v_mfma_i32_16x16x64_i8 v[86:89], v[174:177], v[190:193], v[86:89]
	v_mfma_i32_16x16x64_i8 v[78:81], v[166:169], v[198:201], v[78:81]
	v_mfma_i32_16x16x64_i8 v[74:77], v[174:177], v[198:201], v[74:77]
	v_mfma_i32_16x16x64_i8 v[70:73], v[166:169], v[206:209], v[70:73]
	v_mfma_i32_16x16x64_i8 v[66:69], v[174:177], v[206:209], v[66:69]
	s_setprio 0
	s_barrier
	s_add_i32 s17, s84, s62
	v_lshl_add_u64 v[210:211], s[54:55], 0, v[132:133]
	s_mov_b32 m0, s17
	ds_read_b128 v[178:181], v229 offset:16384
	ds_read_b128 v[182:185], v229 offset:17408
	ds_read_b128 v[186:189], v229 offset:18432
	ds_read_b128 v[190:193], v229 offset:19456
	ds_read_b128 v[194:197], v229 offset:20480
	ds_read_b128 v[198:201], v229 offset:21504
	ds_read_b128 v[202:205], v229 offset:22528
	ds_read_b128 v[206:209], v229 offset:23552
	global_load_lds_dwordx4 v[210:211], off
	s_add_i32 m0, s17, 0x2000
	v_lshl_add_u64 v[212:213], s[54:55], 0, v[136:137]
	s_add_u32 s54, s54, s8
	s_addc_u32 s55, s55, s9
	s_add_i32 s17, s85, s62
	global_load_lds_dwordx4 v[212:213], off
	v_lshl_add_u64 v[214:215], s[54:55], 0, v[132:133]
	s_mov_b32 m0, s17
	v_lshl_add_u64 v[216:217], s[54:55], 0, v[136:137]
	global_load_lds_dwordx4 v[214:215], off
	s_add_i32 m0, s17, 0x2000
	v_lshl_add_u64 v[218:219], s[50:51], 0, v[130:131]
	global_load_lds_dwordx4 v[216:217], off
	s_mov_b32 m0, s63
	v_lshl_add_u64 v[220:221], s[50:51], 0, v[134:135]
	global_load_lds_dwordx4 v[218:219], off
	s_mov_b32 m0, s64
	s_nop 0
	global_load_lds_dwordx4 v[220:221], off
	s_waitcnt vmcnt(8)
	s_waitcnt lgkmcnt(0)
	s_setprio 1
	s_waitcnt lgkmcnt(0)
	v_mfma_i32_16x16x64_i8 v[62:65], v[146:149], v[178:181], v[62:65]
	v_mfma_i32_16x16x64_i8 v[58:61], v[154:157], v[178:181], v[58:61]
	s_barrier
	v_mfma_i32_16x16x64_i8 v[54:57], v[146:149], v[186:189], v[54:57]
	v_mfma_i32_16x16x64_i8 v[50:53], v[154:157], v[186:189], v[50:53]
	v_mfma_i32_16x16x64_i8 v[42:45], v[146:149], v[194:197], v[42:45]
	v_mfma_i32_16x16x64_i8 v[34:37], v[154:157], v[194:197], v[34:37]
	v_mfma_i32_16x16x64_i8 v[26:29], v[146:149], v[202:205], v[26:29]
	v_mfma_i32_16x16x64_i8 v[18:21], v[154:157], v[202:205], v[18:21]
	v_mfma_i32_16x16x64_i8 v[62:65], v[150:153], v[182:185], v[62:65]
	v_mfma_i32_16x16x64_i8 v[58:61], v[158:161], v[182:185], v[58:61]
	v_mfma_i32_16x16x64_i8 v[54:57], v[150:153], v[190:193], v[54:57]
	v_mfma_i32_16x16x64_i8 v[50:53], v[158:161], v[190:193], v[50:53]
	v_mfma_i32_16x16x64_i8 v[42:45], v[150:153], v[198:201], v[42:45]
	v_mfma_i32_16x16x64_i8 v[34:37], v[158:161], v[198:201], v[34:37]
	v_mfma_i32_16x16x64_i8 v[26:29], v[150:153], v[206:209], v[26:29]
	v_mfma_i32_16x16x64_i8 v[18:21], v[158:161], v[206:209], v[18:21]
	s_setprio 0
	s_setprio 1
	v_mfma_i32_16x16x64_i8 v[46:49], v[162:165], v[178:181], v[46:49]
	v_mfma_i32_16x16x64_i8 v[38:41], v[170:173], v[178:181], v[38:41]
	v_mfma_i32_16x16x64_i8 v[30:33], v[162:165], v[186:189], v[30:33]
	v_mfma_i32_16x16x64_i8 v[22:25], v[170:173], v[186:189], v[22:25]
	v_mfma_i32_16x16x64_i8 v[14:17], v[162:165], v[194:197], v[14:17]
	v_mfma_i32_16x16x64_i8 v[10:13], v[170:173], v[194:197], v[10:13]
	v_mfma_i32_16x16x64_i8 v[6:9], v[162:165], v[202:205], v[6:9]
	v_mfma_i32_16x16x64_i8 v[2:5], v[170:173], v[202:205], v[2:5]
	v_mfma_i32_16x16x64_i8 v[46:49], v[166:169], v[182:185], v[46:49]
	v_mfma_i32_16x16x64_i8 v[38:41], v[174:177], v[182:185], v[38:41]
	v_mfma_i32_16x16x64_i8 v[30:33], v[166:169], v[190:193], v[30:33]
	v_mfma_i32_16x16x64_i8 v[22:25], v[174:177], v[190:193], v[22:25]
	v_mfma_i32_16x16x64_i8 v[14:17], v[166:169], v[198:201], v[14:17]
	v_mfma_i32_16x16x64_i8 v[10:13], v[174:177], v[198:201], v[10:13]
	v_mfma_i32_16x16x64_i8 v[6:9], v[166:169], v[206:209], v[6:9]
	v_mfma_i32_16x16x64_i8 v[2:5], v[174:177], v[206:209], v[2:5]
	s_setprio 0
	s_barrier
	s_add_i32 s17, 0, 0x18000
	s_add_i32 s54, 0, 0x1c000
	v_add_u32_e32 v158, s17, v227
	v_add_u32_e32 v174, s54, v227
	ds_read_b128 v[146:149], v158
	ds_read_b128 v[150:153], v158 offset:1024
	ds_read_b128 v[154:157], v158 offset:2048
	ds_read_b128 v[158:161], v158 offset:3072
	ds_read_b128 v[162:165], v174
	ds_read_b128 v[166:169], v174 offset:1024
	ds_read_b128 v[170:173], v174 offset:2048
	ds_read_b128 v[174:177], v174 offset:3072
	s_add_u32 s50, s50, s8
	s_addc_u32 s51, s51, s9
	s_mov_b32 m0, s65
	v_lshl_add_u64 v[222:223], s[50:51], 0, v[130:131]
	ds_read_b128 v[178:181], v229 offset:32768
	ds_read_b128 v[182:185], v229 offset:33792
	ds_read_b128 v[186:189], v229 offset:34816
	ds_read_b128 v[190:193], v229 offset:35840
	ds_read_b128 v[194:197], v229 offset:36864
	ds_read_b128 v[198:201], v229 offset:37888
	ds_read_b128 v[202:205], v229 offset:38912
	ds_read_b128 v[206:209], v229 offset:39936
	global_load_lds_dwordx4 v[222:223], off
	v_lshl_add_u64 v[222:223], s[50:51], 0, v[134:135]
	s_mov_b32 m0, s86
	s_nop 0
	global_load_lds_dwordx4 v[222:223], off
	s_waitcnt vmcnt(8)
	s_waitcnt lgkmcnt(0)
	s_setprio 1
	s_waitcnt lgkmcnt(0)
	v_mfma_i32_16x16x64_i8 v[126:129], v[146:149], v[178:181], v[126:129]
	v_mfma_i32_16x16x64_i8 v[122:125], v[154:157], v[178:181], v[122:125]
	s_barrier
	v_mfma_i32_16x16x64_i8 v[118:121], v[146:149], v[186:189], v[118:121]
	v_mfma_i32_16x16x64_i8 v[114:117], v[154:157], v[186:189], v[114:117]
	v_mfma_i32_16x16x64_i8 v[106:109], v[146:149], v[194:197], v[106:109]
	v_mfma_i32_16x16x64_i8 v[98:101], v[154:157], v[194:197], v[98:101]
	v_mfma_i32_16x16x64_i8 v[90:93], v[146:149], v[202:205], v[90:93]
	v_mfma_i32_16x16x64_i8 v[82:85], v[154:157], v[202:205], v[82:85]
	v_mfma_i32_16x16x64_i8 v[126:129], v[150:153], v[182:185], v[126:129]
	v_mfma_i32_16x16x64_i8 v[122:125], v[158:161], v[182:185], v[122:125]
	v_mfma_i32_16x16x64_i8 v[118:121], v[150:153], v[190:193], v[118:121]
	v_mfma_i32_16x16x64_i8 v[114:117], v[158:161], v[190:193], v[114:117]
	v_mfma_i32_16x16x64_i8 v[106:109], v[150:153], v[198:201], v[106:109]
	v_mfma_i32_16x16x64_i8 v[98:101], v[158:161], v[198:201], v[98:101]
	v_mfma_i32_16x16x64_i8 v[90:93], v[150:153], v[206:209], v[90:93]
	v_mfma_i32_16x16x64_i8 v[82:85], v[158:161], v[206:209], v[82:85]
	s_setprio 0
	s_setprio 1
	v_mfma_i32_16x16x64_i8 v[110:113], v[162:165], v[178:181], v[110:113]
	v_mfma_i32_16x16x64_i8 v[102:105], v[170:173], v[178:181], v[102:105]
	v_mfma_i32_16x16x64_i8 v[94:97], v[162:165], v[186:189], v[94:97]
	v_mfma_i32_16x16x64_i8 v[86:89], v[170:173], v[186:189], v[86:89]
	v_mfma_i32_16x16x64_i8 v[78:81], v[162:165], v[194:197], v[78:81]
	v_mfma_i32_16x16x64_i8 v[74:77], v[170:173], v[194:197], v[74:77]
	v_mfma_i32_16x16x64_i8 v[70:73], v[162:165], v[202:205], v[70:73]
	v_mfma_i32_16x16x64_i8 v[66:69], v[170:173], v[202:205], v[66:69]
	v_mfma_i32_16x16x64_i8 v[110:113], v[166:169], v[182:185], v[110:113]
	v_mfma_i32_16x16x64_i8 v[102:105], v[174:177], v[182:185], v[102:105]
	v_mfma_i32_16x16x64_i8 v[94:97], v[166:169], v[190:193], v[94:97]
	v_mfma_i32_16x16x64_i8 v[86:89], v[174:177], v[190:193], v[86:89]
	v_mfma_i32_16x16x64_i8 v[78:81], v[166:169], v[198:201], v[78:81]
	v_mfma_i32_16x16x64_i8 v[74:77], v[174:177], v[198:201], v[74:77]
	v_mfma_i32_16x16x64_i8 v[70:73], v[166:169], v[206:209], v[70:73]
	v_mfma_i32_16x16x64_i8 v[66:69], v[174:177], v[206:209], v[66:69]
	s_setprio 0
	s_barrier
	s_add_i32 s17, s17, s62
	v_lshl_add_u64 v[210:211], v[210:211], 0, s[36:37]
	s_mov_b32 m0, s17
	ds_read_b128 v[178:181], v229 offset:49152
	ds_read_b128 v[182:185], v229 offset:50176
	ds_read_b128 v[186:189], v229 offset:51200
	ds_read_b128 v[190:193], v229 offset:52224
	ds_read_b128 v[194:197], v229 offset:53248
	ds_read_b128 v[198:201], v229 offset:54272
	ds_read_b128 v[202:205], v229 offset:55296
	ds_read_b128 v[206:209], v229 offset:56320
	global_load_lds_dwordx4 v[210:211], off
	v_lshl_add_u64 v[210:211], v[212:213], 0, s[36:37]
	s_add_i32 m0, s17, 0x2000
	s_add_i32 s17, s54, s62
	global_load_lds_dwordx4 v[210:211], off
	v_lshl_add_u64 v[210:211], v[214:215], 0, s[36:37]
	s_mov_b32 m0, s17
	s_nop 0
	global_load_lds_dwordx4 v[210:211], off
	v_lshl_add_u64 v[210:211], v[216:217], 0, s[36:37]
	s_add_i32 m0, s17, 0x2000
	s_nop 0
	global_load_lds_dwordx4 v[210:211], off
	v_lshl_add_u64 v[210:211], v[218:219], 0, s[36:37]
	s_mov_b32 m0, s95
	s_nop 0
	global_load_lds_dwordx4 v[210:211], off
	v_lshl_add_u64 v[210:211], v[220:221], 0, s[36:37]
	s_mov_b32 m0, s80
	s_nop 0
	global_load_lds_dwordx4 v[210:211], off
	s_waitcnt vmcnt(8)
	s_waitcnt lgkmcnt(0)
	s_setprio 1
	s_waitcnt lgkmcnt(0)
	v_mfma_i32_16x16x64_i8 v[62:65], v[146:149], v[178:181], v[62:65]
	v_mfma_i32_16x16x64_i8 v[58:61], v[154:157], v[178:181], v[58:61]
	s_barrier
	v_mfma_i32_16x16x64_i8 v[54:57], v[146:149], v[186:189], v[54:57]
	v_mfma_i32_16x16x64_i8 v[50:53], v[154:157], v[186:189], v[50:53]
	v_mfma_i32_16x16x64_i8 v[42:45], v[146:149], v[194:197], v[42:45]
	v_mfma_i32_16x16x64_i8 v[34:37], v[154:157], v[194:197], v[34:37]
	v_mfma_i32_16x16x64_i8 v[26:29], v[146:149], v[202:205], v[26:29]
	v_mfma_i32_16x16x64_i8 v[18:21], v[154:157], v[202:205], v[18:21]
	v_mfma_i32_16x16x64_i8 v[62:65], v[150:153], v[182:185], v[62:65]
	v_mfma_i32_16x16x64_i8 v[58:61], v[158:161], v[182:185], v[58:61]
	v_mfma_i32_16x16x64_i8 v[54:57], v[150:153], v[190:193], v[54:57]
	v_mfma_i32_16x16x64_i8 v[50:53], v[158:161], v[190:193], v[50:53]
	v_mfma_i32_16x16x64_i8 v[42:45], v[150:153], v[198:201], v[42:45]
	v_mfma_i32_16x16x64_i8 v[34:37], v[158:161], v[198:201], v[34:37]
	v_mfma_i32_16x16x64_i8 v[26:29], v[150:153], v[206:209], v[26:29]
	v_mfma_i32_16x16x64_i8 v[18:21], v[158:161], v[206:209], v[18:21]
	s_setprio 0
	s_setprio 1
	v_mfma_i32_16x16x64_i8 v[46:49], v[162:165], v[178:181], v[46:49]
	v_mfma_i32_16x16x64_i8 v[38:41], v[170:173], v[178:181], v[38:41]
	v_mfma_i32_16x16x64_i8 v[30:33], v[162:165], v[186:189], v[30:33]
	v_mfma_i32_16x16x64_i8 v[22:25], v[170:173], v[186:189], v[22:25]
	v_mfma_i32_16x16x64_i8 v[14:17], v[162:165], v[194:197], v[14:17]
	v_mfma_i32_16x16x64_i8 v[10:13], v[170:173], v[194:197], v[10:13]
	v_mfma_i32_16x16x64_i8 v[6:9], v[162:165], v[202:205], v[6:9]
	v_mfma_i32_16x16x64_i8 v[2:5], v[170:173], v[202:205], v[2:5]
	v_mfma_i32_16x16x64_i8 v[46:49], v[166:169], v[182:185], v[46:49]
	v_mfma_i32_16x16x64_i8 v[38:41], v[174:177], v[182:185], v[38:41]
	v_mfma_i32_16x16x64_i8 v[30:33], v[166:169], v[190:193], v[30:33]
	v_mfma_i32_16x16x64_i8 v[22:25], v[174:177], v[190:193], v[22:25]
	v_mfma_i32_16x16x64_i8 v[14:17], v[166:169], v[198:201], v[14:17]
	v_mfma_i32_16x16x64_i8 v[10:13], v[174:177], v[198:201], v[10:13]
	v_mfma_i32_16x16x64_i8 v[6:9], v[166:169], v[206:209], v[6:9]
	v_mfma_i32_16x16x64_i8 v[2:5], v[174:177], v[206:209], v[2:5]
	s_setprio 0
	s_add_u32 s46, s46, 0x100
	s_addc_u32 s47, s47, 0
	s_add_u32 vcc_lo, vcc_lo, 0x100
	s_addc_u32 vcc_hi, vcc_hi, 0
	s_cmp_ge_i32 s16, s90
	s_mov_b32 s50, s16
	s_barrier
	s_cbranch_scc0 .LBB0_895
	v_cvt_f32_i32_e32 v220, v126
	v_cvt_f32_i32_e32 v221, v127
	v_cvt_f32_i32_e32 v218, v128
	v_cvt_f32_i32_e32 v219, v129
	v_cvt_f32_i32_e32 v224, v122
	v_cvt_f32_i32_e32 v225, v123
	v_cvt_f32_i32_e32 v222, v124
	v_cvt_f32_i32_e32 v223, v125
	v_cvt_f32_i32_e32 v212, v110
	v_cvt_f32_i32_e32 v213, v111
	v_cvt_f32_i32_e32 v210, v112
	v_cvt_f32_i32_e32 v211, v113
	v_cvt_f32_i32_e32 v216, v102
	v_cvt_f32_i32_e32 v217, v103
	v_cvt_f32_i32_e32 v214, v104
	v_cvt_f32_i32_e32 v215, v105
	v_cvt_f32_i32_e32 v204, v118
	v_cvt_f32_i32_e32 v205, v119
	v_cvt_f32_i32_e32 v202, v120
	v_cvt_f32_i32_e32 v203, v121
	v_cvt_f32_i32_e32 v208, v114
	v_cvt_f32_i32_e32 v209, v115
	v_cvt_f32_i32_e32 v206, v116
	v_cvt_f32_i32_e32 v207, v117
	v_cvt_f32_i32_e32 v198, v94
	v_cvt_f32_i32_e32 v199, v95
	v_cvt_f32_i32_e32 v194, v96
	v_cvt_f32_i32_e32 v195, v97
	v_cvt_f32_i32_e32 v200, v86
	v_cvt_f32_i32_e32 v201, v87
	v_cvt_f32_i32_e32 v196, v88
	v_cvt_f32_i32_e32 v197, v89
	v_cvt_f32_i32_e32 v188, v106
	v_cvt_f32_i32_e32 v189, v107
	v_cvt_f32_i32_e32 v186, v108
	v_cvt_f32_i32_e32 v187, v109
	v_cvt_f32_i32_e32 v192, v98
	v_cvt_f32_i32_e32 v193, v99
	v_cvt_f32_i32_e32 v190, v100
	v_cvt_f32_i32_e32 v191, v101
	v_cvt_f32_i32_e32 v182, v78
	v_cvt_f32_i32_e32 v183, v79
	v_cvt_f32_i32_e32 v178, v80
	v_cvt_f32_i32_e32 v179, v81
	v_cvt_f32_i32_e32 v184, v74
	v_cvt_f32_i32_e32 v185, v75
	v_cvt_f32_i32_e32 v180, v76
	v_cvt_f32_i32_e32 v181, v77
	v_cvt_f32_i32_e32 v170, v90
	v_cvt_f32_i32_e32 v171, v91
	v_cvt_f32_i32_e32 v168, v92
	v_cvt_f32_i32_e32 v169, v93
	v_cvt_f32_i32_e32 v174, v82
	v_cvt_f32_i32_e32 v175, v83
	v_cvt_f32_i32_e32 v172, v84
	v_cvt_f32_i32_e32 v173, v85
	v_cvt_f32_i32_e32 v164, v70
	v_cvt_f32_i32_e32 v165, v71
	v_cvt_f32_i32_e32 v160, v72
	v_cvt_f32_i32_e32 v161, v73
	v_cvt_f32_i32_e32 v166, v66
	v_cvt_f32_i32_e32 v167, v67
	v_cvt_f32_i32_e32 v162, v68
	v_cvt_f32_i32_e32 v163, v69
	v_cvt_f32_i32_e32 v154, v62
	v_cvt_f32_i32_e32 v155, v63
	v_cvt_f32_i32_e32 v152, v64
	v_cvt_f32_i32_e32 v153, v65
	v_cvt_f32_i32_e32 v158, v58
	v_cvt_f32_i32_e32 v159, v59
	v_cvt_f32_i32_e32 v156, v60
	v_cvt_f32_i32_e32 v157, v61
	v_cvt_f32_i32_e32 v148, v46
	v_cvt_f32_i32_e32 v149, v47
	v_cvt_f32_i32_e32 v128, v48
	v_cvt_f32_i32_e32 v129, v49
	v_cvt_f32_i32_e32 v150, v38
	v_cvt_f32_i32_e32 v151, v39
	v_cvt_f32_i32_e32 v146, v40
	v_cvt_f32_i32_e32 v147, v41
	v_cvt_f32_i32_e32 v122, v54
	v_cvt_f32_i32_e32 v123, v55
	v_cvt_f32_i32_e32 v120, v56
	v_cvt_f32_i32_e32 v121, v57
	v_cvt_f32_i32_e32 v126, v50
	v_cvt_f32_i32_e32 v127, v51
	v_cvt_f32_i32_e32 v124, v52
	v_cvt_f32_i32_e32 v125, v53
	v_cvt_f32_i32_e32 v114, v30
	v_cvt_f32_i32_e32 v115, v31
	v_cvt_f32_i32_e32 v110, v32
	v_cvt_f32_i32_e32 v111, v33
	v_cvt_f32_i32_e32 v116, v22
	v_cvt_f32_i32_e32 v117, v23
	v_cvt_f32_i32_e32 v112, v24
	v_cvt_f32_i32_e32 v113, v25
	v_cvt_f32_i32_e32 v102, v42
	v_cvt_f32_i32_e32 v103, v43
	v_cvt_f32_i32_e32 v100, v44
	v_cvt_f32_i32_e32 v101, v45
	v_cvt_f32_i32_e32 v106, v34
	v_cvt_f32_i32_e32 v107, v35
	v_cvt_f32_i32_e32 v104, v36
	v_cvt_f32_i32_e32 v105, v37
	v_cvt_f32_i32_e32 v96, v14
	v_cvt_f32_i32_e32 v97, v15
	v_cvt_f32_i32_e32 v92, v16
	v_cvt_f32_i32_e32 v93, v17
	v_cvt_f32_i32_e32 v98, v10
	v_cvt_f32_i32_e32 v99, v11
	v_cvt_f32_i32_e32 v94, v12
	v_cvt_f32_i32_e32 v95, v13
	v_cvt_f32_i32_e32 v52, v26
	v_cvt_f32_i32_e32 v53, v27
	v_cvt_f32_i32_e32 v50, v28
	v_cvt_f32_i32_e32 v51, v29
	v_cvt_f32_i32_e32 v56, v18
	v_cvt_f32_i32_e32 v57, v19
	v_cvt_f32_i32_e32 v54, v20
	v_cvt_f32_i32_e32 v55, v21
	v_cvt_f32_i32_e32 v46, v6
	v_cvt_f32_i32_e32 v47, v7
	v_cvt_f32_i32_e32 v42, v8
	v_cvt_f32_i32_e32 v43, v9
	v_cvt_f32_i32_e32 v48, v2
	v_cvt_f32_i32_e32 v49, v3
	v_cvt_f32_i32_e32 v44, v4
	v_cvt_f32_i32_e32 v45, v5

.LBB0_1087:
	v_add_u32_e32 v138, s80, v188
	ds_read_b128 v[148:151], v138
	ds_read_b128 v[152:155], v138 offset:1024
	ds_read_b128 v[156:159], v138 offset:2048
	ds_read_b128 v[160:163], v138 offset:3072
	v_add_u32_e32 v138, s81, v188
	ds_read_b128 v[164:167], v138
	ds_read_b128 v[168:171], v138 offset:1024
	ds_read_b128 v[172:175], v138 offset:2048
	ds_read_b128 v[176:179], v138 offset:3072
	s_add_i32 s84, s34, 2
	s_add_u32 s85, s30, 0x80
	s_addc_u32 s35, s31, 0
	s_cmp_eq_u32 s64, s34
	s_cselect_b32 s34, s2, s85
	s_cselect_b32 s35, s3, s35
	s_cselect_b32 s87, s29, s39
	s_cselect_b32 s86, s28, s38
	v_lshl_add_u64 v[184:185], s[30:31], 0, v[140:141]
	s_add_i32 m0, s50, 0xc000
	ds_read_b128 v[180:183], v189
	ds_read_b128 v[190:193], v189 offset:1024
	ds_read_b128 v[194:197], v189 offset:2048
	ds_read_b128 v[198:201], v189 offset:3072
	ds_read_b128 v[202:205], v189 offset:4096
	ds_read_b128 v[206:209], v189 offset:5120
	ds_read_b128 v[210:213], v189 offset:6144
	ds_read_b128 v[214:217], v189 offset:7168
	global_load_lds_dwordx4 v[184:185], off
	v_lshl_add_u64 v[184:185], s[30:31], 0, v[142:143]
	s_add_i32 m0, s50, 0xe000
	s_nop 0
	global_load_lds_dwordx4 v[184:185], off
	s_waitcnt vmcnt(8)
	s_waitcnt lgkmcnt(0)
	s_setprio 1
	s_waitcnt lgkmcnt(0)
	v_mfma_i32_16x16x64_i8 v[126:129], v[148:151], v[180:183], v[126:129]
	v_mfma_i32_16x16x64_i8 v[122:125], v[156:159], v[180:183], v[122:125]
	s_barrier
	v_mfma_i32_16x16x64_i8 v[118:121], v[148:151], v[194:197], v[118:121]
	v_mfma_i32_16x16x64_i8 v[114:117], v[156:159], v[194:197], v[114:117]
	v_mfma_i32_16x16x64_i8 v[106:109], v[148:151], v[202:205], v[106:109]
	v_mfma_i32_16x16x64_i8 v[98:101], v[156:159], v[202:205], v[98:101]
	v_mfma_i32_16x16x64_i8 v[90:93], v[148:151], v[210:213], v[90:93]
	v_mfma_i32_16x16x64_i8 v[82:85], v[156:159], v[210:213], v[82:85]
	v_mfma_i32_16x16x64_i8 v[126:129], v[152:155], v[190:193], v[126:129]
	v_mfma_i32_16x16x64_i8 v[122:125], v[160:163], v[190:193], v[122:125]
	v_mfma_i32_16x16x64_i8 v[118:121], v[152:155], v[198:201], v[118:121]
	v_mfma_i32_16x16x64_i8 v[114:117], v[160:163], v[198:201], v[114:117]
	v_mfma_i32_16x16x64_i8 v[106:109], v[152:155], v[206:209], v[106:109]
	v_mfma_i32_16x16x64_i8 v[98:101], v[160:163], v[206:209], v[98:101]
	v_mfma_i32_16x16x64_i8 v[90:93], v[152:155], v[214:217], v[90:93]
	v_mfma_i32_16x16x64_i8 v[82:85], v[160:163], v[214:217], v[82:85]
	s_setprio 0
	s_setprio 1
	v_mfma_i32_16x16x64_i8 v[110:113], v[164:167], v[180:183], v[110:113]
	v_mfma_i32_16x16x64_i8 v[102:105], v[172:175], v[180:183], v[102:105]
	v_mfma_i32_16x16x64_i8 v[94:97], v[164:167], v[194:197], v[94:97]
	v_mfma_i32_16x16x64_i8 v[86:89], v[172:175], v[194:197], v[86:89]
	v_mfma_i32_16x16x64_i8 v[78:81], v[164:167], v[202:205], v[78:81]
	v_mfma_i32_16x16x64_i8 v[74:77], v[172:175], v[202:205], v[74:77]
	v_mfma_i32_16x16x64_i8 v[70:73], v[164:167], v[210:213], v[70:73]
	v_mfma_i32_16x16x64_i8 v[66:69], v[172:175], v[210:213], v[66:69]
	v_mfma_i32_16x16x64_i8 v[110:113], v[168:171], v[190:193], v[110:113]
	v_mfma_i32_16x16x64_i8 v[102:105], v[176:179], v[190:193], v[102:105]
	v_mfma_i32_16x16x64_i8 v[94:97], v[168:171], v[198:201], v[94:97]
	v_mfma_i32_16x16x64_i8 v[86:89], v[176:179], v[198:201], v[86:89]
	v_mfma_i32_16x16x64_i8 v[78:81], v[168:171], v[206:209], v[78:81]
	v_mfma_i32_16x16x64_i8 v[74:77], v[176:179], v[206:209], v[74:77]
	v_mfma_i32_16x16x64_i8 v[70:73], v[168:171], v[214:217], v[70:73]
	v_mfma_i32_16x16x64_i8 v[66:69], v[176:179], v[214:217], v[66:69]
	s_setprio 0
	s_barrier
	s_add_i32 s85, s80, s47
	v_lshl_add_u64 v[184:185], s[86:87], 0, v[132:133]
	s_mov_b32 m0, s85
	ds_read_b128 v[180:183], v189 offset:16384
	ds_read_b128 v[190:193], v189 offset:17408
	ds_read_b128 v[194:197], v189 offset:18432
	ds_read_b128 v[198:201], v189 offset:19456
	ds_read_b128 v[202:205], v189 offset:20480
	ds_read_b128 v[206:209], v189 offset:21504
	ds_read_b128 v[210:213], v189 offset:22528
	ds_read_b128 v[214:217], v189 offset:23552
	global_load_lds_dwordx4 v[184:185], off
	s_add_i32 m0, s85, 0x2000
	v_lshl_add_u64 v[218:219], s[86:87], 0, v[136:137]
	s_add_u32 s86, s86, s6
	s_addc_u32 s87, s87, s7
	s_add_i32 s85, s81, s47
	global_load_lds_dwordx4 v[218:219], off
	v_lshl_add_u64 v[220:221], s[86:87], 0, v[132:133]
	s_mov_b32 m0, s85
	v_lshl_add_u64 v[222:223], s[86:87], 0, v[136:137]
	global_load_lds_dwordx4 v[220:221], off
	s_add_i32 m0, s85, 0x2000
	v_lshl_add_u64 v[224:225], s[34:35], 0, v[130:131]
	global_load_lds_dwordx4 v[222:223], off
	s_mov_b32 m0, s50
	v_lshl_add_u64 v[226:227], s[34:35], 0, v[134:135]
	global_load_lds_dwordx4 v[224:225], off
	s_mov_b32 m0, s51
	s_nop 0
	global_load_lds_dwordx4 v[226:227], off
	s_waitcnt vmcnt(8)
	s_waitcnt lgkmcnt(0)
	s_setprio 1
	s_waitcnt lgkmcnt(0)
	v_mfma_i32_16x16x64_i8 v[62:65], v[148:151], v[180:183], v[62:65]
	v_mfma_i32_16x16x64_i8 v[58:61], v[156:159], v[180:183], v[58:61]
	s_barrier
	v_mfma_i32_16x16x64_i8 v[54:57], v[148:151], v[194:197], v[54:57]
	v_mfma_i32_16x16x64_i8 v[50:53], v[156:159], v[194:197], v[50:53]
	v_mfma_i32_16x16x64_i8 v[42:45], v[148:151], v[202:205], v[42:45]
	v_mfma_i32_16x16x64_i8 v[34:37], v[156:159], v[202:205], v[34:37]
	v_mfma_i32_16x16x64_i8 v[26:29], v[148:151], v[210:213], v[26:29]
	v_mfma_i32_16x16x64_i8 v[18:21], v[156:159], v[210:213], v[18:21]
	v_mfma_i32_16x16x64_i8 v[62:65], v[152:155], v[190:193], v[62:65]
	v_mfma_i32_16x16x64_i8 v[58:61], v[160:163], v[190:193], v[58:61]
	v_mfma_i32_16x16x64_i8 v[54:57], v[152:155], v[198:201], v[54:57]
	v_mfma_i32_16x16x64_i8 v[50:53], v[160:163], v[198:201], v[50:53]
	v_mfma_i32_16x16x64_i8 v[42:45], v[152:155], v[206:209], v[42:45]
	v_mfma_i32_16x16x64_i8 v[34:37], v[160:163], v[206:209], v[34:37]
	v_mfma_i32_16x16x64_i8 v[26:29], v[152:155], v[214:217], v[26:29]
	v_mfma_i32_16x16x64_i8 v[18:21], v[160:163], v[214:217], v[18:21]
	s_setprio 0
	s_setprio 1
	v_mfma_i32_16x16x64_i8 v[46:49], v[164:167], v[180:183], v[46:49]
	v_mfma_i32_16x16x64_i8 v[38:41], v[172:175], v[180:183], v[38:41]
	v_mfma_i32_16x16x64_i8 v[30:33], v[164:167], v[194:197], v[30:33]
	v_mfma_i32_16x16x64_i8 v[22:25], v[172:175], v[194:197], v[22:25]
	v_mfma_i32_16x16x64_i8 v[14:17], v[164:167], v[202:205], v[14:17]
	v_mfma_i32_16x16x64_i8 v[10:13], v[172:175], v[202:205], v[10:13]
	v_mfma_i32_16x16x64_i8 v[6:9], v[164:167], v[210:213], v[6:9]
	v_mfma_i32_16x16x64_i8 v[2:5], v[172:175], v[210:213], v[2:5]
	v_mfma_i32_16x16x64_i8 v[46:49], v[168:171], v[190:193], v[46:49]
	v_mfma_i32_16x16x64_i8 v[38:41], v[176:179], v[190:193], v[38:41]
	v_mfma_i32_16x16x64_i8 v[30:33], v[168:171], v[198:201], v[30:33]
	v_mfma_i32_16x16x64_i8 v[22:25], v[176:179], v[198:201], v[22:25]
	v_mfma_i32_16x16x64_i8 v[14:17], v[168:171], v[206:209], v[14:17]
	v_mfma_i32_16x16x64_i8 v[10:13], v[176:179], v[206:209], v[10:13]
	v_mfma_i32_16x16x64_i8 v[6:9], v[168:171], v[214:217], v[6:9]
	v_mfma_i32_16x16x64_i8 v[2:5], v[176:179], v[214:217], v[2:5]
	s_setprio 0
	s_barrier
	s_add_i32 s85, 0, 0x18000
	v_add_u32_e32 v138, s85, v188
	s_add_i32 s86, 0, 0x1c000
	ds_read_b128 v[148:151], v138
	ds_read_b128 v[152:155], v138 offset:1024
	ds_read_b128 v[156:159], v138 offset:2048
	ds_read_b128 v[160:163], v138 offset:3072
	v_add_u32_e32 v138, s86, v188
	ds_read_b128 v[164:167], v138
	ds_read_b128 v[168:171], v138 offset:1024
	ds_read_b128 v[172:175], v138 offset:2048
	ds_read_b128 v[176:179], v138 offset:3072
	s_add_u32 s34, s34, s6
	s_addc_u32 s35, s35, s7
	s_mov_b32 m0, s54
	v_lshl_add_u64 v[228:229], s[34:35], 0, v[130:131]
	ds_read_b128 v[180:183], v189 offset:32768
	ds_read_b128 v[190:193], v189 offset:33792
	ds_read_b128 v[194:197], v189 offset:34816
	ds_read_b128 v[198:201], v189 offset:35840
	ds_read_b128 v[202:205], v189 offset:36864
	ds_read_b128 v[206:209], v189 offset:37888
	ds_read_b128 v[210:213], v189 offset:38912
	ds_read_b128 v[214:217], v189 offset:39936
	global_load_lds_dwordx4 v[228:229], off
	v_lshl_add_u64 v[228:229], s[34:35], 0, v[134:135]
	s_mov_b32 m0, s55
	s_nop 0
	global_load_lds_dwordx4 v[228:229], off
	s_waitcnt vmcnt(8)
	s_waitcnt lgkmcnt(0)
	s_setprio 1
	s_waitcnt lgkmcnt(0)
	v_mfma_i32_16x16x64_i8 v[126:129], v[148:151], v[180:183], v[126:129]
	v_mfma_i32_16x16x64_i8 v[122:125], v[156:159], v[180:183], v[122:125]
	s_barrier
	v_mfma_i32_16x16x64_i8 v[118:121], v[148:151], v[194:197], v[118:121]
	v_mfma_i32_16x16x64_i8 v[114:117], v[156:159], v[194:197], v[114:117]
	v_mfma_i32_16x16x64_i8 v[106:109], v[148:151], v[202:205], v[106:109]
	v_mfma_i32_16x16x64_i8 v[98:101], v[156:159], v[202:205], v[98:101]
	v_mfma_i32_16x16x64_i8 v[90:93], v[148:151], v[210:213], v[90:93]
	v_mfma_i32_16x16x64_i8 v[82:85], v[156:159], v[210:213], v[82:85]
	v_mfma_i32_16x16x64_i8 v[126:129], v[152:155], v[190:193], v[126:129]
	v_mfma_i32_16x16x64_i8 v[122:125], v[160:163], v[190:193], v[122:125]
	v_mfma_i32_16x16x64_i8 v[118:121], v[152:155], v[198:201], v[118:121]
	v_mfma_i32_16x16x64_i8 v[114:117], v[160:163], v[198:201], v[114:117]
	v_mfma_i32_16x16x64_i8 v[106:109], v[152:155], v[206:209], v[106:109]
	v_mfma_i32_16x16x64_i8 v[98:101], v[160:163], v[206:209], v[98:101]
	v_mfma_i32_16x16x64_i8 v[90:93], v[152:155], v[214:217], v[90:93]
	v_mfma_i32_16x16x64_i8 v[82:85], v[160:163], v[214:217], v[82:85]
	s_setprio 0
	s_setprio 1
	v_mfma_i32_16x16x64_i8 v[110:113], v[164:167], v[180:183], v[110:113]
	v_mfma_i32_16x16x64_i8 v[102:105], v[172:175], v[180:183], v[102:105]
	v_mfma_i32_16x16x64_i8 v[94:97], v[164:167], v[194:197], v[94:97]
	v_mfma_i32_16x16x64_i8 v[86:89], v[172:175], v[194:197], v[86:89]
	v_mfma_i32_16x16x64_i8 v[78:81], v[164:167], v[202:205], v[78:81]
	v_mfma_i32_16x16x64_i8 v[74:77], v[172:175], v[202:205], v[74:77]
	v_mfma_i32_16x16x64_i8 v[70:73], v[164:167], v[210:213], v[70:73]
	v_mfma_i32_16x16x64_i8 v[66:69], v[172:175], v[210:213], v[66:69]
	v_mfma_i32_16x16x64_i8 v[110:113], v[168:171], v[190:193], v[110:113]
	v_mfma_i32_16x16x64_i8 v[102:105], v[176:179], v[190:193], v[102:105]
	v_mfma_i32_16x16x64_i8 v[94:97], v[168:171], v[198:201], v[94:97]
	v_mfma_i32_16x16x64_i8 v[86:89], v[176:179], v[198:201], v[86:89]
	v_mfma_i32_16x16x64_i8 v[78:81], v[168:171], v[206:209], v[78:81]
	v_mfma_i32_16x16x64_i8 v[74:77], v[176:179], v[206:209], v[74:77]
	v_mfma_i32_16x16x64_i8 v[70:73], v[168:171], v[214:217], v[70:73]
	v_mfma_i32_16x16x64_i8 v[66:69], v[176:179], v[214:217], v[66:69]
	s_setprio 0
	s_barrier
	s_add_i32 s34, s85, s47
	v_lshl_add_u64 v[184:185], v[184:185], 0, s[22:23]
	s_mov_b32 m0, s34
	ds_read_b128 v[180:183], v189 offset:49152
	ds_read_b128 v[190:193], v189 offset:50176
	ds_read_b128 v[194:197], v189 offset:51200
	ds_read_b128 v[198:201], v189 offset:52224
	ds_read_b128 v[202:205], v189 offset:53248
	ds_read_b128 v[206:209], v189 offset:54272
	ds_read_b128 v[210:213], v189 offset:55296
	ds_read_b128 v[214:217], v189 offset:56320
	global_load_lds_dwordx4 v[184:185], off
	v_lshl_add_u64 v[184:185], v[218:219], 0, s[22:23]
	s_add_i32 m0, s34, 0x2000
	s_add_i32 s34, s86, s47
	global_load_lds_dwordx4 v[184:185], off
	v_lshl_add_u64 v[184:185], v[220:221], 0, s[22:23]
	s_mov_b32 m0, s34
	s_nop 0
	global_load_lds_dwordx4 v[184:185], off
	v_lshl_add_u64 v[184:185], v[222:223], 0, s[22:23]
	s_add_i32 m0, s34, 0x2000
	s_nop 0
	global_load_lds_dwordx4 v[184:185], off
	v_lshl_add_u64 v[184:185], v[224:225], 0, s[22:23]
	s_mov_b32 m0, s59
	s_nop 0
	global_load_lds_dwordx4 v[184:185], off
	v_lshl_add_u64 v[184:185], v[226:227], 0, s[22:23]
	s_mov_b32 m0, s60
	s_nop 0
	global_load_lds_dwordx4 v[184:185], off
	s_waitcnt vmcnt(8)
	s_waitcnt lgkmcnt(0)
	s_setprio 1
	s_waitcnt lgkmcnt(0)
	v_mfma_i32_16x16x64_i8 v[62:65], v[148:151], v[180:183], v[62:65]
	v_mfma_i32_16x16x64_i8 v[58:61], v[156:159], v[180:183], v[58:61]
	s_barrier
	v_mfma_i32_16x16x64_i8 v[54:57], v[148:151], v[194:197], v[54:57]
	v_mfma_i32_16x16x64_i8 v[50:53], v[156:159], v[194:197], v[50:53]
	v_mfma_i32_16x16x64_i8 v[42:45], v[148:151], v[202:205], v[42:45]
	v_mfma_i32_16x16x64_i8 v[34:37], v[156:159], v[202:205], v[34:37]
	v_mfma_i32_16x16x64_i8 v[26:29], v[148:151], v[210:213], v[26:29]
	v_mfma_i32_16x16x64_i8 v[18:21], v[156:159], v[210:213], v[18:21]
	v_mfma_i32_16x16x64_i8 v[62:65], v[152:155], v[190:193], v[62:65]
	v_mfma_i32_16x16x64_i8 v[58:61], v[160:163], v[190:193], v[58:61]
	v_mfma_i32_16x16x64_i8 v[54:57], v[152:155], v[198:201], v[54:57]
	v_mfma_i32_16x16x64_i8 v[50:53], v[160:163], v[198:201], v[50:53]
	v_mfma_i32_16x16x64_i8 v[42:45], v[152:155], v[206:209], v[42:45]
	v_mfma_i32_16x16x64_i8 v[34:37], v[160:163], v[206:209], v[34:37]
	v_mfma_i32_16x16x64_i8 v[26:29], v[152:155], v[214:217], v[26:29]
	v_mfma_i32_16x16x64_i8 v[18:21], v[160:163], v[214:217], v[18:21]
	s_setprio 0
	s_setprio 1
	v_mfma_i32_16x16x64_i8 v[46:49], v[164:167], v[180:183], v[46:49]
	v_mfma_i32_16x16x64_i8 v[38:41], v[172:175], v[180:183], v[38:41]
	v_mfma_i32_16x16x64_i8 v[30:33], v[164:167], v[194:197], v[30:33]
	v_mfma_i32_16x16x64_i8 v[22:25], v[172:175], v[194:197], v[22:25]
	v_mfma_i32_16x16x64_i8 v[14:17], v[164:167], v[202:205], v[14:17]
	v_mfma_i32_16x16x64_i8 v[10:13], v[172:175], v[202:205], v[10:13]
	v_mfma_i32_16x16x64_i8 v[6:9], v[164:167], v[210:213], v[6:9]
	v_mfma_i32_16x16x64_i8 v[2:5], v[172:175], v[210:213], v[2:5]
	v_mfma_i32_16x16x64_i8 v[46:49], v[168:171], v[190:193], v[46:49]
	v_mfma_i32_16x16x64_i8 v[38:41], v[176:179], v[190:193], v[38:41]
	v_mfma_i32_16x16x64_i8 v[30:33], v[168:171], v[198:201], v[30:33]
	v_mfma_i32_16x16x64_i8 v[22:25], v[176:179], v[198:201], v[22:25]
	v_mfma_i32_16x16x64_i8 v[14:17], v[168:171], v[206:209], v[14:17]
	v_mfma_i32_16x16x64_i8 v[10:13], v[176:179], v[206:209], v[10:13]
	v_mfma_i32_16x16x64_i8 v[6:9], v[168:171], v[214:217], v[6:9]
	v_mfma_i32_16x16x64_i8 v[2:5], v[176:179], v[214:217], v[2:5]
	s_setprio 0
	s_add_u32 s30, s30, 0x100
	s_addc_u32 s31, s31, 0
	s_add_u32 s38, s38, 0x100
	s_addc_u32 s39, s39, 0
	s_cmp_ge_i32 s84, s61
	s_mov_b32 s34, s84
	s_barrier
	s_cbranch_scc0 .LBB0_1087
	v_cvt_f32_i32_e32 v172, v126
	v_cvt_f32_i32_e32 v173, v127
	v_cvt_f32_i32_e32 v170, v128
	v_cvt_f32_i32_e32 v171, v129
	v_cvt_f32_i32_e32 v174, v122
	v_cvt_f32_i32_e32 v175, v123
	v_cvt_f32_i32_e32 v176, v124
	v_cvt_f32_i32_e32 v177, v125
	v_cvt_f32_i32_e32 v180, v110
	v_cvt_f32_i32_e32 v181, v111
	v_cvt_f32_i32_e32 v182, v112
	v_cvt_f32_i32_e32 v183, v113
	v_cvt_f32_i32_e32 v178, v102
	v_cvt_f32_i32_e32 v179, v103
	v_cvt_f32_i32_e32 v184, v104
	v_cvt_f32_i32_e32 v185, v105
	v_cvt_f32_i32_e32 v152, v118
	v_cvt_f32_i32_e32 v153, v119
	v_cvt_f32_i32_e32 v154, v120
	v_cvt_f32_i32_e32 v155, v121
	v_cvt_f32_i32_e32 v156, v114
	v_cvt_f32_i32_e32 v157, v115
	v_cvt_f32_i32_e32 v158, v116
	v_cvt_f32_i32_e32 v159, v117
	v_cvt_f32_i32_e32 v160, v94
	v_cvt_f32_i32_e32 v161, v95
	v_cvt_f32_i32_e32 v162, v96
	v_cvt_f32_i32_e32 v163, v97
	v_cvt_f32_i32_e32 v164, v86
	v_cvt_f32_i32_e32 v165, v87
	v_cvt_f32_i32_e32 v166, v88
	v_cvt_f32_i32_e32 v167, v89
	v_cvt_f32_i32_e32 v118, v106
	v_cvt_f32_i32_e32 v119, v107
	v_cvt_f32_i32_e32 v120, v108
	v_cvt_f32_i32_e32 v121, v109
	v_cvt_f32_i32_e32 v122, v98
	v_cvt_f32_i32_e32 v123, v99
	v_cvt_f32_i32_e32 v124, v100
	v_cvt_f32_i32_e32 v125, v101
	v_cvt_f32_i32_e32 v126, v78
	v_cvt_f32_i32_e32 v127, v79
	v_cvt_f32_i32_e32 v128, v80
	v_cvt_f32_i32_e32 v129, v81
	v_cvt_f32_i32_e32 v148, v74
	v_cvt_f32_i32_e32 v149, v75
	v_cvt_f32_i32_e32 v150, v76
	v_cvt_f32_i32_e32 v151, v77
	v_cvt_f32_i32_e32 v102, v90
	v_cvt_f32_i32_e32 v103, v91
	v_cvt_f32_i32_e32 v104, v92
	v_cvt_f32_i32_e32 v105, v93
	v_cvt_f32_i32_e32 v106, v82
	v_cvt_f32_i32_e32 v107, v83
	v_cvt_f32_i32_e32 v108, v84
	v_cvt_f32_i32_e32 v109, v85
	v_cvt_f32_i32_e32 v110, v70
	v_cvt_f32_i32_e32 v111, v71
	v_cvt_f32_i32_e32 v112, v72
	v_cvt_f32_i32_e32 v113, v73
	v_cvt_f32_i32_e32 v114, v66
	v_cvt_f32_i32_e32 v115, v67
	v_cvt_f32_i32_e32 v116, v68
	v_cvt_f32_i32_e32 v117, v69
	v_cvt_f32_i32_e32 v82, v62
	v_cvt_f32_i32_e32 v83, v63
	v_cvt_f32_i32_e32 v84, v64
	v_cvt_f32_i32_e32 v85, v65
	v_cvt_f32_i32_e32 v86, v58
	v_cvt_f32_i32_e32 v87, v59
	v_cvt_f32_i32_e32 v88, v60
	v_cvt_f32_i32_e32 v89, v61
	v_cvt_f32_i32_e32 v92, v46
	v_cvt_f32_i32_e32 v93, v47
	v_cvt_f32_i32_e32 v94, v48
	v_cvt_f32_i32_e32 v95, v49
	v_cvt_f32_i32_e32 v96, v38
	v_cvt_f32_i32_e32 v97, v39
	v_cvt_f32_i32_e32 v98, v40
	v_cvt_f32_i32_e32 v99, v41
	v_cvt_f32_i32_e32 v66, v54
	v_cvt_f32_i32_e32 v67, v55
	v_cvt_f32_i32_e32 v68, v56
	v_cvt_f32_i32_e32 v69, v57
	v_cvt_f32_i32_e32 v70, v50
	v_cvt_f32_i32_e32 v71, v51
	v_cvt_f32_i32_e32 v72, v52
	v_cvt_f32_i32_e32 v73, v53
	v_cvt_f32_i32_e32 v74, v30
	v_cvt_f32_i32_e32 v75, v31
	v_cvt_f32_i32_e32 v76, v32
	v_cvt_f32_i32_e32 v77, v33
	v_cvt_f32_i32_e32 v78, v22
	v_cvt_f32_i32_e32 v79, v23
	v_cvt_f32_i32_e32 v80, v24
	v_cvt_f32_i32_e32 v81, v25
	v_cvt_f32_i32_e32 v50, v42
	v_cvt_f32_i32_e32 v51, v43
	v_cvt_f32_i32_e32 v52, v44
	v_cvt_f32_i32_e32 v53, v45
	v_cvt_f32_i32_e32 v54, v34
	v_cvt_f32_i32_e32 v55, v35
	v_cvt_f32_i32_e32 v56, v36
	v_cvt_f32_i32_e32 v57, v37
	v_cvt_f32_i32_e32 v58, v14
	v_cvt_f32_i32_e32 v59, v15
	v_cvt_f32_i32_e32 v60, v16
	v_cvt_f32_i32_e32 v61, v17
	v_cvt_f32_i32_e32 v62, v10
	v_cvt_f32_i32_e32 v63, v11
	v_cvt_f32_i32_e32 v64, v12
	v_cvt_f32_i32_e32 v65, v13
	v_cvt_f32_i32_e32 v34, v26
	v_cvt_f32_i32_e32 v35, v27
	v_cvt_f32_i32_e32 v36, v28
	v_cvt_f32_i32_e32 v37, v29
	v_cvt_f32_i32_e32 v38, v18
	v_cvt_f32_i32_e32 v39, v19
	v_cvt_f32_i32_e32 v40, v20
	v_cvt_f32_i32_e32 v41, v21
	v_cvt_f32_i32_e32 v42, v6
	v_cvt_f32_i32_e32 v43, v7
	v_cvt_f32_i32_e32 v44, v8
	v_cvt_f32_i32_e32 v45, v9
	v_cvt_f32_i32_e32 v46, v2
	v_cvt_f32_i32_e32 v47, v3
	v_cvt_f32_i32_e32 v48, v4
	v_cvt_f32_i32_e32 v49, v5

.LBB0_1170:
	s_waitcnt lgkmcnt(0)
	ds_read_b128 v[114:117], v209
	ds_read_b128 v[118:121], v209 offset:1024
	ds_read_b128 v[122:125], v209 offset:2048
	ds_read_b128 v[126:129], v209 offset:3072
	ds_read_b128 v[146:149], v210
	ds_read_b128 v[150:153], v210 offset:1024
	ds_read_b128 v[154:157], v210 offset:2048
	ds_read_b128 v[158:161], v210 offset:3072
	s_add_i32 s92, s42, 2
	s_add_u32 s43, s38, 0x4000
	s_addc_u32 s44, s39, 0
	s_cmp_eq_u32 s81, s42
	s_cselect_b32 s45, s5, s44
	s_cselect_b32 s44, s4, s43
	s_cselect_b32 s94, s36, s90
	s_cselect_b32 s95, s37, s91
	s_add_u32 s42, s44, 0x8000
	s_addc_u32 s43, s45, 0
	v_lshl_add_u64 v[218:219], s[38:39], 0, v[170:171]
	s_add_i32 m0, s55, 0xc000
	ds_read_b128 v[178:181], v211
	ds_read_b128 v[182:185], v211 offset:1024
	ds_read_b128 v[186:189], v211 offset:2048
	ds_read_b128 v[190:193], v211 offset:3072
	ds_read_b128 v[194:197], v211 offset:4096
	ds_read_b128 v[198:201], v211 offset:5120
	ds_read_b128 v[202:205], v211 offset:6144
	ds_read_b128 v[214:217], v211 offset:7168
	global_load_lds_dwordx4 v[218:219], off
	v_lshl_add_u64 v[218:219], s[38:39], 0, v[172:173]
	s_add_i32 m0, s55, 0xe000
	s_nop 0
	global_load_lds_dwordx4 v[218:219], off
	s_waitcnt vmcnt(8)
	s_waitcnt lgkmcnt(0)
	s_setprio 1
	s_waitcnt lgkmcnt(0)
	v_mfma_f32_16x16x32_bf16 v[142:145], v[114:117], v[178:181], v[142:145]
	v_mfma_f32_16x16x32_bf16 v[138:141], v[122:125], v[178:181], v[138:141]
	s_barrier
	v_mfma_f32_16x16x32_bf16 v[110:113], v[114:117], v[186:189], v[110:113]
	v_mfma_f32_16x16x32_bf16 v[106:109], v[122:125], v[186:189], v[106:109]
	v_mfma_f32_16x16x32_bf16 v[94:97], v[114:117], v[194:197], v[94:97]
	v_mfma_f32_16x16x32_bf16 v[90:93], v[122:125], v[194:197], v[90:93]
	v_mfma_f32_16x16x32_bf16 v[78:81], v[114:117], v[202:205], v[78:81]
	v_mfma_f32_16x16x32_bf16 v[74:77], v[122:125], v[202:205], v[74:77]
	v_mfma_f32_16x16x32_bf16 v[142:145], v[118:121], v[182:185], v[142:145]
	v_mfma_f32_16x16x32_bf16 v[138:141], v[126:129], v[182:185], v[138:141]
	v_mfma_f32_16x16x32_bf16 v[110:113], v[118:121], v[190:193], v[110:113]
	v_mfma_f32_16x16x32_bf16 v[106:109], v[126:129], v[190:193], v[106:109]
	v_mfma_f32_16x16x32_bf16 v[94:97], v[118:121], v[198:201], v[94:97]
	v_mfma_f32_16x16x32_bf16 v[90:93], v[126:129], v[198:201], v[90:93]
	v_mfma_f32_16x16x32_bf16 v[78:81], v[118:121], v[214:217], v[78:81]
	v_mfma_f32_16x16x32_bf16 v[74:77], v[126:129], v[214:217], v[74:77]
	s_setprio 0
	s_setprio 1
	v_mfma_f32_16x16x32_bf16 v[134:137], v[146:149], v[178:181], v[134:137]
	v_mfma_f32_16x16x32_bf16 v[130:133], v[154:157], v[178:181], v[130:133]
	v_mfma_f32_16x16x32_bf16 v[102:105], v[146:149], v[186:189], v[102:105]
	v_mfma_f32_16x16x32_bf16 v[98:101], v[154:157], v[186:189], v[98:101]
	v_mfma_f32_16x16x32_bf16 v[86:89], v[146:149], v[194:197], v[86:89]
	v_mfma_f32_16x16x32_bf16 v[82:85], v[154:157], v[194:197], v[82:85]
	v_mfma_f32_16x16x32_bf16 v[70:73], v[146:149], v[202:205], v[70:73]
	v_mfma_f32_16x16x32_bf16 v[66:69], v[154:157], v[202:205], v[66:69]
	v_mfma_f32_16x16x32_bf16 v[134:137], v[150:153], v[182:185], v[134:137]
	v_mfma_f32_16x16x32_bf16 v[130:133], v[158:161], v[182:185], v[130:133]
	v_mfma_f32_16x16x32_bf16 v[102:105], v[150:153], v[190:193], v[102:105]
	v_mfma_f32_16x16x32_bf16 v[98:101], v[158:161], v[190:193], v[98:101]
	v_mfma_f32_16x16x32_bf16 v[86:89], v[150:153], v[198:201], v[86:89]
	v_mfma_f32_16x16x32_bf16 v[82:85], v[158:161], v[198:201], v[82:85]
	v_mfma_f32_16x16x32_bf16 v[70:73], v[150:153], v[214:217], v[70:73]
	v_mfma_f32_16x16x32_bf16 v[66:69], v[158:161], v[214:217], v[66:69]
	s_setprio 0
	s_barrier
	s_add_i32 s93, s84, s54
	v_lshl_add_u64 v[218:219], s[94:95], 0, v[164:165]
	s_mov_b32 m0, s93
	ds_read_b128 v[178:181], v211 offset:16384
	ds_read_b128 v[182:185], v211 offset:17408
	ds_read_b128 v[186:189], v211 offset:18432
	ds_read_b128 v[190:193], v211 offset:19456
	ds_read_b128 v[194:197], v211 offset:20480
	ds_read_b128 v[198:201], v211 offset:21504
	ds_read_b128 v[202:205], v211 offset:22528
	ds_read_b128 v[214:217], v211 offset:23552
	global_load_lds_dwordx4 v[218:219], off
	s_add_i32 m0, s93, 0x2000
	v_lshl_add_u64 v[220:221], s[94:95], 0, v[168:169]
	s_add_u32 s94, s94, s8
	s_addc_u32 s95, s95, s9
	s_add_i32 s93, s85, s54
	global_load_lds_dwordx4 v[220:221], off
	v_lshl_add_u64 v[222:223], s[94:95], 0, v[164:165]
	s_mov_b32 m0, s93
	v_lshl_add_u64 v[224:225], s[94:95], 0, v[168:169]
	global_load_lds_dwordx4 v[222:223], off
	s_add_i32 m0, s93, 0x2000
	v_lshl_add_u64 v[226:227], s[44:45], 0, v[162:163]
	global_load_lds_dwordx4 v[224:225], off
	s_mov_b32 m0, s55
	s_nop 0
	global_load_lds_dwordx4 v[226:227], off
	v_lshl_add_u64 v[226:227], s[44:45], 0, v[166:167]
	s_mov_b32 m0, s56
	s_nop 0
	global_load_lds_dwordx4 v[226:227], off
	s_waitcnt vmcnt(8)
	s_waitcnt lgkmcnt(0)
	s_setprio 1
	s_waitcnt lgkmcnt(0)
	v_mfma_f32_16x16x32_bf16 v[62:65], v[114:117], v[178:181], v[62:65]
	v_mfma_f32_16x16x32_bf16 v[58:61], v[122:125], v[178:181], v[58:61]
	s_barrier
	v_mfma_f32_16x16x32_bf16 v[46:49], v[114:117], v[186:189], v[46:49]
	v_mfma_f32_16x16x32_bf16 v[42:45], v[122:125], v[186:189], v[42:45]
	v_mfma_f32_16x16x32_bf16 v[30:33], v[114:117], v[194:197], v[30:33]
	v_mfma_f32_16x16x32_bf16 v[26:29], v[122:125], v[194:197], v[26:29]
	v_mfma_f32_16x16x32_bf16 v[14:17], v[114:117], v[202:205], v[14:17]
	v_mfma_f32_16x16x32_bf16 v[10:13], v[122:125], v[202:205], v[10:13]
	v_mfma_f32_16x16x32_bf16 v[62:65], v[118:121], v[182:185], v[62:65]
	v_mfma_f32_16x16x32_bf16 v[58:61], v[126:129], v[182:185], v[58:61]
	v_mfma_f32_16x16x32_bf16 v[46:49], v[118:121], v[190:193], v[46:49]
	v_mfma_f32_16x16x32_bf16 v[42:45], v[126:129], v[190:193], v[42:45]
	v_mfma_f32_16x16x32_bf16 v[30:33], v[118:121], v[198:201], v[30:33]
	v_mfma_f32_16x16x32_bf16 v[26:29], v[126:129], v[198:201], v[26:29]
	v_mfma_f32_16x16x32_bf16 v[14:17], v[118:121], v[214:217], v[14:17]
	v_mfma_f32_16x16x32_bf16 v[10:13], v[126:129], v[214:217], v[10:13]
	s_setprio 0
	s_setprio 1
	v_mfma_f32_16x16x32_bf16 v[54:57], v[146:149], v[178:181], v[54:57]
	v_mfma_f32_16x16x32_bf16 v[50:53], v[154:157], v[178:181], v[50:53]
	v_mfma_f32_16x16x32_bf16 v[38:41], v[146:149], v[186:189], v[38:41]
	v_mfma_f32_16x16x32_bf16 v[34:37], v[154:157], v[186:189], v[34:37]
	v_mfma_f32_16x16x32_bf16 v[22:25], v[146:149], v[194:197], v[22:25]
	v_mfma_f32_16x16x32_bf16 v[18:21], v[154:157], v[194:197], v[18:21]
	v_mfma_f32_16x16x32_bf16 v[6:9], v[146:149], v[202:205], v[6:9]
	v_mfma_f32_16x16x32_bf16 v[2:5], v[154:157], v[202:205], v[2:5]
	v_mfma_f32_16x16x32_bf16 v[54:57], v[150:153], v[182:185], v[54:57]
	v_mfma_f32_16x16x32_bf16 v[50:53], v[158:161], v[182:185], v[50:53]
	v_mfma_f32_16x16x32_bf16 v[38:41], v[150:153], v[190:193], v[38:41]
	v_mfma_f32_16x16x32_bf16 v[34:37], v[158:161], v[190:193], v[34:37]
	v_mfma_f32_16x16x32_bf16 v[22:25], v[150:153], v[198:201], v[22:25]
	v_mfma_f32_16x16x32_bf16 v[18:21], v[158:161], v[198:201], v[18:21]
	v_mfma_f32_16x16x32_bf16 v[6:9], v[150:153], v[214:217], v[6:9]
	v_mfma_f32_16x16x32_bf16 v[2:5], v[158:161], v[214:217], v[2:5]
	s_setprio 0
	s_barrier
	s_add_i32 s93, 0, 0x18000
	s_add_i32 s94, 0, 0x1c000
	v_add_u32_e32 v126, s93, v207
	v_add_u32_e32 v158, s94, v207
	ds_read_b128 v[114:117], v126
	ds_read_b128 v[118:121], v126 offset:1024
	ds_read_b128 v[122:125], v126 offset:2048
	ds_read_b128 v[126:129], v126 offset:3072
	ds_read_b128 v[146:149], v158
	ds_read_b128 v[150:153], v158 offset:1024
	ds_read_b128 v[154:157], v158 offset:2048
	ds_read_b128 v[158:161], v158 offset:3072
	s_add_u32 s44, s44, 0x4000
	s_addc_u32 s45, s45, 0
	s_mov_b32 m0, s57
	v_lshl_add_u64 v[226:227], s[44:45], 0, v[162:163]
	ds_read_b128 v[178:181], v211 offset:32768
	ds_read_b128 v[182:185], v211 offset:33792
	ds_read_b128 v[186:189], v211 offset:34816
	ds_read_b128 v[190:193], v211 offset:35840
	ds_read_b128 v[194:197], v211 offset:36864
	ds_read_b128 v[198:201], v211 offset:37888
	ds_read_b128 v[202:205], v211 offset:38912
	ds_read_b128 v[214:217], v211 offset:39936
	global_load_lds_dwordx4 v[226:227], off
	v_lshl_add_u64 v[226:227], s[44:45], 0, v[166:167]
	s_mov_b32 m0, s58
	s_nop 0
	global_load_lds_dwordx4 v[226:227], off
	s_waitcnt vmcnt(8)
	s_waitcnt lgkmcnt(0)
	s_setprio 1
	s_waitcnt lgkmcnt(0)
	v_mfma_f32_16x16x32_bf16 v[142:145], v[114:117], v[178:181], v[142:145]
	v_mfma_f32_16x16x32_bf16 v[138:141], v[122:125], v[178:181], v[138:141]
	s_barrier
	v_mfma_f32_16x16x32_bf16 v[110:113], v[114:117], v[186:189], v[110:113]
	v_mfma_f32_16x16x32_bf16 v[106:109], v[122:125], v[186:189], v[106:109]
	v_mfma_f32_16x16x32_bf16 v[94:97], v[114:117], v[194:197], v[94:97]
	v_mfma_f32_16x16x32_bf16 v[90:93], v[122:125], v[194:197], v[90:93]
	v_mfma_f32_16x16x32_bf16 v[78:81], v[114:117], v[202:205], v[78:81]
	v_mfma_f32_16x16x32_bf16 v[74:77], v[122:125], v[202:205], v[74:77]
	v_mfma_f32_16x16x32_bf16 v[142:145], v[118:121], v[182:185], v[142:145]
	v_mfma_f32_16x16x32_bf16 v[138:141], v[126:129], v[182:185], v[138:141]
	v_mfma_f32_16x16x32_bf16 v[110:113], v[118:121], v[190:193], v[110:113]
	v_mfma_f32_16x16x32_bf16 v[106:109], v[126:129], v[190:193], v[106:109]
	v_mfma_f32_16x16x32_bf16 v[94:97], v[118:121], v[198:201], v[94:97]
	v_mfma_f32_16x16x32_bf16 v[90:93], v[126:129], v[198:201], v[90:93]
	v_mfma_f32_16x16x32_bf16 v[78:81], v[118:121], v[214:217], v[78:81]
	v_mfma_f32_16x16x32_bf16 v[74:77], v[126:129], v[214:217], v[74:77]
	s_setprio 0
	s_setprio 1
	v_mfma_f32_16x16x32_bf16 v[134:137], v[146:149], v[178:181], v[134:137]
	v_mfma_f32_16x16x32_bf16 v[130:133], v[154:157], v[178:181], v[130:133]
	v_mfma_f32_16x16x32_bf16 v[102:105], v[146:149], v[186:189], v[102:105]
	v_mfma_f32_16x16x32_bf16 v[98:101], v[154:157], v[186:189], v[98:101]
	v_mfma_f32_16x16x32_bf16 v[86:89], v[146:149], v[194:197], v[86:89]
	v_mfma_f32_16x16x32_bf16 v[82:85], v[154:157], v[194:197], v[82:85]
	v_mfma_f32_16x16x32_bf16 v[70:73], v[146:149], v[202:205], v[70:73]
	v_mfma_f32_16x16x32_bf16 v[66:69], v[154:157], v[202:205], v[66:69]
	v_mfma_f32_16x16x32_bf16 v[134:137], v[150:153], v[182:185], v[134:137]
	v_mfma_f32_16x16x32_bf16 v[130:133], v[158:161], v[182:185], v[130:133]
	v_mfma_f32_16x16x32_bf16 v[102:105], v[150:153], v[190:193], v[102:105]
	v_mfma_f32_16x16x32_bf16 v[98:101], v[158:161], v[190:193], v[98:101]
	v_mfma_f32_16x16x32_bf16 v[86:89], v[150:153], v[198:201], v[86:89]
	v_mfma_f32_16x16x32_bf16 v[82:85], v[158:161], v[198:201], v[82:85]
	v_mfma_f32_16x16x32_bf16 v[70:73], v[150:153], v[214:217], v[70:73]
	v_mfma_f32_16x16x32_bf16 v[66:69], v[158:161], v[214:217], v[66:69]
	s_setprio 0
	s_barrier
	s_add_i32 s44, s93, s54
	v_lshl_add_u64 v[218:219], v[218:219], 0, s[28:29]
	s_mov_b32 m0, s44
	ds_read_b128 v[178:181], v211 offset:49152
	ds_read_b128 v[182:185], v211 offset:50176
	ds_read_b128 v[186:189], v211 offset:51200
	ds_read_b128 v[190:193], v211 offset:52224
	ds_read_b128 v[194:197], v211 offset:53248
	ds_read_b128 v[198:201], v211 offset:54272
	ds_read_b128 v[202:205], v211 offset:55296
	ds_read_b128 v[214:217], v211 offset:56320
	global_load_lds_dwordx4 v[218:219], off
	v_lshl_add_u64 v[218:219], v[220:221], 0, s[28:29]
	s_add_i32 m0, s44, 0x2000
	s_add_i32 s44, s94, s54
	global_load_lds_dwordx4 v[218:219], off
	v_lshl_add_u64 v[218:219], v[222:223], 0, s[28:29]
	s_mov_b32 m0, s44
	s_nop 0
	global_load_lds_dwordx4 v[218:219], off
	v_lshl_add_u64 v[218:219], v[224:225], 0, s[28:29]
	s_add_i32 m0, s44, 0x2000
	s_nop 0
	global_load_lds_dwordx4 v[218:219], off
	v_lshl_add_u64 v[218:219], s[42:43], 0, v[162:163]
	s_mov_b32 m0, s65
	s_nop 0
	global_load_lds_dwordx4 v[218:219], off
	v_lshl_add_u64 v[218:219], s[42:43], 0, v[166:167]
	s_mov_b32 m0, s80
	s_nop 0
	global_load_lds_dwordx4 v[218:219], off
	s_waitcnt vmcnt(8)
	s_waitcnt lgkmcnt(0)
	s_setprio 1
	s_waitcnt lgkmcnt(0)
	v_mfma_f32_16x16x32_bf16 v[62:65], v[114:117], v[178:181], v[62:65]
	v_mfma_f32_16x16x32_bf16 v[58:61], v[122:125], v[178:181], v[58:61]
	s_barrier
	v_mfma_f32_16x16x32_bf16 v[46:49], v[114:117], v[186:189], v[46:49]
	v_mfma_f32_16x16x32_bf16 v[42:45], v[122:125], v[186:189], v[42:45]
	v_mfma_f32_16x16x32_bf16 v[30:33], v[114:117], v[194:197], v[30:33]
	v_mfma_f32_16x16x32_bf16 v[26:29], v[122:125], v[194:197], v[26:29]
	v_mfma_f32_16x16x32_bf16 v[14:17], v[114:117], v[202:205], v[14:17]
	v_mfma_f32_16x16x32_bf16 v[10:13], v[122:125], v[202:205], v[10:13]
	v_mfma_f32_16x16x32_bf16 v[62:65], v[118:121], v[182:185], v[62:65]
	v_mfma_f32_16x16x32_bf16 v[58:61], v[126:129], v[182:185], v[58:61]
	v_mfma_f32_16x16x32_bf16 v[46:49], v[118:121], v[190:193], v[46:49]
	v_mfma_f32_16x16x32_bf16 v[42:45], v[126:129], v[190:193], v[42:45]
	v_mfma_f32_16x16x32_bf16 v[30:33], v[118:121], v[198:201], v[30:33]
	v_mfma_f32_16x16x32_bf16 v[26:29], v[126:129], v[198:201], v[26:29]
	v_mfma_f32_16x16x32_bf16 v[14:17], v[118:121], v[214:217], v[14:17]
	v_mfma_f32_16x16x32_bf16 v[10:13], v[126:129], v[214:217], v[10:13]
	s_setprio 0
	s_setprio 1
	v_mfma_f32_16x16x32_bf16 v[54:57], v[146:149], v[178:181], v[54:57]
	v_mfma_f32_16x16x32_bf16 v[50:53], v[154:157], v[178:181], v[50:53]
	v_mfma_f32_16x16x32_bf16 v[38:41], v[146:149], v[186:189], v[38:41]
	v_mfma_f32_16x16x32_bf16 v[34:37], v[154:157], v[186:189], v[34:37]
	v_mfma_f32_16x16x32_bf16 v[22:25], v[146:149], v[194:197], v[22:25]
	v_mfma_f32_16x16x32_bf16 v[18:21], v[154:157], v[194:197], v[18:21]
	v_mfma_f32_16x16x32_bf16 v[6:9], v[146:149], v[202:205], v[6:9]
	v_mfma_f32_16x16x32_bf16 v[2:5], v[154:157], v[202:205], v[2:5]
	v_mfma_f32_16x16x32_bf16 v[54:57], v[150:153], v[182:185], v[54:57]
	v_mfma_f32_16x16x32_bf16 v[50:53], v[158:161], v[182:185], v[50:53]
	v_mfma_f32_16x16x32_bf16 v[38:41], v[150:153], v[190:193], v[38:41]
	v_mfma_f32_16x16x32_bf16 v[34:37], v[158:161], v[190:193], v[34:37]
	v_mfma_f32_16x16x32_bf16 v[22:25], v[150:153], v[198:201], v[22:25]
	v_mfma_f32_16x16x32_bf16 v[18:21], v[158:161], v[198:201], v[18:21]
	v_mfma_f32_16x16x32_bf16 v[6:9], v[150:153], v[214:217], v[6:9]
	v_mfma_f32_16x16x32_bf16 v[2:5], v[158:161], v[214:217], v[2:5]
	s_setprio 0
	s_add_u32 s90, s90, 0x100
	s_addc_u32 s91, s91, 0
	s_add_u32 s38, s38, 0x10000
	s_addc_u32 s39, s39, 0
	s_cmp_ge_i32 s92, s64
	s_mov_b32 s42, s92
	s_barrier
	s_cbranch_scc0 .LBB0_1170

.LBB0_1276:
	ds_read_b128 v[114:117], v171
	ds_read_b128 v[118:121], v171 offset:1024
	ds_read_b128 v[122:125], v171 offset:2048
	ds_read_b128 v[130:133], v171 offset:3072
	ds_read_b128 v[162:165], v172
	ds_read_b128 v[176:179], v172 offset:1024
	ds_read_b128 v[180:183], v172 offset:2048
	ds_read_b128 v[184:187], v172 offset:3072
	s_add_i32 s82, s30, 2
	s_add_u32 s83, s2, 0x80
	s_addc_u32 s31, s3, 0
	s_cmp_eq_u32 s58, s30
	s_cselect_b32 s30, s26, s83
	s_cselect_b32 s31, s27, s31
	s_cselect_b32 s85, s29, s35
	s_cselect_b32 s84, s28, s34
	v_lshl_add_u64 v[220:221], s[2:3], 0, v[154:155]
	s_add_i32 m0, s44, 0xc000
	ds_read_b128 v[188:191], v173
	ds_read_b128 v[192:195], v173 offset:1024
	ds_read_b128 v[196:199], v173 offset:2048
	ds_read_b128 v[200:203], v173 offset:3072
	ds_read_b128 v[204:207], v173 offset:4096
	ds_read_b128 v[208:211], v173 offset:5120
	ds_read_b128 v[212:215], v173 offset:6144
	ds_read_b128 v[216:219], v173 offset:7168
	global_load_lds_dwordx4 v[220:221], off
	v_lshl_add_u64 v[220:221], s[2:3], 0, v[156:157]
	s_add_i32 m0, s44, 0xe000
	s_nop 0
	global_load_lds_dwordx4 v[220:221], off
	s_waitcnt vmcnt(8)
	s_waitcnt lgkmcnt(0)
	s_setprio 1
	s_waitcnt lgkmcnt(0)
	v_mfma_f32_16x16x32_bf16 v[142:145], v[114:117], v[188:191], v[142:145]
	v_mfma_f32_16x16x32_bf16 v[138:141], v[122:125], v[188:191], v[138:141]
	s_barrier
	v_mfma_f32_16x16x32_bf16 v[110:113], v[114:117], v[196:199], v[110:113]
	v_mfma_f32_16x16x32_bf16 v[106:109], v[122:125], v[196:199], v[106:109]
	v_mfma_f32_16x16x32_bf16 v[94:97], v[114:117], v[204:207], v[94:97]
	v_mfma_f32_16x16x32_bf16 v[90:93], v[122:125], v[204:207], v[90:93]
	v_mfma_f32_16x16x32_bf16 v[78:81], v[114:117], v[212:215], v[78:81]
	v_mfma_f32_16x16x32_bf16 v[74:77], v[122:125], v[212:215], v[74:77]
	v_mfma_f32_16x16x32_bf16 v[142:145], v[118:121], v[192:195], v[142:145]
	v_mfma_f32_16x16x32_bf16 v[138:141], v[130:133], v[192:195], v[138:141]
	v_mfma_f32_16x16x32_bf16 v[110:113], v[118:121], v[200:203], v[110:113]
	v_mfma_f32_16x16x32_bf16 v[106:109], v[130:133], v[200:203], v[106:109]
	v_mfma_f32_16x16x32_bf16 v[94:97], v[118:121], v[208:211], v[94:97]
	v_mfma_f32_16x16x32_bf16 v[90:93], v[130:133], v[208:211], v[90:93]
	v_mfma_f32_16x16x32_bf16 v[78:81], v[118:121], v[216:219], v[78:81]
	v_mfma_f32_16x16x32_bf16 v[74:77], v[130:133], v[216:219], v[74:77]
	s_setprio 0
	s_setprio 1
	v_mfma_f32_16x16x32_bf16 v[134:137], v[162:165], v[188:191], v[134:137]
	v_mfma_f32_16x16x32_bf16 v[126:129], v[180:183], v[188:191], v[126:129]
	v_mfma_f32_16x16x32_bf16 v[102:105], v[162:165], v[196:199], v[102:105]
	v_mfma_f32_16x16x32_bf16 v[98:101], v[180:183], v[196:199], v[98:101]
	v_mfma_f32_16x16x32_bf16 v[86:89], v[162:165], v[204:207], v[86:89]
	v_mfma_f32_16x16x32_bf16 v[82:85], v[180:183], v[204:207], v[82:85]
	v_mfma_f32_16x16x32_bf16 v[70:73], v[162:165], v[212:215], v[70:73]
	v_mfma_f32_16x16x32_bf16 v[66:69], v[180:183], v[212:215], v[66:69]
	v_mfma_f32_16x16x32_bf16 v[134:137], v[176:179], v[192:195], v[134:137]
	v_mfma_f32_16x16x32_bf16 v[126:129], v[184:187], v[192:195], v[126:129]
	v_mfma_f32_16x16x32_bf16 v[102:105], v[176:179], v[200:203], v[102:105]
	v_mfma_f32_16x16x32_bf16 v[98:101], v[184:187], v[200:203], v[98:101]
	v_mfma_f32_16x16x32_bf16 v[86:89], v[176:179], v[208:211], v[86:89]
	v_mfma_f32_16x16x32_bf16 v[82:85], v[184:187], v[208:211], v[82:85]
	v_mfma_f32_16x16x32_bf16 v[70:73], v[176:179], v[216:219], v[70:73]
	v_mfma_f32_16x16x32_bf16 v[66:69], v[184:187], v[216:219], v[66:69]
	s_setprio 0
	s_barrier
	s_add_i32 s83, s61, s37
	v_lshl_add_u64 v[220:221], s[84:85], 0, v[148:149]
	s_mov_b32 m0, s83
	ds_read_b128 v[188:191], v173 offset:16384
	ds_read_b128 v[192:195], v173 offset:17408
	ds_read_b128 v[196:199], v173 offset:18432
	ds_read_b128 v[200:203], v173 offset:19456
	ds_read_b128 v[204:207], v173 offset:20480
	ds_read_b128 v[208:211], v173 offset:21504
	ds_read_b128 v[212:215], v173 offset:22528
	ds_read_b128 v[216:219], v173 offset:23552
	global_load_lds_dwordx4 v[220:221], off
	s_add_i32 m0, s83, 0x2000
	v_lshl_add_u64 v[222:223], s[84:85], 0, v[152:153]
	s_add_u32 s84, s84, s6
	s_addc_u32 s85, s85, s7
	s_add_i32 s83, s62, s37
	global_load_lds_dwordx4 v[222:223], off
	v_lshl_add_u64 v[224:225], s[84:85], 0, v[148:149]
	s_mov_b32 m0, s83
	v_lshl_add_u64 v[226:227], s[84:85], 0, v[152:153]
	global_load_lds_dwordx4 v[224:225], off
	s_add_i32 m0, s83, 0x2000
	v_lshl_add_u64 v[228:229], s[30:31], 0, v[146:147]
	global_load_lds_dwordx4 v[226:227], off
	s_mov_b32 m0, s44
	v_lshl_add_u64 v[230:231], s[30:31], 0, v[150:151]
	global_load_lds_dwordx4 v[228:229], off
	s_mov_b32 m0, s45
	s_nop 0
	global_load_lds_dwordx4 v[230:231], off
	s_waitcnt vmcnt(8)
	s_waitcnt lgkmcnt(0)
	s_setprio 1
	s_waitcnt lgkmcnt(0)
	v_mfma_f32_16x16x32_bf16 v[62:65], v[114:117], v[188:191], v[62:65]
	v_mfma_f32_16x16x32_bf16 v[58:61], v[122:125], v[188:191], v[58:61]
	s_barrier
	v_mfma_f32_16x16x32_bf16 v[46:49], v[114:117], v[196:199], v[46:49]
	v_mfma_f32_16x16x32_bf16 v[42:45], v[122:125], v[196:199], v[42:45]
	v_mfma_f32_16x16x32_bf16 v[30:33], v[114:117], v[204:207], v[30:33]
	v_mfma_f32_16x16x32_bf16 v[26:29], v[122:125], v[204:207], v[26:29]
	v_mfma_f32_16x16x32_bf16 v[14:17], v[114:117], v[212:215], v[14:17]
	v_mfma_f32_16x16x32_bf16 v[10:13], v[122:125], v[212:215], v[10:13]
	v_mfma_f32_16x16x32_bf16 v[62:65], v[118:121], v[192:195], v[62:65]
	v_mfma_f32_16x16x32_bf16 v[58:61], v[130:133], v[192:195], v[58:61]
	v_mfma_f32_16x16x32_bf16 v[46:49], v[118:121], v[200:203], v[46:49]
	v_mfma_f32_16x16x32_bf16 v[42:45], v[130:133], v[200:203], v[42:45]
	v_mfma_f32_16x16x32_bf16 v[30:33], v[118:121], v[208:211], v[30:33]
	v_mfma_f32_16x16x32_bf16 v[26:29], v[130:133], v[208:211], v[26:29]
	v_mfma_f32_16x16x32_bf16 v[14:17], v[118:121], v[216:219], v[14:17]
	v_mfma_f32_16x16x32_bf16 v[10:13], v[130:133], v[216:219], v[10:13]
	s_setprio 0
	s_setprio 1
	v_mfma_f32_16x16x32_bf16 v[54:57], v[162:165], v[188:191], v[54:57]
	v_mfma_f32_16x16x32_bf16 v[50:53], v[180:183], v[188:191], v[50:53]
	v_mfma_f32_16x16x32_bf16 v[38:41], v[162:165], v[196:199], v[38:41]
	v_mfma_f32_16x16x32_bf16 v[34:37], v[180:183], v[196:199], v[34:37]
	v_mfma_f32_16x16x32_bf16 v[22:25], v[162:165], v[204:207], v[22:25]
	v_mfma_f32_16x16x32_bf16 v[18:21], v[180:183], v[204:207], v[18:21]
	v_mfma_f32_16x16x32_bf16 v[6:9], v[162:165], v[212:215], v[6:9]
	v_mfma_f32_16x16x32_bf16 v[2:5], v[180:183], v[212:215], v[2:5]
	v_mfma_f32_16x16x32_bf16 v[54:57], v[176:179], v[192:195], v[54:57]
	v_mfma_f32_16x16x32_bf16 v[50:53], v[184:187], v[192:195], v[50:53]
	v_mfma_f32_16x16x32_bf16 v[38:41], v[176:179], v[200:203], v[38:41]
	v_mfma_f32_16x16x32_bf16 v[34:37], v[184:187], v[200:203], v[34:37]
	v_mfma_f32_16x16x32_bf16 v[22:25], v[176:179], v[208:211], v[22:25]
	v_mfma_f32_16x16x32_bf16 v[18:21], v[184:187], v[208:211], v[18:21]
	v_mfma_f32_16x16x32_bf16 v[6:9], v[176:179], v[216:219], v[6:9]
	v_mfma_f32_16x16x32_bf16 v[2:5], v[184:187], v[216:219], v[2:5]
	s_setprio 0
	s_barrier
	s_add_i32 s83, 0, 0x18000
	s_add_i32 s84, 0, 0x1c000
	v_add_u32_e32 v130, s83, v168
	v_add_u32_e32 v166, s84, v168
	ds_read_b128 v[114:117], v130
	ds_read_b128 v[118:121], v130 offset:1024
	ds_read_b128 v[122:125], v130 offset:2048
	ds_read_b128 v[130:133], v130 offset:3072
	ds_read_b128 v[162:165], v166
	ds_read_b128 v[176:179], v166 offset:1024
	ds_read_b128 v[180:183], v166 offset:2048
	ds_read_b128 v[184:187], v166 offset:3072
	s_add_u32 s30, s30, s6
	s_addc_u32 s31, s31, s7
	s_mov_b32 m0, s46
	v_lshl_add_u64 v[232:233], s[30:31], 0, v[146:147]
	ds_read_b128 v[188:191], v173 offset:32768
	ds_read_b128 v[192:195], v173 offset:33792
	ds_read_b128 v[196:199], v173 offset:34816
	ds_read_b128 v[200:203], v173 offset:35840
	ds_read_b128 v[204:207], v173 offset:36864
	ds_read_b128 v[208:211], v173 offset:37888
	ds_read_b128 v[212:215], v173 offset:38912
	ds_read_b128 v[216:219], v173 offset:39936
	global_load_lds_dwordx4 v[232:233], off
	v_lshl_add_u64 v[232:233], s[30:31], 0, v[150:151]
	s_mov_b32 m0, s47
	s_nop 0
	global_load_lds_dwordx4 v[232:233], off
	s_waitcnt vmcnt(8)
	s_waitcnt lgkmcnt(0)
	s_setprio 1
	s_waitcnt lgkmcnt(0)
	v_mfma_f32_16x16x32_bf16 v[142:145], v[114:117], v[188:191], v[142:145]
	v_mfma_f32_16x16x32_bf16 v[138:141], v[122:125], v[188:191], v[138:141]
	s_barrier
	v_mfma_f32_16x16x32_bf16 v[110:113], v[114:117], v[196:199], v[110:113]
	v_mfma_f32_16x16x32_bf16 v[106:109], v[122:125], v[196:199], v[106:109]
	v_mfma_f32_16x16x32_bf16 v[94:97], v[114:117], v[204:207], v[94:97]
	v_mfma_f32_16x16x32_bf16 v[90:93], v[122:125], v[204:207], v[90:93]
	v_mfma_f32_16x16x32_bf16 v[78:81], v[114:117], v[212:215], v[78:81]
	v_mfma_f32_16x16x32_bf16 v[74:77], v[122:125], v[212:215], v[74:77]
	v_mfma_f32_16x16x32_bf16 v[142:145], v[118:121], v[192:195], v[142:145]
	v_mfma_f32_16x16x32_bf16 v[138:141], v[130:133], v[192:195], v[138:141]
	v_mfma_f32_16x16x32_bf16 v[110:113], v[118:121], v[200:203], v[110:113]
	v_mfma_f32_16x16x32_bf16 v[106:109], v[130:133], v[200:203], v[106:109]
	v_mfma_f32_16x16x32_bf16 v[94:97], v[118:121], v[208:211], v[94:97]
	v_mfma_f32_16x16x32_bf16 v[90:93], v[130:133], v[208:211], v[90:93]
	v_mfma_f32_16x16x32_bf16 v[78:81], v[118:121], v[216:219], v[78:81]
	v_mfma_f32_16x16x32_bf16 v[74:77], v[130:133], v[216:219], v[74:77]
	s_setprio 0
	s_setprio 1
	v_mfma_f32_16x16x32_bf16 v[134:137], v[162:165], v[188:191], v[134:137]
	v_mfma_f32_16x16x32_bf16 v[126:129], v[180:183], v[188:191], v[126:129]
	v_mfma_f32_16x16x32_bf16 v[102:105], v[162:165], v[196:199], v[102:105]
	v_mfma_f32_16x16x32_bf16 v[98:101], v[180:183], v[196:199], v[98:101]
	v_mfma_f32_16x16x32_bf16 v[86:89], v[162:165], v[204:207], v[86:89]
	v_mfma_f32_16x16x32_bf16 v[82:85], v[180:183], v[204:207], v[82:85]
	v_mfma_f32_16x16x32_bf16 v[70:73], v[162:165], v[212:215], v[70:73]
	v_mfma_f32_16x16x32_bf16 v[66:69], v[180:183], v[212:215], v[66:69]
	v_mfma_f32_16x16x32_bf16 v[134:137], v[176:179], v[192:195], v[134:137]
	v_mfma_f32_16x16x32_bf16 v[126:129], v[184:187], v[192:195], v[126:129]
	v_mfma_f32_16x16x32_bf16 v[102:105], v[176:179], v[200:203], v[102:105]
	v_mfma_f32_16x16x32_bf16 v[98:101], v[184:187], v[200:203], v[98:101]
	v_mfma_f32_16x16x32_bf16 v[86:89], v[176:179], v[208:211], v[86:89]
	v_mfma_f32_16x16x32_bf16 v[82:85], v[184:187], v[208:211], v[82:85]
	v_mfma_f32_16x16x32_bf16 v[70:73], v[176:179], v[216:219], v[70:73]
	v_mfma_f32_16x16x32_bf16 v[66:69], v[184:187], v[216:219], v[66:69]
	s_setprio 0
	s_barrier
	s_add_i32 s30, s83, s37
	v_lshl_add_u64 v[220:221], v[220:221], 0, s[20:21]
	s_mov_b32 m0, s30
	ds_read_b128 v[188:191], v173 offset:49152
	ds_read_b128 v[192:195], v173 offset:50176
	ds_read_b128 v[196:199], v173 offset:51200
	ds_read_b128 v[200:203], v173 offset:52224
	ds_read_b128 v[204:207], v173 offset:53248
	ds_read_b128 v[208:211], v173 offset:54272
	ds_read_b128 v[212:215], v173 offset:55296
	ds_read_b128 v[216:219], v173 offset:56320
	global_load_lds_dwordx4 v[220:221], off
	v_lshl_add_u64 v[220:221], v[222:223], 0, s[20:21]
	s_add_i32 m0, s30, 0x2000
	s_add_i32 s30, s84, s37
	global_load_lds_dwordx4 v[220:221], off
	v_lshl_add_u64 v[220:221], v[224:225], 0, s[20:21]
	s_mov_b32 m0, s30
	s_nop 0
	global_load_lds_dwordx4 v[220:221], off
	v_lshl_add_u64 v[220:221], v[226:227], 0, s[20:21]
	s_add_i32 m0, s30, 0x2000
	s_nop 0
	global_load_lds_dwordx4 v[220:221], off
	v_lshl_add_u64 v[220:221], v[228:229], 0, s[20:21]
	s_mov_b32 m0, s55
	s_nop 0
	global_load_lds_dwordx4 v[220:221], off
	v_lshl_add_u64 v[220:221], v[230:231], 0, s[20:21]
	s_mov_b32 m0, s56
	s_nop 0
	global_load_lds_dwordx4 v[220:221], off
	s_waitcnt vmcnt(8)
	s_waitcnt lgkmcnt(0)
	s_setprio 1
	s_waitcnt lgkmcnt(0)
	v_mfma_f32_16x16x32_bf16 v[62:65], v[114:117], v[188:191], v[62:65]
	v_mfma_f32_16x16x32_bf16 v[58:61], v[122:125], v[188:191], v[58:61]
	s_barrier
	v_mfma_f32_16x16x32_bf16 v[46:49], v[114:117], v[196:199], v[46:49]
	v_mfma_f32_16x16x32_bf16 v[42:45], v[122:125], v[196:199], v[42:45]
	v_mfma_f32_16x16x32_bf16 v[30:33], v[114:117], v[204:207], v[30:33]
	v_mfma_f32_16x16x32_bf16 v[26:29], v[122:125], v[204:207], v[26:29]
	v_mfma_f32_16x16x32_bf16 v[14:17], v[114:117], v[212:215], v[14:17]
	v_mfma_f32_16x16x32_bf16 v[10:13], v[122:125], v[212:215], v[10:13]
	v_mfma_f32_16x16x32_bf16 v[62:65], v[118:121], v[192:195], v[62:65]
	v_mfma_f32_16x16x32_bf16 v[58:61], v[130:133], v[192:195], v[58:61]
	v_mfma_f32_16x16x32_bf16 v[46:49], v[118:121], v[200:203], v[46:49]
	v_mfma_f32_16x16x32_bf16 v[42:45], v[130:133], v[200:203], v[42:45]
	v_mfma_f32_16x16x32_bf16 v[30:33], v[118:121], v[208:211], v[30:33]
	v_mfma_f32_16x16x32_bf16 v[26:29], v[130:133], v[208:211], v[26:29]
	v_mfma_f32_16x16x32_bf16 v[14:17], v[118:121], v[216:219], v[14:17]
	v_mfma_f32_16x16x32_bf16 v[10:13], v[130:133], v[216:219], v[10:13]
	s_setprio 0
	s_setprio 1
	v_mfma_f32_16x16x32_bf16 v[54:57], v[162:165], v[188:191], v[54:57]
	v_mfma_f32_16x16x32_bf16 v[50:53], v[180:183], v[188:191], v[50:53]
	v_mfma_f32_16x16x32_bf16 v[38:41], v[162:165], v[196:199], v[38:41]
	v_mfma_f32_16x16x32_bf16 v[34:37], v[180:183], v[196:199], v[34:37]
	v_mfma_f32_16x16x32_bf16 v[22:25], v[162:165], v[204:207], v[22:25]
	v_mfma_f32_16x16x32_bf16 v[18:21], v[180:183], v[204:207], v[18:21]
	v_mfma_f32_16x16x32_bf16 v[6:9], v[162:165], v[212:215], v[6:9]
	v_mfma_f32_16x16x32_bf16 v[2:5], v[180:183], v[212:215], v[2:5]
	v_mfma_f32_16x16x32_bf16 v[54:57], v[176:179], v[192:195], v[54:57]
	v_mfma_f32_16x16x32_bf16 v[50:53], v[184:187], v[192:195], v[50:53]
	v_mfma_f32_16x16x32_bf16 v[38:41], v[176:179], v[200:203], v[38:41]
	v_mfma_f32_16x16x32_bf16 v[34:37], v[184:187], v[200:203], v[34:37]
	v_mfma_f32_16x16x32_bf16 v[22:25], v[176:179], v[208:211], v[22:25]
	v_mfma_f32_16x16x32_bf16 v[18:21], v[184:187], v[208:211], v[18:21]
	v_mfma_f32_16x16x32_bf16 v[6:9], v[176:179], v[216:219], v[6:9]
	v_mfma_f32_16x16x32_bf16 v[2:5], v[184:187], v[216:219], v[2:5]
	s_setprio 0
	s_add_u32 s2, s2, 0x100
	s_addc_u32 s3, s3, 0
	s_add_u32 s34, s34, 0x100
	s_addc_u32 s35, s35, 0
	s_cmp_ge_i32 s82, s57
	s_mov_b32 s30, s82
	s_barrier
	s_cbranch_scc0 .LBB0_1276

.LBB0_1461:
	ds_read_b128 v[148:151], v168
	ds_read_b128 v[172:175], v168 offset:1024
	ds_read_b128 v[176:179], v168 offset:2048
	ds_read_b128 v[180:183], v168 offset:3072
	ds_read_b128 v[184:187], v169
	ds_read_b128 v[188:191], v169 offset:1024
	ds_read_b128 v[192:195], v169 offset:2048
	ds_read_b128 v[196:199], v169 offset:3072
	s_add_i32 s67, s26, 2
	s_add_u32 s68, s24, 0x80
	s_addc_u32 s27, s25, 0
	s_cmp_eq_u32 s50, s26
	s_cselect_b32 s26, s2, s68
	s_cselect_b32 s27, s3, s27
	s_cselect_b32 s69, s23, s66
	s_cselect_b32 s68, s22, s65
	v_lshl_add_u64 v[232:233], s[24:25], 0, v[140:141]
	s_add_i32 m0, s37, 0xc000
	ds_read_b128 v[200:203], v170
	ds_read_b128 v[204:207], v170 offset:1024
	ds_read_b128 v[208:211], v170 offset:2048
	ds_read_b128 v[212:215], v170 offset:3072
	ds_read_b128 v[216:219], v170 offset:4096
	ds_read_b128 v[220:223], v170 offset:5120
	ds_read_b128 v[224:227], v170 offset:6144
	ds_read_b128 v[228:231], v170 offset:7168
	global_load_lds_dwordx4 v[232:233], off
	v_lshl_add_u64 v[232:233], s[24:25], 0, v[142:143]
	s_add_i32 m0, s37, 0xe000
	s_nop 0
	global_load_lds_dwordx4 v[232:233], off
	s_waitcnt vmcnt(8)
	s_waitcnt lgkmcnt(0)
	s_setprio 1
	s_waitcnt lgkmcnt(0)
	v_mfma_f32_16x16x32_bf16 v[128:131], v[148:151], v[200:203], v[128:131]
	v_mfma_f32_16x16x32_bf16 v[124:127], v[176:179], v[200:203], v[124:127]
	s_barrier
	v_mfma_f32_16x16x32_bf16 v[120:123], v[148:151], v[208:211], v[120:123]
	v_mfma_f32_16x16x32_bf16 v[116:119], v[176:179], v[208:211], v[116:119]
	v_mfma_f32_16x16x32_bf16 v[112:115], v[148:151], v[216:219], v[112:115]
	v_mfma_f32_16x16x32_bf16 v[108:111], v[176:179], v[216:219], v[108:111]
	v_mfma_f32_16x16x32_bf16 v[104:107], v[148:151], v[224:227], v[104:107]
	v_mfma_f32_16x16x32_bf16 v[100:103], v[176:179], v[224:227], v[100:103]
	v_mfma_f32_16x16x32_bf16 v[128:131], v[172:175], v[204:207], v[128:131]
	v_mfma_f32_16x16x32_bf16 v[124:127], v[180:183], v[204:207], v[124:127]
	v_mfma_f32_16x16x32_bf16 v[120:123], v[172:175], v[212:215], v[120:123]
	v_mfma_f32_16x16x32_bf16 v[116:119], v[180:183], v[212:215], v[116:119]
	v_mfma_f32_16x16x32_bf16 v[112:115], v[172:175], v[220:223], v[112:115]
	v_mfma_f32_16x16x32_bf16 v[108:111], v[180:183], v[220:223], v[108:111]
	v_mfma_f32_16x16x32_bf16 v[104:107], v[172:175], v[228:231], v[104:107]
	v_mfma_f32_16x16x32_bf16 v[100:103], v[180:183], v[228:231], v[100:103]
	s_setprio 0
	s_setprio 1
	v_mfma_f32_16x16x32_bf16 v[64:67], v[184:187], v[200:203], v[64:67]
	v_mfma_f32_16x16x32_bf16 v[60:63], v[192:195], v[200:203], v[60:63]
	v_mfma_f32_16x16x32_bf16 v[56:59], v[184:187], v[208:211], v[56:59]
	v_mfma_f32_16x16x32_bf16 v[52:55], v[192:195], v[208:211], v[52:55]
	v_mfma_f32_16x16x32_bf16 v[48:51], v[184:187], v[216:219], v[48:51]
	v_mfma_f32_16x16x32_bf16 v[44:47], v[192:195], v[216:219], v[44:47]
	v_mfma_f32_16x16x32_bf16 v[40:43], v[184:187], v[224:227], v[40:43]
	v_mfma_f32_16x16x32_bf16 v[36:39], v[192:195], v[224:227], v[36:39]
	v_mfma_f32_16x16x32_bf16 v[64:67], v[188:191], v[204:207], v[64:67]
	v_mfma_f32_16x16x32_bf16 v[60:63], v[196:199], v[204:207], v[60:63]
	v_mfma_f32_16x16x32_bf16 v[56:59], v[188:191], v[212:215], v[56:59]
	v_mfma_f32_16x16x32_bf16 v[52:55], v[196:199], v[212:215], v[52:55]
	v_mfma_f32_16x16x32_bf16 v[48:51], v[188:191], v[220:223], v[48:51]
	v_mfma_f32_16x16x32_bf16 v[44:47], v[196:199], v[220:223], v[44:47]
	v_mfma_f32_16x16x32_bf16 v[40:43], v[188:191], v[228:231], v[40:43]
	v_mfma_f32_16x16x32_bf16 v[36:39], v[196:199], v[228:231], v[36:39]
	s_setprio 0
	s_barrier
	s_add_i32 s80, s57, s36
	v_lshl_add_u64 v[232:233], s[68:69], 0, v[134:135]
	s_mov_b32 m0, s80
	ds_read_b128 v[200:203], v170 offset:16384
	ds_read_b128 v[204:207], v170 offset:17408
	ds_read_b128 v[208:211], v170 offset:18432
	ds_read_b128 v[212:215], v170 offset:19456
	ds_read_b128 v[216:219], v170 offset:20480
	ds_read_b128 v[220:223], v170 offset:21504
	ds_read_b128 v[224:227], v170 offset:22528
	ds_read_b128 v[228:231], v170 offset:23552
	global_load_lds_dwordx4 v[232:233], off
	s_add_i32 m0, s80, 0x2000
	v_lshl_add_u64 v[234:235], s[68:69], 0, v[138:139]
	s_add_u32 s68, s68, s6
	s_addc_u32 s69, s69, s7
	s_add_i32 s80, s58, s36
	global_load_lds_dwordx4 v[234:235], off
	v_lshl_add_u64 v[236:237], s[68:69], 0, v[134:135]
	s_mov_b32 m0, s80
	v_lshl_add_u64 v[238:239], s[68:69], 0, v[138:139]
	global_load_lds_dwordx4 v[236:237], off
	s_add_i32 m0, s80, 0x2000
	v_lshl_add_u64 v[240:241], s[26:27], 0, v[132:133]
	global_load_lds_dwordx4 v[238:239], off
	s_mov_b32 m0, s37
	v_lshl_add_u64 v[242:243], s[26:27], 0, v[136:137]
	global_load_lds_dwordx4 v[240:241], off
	s_mov_b32 m0, s38
	s_nop 0
	global_load_lds_dwordx4 v[242:243], off
	s_waitcnt vmcnt(8)
	s_waitcnt lgkmcnt(0)
	s_setprio 1
	s_waitcnt lgkmcnt(0)
	v_mfma_f32_16x16x32_bf16 v[96:99], v[148:151], v[200:203], v[96:99]
	v_mfma_f32_16x16x32_bf16 v[92:95], v[176:179], v[200:203], v[92:95]
	s_barrier
	v_mfma_f32_16x16x32_bf16 v[88:91], v[148:151], v[208:211], v[88:91]
	v_mfma_f32_16x16x32_bf16 v[84:87], v[176:179], v[208:211], v[84:87]
	v_mfma_f32_16x16x32_bf16 v[80:83], v[148:151], v[216:219], v[80:83]
	v_mfma_f32_16x16x32_bf16 v[76:79], v[176:179], v[216:219], v[76:79]
	v_mfma_f32_16x16x32_bf16 v[72:75], v[148:151], v[224:227], v[72:75]
	v_mfma_f32_16x16x32_bf16 v[68:71], v[176:179], v[224:227], v[68:71]
	v_mfma_f32_16x16x32_bf16 v[96:99], v[172:175], v[204:207], v[96:99]
	v_mfma_f32_16x16x32_bf16 v[92:95], v[180:183], v[204:207], v[92:95]
	v_mfma_f32_16x16x32_bf16 v[88:91], v[172:175], v[212:215], v[88:91]
	v_mfma_f32_16x16x32_bf16 v[84:87], v[180:183], v[212:215], v[84:87]
	v_mfma_f32_16x16x32_bf16 v[80:83], v[172:175], v[220:223], v[80:83]
	v_mfma_f32_16x16x32_bf16 v[76:79], v[180:183], v[220:223], v[76:79]
	v_mfma_f32_16x16x32_bf16 v[72:75], v[172:175], v[228:231], v[72:75]
	v_mfma_f32_16x16x32_bf16 v[68:71], v[180:183], v[228:231], v[68:71]
	s_setprio 0
	s_setprio 1
	v_mfma_f32_16x16x32_bf16 v[32:35], v[184:187], v[200:203], v[32:35]
	v_mfma_f32_16x16x32_bf16 v[28:31], v[192:195], v[200:203], v[28:31]
	v_mfma_f32_16x16x32_bf16 v[24:27], v[184:187], v[208:211], v[24:27]
	v_mfma_f32_16x16x32_bf16 v[20:23], v[192:195], v[208:211], v[20:23]
	v_mfma_f32_16x16x32_bf16 v[16:19], v[184:187], v[216:219], v[16:19]
	v_mfma_f32_16x16x32_bf16 v[12:15], v[192:195], v[216:219], v[12:15]
	v_mfma_f32_16x16x32_bf16 v[8:11], v[184:187], v[224:227], v[8:11]
	v_mfma_f32_16x16x32_bf16 v[4:7], v[192:195], v[224:227], v[4:7]
	v_mfma_f32_16x16x32_bf16 v[32:35], v[188:191], v[204:207], v[32:35]
	v_mfma_f32_16x16x32_bf16 v[28:31], v[196:199], v[204:207], v[28:31]
	v_mfma_f32_16x16x32_bf16 v[24:27], v[188:191], v[212:215], v[24:27]
	v_mfma_f32_16x16x32_bf16 v[20:23], v[196:199], v[212:215], v[20:23]
	v_mfma_f32_16x16x32_bf16 v[16:19], v[188:191], v[220:223], v[16:19]
	v_mfma_f32_16x16x32_bf16 v[12:15], v[196:199], v[220:223], v[12:15]
	v_mfma_f32_16x16x32_bf16 v[8:11], v[188:191], v[228:231], v[8:11]
	v_mfma_f32_16x16x32_bf16 v[4:7], v[196:199], v[228:231], v[4:7]
	s_setprio 0
	s_barrier
	s_add_i32 s68, 0, 0x18000
	v_add_u32_e32 v3, s68, v166
	s_add_i32 s69, 0, 0x1c000
	ds_read_b128 v[148:151], v3
	ds_read_b128 v[172:175], v3 offset:1024
	ds_read_b128 v[176:179], v3 offset:2048
	ds_read_b128 v[180:183], v3 offset:3072
	v_add_u32_e32 v3, s69, v166
	ds_read_b128 v[184:187], v3
	ds_read_b128 v[188:191], v3 offset:1024
	ds_read_b128 v[192:195], v3 offset:2048
	ds_read_b128 v[196:199], v3 offset:3072
	s_add_u32 s26, s26, s6
	s_addc_u32 s27, s27, s7
	s_mov_b32 m0, s39
	v_lshl_add_u64 v[244:245], s[26:27], 0, v[132:133]
	ds_read_b128 v[200:203], v170 offset:32768
	ds_read_b128 v[204:207], v170 offset:33792
	ds_read_b128 v[208:211], v170 offset:34816
	ds_read_b128 v[212:215], v170 offset:35840
	ds_read_b128 v[216:219], v170 offset:36864
	ds_read_b128 v[220:223], v170 offset:37888
	ds_read_b128 v[224:227], v170 offset:38912
	ds_read_b128 v[228:231], v170 offset:39936
	global_load_lds_dwordx4 v[244:245], off
	v_lshl_add_u64 v[244:245], s[26:27], 0, v[136:137]
	s_mov_b32 m0, s42
	s_nop 0
	global_load_lds_dwordx4 v[244:245], off
	s_waitcnt vmcnt(8)
	s_waitcnt lgkmcnt(0)
	s_setprio 1
	s_waitcnt lgkmcnt(0)
	v_mfma_f32_16x16x32_bf16 v[128:131], v[148:151], v[200:203], v[128:131]
	v_mfma_f32_16x16x32_bf16 v[124:127], v[176:179], v[200:203], v[124:127]
	s_barrier
	v_mfma_f32_16x16x32_bf16 v[120:123], v[148:151], v[208:211], v[120:123]
	v_mfma_f32_16x16x32_bf16 v[116:119], v[176:179], v[208:211], v[116:119]
	v_mfma_f32_16x16x32_bf16 v[112:115], v[148:151], v[216:219], v[112:115]
	v_mfma_f32_16x16x32_bf16 v[108:111], v[176:179], v[216:219], v[108:111]
	v_mfma_f32_16x16x32_bf16 v[104:107], v[148:151], v[224:227], v[104:107]
	v_mfma_f32_16x16x32_bf16 v[100:103], v[176:179], v[224:227], v[100:103]
	v_mfma_f32_16x16x32_bf16 v[128:131], v[172:175], v[204:207], v[128:131]
	v_mfma_f32_16x16x32_bf16 v[124:127], v[180:183], v[204:207], v[124:127]
	v_mfma_f32_16x16x32_bf16 v[120:123], v[172:175], v[212:215], v[120:123]
	v_mfma_f32_16x16x32_bf16 v[116:119], v[180:183], v[212:215], v[116:119]
	v_mfma_f32_16x16x32_bf16 v[112:115], v[172:175], v[220:223], v[112:115]
	v_mfma_f32_16x16x32_bf16 v[108:111], v[180:183], v[220:223], v[108:111]
	v_mfma_f32_16x16x32_bf16 v[104:107], v[172:175], v[228:231], v[104:107]
	v_mfma_f32_16x16x32_bf16 v[100:103], v[180:183], v[228:231], v[100:103]
	s_setprio 0
	s_setprio 1
	v_mfma_f32_16x16x32_bf16 v[64:67], v[184:187], v[200:203], v[64:67]
	v_mfma_f32_16x16x32_bf16 v[60:63], v[192:195], v[200:203], v[60:63]
	v_mfma_f32_16x16x32_bf16 v[56:59], v[184:187], v[208:211], v[56:59]
	v_mfma_f32_16x16x32_bf16 v[52:55], v[192:195], v[208:211], v[52:55]
	v_mfma_f32_16x16x32_bf16 v[48:51], v[184:187], v[216:219], v[48:51]
	v_mfma_f32_16x16x32_bf16 v[44:47], v[192:195], v[216:219], v[44:47]
	v_mfma_f32_16x16x32_bf16 v[40:43], v[184:187], v[224:227], v[40:43]
	v_mfma_f32_16x16x32_bf16 v[36:39], v[192:195], v[224:227], v[36:39]
	v_mfma_f32_16x16x32_bf16 v[64:67], v[188:191], v[204:207], v[64:67]
	v_mfma_f32_16x16x32_bf16 v[60:63], v[196:199], v[204:207], v[60:63]
	v_mfma_f32_16x16x32_bf16 v[56:59], v[188:191], v[212:215], v[56:59]
	v_mfma_f32_16x16x32_bf16 v[52:55], v[196:199], v[212:215], v[52:55]
	v_mfma_f32_16x16x32_bf16 v[48:51], v[188:191], v[220:223], v[48:51]
	v_mfma_f32_16x16x32_bf16 v[44:47], v[196:199], v[220:223], v[44:47]
	v_mfma_f32_16x16x32_bf16 v[40:43], v[188:191], v[228:231], v[40:43]
	v_mfma_f32_16x16x32_bf16 v[36:39], v[196:199], v[228:231], v[36:39]
	s_setprio 0
	s_barrier
	s_add_i32 s26, s68, s36
	v_lshl_add_u64 v[232:233], v[232:233], 0, s[16:17]
	s_mov_b32 m0, s26
	ds_read_b128 v[200:203], v170 offset:49152
	ds_read_b128 v[204:207], v170 offset:50176
	ds_read_b128 v[208:211], v170 offset:51200
	ds_read_b128 v[212:215], v170 offset:52224
	ds_read_b128 v[216:219], v170 offset:53248
	ds_read_b128 v[220:223], v170 offset:54272
	ds_read_b128 v[224:227], v170 offset:55296
	ds_read_b128 v[228:231], v170 offset:56320
	global_load_lds_dwordx4 v[232:233], off
	v_lshl_add_u64 v[232:233], v[234:235], 0, s[16:17]
	s_add_i32 m0, s26, 0x2000
	s_add_i32 s26, s69, s36
	global_load_lds_dwordx4 v[232:233], off
	v_lshl_add_u64 v[232:233], v[236:237], 0, s[16:17]
	s_mov_b32 m0, s26
	s_nop 0
	global_load_lds_dwordx4 v[232:233], off
	v_lshl_add_u64 v[232:233], v[238:239], 0, s[16:17]
	s_add_i32 m0, s26, 0x2000
	s_nop 0
	global_load_lds_dwordx4 v[232:233], off
	v_lshl_add_u64 v[232:233], v[240:241], 0, s[16:17]
	s_mov_b32 m0, s44
	s_nop 0
	global_load_lds_dwordx4 v[232:233], off
	v_lshl_add_u64 v[232:233], v[242:243], 0, s[16:17]
	s_mov_b32 m0, s45
	s_nop 0
	global_load_lds_dwordx4 v[232:233], off
	s_waitcnt vmcnt(8)
	s_waitcnt lgkmcnt(0)
	s_setprio 1
	s_waitcnt lgkmcnt(0)
	v_mfma_f32_16x16x32_bf16 v[96:99], v[148:151], v[200:203], v[96:99]
	v_mfma_f32_16x16x32_bf16 v[92:95], v[176:179], v[200:203], v[92:95]
	s_barrier
	v_mfma_f32_16x16x32_bf16 v[88:91], v[148:151], v[208:211], v[88:91]
	v_mfma_f32_16x16x32_bf16 v[84:87], v[176:179], v[208:211], v[84:87]
	v_mfma_f32_16x16x32_bf16 v[80:83], v[148:151], v[216:219], v[80:83]
	v_mfma_f32_16x16x32_bf16 v[76:79], v[176:179], v[216:219], v[76:79]
	v_mfma_f32_16x16x32_bf16 v[72:75], v[148:151], v[224:227], v[72:75]
	v_mfma_f32_16x16x32_bf16 v[68:71], v[176:179], v[224:227], v[68:71]
	v_mfma_f32_16x16x32_bf16 v[96:99], v[172:175], v[204:207], v[96:99]
	v_mfma_f32_16x16x32_bf16 v[92:95], v[180:183], v[204:207], v[92:95]
	v_mfma_f32_16x16x32_bf16 v[88:91], v[172:175], v[212:215], v[88:91]
	v_mfma_f32_16x16x32_bf16 v[84:87], v[180:183], v[212:215], v[84:87]
	v_mfma_f32_16x16x32_bf16 v[80:83], v[172:175], v[220:223], v[80:83]
	v_mfma_f32_16x16x32_bf16 v[76:79], v[180:183], v[220:223], v[76:79]
	v_mfma_f32_16x16x32_bf16 v[72:75], v[172:175], v[228:231], v[72:75]
	v_mfma_f32_16x16x32_bf16 v[68:71], v[180:183], v[228:231], v[68:71]
	s_setprio 0
	s_setprio 1
	v_mfma_f32_16x16x32_bf16 v[32:35], v[184:187], v[200:203], v[32:35]
	v_mfma_f32_16x16x32_bf16 v[28:31], v[192:195], v[200:203], v[28:31]
	v_mfma_f32_16x16x32_bf16 v[24:27], v[184:187], v[208:211], v[24:27]
	v_mfma_f32_16x16x32_bf16 v[20:23], v[192:195], v[208:211], v[20:23]
	v_mfma_f32_16x16x32_bf16 v[16:19], v[184:187], v[216:219], v[16:19]
	v_mfma_f32_16x16x32_bf16 v[12:15], v[192:195], v[216:219], v[12:15]
	v_mfma_f32_16x16x32_bf16 v[8:11], v[184:187], v[224:227], v[8:11]
	v_mfma_f32_16x16x32_bf16 v[4:7], v[192:195], v[224:227], v[4:7]
	v_mfma_f32_16x16x32_bf16 v[32:35], v[188:191], v[204:207], v[32:35]
	v_mfma_f32_16x16x32_bf16 v[28:31], v[196:199], v[204:207], v[28:31]
	v_mfma_f32_16x16x32_bf16 v[24:27], v[188:191], v[212:215], v[24:27]
	v_mfma_f32_16x16x32_bf16 v[20:23], v[196:199], v[212:215], v[20:23]
	v_mfma_f32_16x16x32_bf16 v[16:19], v[188:191], v[220:223], v[16:19]
	v_mfma_f32_16x16x32_bf16 v[12:15], v[196:199], v[220:223], v[12:15]
	v_mfma_f32_16x16x32_bf16 v[8:11], v[188:191], v[228:231], v[8:11]
	v_mfma_f32_16x16x32_bf16 v[4:7], v[196:199], v[228:231], v[4:7]
	s_setprio 0
	s_add_u32 s24, s24, 0x100
	s_addc_u32 s25, s25, 0
	s_add_u32 s65, s65, 0x100
	s_addc_u32 s66, s66, 0
	s_cmp_ge_i32 s67, s46
	s_mov_b32 s26, s67
	s_barrier
	s_cbranch_scc0 .LBB0_1461

.LBB0_1514:
	ds_read_b128 v[152:155], v149
	ds_read_b128 v[156:159], v149 offset:1024
	ds_read_b128 v[160:163], v149 offset:2048
	ds_read_b128 v[164:167], v149 offset:3072
	ds_read_b128 v[168:171], v150
	ds_read_b128 v[172:175], v150 offset:1024
	ds_read_b128 v[176:179], v150 offset:2048
	ds_read_b128 v[180:183], v150 offset:3072
	s_add_i32 s69, s36, 2
	s_add_u32 s80, s34, 0x80
	s_addc_u32 s37, s35, 0
	s_cmp_eq_u32 s59, s36
	s_cselect_b32 s36, s2, s80
	s_cselect_b32 s37, s3, s37
	s_cselect_b32 s81, s31, s68
	s_cselect_b32 s80, s30, s67
	v_lshl_add_u64 v[216:217], s[34:35], 0, v[138:139]
	s_add_i32 m0, s47, 0xc000
	ds_read_b128 v[184:187], v151
	ds_read_b128 v[188:191], v151 offset:1024
	ds_read_b128 v[192:195], v151 offset:2048
	ds_read_b128 v[196:199], v151 offset:3072
	ds_read_b128 v[200:203], v151 offset:4096
	ds_read_b128 v[204:207], v151 offset:5120
	ds_read_b128 v[208:211], v151 offset:6144
	ds_read_b128 v[212:215], v151 offset:7168
	global_load_lds_dwordx4 v[216:217], off
	v_lshl_add_u64 v[216:217], s[34:35], 0, v[140:141]
	s_add_i32 m0, s47, 0xe000
	s_nop 0
	global_load_lds_dwordx4 v[216:217], off
	s_waitcnt vmcnt(8)
	s_waitcnt lgkmcnt(0)
	s_setprio 1
	s_waitcnt lgkmcnt(0)
	v_mfma_f32_16x16x32_bf16 v[122:125], v[152:155], v[184:187], v[122:125]
	v_mfma_f32_16x16x32_bf16 v[126:129], v[160:163], v[184:187], v[126:129]
	s_barrier
	v_mfma_f32_16x16x32_bf16 v[110:113], v[152:155], v[192:195], v[110:113]
	v_mfma_f32_16x16x32_bf16 v[106:109], v[160:163], v[192:195], v[106:109]
	v_mfma_f32_16x16x32_bf16 v[94:97], v[152:155], v[200:203], v[94:97]
	v_mfma_f32_16x16x32_bf16 v[90:93], v[160:163], v[200:203], v[90:93]
	v_mfma_f32_16x16x32_bf16 v[78:81], v[152:155], v[208:211], v[78:81]
	v_mfma_f32_16x16x32_bf16 v[74:77], v[160:163], v[208:211], v[74:77]
	v_mfma_f32_16x16x32_bf16 v[122:125], v[156:159], v[188:191], v[122:125]
	v_mfma_f32_16x16x32_bf16 v[126:129], v[164:167], v[188:191], v[126:129]
	v_mfma_f32_16x16x32_bf16 v[110:113], v[156:159], v[196:199], v[110:113]
	v_mfma_f32_16x16x32_bf16 v[106:109], v[164:167], v[196:199], v[106:109]
	v_mfma_f32_16x16x32_bf16 v[94:97], v[156:159], v[204:207], v[94:97]
	v_mfma_f32_16x16x32_bf16 v[90:93], v[164:167], v[204:207], v[90:93]
	v_mfma_f32_16x16x32_bf16 v[78:81], v[156:159], v[212:215], v[78:81]
	v_mfma_f32_16x16x32_bf16 v[74:77], v[164:167], v[212:215], v[74:77]
	s_setprio 0
	s_setprio 1
	v_mfma_f32_16x16x32_bf16 v[118:121], v[168:171], v[184:187], v[118:121]
	v_mfma_f32_16x16x32_bf16 v[114:117], v[176:179], v[184:187], v[114:117]
	v_mfma_f32_16x16x32_bf16 v[102:105], v[168:171], v[192:195], v[102:105]
	v_mfma_f32_16x16x32_bf16 v[98:101], v[176:179], v[192:195], v[98:101]
	v_mfma_f32_16x16x32_bf16 v[86:89], v[168:171], v[200:203], v[86:89]
	v_mfma_f32_16x16x32_bf16 v[82:85], v[176:179], v[200:203], v[82:85]
	v_mfma_f32_16x16x32_bf16 v[70:73], v[168:171], v[208:211], v[70:73]
	v_mfma_f32_16x16x32_bf16 v[66:69], v[176:179], v[208:211], v[66:69]
	v_mfma_f32_16x16x32_bf16 v[118:121], v[172:175], v[188:191], v[118:121]
	v_mfma_f32_16x16x32_bf16 v[114:117], v[180:183], v[188:191], v[114:117]
	v_mfma_f32_16x16x32_bf16 v[102:105], v[172:175], v[196:199], v[102:105]
	v_mfma_f32_16x16x32_bf16 v[98:101], v[180:183], v[196:199], v[98:101]
	v_mfma_f32_16x16x32_bf16 v[86:89], v[172:175], v[204:207], v[86:89]
	v_mfma_f32_16x16x32_bf16 v[82:85], v[180:183], v[204:207], v[82:85]
	v_mfma_f32_16x16x32_bf16 v[70:73], v[172:175], v[212:215], v[70:73]
	v_mfma_f32_16x16x32_bf16 v[66:69], v[180:183], v[212:215], v[66:69]
	s_setprio 0
	s_barrier
	s_add_i32 s82, s61, s44
	v_lshl_add_u64 v[216:217], s[80:81], 0, v[134:135]
	s_mov_b32 m0, s82
	ds_read_b128 v[184:187], v151 offset:16384
	ds_read_b128 v[188:191], v151 offset:17408
	ds_read_b128 v[192:195], v151 offset:18432
	ds_read_b128 v[196:199], v151 offset:19456
	ds_read_b128 v[200:203], v151 offset:20480
	ds_read_b128 v[204:207], v151 offset:21504
	ds_read_b128 v[208:211], v151 offset:22528
	ds_read_b128 v[212:215], v151 offset:23552
	global_load_lds_dwordx4 v[216:217], off
	s_add_i32 m0, s82, 0x2000
	v_lshl_add_u64 v[218:219], s[80:81], 0, v[130:131]
	s_add_u32 s80, s80, s6
	s_addc_u32 s81, s81, s7
	s_add_i32 s82, s62, s44
	global_load_lds_dwordx4 v[218:219], off
	v_lshl_add_u64 v[220:221], s[80:81], 0, v[134:135]
	s_mov_b32 m0, s82
	v_lshl_add_u64 v[222:223], s[80:81], 0, v[130:131]
	global_load_lds_dwordx4 v[220:221], off
	s_add_i32 m0, s82, 0x2000
	v_lshl_add_u64 v[224:225], s[36:37], 0, v[136:137]
	global_load_lds_dwordx4 v[222:223], off
	s_mov_b32 m0, s47
	v_lshl_add_u64 v[226:227], s[36:37], 0, v[132:133]
	global_load_lds_dwordx4 v[224:225], off
	s_mov_b32 m0, s50
	s_nop 0
	global_load_lds_dwordx4 v[226:227], off
	s_waitcnt vmcnt(8)
	s_waitcnt lgkmcnt(0)
	s_setprio 1
	s_waitcnt lgkmcnt(0)
	v_mfma_f32_16x16x32_bf16 v[62:65], v[152:155], v[184:187], v[62:65]
	v_mfma_f32_16x16x32_bf16 v[58:61], v[160:163], v[184:187], v[58:61]
	s_barrier
	v_mfma_f32_16x16x32_bf16 v[46:49], v[152:155], v[192:195], v[46:49]
	v_mfma_f32_16x16x32_bf16 v[42:45], v[160:163], v[192:195], v[42:45]
	v_mfma_f32_16x16x32_bf16 v[30:33], v[152:155], v[200:203], v[30:33]
	v_mfma_f32_16x16x32_bf16 v[26:29], v[160:163], v[200:203], v[26:29]
	v_mfma_f32_16x16x32_bf16 v[14:17], v[152:155], v[208:211], v[14:17]
	v_mfma_f32_16x16x32_bf16 v[10:13], v[160:163], v[208:211], v[10:13]
	v_mfma_f32_16x16x32_bf16 v[62:65], v[156:159], v[188:191], v[62:65]
	v_mfma_f32_16x16x32_bf16 v[58:61], v[164:167], v[188:191], v[58:61]
	v_mfma_f32_16x16x32_bf16 v[46:49], v[156:159], v[196:199], v[46:49]
	v_mfma_f32_16x16x32_bf16 v[42:45], v[164:167], v[196:199], v[42:45]
	v_mfma_f32_16x16x32_bf16 v[30:33], v[156:159], v[204:207], v[30:33]
	v_mfma_f32_16x16x32_bf16 v[26:29], v[164:167], v[204:207], v[26:29]
	v_mfma_f32_16x16x32_bf16 v[14:17], v[156:159], v[212:215], v[14:17]
	v_mfma_f32_16x16x32_bf16 v[10:13], v[164:167], v[212:215], v[10:13]
	s_setprio 0
	s_setprio 1
	v_mfma_f32_16x16x32_bf16 v[54:57], v[168:171], v[184:187], v[54:57]
	v_mfma_f32_16x16x32_bf16 v[50:53], v[176:179], v[184:187], v[50:53]
	v_mfma_f32_16x16x32_bf16 v[38:41], v[168:171], v[192:195], v[38:41]
	v_mfma_f32_16x16x32_bf16 v[34:37], v[176:179], v[192:195], v[34:37]
	v_mfma_f32_16x16x32_bf16 v[22:25], v[168:171], v[200:203], v[22:25]
	v_mfma_f32_16x16x32_bf16 v[18:21], v[176:179], v[200:203], v[18:21]
	v_mfma_f32_16x16x32_bf16 v[6:9], v[168:171], v[208:211], v[6:9]
	v_mfma_f32_16x16x32_bf16 v[2:5], v[176:179], v[208:211], v[2:5]
	v_mfma_f32_16x16x32_bf16 v[54:57], v[172:175], v[188:191], v[54:57]
	v_mfma_f32_16x16x32_bf16 v[50:53], v[180:183], v[188:191], v[50:53]
	v_mfma_f32_16x16x32_bf16 v[38:41], v[172:175], v[196:199], v[38:41]
	v_mfma_f32_16x16x32_bf16 v[34:37], v[180:183], v[196:199], v[34:37]
	v_mfma_f32_16x16x32_bf16 v[22:25], v[172:175], v[204:207], v[22:25]
	v_mfma_f32_16x16x32_bf16 v[18:21], v[180:183], v[204:207], v[18:21]
	v_mfma_f32_16x16x32_bf16 v[6:9], v[172:175], v[212:215], v[6:9]
	v_mfma_f32_16x16x32_bf16 v[2:5], v[180:183], v[212:215], v[2:5]
	s_setprio 0
	s_barrier
	s_add_i32 s80, 0, 0x18000
	s_add_i32 s81, 0, 0x1c000
	v_add_u32_e32 v164, s80, v147
	v_add_u32_e32 v180, s81, v147
	ds_read_b128 v[152:155], v164
	ds_read_b128 v[156:159], v164 offset:1024
	ds_read_b128 v[160:163], v164 offset:2048
	ds_read_b128 v[164:167], v164 offset:3072
	ds_read_b128 v[168:171], v180
	ds_read_b128 v[172:175], v180 offset:1024
	ds_read_b128 v[176:179], v180 offset:2048
	ds_read_b128 v[180:183], v180 offset:3072
	s_add_u32 s36, s36, s6
	s_addc_u32 s37, s37, s7
	s_mov_b32 m0, s51
	v_lshl_add_u64 v[228:229], s[36:37], 0, v[136:137]
	ds_read_b128 v[184:187], v151 offset:32768
	ds_read_b128 v[188:191], v151 offset:33792
	ds_read_b128 v[192:195], v151 offset:34816
	ds_read_b128 v[196:199], v151 offset:35840
	ds_read_b128 v[200:203], v151 offset:36864
	ds_read_b128 v[204:207], v151 offset:37888
	ds_read_b128 v[208:211], v151 offset:38912
	ds_read_b128 v[212:215], v151 offset:39936
	global_load_lds_dwordx4 v[228:229], off
	v_lshl_add_u64 v[228:229], s[36:37], 0, v[132:133]
	s_mov_b32 m0, s54
	s_nop 0
	global_load_lds_dwordx4 v[228:229], off
	s_waitcnt vmcnt(8)
	s_waitcnt lgkmcnt(0)
	s_setprio 1
	s_waitcnt lgkmcnt(0)
	v_mfma_f32_16x16x32_bf16 v[122:125], v[152:155], v[184:187], v[122:125]
	v_mfma_f32_16x16x32_bf16 v[126:129], v[160:163], v[184:187], v[126:129]
	s_barrier
	v_mfma_f32_16x16x32_bf16 v[110:113], v[152:155], v[192:195], v[110:113]
	v_mfma_f32_16x16x32_bf16 v[106:109], v[160:163], v[192:195], v[106:109]
	v_mfma_f32_16x16x32_bf16 v[94:97], v[152:155], v[200:203], v[94:97]
	v_mfma_f32_16x16x32_bf16 v[90:93], v[160:163], v[200:203], v[90:93]
	v_mfma_f32_16x16x32_bf16 v[78:81], v[152:155], v[208:211], v[78:81]
	v_mfma_f32_16x16x32_bf16 v[74:77], v[160:163], v[208:211], v[74:77]
	v_mfma_f32_16x16x32_bf16 v[122:125], v[156:159], v[188:191], v[122:125]
	v_mfma_f32_16x16x32_bf16 v[126:129], v[164:167], v[188:191], v[126:129]
	v_mfma_f32_16x16x32_bf16 v[110:113], v[156:159], v[196:199], v[110:113]
	v_mfma_f32_16x16x32_bf16 v[106:109], v[164:167], v[196:199], v[106:109]
	v_mfma_f32_16x16x32_bf16 v[94:97], v[156:159], v[204:207], v[94:97]
	v_mfma_f32_16x16x32_bf16 v[90:93], v[164:167], v[204:207], v[90:93]
	v_mfma_f32_16x16x32_bf16 v[78:81], v[156:159], v[212:215], v[78:81]
	v_mfma_f32_16x16x32_bf16 v[74:77], v[164:167], v[212:215], v[74:77]
	s_setprio 0
	s_setprio 1
	v_mfma_f32_16x16x32_bf16 v[118:121], v[168:171], v[184:187], v[118:121]
	v_mfma_f32_16x16x32_bf16 v[114:117], v[176:179], v[184:187], v[114:117]
	v_mfma_f32_16x16x32_bf16 v[102:105], v[168:171], v[192:195], v[102:105]
	v_mfma_f32_16x16x32_bf16 v[98:101], v[176:179], v[192:195], v[98:101]
	v_mfma_f32_16x16x32_bf16 v[86:89], v[168:171], v[200:203], v[86:89]
	v_mfma_f32_16x16x32_bf16 v[82:85], v[176:179], v[200:203], v[82:85]
	v_mfma_f32_16x16x32_bf16 v[70:73], v[168:171], v[208:211], v[70:73]
	v_mfma_f32_16x16x32_bf16 v[66:69], v[176:179], v[208:211], v[66:69]
	v_mfma_f32_16x16x32_bf16 v[118:121], v[172:175], v[188:191], v[118:121]
	v_mfma_f32_16x16x32_bf16 v[114:117], v[180:183], v[188:191], v[114:117]
	v_mfma_f32_16x16x32_bf16 v[102:105], v[172:175], v[196:199], v[102:105]
	v_mfma_f32_16x16x32_bf16 v[98:101], v[180:183], v[196:199], v[98:101]
	v_mfma_f32_16x16x32_bf16 v[86:89], v[172:175], v[204:207], v[86:89]
	v_mfma_f32_16x16x32_bf16 v[82:85], v[180:183], v[204:207], v[82:85]
	v_mfma_f32_16x16x32_bf16 v[70:73], v[172:175], v[212:215], v[70:73]
	v_mfma_f32_16x16x32_bf16 v[66:69], v[180:183], v[212:215], v[66:69]
	s_setprio 0
	s_barrier
	s_add_i32 s36, s80, s44
	v_lshl_add_u64 v[216:217], v[216:217], 0, s[16:17]
	s_mov_b32 m0, s36
	ds_read_b128 v[184:187], v151 offset:49152
	ds_read_b128 v[188:191], v151 offset:50176
	ds_read_b128 v[192:195], v151 offset:51200
	ds_read_b128 v[196:199], v151 offset:52224
	ds_read_b128 v[200:203], v151 offset:53248
	ds_read_b128 v[204:207], v151 offset:54272
	ds_read_b128 v[208:211], v151 offset:55296
	ds_read_b128 v[212:215], v151 offset:56320
	global_load_lds_dwordx4 v[216:217], off
	v_lshl_add_u64 v[216:217], v[218:219], 0, s[16:17]
	s_add_i32 m0, s36, 0x2000
	s_add_i32 s36, s81, s44
	global_load_lds_dwordx4 v[216:217], off
	v_lshl_add_u64 v[216:217], v[220:221], 0, s[16:17]
	s_mov_b32 m0, s36
	s_nop 0
	global_load_lds_dwordx4 v[216:217], off
	v_lshl_add_u64 v[216:217], v[222:223], 0, s[16:17]
	s_add_i32 m0, s36, 0x2000
	s_nop 0
	global_load_lds_dwordx4 v[216:217], off
	v_lshl_add_u64 v[216:217], v[224:225], 0, s[16:17]
	s_mov_b32 m0, s56
	s_nop 0
	global_load_lds_dwordx4 v[216:217], off
	v_lshl_add_u64 v[216:217], v[226:227], 0, s[16:17]
	s_mov_b32 m0, s57
	s_nop 0
	global_load_lds_dwordx4 v[216:217], off
	s_waitcnt vmcnt(8)
	s_waitcnt lgkmcnt(0)
	s_setprio 1
	s_waitcnt lgkmcnt(0)
	v_mfma_f32_16x16x32_bf16 v[62:65], v[152:155], v[184:187], v[62:65]
	v_mfma_f32_16x16x32_bf16 v[58:61], v[160:163], v[184:187], v[58:61]
	s_barrier
	v_mfma_f32_16x16x32_bf16 v[46:49], v[152:155], v[192:195], v[46:49]
	v_mfma_f32_16x16x32_bf16 v[42:45], v[160:163], v[192:195], v[42:45]
	v_mfma_f32_16x16x32_bf16 v[30:33], v[152:155], v[200:203], v[30:33]
	v_mfma_f32_16x16x32_bf16 v[26:29], v[160:163], v[200:203], v[26:29]
	v_mfma_f32_16x16x32_bf16 v[14:17], v[152:155], v[208:211], v[14:17]
	v_mfma_f32_16x16x32_bf16 v[10:13], v[160:163], v[208:211], v[10:13]
	v_mfma_f32_16x16x32_bf16 v[62:65], v[156:159], v[188:191], v[62:65]
	v_mfma_f32_16x16x32_bf16 v[58:61], v[164:167], v[188:191], v[58:61]
	v_mfma_f32_16x16x32_bf16 v[46:49], v[156:159], v[196:199], v[46:49]
	v_mfma_f32_16x16x32_bf16 v[42:45], v[164:167], v[196:199], v[42:45]
	v_mfma_f32_16x16x32_bf16 v[30:33], v[156:159], v[204:207], v[30:33]
	v_mfma_f32_16x16x32_bf16 v[26:29], v[164:167], v[204:207], v[26:29]
	v_mfma_f32_16x16x32_bf16 v[14:17], v[156:159], v[212:215], v[14:17]
	v_mfma_f32_16x16x32_bf16 v[10:13], v[164:167], v[212:215], v[10:13]
	s_setprio 0
	s_setprio 1
	v_mfma_f32_16x16x32_bf16 v[54:57], v[168:171], v[184:187], v[54:57]
	v_mfma_f32_16x16x32_bf16 v[50:53], v[176:179], v[184:187], v[50:53]
	v_mfma_f32_16x16x32_bf16 v[38:41], v[168:171], v[192:195], v[38:41]
	v_mfma_f32_16x16x32_bf16 v[34:37], v[176:179], v[192:195], v[34:37]
	v_mfma_f32_16x16x32_bf16 v[22:25], v[168:171], v[200:203], v[22:25]
	v_mfma_f32_16x16x32_bf16 v[18:21], v[176:179], v[200:203], v[18:21]
	v_mfma_f32_16x16x32_bf16 v[6:9], v[168:171], v[208:211], v[6:9]
	v_mfma_f32_16x16x32_bf16 v[2:5], v[176:179], v[208:211], v[2:5]
	v_mfma_f32_16x16x32_bf16 v[54:57], v[172:175], v[188:191], v[54:57]
	v_mfma_f32_16x16x32_bf16 v[50:53], v[180:183], v[188:191], v[50:53]
	v_mfma_f32_16x16x32_bf16 v[38:41], v[172:175], v[196:199], v[38:41]
	v_mfma_f32_16x16x32_bf16 v[34:37], v[180:183], v[196:199], v[34:37]
	v_mfma_f32_16x16x32_bf16 v[22:25], v[172:175], v[204:207], v[22:25]
	v_mfma_f32_16x16x32_bf16 v[18:21], v[180:183], v[204:207], v[18:21]
	v_mfma_f32_16x16x32_bf16 v[6:9], v[172:175], v[212:215], v[6:9]
	v_mfma_f32_16x16x32_bf16 v[2:5], v[180:183], v[212:215], v[2:5]
	s_setprio 0
	s_add_u32 s34, s34, 0x100
	s_addc_u32 s35, s35, 0
	s_add_u32 s67, s67, 0x100
	s_addc_u32 s68, s68, 0
	s_cmp_ge_i32 s69, s58
	s_mov_b32 s36, s69
	s_barrier
	s_cbranch_scc0 .LBB0_1514

.LBB0_1754:
	v_add_u32_e32 v158, s80, v229
	v_add_u32_e32 v174, s81, v229
	ds_read_b128 v[146:149], v158
	ds_read_b128 v[150:153], v158 offset:1024
	ds_read_b128 v[154:157], v158 offset:2048
	ds_read_b128 v[158:161], v158 offset:3072
	ds_read_b128 v[162:165], v174
	ds_read_b128 v[166:169], v174 offset:1024
	ds_read_b128 v[170:173], v174 offset:2048
	ds_read_b128 v[174:177], v174 offset:3072
	s_add_i32 s88, s44, 2
	s_add_u32 s89, s42, 0x80
	s_addc_u32 s45, s43, 0
	s_cmp_eq_u32 s67, s44
	s_cselect_b32 s44, s4, s89
	s_cselect_b32 s45, s5, s45
	s_cselect_b32 s91, s39, s87
	s_cselect_b32 s90, s38, s86
	v_lshl_add_u64 v[210:211], s[42:43], 0, v[138:139]
	s_add_i32 m0, s55, 0xc000
	ds_read_b128 v[178:181], v231
	ds_read_b128 v[182:185], v231 offset:1024
	ds_read_b128 v[186:189], v231 offset:2048
	ds_read_b128 v[190:193], v231 offset:3072
	ds_read_b128 v[194:197], v231 offset:4096
	ds_read_b128 v[198:201], v231 offset:5120
	ds_read_b128 v[202:205], v231 offset:6144
	ds_read_b128 v[206:209], v231 offset:7168
	global_load_lds_dwordx4 v[210:211], off
	v_lshl_add_u64 v[210:211], s[42:43], 0, v[140:141]
	s_add_i32 m0, s55, 0xe000
	s_nop 0
	global_load_lds_dwordx4 v[210:211], off
	s_waitcnt vmcnt(8)
	s_waitcnt lgkmcnt(0)
	s_setprio 1
	s_waitcnt lgkmcnt(0)
	v_mfma_i32_16x16x64_i8 v[126:129], v[146:149], v[178:181], v[126:129]
	v_mfma_i32_16x16x64_i8 v[122:125], v[154:157], v[178:181], v[122:125]
	s_barrier
	v_mfma_i32_16x16x64_i8 v[118:121], v[146:149], v[186:189], v[118:121]
	v_mfma_i32_16x16x64_i8 v[114:117], v[154:157], v[186:189], v[114:117]
	v_mfma_i32_16x16x64_i8 v[106:109], v[146:149], v[194:197], v[106:109]
	v_mfma_i32_16x16x64_i8 v[98:101], v[154:157], v[194:197], v[98:101]
	v_mfma_i32_16x16x64_i8 v[90:93], v[146:149], v[202:205], v[90:93]
	v_mfma_i32_16x16x64_i8 v[82:85], v[154:157], v[202:205], v[82:85]
	v_mfma_i32_16x16x64_i8 v[126:129], v[150:153], v[182:185], v[126:129]
	v_mfma_i32_16x16x64_i8 v[122:125], v[158:161], v[182:185], v[122:125]
	v_mfma_i32_16x16x64_i8 v[118:121], v[150:153], v[190:193], v[118:121]
	v_mfma_i32_16x16x64_i8 v[114:117], v[158:161], v[190:193], v[114:117]
	v_mfma_i32_16x16x64_i8 v[106:109], v[150:153], v[198:201], v[106:109]
	v_mfma_i32_16x16x64_i8 v[98:101], v[158:161], v[198:201], v[98:101]
	v_mfma_i32_16x16x64_i8 v[90:93], v[150:153], v[206:209], v[90:93]
	v_mfma_i32_16x16x64_i8 v[82:85], v[158:161], v[206:209], v[82:85]
	s_setprio 0
	s_setprio 1
	v_mfma_i32_16x16x64_i8 v[110:113], v[162:165], v[178:181], v[110:113]
	v_mfma_i32_16x16x64_i8 v[102:105], v[170:173], v[178:181], v[102:105]
	v_mfma_i32_16x16x64_i8 v[94:97], v[162:165], v[186:189], v[94:97]
	v_mfma_i32_16x16x64_i8 v[86:89], v[170:173], v[186:189], v[86:89]
	v_mfma_i32_16x16x64_i8 v[78:81], v[162:165], v[194:197], v[78:81]
	v_mfma_i32_16x16x64_i8 v[74:77], v[170:173], v[194:197], v[74:77]
	v_mfma_i32_16x16x64_i8 v[70:73], v[162:165], v[202:205], v[70:73]
	v_mfma_i32_16x16x64_i8 v[66:69], v[170:173], v[202:205], v[66:69]
	v_mfma_i32_16x16x64_i8 v[110:113], v[166:169], v[182:185], v[110:113]
	v_mfma_i32_16x16x64_i8 v[102:105], v[174:177], v[182:185], v[102:105]
	v_mfma_i32_16x16x64_i8 v[94:97], v[166:169], v[190:193], v[94:97]
	v_mfma_i32_16x16x64_i8 v[86:89], v[174:177], v[190:193], v[86:89]
	v_mfma_i32_16x16x64_i8 v[78:81], v[166:169], v[198:201], v[78:81]
	v_mfma_i32_16x16x64_i8 v[74:77], v[174:177], v[198:201], v[74:77]
	v_mfma_i32_16x16x64_i8 v[70:73], v[166:169], v[206:209], v[70:73]
	v_mfma_i32_16x16x64_i8 v[66:69], v[174:177], v[206:209], v[66:69]
	s_setprio 0
	s_barrier
	s_add_i32 s89, s80, s54
	v_lshl_add_u64 v[210:211], s[90:91], 0, v[132:133]
	s_mov_b32 m0, s89
	ds_read_b128 v[178:181], v231 offset:16384
	ds_read_b128 v[182:185], v231 offset:17408
	ds_read_b128 v[186:189], v231 offset:18432
	ds_read_b128 v[190:193], v231 offset:19456
	ds_read_b128 v[194:197], v231 offset:20480
	ds_read_b128 v[198:201], v231 offset:21504
	ds_read_b128 v[202:205], v231 offset:22528
	ds_read_b128 v[206:209], v231 offset:23552
	global_load_lds_dwordx4 v[210:211], off
	s_add_i32 m0, s89, 0x2000
	v_lshl_add_u64 v[212:213], s[90:91], 0, v[136:137]
	s_add_u32 s90, s90, s8
	s_addc_u32 s91, s91, s9
	s_add_i32 s89, s81, s54
	global_load_lds_dwordx4 v[212:213], off
	v_lshl_add_u64 v[214:215], s[90:91], 0, v[132:133]
	s_mov_b32 m0, s89
	v_lshl_add_u64 v[216:217], s[90:91], 0, v[136:137]
	global_load_lds_dwordx4 v[214:215], off
	s_add_i32 m0, s89, 0x2000
	v_lshl_add_u64 v[218:219], s[44:45], 0, v[130:131]
	global_load_lds_dwordx4 v[216:217], off
	s_mov_b32 m0, s55
	v_lshl_add_u64 v[220:221], s[44:45], 0, v[134:135]
	global_load_lds_dwordx4 v[218:219], off
	s_mov_b32 m0, s56
	s_nop 0
	global_load_lds_dwordx4 v[220:221], off
	s_waitcnt vmcnt(8)
	s_waitcnt lgkmcnt(0)
	s_setprio 1
	s_waitcnt lgkmcnt(0)
	v_mfma_i32_16x16x64_i8 v[62:65], v[146:149], v[178:181], v[62:65]
	v_mfma_i32_16x16x64_i8 v[58:61], v[154:157], v[178:181], v[58:61]
	s_barrier
	v_mfma_i32_16x16x64_i8 v[54:57], v[146:149], v[186:189], v[54:57]
	v_mfma_i32_16x16x64_i8 v[50:53], v[154:157], v[186:189], v[50:53]
	v_mfma_i32_16x16x64_i8 v[42:45], v[146:149], v[194:197], v[42:45]
	v_mfma_i32_16x16x64_i8 v[34:37], v[154:157], v[194:197], v[34:37]
	v_mfma_i32_16x16x64_i8 v[26:29], v[146:149], v[202:205], v[26:29]
	v_mfma_i32_16x16x64_i8 v[18:21], v[154:157], v[202:205], v[18:21]
	v_mfma_i32_16x16x64_i8 v[62:65], v[150:153], v[182:185], v[62:65]
	v_mfma_i32_16x16x64_i8 v[58:61], v[158:161], v[182:185], v[58:61]
	v_mfma_i32_16x16x64_i8 v[54:57], v[150:153], v[190:193], v[54:57]
	v_mfma_i32_16x16x64_i8 v[50:53], v[158:161], v[190:193], v[50:53]
	v_mfma_i32_16x16x64_i8 v[42:45], v[150:153], v[198:201], v[42:45]
	v_mfma_i32_16x16x64_i8 v[34:37], v[158:161], v[198:201], v[34:37]
	v_mfma_i32_16x16x64_i8 v[26:29], v[150:153], v[206:209], v[26:29]
	v_mfma_i32_16x16x64_i8 v[18:21], v[158:161], v[206:209], v[18:21]
	s_setprio 0
	s_setprio 1
	v_mfma_i32_16x16x64_i8 v[46:49], v[162:165], v[178:181], v[46:49]
	v_mfma_i32_16x16x64_i8 v[38:41], v[170:173], v[178:181], v[38:41]
	v_mfma_i32_16x16x64_i8 v[30:33], v[162:165], v[186:189], v[30:33]
	v_mfma_i32_16x16x64_i8 v[22:25], v[170:173], v[186:189], v[22:25]
	v_mfma_i32_16x16x64_i8 v[14:17], v[162:165], v[194:197], v[14:17]
	v_mfma_i32_16x16x64_i8 v[10:13], v[170:173], v[194:197], v[10:13]
	v_mfma_i32_16x16x64_i8 v[6:9], v[162:165], v[202:205], v[6:9]
	v_mfma_i32_16x16x64_i8 v[2:5], v[170:173], v[202:205], v[2:5]
	v_mfma_i32_16x16x64_i8 v[46:49], v[166:169], v[182:185], v[46:49]
	v_mfma_i32_16x16x64_i8 v[38:41], v[174:177], v[182:185], v[38:41]
	v_mfma_i32_16x16x64_i8 v[30:33], v[166:169], v[190:193], v[30:33]
	v_mfma_i32_16x16x64_i8 v[22:25], v[174:177], v[190:193], v[22:25]
	v_mfma_i32_16x16x64_i8 v[14:17], v[166:169], v[198:201], v[14:17]
	v_mfma_i32_16x16x64_i8 v[10:13], v[174:177], v[198:201], v[10:13]
	v_mfma_i32_16x16x64_i8 v[6:9], v[166:169], v[206:209], v[6:9]
	v_mfma_i32_16x16x64_i8 v[2:5], v[174:177], v[206:209], v[2:5]
	s_setprio 0
	s_barrier
	s_add_i32 s89, 0, 0x18000
	s_add_i32 s90, 0, 0x1c000
	v_add_u32_e32 v158, s89, v229
	v_add_u32_e32 v174, s90, v229
	ds_read_b128 v[146:149], v158
	ds_read_b128 v[150:153], v158 offset:1024
	ds_read_b128 v[154:157], v158 offset:2048
	ds_read_b128 v[158:161], v158 offset:3072
	ds_read_b128 v[162:165], v174
	ds_read_b128 v[166:169], v174 offset:1024
	ds_read_b128 v[170:173], v174 offset:2048
	ds_read_b128 v[174:177], v174 offset:3072
	s_add_u32 s44, s44, s8
	s_addc_u32 s45, s45, s9
	s_mov_b32 m0, s57
	v_lshl_add_u64 v[222:223], s[44:45], 0, v[130:131]
	ds_read_b128 v[178:181], v231 offset:32768
	ds_read_b128 v[182:185], v231 offset:33792
	ds_read_b128 v[186:189], v231 offset:34816
	ds_read_b128 v[190:193], v231 offset:35840
	ds_read_b128 v[194:197], v231 offset:36864
	ds_read_b128 v[198:201], v231 offset:37888
	ds_read_b128 v[202:205], v231 offset:38912
	ds_read_b128 v[206:209], v231 offset:39936
	global_load_lds_dwordx4 v[222:223], off
	v_lshl_add_u64 v[222:223], s[44:45], 0, v[134:135]
	s_mov_b32 m0, s58
	s_nop 0
	global_load_lds_dwordx4 v[222:223], off
	s_waitcnt vmcnt(8)
	s_waitcnt lgkmcnt(0)
	s_setprio 1
	s_waitcnt lgkmcnt(0)
	v_mfma_i32_16x16x64_i8 v[126:129], v[146:149], v[178:181], v[126:129]
	v_mfma_i32_16x16x64_i8 v[122:125], v[154:157], v[178:181], v[122:125]
	s_barrier
	v_mfma_i32_16x16x64_i8 v[118:121], v[146:149], v[186:189], v[118:121]
	v_mfma_i32_16x16x64_i8 v[114:117], v[154:157], v[186:189], v[114:117]
	v_mfma_i32_16x16x64_i8 v[106:109], v[146:149], v[194:197], v[106:109]
	v_mfma_i32_16x16x64_i8 v[98:101], v[154:157], v[194:197], v[98:101]
	v_mfma_i32_16x16x64_i8 v[90:93], v[146:149], v[202:205], v[90:93]
	v_mfma_i32_16x16x64_i8 v[82:85], v[154:157], v[202:205], v[82:85]
	v_mfma_i32_16x16x64_i8 v[126:129], v[150:153], v[182:185], v[126:129]
	v_mfma_i32_16x16x64_i8 v[122:125], v[158:161], v[182:185], v[122:125]
	v_mfma_i32_16x16x64_i8 v[118:121], v[150:153], v[190:193], v[118:121]
	v_mfma_i32_16x16x64_i8 v[114:117], v[158:161], v[190:193], v[114:117]
	v_mfma_i32_16x16x64_i8 v[106:109], v[150:153], v[198:201], v[106:109]
	v_mfma_i32_16x16x64_i8 v[98:101], v[158:161], v[198:201], v[98:101]
	v_mfma_i32_16x16x64_i8 v[90:93], v[150:153], v[206:209], v[90:93]
	v_mfma_i32_16x16x64_i8 v[82:85], v[158:161], v[206:209], v[82:85]
	s_setprio 0
	s_setprio 1
	v_mfma_i32_16x16x64_i8 v[110:113], v[162:165], v[178:181], v[110:113]
	v_mfma_i32_16x16x64_i8 v[102:105], v[170:173], v[178:181], v[102:105]
	v_mfma_i32_16x16x64_i8 v[94:97], v[162:165], v[186:189], v[94:97]
	v_mfma_i32_16x16x64_i8 v[86:89], v[170:173], v[186:189], v[86:89]
	v_mfma_i32_16x16x64_i8 v[78:81], v[162:165], v[194:197], v[78:81]
	v_mfma_i32_16x16x64_i8 v[74:77], v[170:173], v[194:197], v[74:77]
	v_mfma_i32_16x16x64_i8 v[70:73], v[162:165], v[202:205], v[70:73]
	v_mfma_i32_16x16x64_i8 v[66:69], v[170:173], v[202:205], v[66:69]
	v_mfma_i32_16x16x64_i8 v[110:113], v[166:169], v[182:185], v[110:113]
	v_mfma_i32_16x16x64_i8 v[102:105], v[174:177], v[182:185], v[102:105]
	v_mfma_i32_16x16x64_i8 v[94:97], v[166:169], v[190:193], v[94:97]
	v_mfma_i32_16x16x64_i8 v[86:89], v[174:177], v[190:193], v[86:89]
	v_mfma_i32_16x16x64_i8 v[78:81], v[166:169], v[198:201], v[78:81]
	v_mfma_i32_16x16x64_i8 v[74:77], v[174:177], v[198:201], v[74:77]
	v_mfma_i32_16x16x64_i8 v[70:73], v[166:169], v[206:209], v[70:73]
	v_mfma_i32_16x16x64_i8 v[66:69], v[174:177], v[206:209], v[66:69]
	s_setprio 0
	s_barrier
	s_add_i32 s44, s89, s54
	v_lshl_add_u64 v[210:211], v[210:211], 0, s[30:31]
	s_mov_b32 m0, s44
	ds_read_b128 v[178:181], v231 offset:49152
	ds_read_b128 v[182:185], v231 offset:50176
	ds_read_b128 v[186:189], v231 offset:51200
	ds_read_b128 v[190:193], v231 offset:52224
	ds_read_b128 v[194:197], v231 offset:53248
	ds_read_b128 v[198:201], v231 offset:54272
	ds_read_b128 v[202:205], v231 offset:55296
	ds_read_b128 v[206:209], v231 offset:56320
	global_load_lds_dwordx4 v[210:211], off
	v_lshl_add_u64 v[210:211], v[212:213], 0, s[30:31]
	s_add_i32 m0, s44, 0x2000
	s_add_i32 s44, s90, s54
	global_load_lds_dwordx4 v[210:211], off
	v_lshl_add_u64 v[210:211], v[214:215], 0, s[30:31]
	s_mov_b32 m0, s44
	s_nop 0
	global_load_lds_dwordx4 v[210:211], off
	v_lshl_add_u64 v[210:211], v[216:217], 0, s[30:31]
	s_add_i32 m0, s44, 0x2000
	s_nop 0
	global_load_lds_dwordx4 v[210:211], off
	v_lshl_add_u64 v[210:211], v[218:219], 0, s[30:31]
	s_mov_b32 m0, s63
	s_nop 0
	global_load_lds_dwordx4 v[210:211], off
	v_lshl_add_u64 v[210:211], v[220:221], 0, s[30:31]
	s_mov_b32 m0, s64
	s_nop 0
	global_load_lds_dwordx4 v[210:211], off
	s_waitcnt vmcnt(8)
	s_waitcnt lgkmcnt(0)
	s_setprio 1
	s_waitcnt lgkmcnt(0)
	v_mfma_i32_16x16x64_i8 v[62:65], v[146:149], v[178:181], v[62:65]
	v_mfma_i32_16x16x64_i8 v[58:61], v[154:157], v[178:181], v[58:61]
	s_barrier
	v_mfma_i32_16x16x64_i8 v[54:57], v[146:149], v[186:189], v[54:57]
	v_mfma_i32_16x16x64_i8 v[50:53], v[154:157], v[186:189], v[50:53]
	v_mfma_i32_16x16x64_i8 v[42:45], v[146:149], v[194:197], v[42:45]
	v_mfma_i32_16x16x64_i8 v[34:37], v[154:157], v[194:197], v[34:37]
	v_mfma_i32_16x16x64_i8 v[26:29], v[146:149], v[202:205], v[26:29]
	v_mfma_i32_16x16x64_i8 v[18:21], v[154:157], v[202:205], v[18:21]
	v_mfma_i32_16x16x64_i8 v[62:65], v[150:153], v[182:185], v[62:65]
	v_mfma_i32_16x16x64_i8 v[58:61], v[158:161], v[182:185], v[58:61]
	v_mfma_i32_16x16x64_i8 v[54:57], v[150:153], v[190:193], v[54:57]
	v_mfma_i32_16x16x64_i8 v[50:53], v[158:161], v[190:193], v[50:53]
	v_mfma_i32_16x16x64_i8 v[42:45], v[150:153], v[198:201], v[42:45]
	v_mfma_i32_16x16x64_i8 v[34:37], v[158:161], v[198:201], v[34:37]
	v_mfma_i32_16x16x64_i8 v[26:29], v[150:153], v[206:209], v[26:29]
	v_mfma_i32_16x16x64_i8 v[18:21], v[158:161], v[206:209], v[18:21]
	s_setprio 0
	s_setprio 1
	v_mfma_i32_16x16x64_i8 v[46:49], v[162:165], v[178:181], v[46:49]
	v_mfma_i32_16x16x64_i8 v[38:41], v[170:173], v[178:181], v[38:41]
	v_mfma_i32_16x16x64_i8 v[30:33], v[162:165], v[186:189], v[30:33]
	v_mfma_i32_16x16x64_i8 v[22:25], v[170:173], v[186:189], v[22:25]
	v_mfma_i32_16x16x64_i8 v[14:17], v[162:165], v[194:197], v[14:17]
	v_mfma_i32_16x16x64_i8 v[10:13], v[170:173], v[194:197], v[10:13]
	v_mfma_i32_16x16x64_i8 v[6:9], v[162:165], v[202:205], v[6:9]
	v_mfma_i32_16x16x64_i8 v[2:5], v[170:173], v[202:205], v[2:5]
	v_mfma_i32_16x16x64_i8 v[46:49], v[166:169], v[182:185], v[46:49]
	v_mfma_i32_16x16x64_i8 v[38:41], v[174:177], v[182:185], v[38:41]
	v_mfma_i32_16x16x64_i8 v[30:33], v[166:169], v[190:193], v[30:33]
	v_mfma_i32_16x16x64_i8 v[22:25], v[174:177], v[190:193], v[22:25]
	v_mfma_i32_16x16x64_i8 v[14:17], v[166:169], v[198:201], v[14:17]
	v_mfma_i32_16x16x64_i8 v[10:13], v[174:177], v[198:201], v[10:13]
	v_mfma_i32_16x16x64_i8 v[6:9], v[166:169], v[206:209], v[6:9]
	v_mfma_i32_16x16x64_i8 v[2:5], v[174:177], v[206:209], v[2:5]
	s_setprio 0
	s_add_u32 s42, s42, 0x100
	s_addc_u32 s43, s43, 0
	s_add_u32 s86, s86, 0x100
	s_addc_u32 s87, s87, 0
	s_cmp_ge_i32 s88, s66
	s_mov_b32 s44, s88
	s_barrier
	s_cbranch_scc0 .LBB0_1754
	v_cvt_f32_i32_e32 v214, v126
	v_cvt_f32_i32_e32 v215, v127
	v_cvt_f32_i32_e32 v212, v128
	v_cvt_f32_i32_e32 v213, v129
	v_cvt_f32_i32_e32 v218, v122
	v_cvt_f32_i32_e32 v219, v123
	v_cvt_f32_i32_e32 v216, v124
	v_cvt_f32_i32_e32 v217, v125
	v_cvt_f32_i32_e32 v222, v110
	v_cvt_f32_i32_e32 v223, v111
	v_cvt_f32_i32_e32 v220, v112
	v_cvt_f32_i32_e32 v221, v113
	v_cvt_f32_i32_e32 v226, v102
	v_cvt_f32_i32_e32 v227, v103
	v_cvt_f32_i32_e32 v224, v104
	v_cvt_f32_i32_e32 v225, v105
	v_cvt_f32_i32_e32 v194, v118
	v_cvt_f32_i32_e32 v195, v119
	v_cvt_f32_i32_e32 v192, v120
	v_cvt_f32_i32_e32 v193, v121
	v_cvt_f32_i32_e32 v200, v114
	v_cvt_f32_i32_e32 v201, v115
	v_cvt_f32_i32_e32 v198, v116
	v_cvt_f32_i32_e32 v199, v117
	v_cvt_f32_i32_e32 v206, v94
	v_cvt_f32_i32_e32 v207, v95
	v_cvt_f32_i32_e32 v202, v96
	v_cvt_f32_i32_e32 v203, v97
	v_cvt_f32_i32_e32 v208, v86
	v_cvt_f32_i32_e32 v209, v87
	v_cvt_f32_i32_e32 v204, v88
	v_cvt_f32_i32_e32 v205, v89
	v_cvt_f32_i32_e32 v178, v106
	v_cvt_f32_i32_e32 v179, v107
	v_cvt_f32_i32_e32 v176, v108
	v_cvt_f32_i32_e32 v177, v109
	v_cvt_f32_i32_e32 v182, v98
	v_cvt_f32_i32_e32 v183, v99
	v_cvt_f32_i32_e32 v180, v100
	v_cvt_f32_i32_e32 v181, v101
	v_cvt_f32_i32_e32 v188, v78
	v_cvt_f32_i32_e32 v189, v79
	v_cvt_f32_i32_e32 v184, v80
	v_cvt_f32_i32_e32 v185, v81
	v_cvt_f32_i32_e32 v190, v74
	v_cvt_f32_i32_e32 v191, v75
	v_cvt_f32_i32_e32 v186, v76
	v_cvt_f32_i32_e32 v187, v77
	v_cvt_f32_i32_e32 v162, v90
	v_cvt_f32_i32_e32 v163, v91
	v_cvt_f32_i32_e32 v160, v92
	v_cvt_f32_i32_e32 v161, v93
	v_cvt_f32_i32_e32 v166, v82
	v_cvt_f32_i32_e32 v167, v83
	v_cvt_f32_i32_e32 v164, v84
	v_cvt_f32_i32_e32 v165, v85
	v_cvt_f32_i32_e32 v172, v70
	v_cvt_f32_i32_e32 v173, v71
	v_cvt_f32_i32_e32 v168, v72
	v_cvt_f32_i32_e32 v169, v73
	v_cvt_f32_i32_e32 v174, v66
	v_cvt_f32_i32_e32 v175, v67
	v_cvt_f32_i32_e32 v170, v68
	v_cvt_f32_i32_e32 v171, v69
	v_cvt_f32_i32_e32 v146, v62
	v_cvt_f32_i32_e32 v147, v63
	v_cvt_f32_i32_e32 v128, v64
	v_cvt_f32_i32_e32 v129, v65
	v_cvt_f32_i32_e32 v150, v58
	v_cvt_f32_i32_e32 v151, v59
	v_cvt_f32_i32_e32 v148, v60
	v_cvt_f32_i32_e32 v149, v61
	v_cvt_f32_i32_e32 v156, v46
	v_cvt_f32_i32_e32 v157, v47
	v_cvt_f32_i32_e32 v152, v48
	v_cvt_f32_i32_e32 v153, v49
	v_cvt_f32_i32_e32 v158, v38
	v_cvt_f32_i32_e32 v159, v39
	v_cvt_f32_i32_e32 v154, v40
	v_cvt_f32_i32_e32 v155, v41
	v_cvt_f32_i32_e32 v114, v54
	v_cvt_f32_i32_e32 v115, v55
	v_cvt_f32_i32_e32 v112, v56
	v_cvt_f32_i32_e32 v113, v57
	v_cvt_f32_i32_e32 v118, v50
	v_cvt_f32_i32_e32 v119, v51
	v_cvt_f32_i32_e32 v116, v52
	v_cvt_f32_i32_e32 v117, v53
	v_cvt_f32_i32_e32 v124, v30
	v_cvt_f32_i32_e32 v125, v31
	v_cvt_f32_i32_e32 v120, v32
	v_cvt_f32_i32_e32 v121, v33
	v_cvt_f32_i32_e32 v126, v22
	v_cvt_f32_i32_e32 v127, v23
	v_cvt_f32_i32_e32 v122, v24
	v_cvt_f32_i32_e32 v123, v25
	v_cvt_f32_i32_e32 v64, v42
	v_cvt_f32_i32_e32 v65, v43
	v_cvt_f32_i32_e32 v62, v44
	v_cvt_f32_i32_e32 v63, v45
	v_cvt_f32_i32_e32 v68, v34
	v_cvt_f32_i32_e32 v69, v35
	v_cvt_f32_i32_e32 v66, v36
	v_cvt_f32_i32_e32 v67, v37
	v_cvt_f32_i32_e32 v74, v14
	v_cvt_f32_i32_e32 v75, v15
	v_cvt_f32_i32_e32 v70, v16
	v_cvt_f32_i32_e32 v71, v17
	v_cvt_f32_i32_e32 v76, v10
	v_cvt_f32_i32_e32 v77, v11
	v_cvt_f32_i32_e32 v72, v12
	v_cvt_f32_i32_e32 v73, v13
	v_cvt_f32_i32_e32 v48, v26
	v_cvt_f32_i32_e32 v49, v27
	v_cvt_f32_i32_e32 v46, v28
	v_cvt_f32_i32_e32 v47, v29
	v_cvt_f32_i32_e32 v52, v18
	v_cvt_f32_i32_e32 v53, v19
	v_cvt_f32_i32_e32 v50, v20
	v_cvt_f32_i32_e32 v51, v21
	v_cvt_f32_i32_e32 v58, v6
	v_cvt_f32_i32_e32 v59, v7
	v_cvt_f32_i32_e32 v54, v8
	v_cvt_f32_i32_e32 v55, v9
	v_cvt_f32_i32_e32 v60, v2
	v_cvt_f32_i32_e32 v61, v3
	v_cvt_f32_i32_e32 v56, v4
	v_cvt_f32_i32_e32 v57, v5

.LBB0_1939:
	v_add_u32_e32 v138, s62, v188
	ds_read_b128 v[148:151], v138
	ds_read_b128 v[152:155], v138 offset:1024
	ds_read_b128 v[156:159], v138 offset:2048
	ds_read_b128 v[160:163], v138 offset:3072
	v_add_u32_e32 v138, s63, v188
	ds_read_b128 v[164:167], v138
	ds_read_b128 v[168:171], v138 offset:1024
	ds_read_b128 v[172:175], v138 offset:2048
	ds_read_b128 v[176:179], v138 offset:3072
	s_add_i32 s66, s28, 2
	s_add_u32 s67, s26, 0x80
	s_addc_u32 s29, s27, 0
	s_cmp_eq_u32 s60, s28
	s_cselect_b32 s28, s2, s67
	s_cselect_b32 s29, s3, s29
	s_cselect_b32 s69, s25, s35
	s_cselect_b32 s68, s24, s34
	v_lshl_add_u64 v[184:185], s[26:27], 0, v[140:141]
	s_add_i32 m0, s44, 0xc000
	ds_read_b128 v[180:183], v189
	ds_read_b128 v[190:193], v189 offset:1024
	ds_read_b128 v[194:197], v189 offset:2048
	ds_read_b128 v[198:201], v189 offset:3072
	ds_read_b128 v[202:205], v189 offset:4096
	ds_read_b128 v[206:209], v189 offset:5120
	ds_read_b128 v[210:213], v189 offset:6144
	ds_read_b128 v[214:217], v189 offset:7168
	global_load_lds_dwordx4 v[184:185], off
	v_lshl_add_u64 v[184:185], s[26:27], 0, v[142:143]
	s_add_i32 m0, s44, 0xe000
	s_nop 0
	global_load_lds_dwordx4 v[184:185], off
	s_waitcnt vmcnt(8)
	s_waitcnt lgkmcnt(0)
	s_setprio 1
	s_waitcnt lgkmcnt(0)
	v_mfma_i32_16x16x64_i8 v[126:129], v[148:151], v[180:183], v[126:129]
	v_mfma_i32_16x16x64_i8 v[122:125], v[156:159], v[180:183], v[122:125]
	s_barrier
	v_mfma_i32_16x16x64_i8 v[118:121], v[148:151], v[194:197], v[118:121]
	v_mfma_i32_16x16x64_i8 v[114:117], v[156:159], v[194:197], v[114:117]
	v_mfma_i32_16x16x64_i8 v[106:109], v[148:151], v[202:205], v[106:109]
	v_mfma_i32_16x16x64_i8 v[98:101], v[156:159], v[202:205], v[98:101]
	v_mfma_i32_16x16x64_i8 v[90:93], v[148:151], v[210:213], v[90:93]
	v_mfma_i32_16x16x64_i8 v[82:85], v[156:159], v[210:213], v[82:85]
	v_mfma_i32_16x16x64_i8 v[126:129], v[152:155], v[190:193], v[126:129]
	v_mfma_i32_16x16x64_i8 v[122:125], v[160:163], v[190:193], v[122:125]
	v_mfma_i32_16x16x64_i8 v[118:121], v[152:155], v[198:201], v[118:121]
	v_mfma_i32_16x16x64_i8 v[114:117], v[160:163], v[198:201], v[114:117]
	v_mfma_i32_16x16x64_i8 v[106:109], v[152:155], v[206:209], v[106:109]
	v_mfma_i32_16x16x64_i8 v[98:101], v[160:163], v[206:209], v[98:101]
	v_mfma_i32_16x16x64_i8 v[90:93], v[152:155], v[214:217], v[90:93]
	v_mfma_i32_16x16x64_i8 v[82:85], v[160:163], v[214:217], v[82:85]
	s_setprio 0
	s_setprio 1
	v_mfma_i32_16x16x64_i8 v[110:113], v[164:167], v[180:183], v[110:113]
	v_mfma_i32_16x16x64_i8 v[102:105], v[172:175], v[180:183], v[102:105]
	v_mfma_i32_16x16x64_i8 v[94:97], v[164:167], v[194:197], v[94:97]
	v_mfma_i32_16x16x64_i8 v[86:89], v[172:175], v[194:197], v[86:89]
	v_mfma_i32_16x16x64_i8 v[78:81], v[164:167], v[202:205], v[78:81]
	v_mfma_i32_16x16x64_i8 v[74:77], v[172:175], v[202:205], v[74:77]
	v_mfma_i32_16x16x64_i8 v[70:73], v[164:167], v[210:213], v[70:73]
	v_mfma_i32_16x16x64_i8 v[66:69], v[172:175], v[210:213], v[66:69]
	v_mfma_i32_16x16x64_i8 v[110:113], v[168:171], v[190:193], v[110:113]
	v_mfma_i32_16x16x64_i8 v[102:105], v[176:179], v[190:193], v[102:105]
	v_mfma_i32_16x16x64_i8 v[94:97], v[168:171], v[198:201], v[94:97]
	v_mfma_i32_16x16x64_i8 v[86:89], v[176:179], v[198:201], v[86:89]
	v_mfma_i32_16x16x64_i8 v[78:81], v[168:171], v[206:209], v[78:81]
	v_mfma_i32_16x16x64_i8 v[74:77], v[176:179], v[206:209], v[74:77]
	v_mfma_i32_16x16x64_i8 v[70:73], v[168:171], v[214:217], v[70:73]
	v_mfma_i32_16x16x64_i8 v[66:69], v[176:179], v[214:217], v[66:69]
	s_setprio 0
	s_barrier
	s_add_i32 s67, s62, s43
	v_lshl_add_u64 v[184:185], s[68:69], 0, v[132:133]
	s_mov_b32 m0, s67
	ds_read_b128 v[180:183], v189 offset:16384
	ds_read_b128 v[190:193], v189 offset:17408
	ds_read_b128 v[194:197], v189 offset:18432
	ds_read_b128 v[198:201], v189 offset:19456
	ds_read_b128 v[202:205], v189 offset:20480
	ds_read_b128 v[206:209], v189 offset:21504
	ds_read_b128 v[210:213], v189 offset:22528
	ds_read_b128 v[214:217], v189 offset:23552
	global_load_lds_dwordx4 v[184:185], off
	s_add_i32 m0, s67, 0x2000
	v_lshl_add_u64 v[218:219], s[68:69], 0, v[136:137]
	s_add_u32 s68, s68, s6
	s_addc_u32 s69, s69, s7
	s_add_i32 s67, s63, s43
	global_load_lds_dwordx4 v[218:219], off
	v_lshl_add_u64 v[220:221], s[68:69], 0, v[132:133]
	s_mov_b32 m0, s67
	v_lshl_add_u64 v[222:223], s[68:69], 0, v[136:137]
	global_load_lds_dwordx4 v[220:221], off
	s_add_i32 m0, s67, 0x2000
	v_lshl_add_u64 v[224:225], s[28:29], 0, v[130:131]
	global_load_lds_dwordx4 v[222:223], off
	s_mov_b32 m0, s44
	v_lshl_add_u64 v[226:227], s[28:29], 0, v[134:135]
	global_load_lds_dwordx4 v[224:225], off
	s_mov_b32 m0, s45
	s_nop 0
	global_load_lds_dwordx4 v[226:227], off
	s_waitcnt vmcnt(8)
	s_waitcnt lgkmcnt(0)
	s_setprio 1
	s_waitcnt lgkmcnt(0)
	v_mfma_i32_16x16x64_i8 v[62:65], v[148:151], v[180:183], v[62:65]
	v_mfma_i32_16x16x64_i8 v[58:61], v[156:159], v[180:183], v[58:61]
	s_barrier
	v_mfma_i32_16x16x64_i8 v[54:57], v[148:151], v[194:197], v[54:57]
	v_mfma_i32_16x16x64_i8 v[50:53], v[156:159], v[194:197], v[50:53]
	v_mfma_i32_16x16x64_i8 v[42:45], v[148:151], v[202:205], v[42:45]
	v_mfma_i32_16x16x64_i8 v[34:37], v[156:159], v[202:205], v[34:37]
	v_mfma_i32_16x16x64_i8 v[26:29], v[148:151], v[210:213], v[26:29]
	v_mfma_i32_16x16x64_i8 v[18:21], v[156:159], v[210:213], v[18:21]
	v_mfma_i32_16x16x64_i8 v[62:65], v[152:155], v[190:193], v[62:65]
	v_mfma_i32_16x16x64_i8 v[58:61], v[160:163], v[190:193], v[58:61]
	v_mfma_i32_16x16x64_i8 v[54:57], v[152:155], v[198:201], v[54:57]
	v_mfma_i32_16x16x64_i8 v[50:53], v[160:163], v[198:201], v[50:53]
	v_mfma_i32_16x16x64_i8 v[42:45], v[152:155], v[206:209], v[42:45]
	v_mfma_i32_16x16x64_i8 v[34:37], v[160:163], v[206:209], v[34:37]
	v_mfma_i32_16x16x64_i8 v[26:29], v[152:155], v[214:217], v[26:29]
	v_mfma_i32_16x16x64_i8 v[18:21], v[160:163], v[214:217], v[18:21]
	s_setprio 0
	s_setprio 1
	v_mfma_i32_16x16x64_i8 v[46:49], v[164:167], v[180:183], v[46:49]
	v_mfma_i32_16x16x64_i8 v[38:41], v[172:175], v[180:183], v[38:41]
	v_mfma_i32_16x16x64_i8 v[30:33], v[164:167], v[194:197], v[30:33]
	v_mfma_i32_16x16x64_i8 v[22:25], v[172:175], v[194:197], v[22:25]
	v_mfma_i32_16x16x64_i8 v[14:17], v[164:167], v[202:205], v[14:17]
	v_mfma_i32_16x16x64_i8 v[10:13], v[172:175], v[202:205], v[10:13]
	v_mfma_i32_16x16x64_i8 v[6:9], v[164:167], v[210:213], v[6:9]
	v_mfma_i32_16x16x64_i8 v[2:5], v[172:175], v[210:213], v[2:5]
	v_mfma_i32_16x16x64_i8 v[46:49], v[168:171], v[190:193], v[46:49]
	v_mfma_i32_16x16x64_i8 v[38:41], v[176:179], v[190:193], v[38:41]
	v_mfma_i32_16x16x64_i8 v[30:33], v[168:171], v[198:201], v[30:33]
	v_mfma_i32_16x16x64_i8 v[22:25], v[176:179], v[198:201], v[22:25]
	v_mfma_i32_16x16x64_i8 v[14:17], v[168:171], v[206:209], v[14:17]
	v_mfma_i32_16x16x64_i8 v[10:13], v[176:179], v[206:209], v[10:13]
	v_mfma_i32_16x16x64_i8 v[6:9], v[168:171], v[214:217], v[6:9]
	v_mfma_i32_16x16x64_i8 v[2:5], v[176:179], v[214:217], v[2:5]
	s_setprio 0
	s_barrier
	s_add_i32 s67, 0, 0x18000
	v_add_u32_e32 v138, s67, v188
	s_add_i32 s68, 0, 0x1c000
	ds_read_b128 v[148:151], v138
	ds_read_b128 v[152:155], v138 offset:1024
	ds_read_b128 v[156:159], v138 offset:2048
	ds_read_b128 v[160:163], v138 offset:3072
	v_add_u32_e32 v138, s68, v188
	ds_read_b128 v[164:167], v138
	ds_read_b128 v[168:171], v138 offset:1024
	ds_read_b128 v[172:175], v138 offset:2048
	ds_read_b128 v[176:179], v138 offset:3072
	s_add_u32 s28, s28, s6
	s_addc_u32 s29, s29, s7
	s_mov_b32 m0, s46
	v_lshl_add_u64 v[228:229], s[28:29], 0, v[130:131]
	ds_read_b128 v[180:183], v189 offset:32768
	ds_read_b128 v[190:193], v189 offset:33792
	ds_read_b128 v[194:197], v189 offset:34816
	ds_read_b128 v[198:201], v189 offset:35840
	ds_read_b128 v[202:205], v189 offset:36864
	ds_read_b128 v[206:209], v189 offset:37888
	ds_read_b128 v[210:213], v189 offset:38912
	ds_read_b128 v[214:217], v189 offset:39936
	global_load_lds_dwordx4 v[228:229], off
	v_lshl_add_u64 v[228:229], s[28:29], 0, v[134:135]
	s_mov_b32 m0, s47
	s_nop 0
	global_load_lds_dwordx4 v[228:229], off
	s_waitcnt vmcnt(8)
	s_waitcnt lgkmcnt(0)
	s_setprio 1
	s_waitcnt lgkmcnt(0)
	v_mfma_i32_16x16x64_i8 v[126:129], v[148:151], v[180:183], v[126:129]
	v_mfma_i32_16x16x64_i8 v[122:125], v[156:159], v[180:183], v[122:125]
	s_barrier
	v_mfma_i32_16x16x64_i8 v[118:121], v[148:151], v[194:197], v[118:121]
	v_mfma_i32_16x16x64_i8 v[114:117], v[156:159], v[194:197], v[114:117]
	v_mfma_i32_16x16x64_i8 v[106:109], v[148:151], v[202:205], v[106:109]
	v_mfma_i32_16x16x64_i8 v[98:101], v[156:159], v[202:205], v[98:101]
	v_mfma_i32_16x16x64_i8 v[90:93], v[148:151], v[210:213], v[90:93]
	v_mfma_i32_16x16x64_i8 v[82:85], v[156:159], v[210:213], v[82:85]
	v_mfma_i32_16x16x64_i8 v[126:129], v[152:155], v[190:193], v[126:129]
	v_mfma_i32_16x16x64_i8 v[122:125], v[160:163], v[190:193], v[122:125]
	v_mfma_i32_16x16x64_i8 v[118:121], v[152:155], v[198:201], v[118:121]
	v_mfma_i32_16x16x64_i8 v[114:117], v[160:163], v[198:201], v[114:117]
	v_mfma_i32_16x16x64_i8 v[106:109], v[152:155], v[206:209], v[106:109]
	v_mfma_i32_16x16x64_i8 v[98:101], v[160:163], v[206:209], v[98:101]
	v_mfma_i32_16x16x64_i8 v[90:93], v[152:155], v[214:217], v[90:93]
	v_mfma_i32_16x16x64_i8 v[82:85], v[160:163], v[214:217], v[82:85]
	s_setprio 0
	s_setprio 1
	v_mfma_i32_16x16x64_i8 v[110:113], v[164:167], v[180:183], v[110:113]
	v_mfma_i32_16x16x64_i8 v[102:105], v[172:175], v[180:183], v[102:105]
	v_mfma_i32_16x16x64_i8 v[94:97], v[164:167], v[194:197], v[94:97]
	v_mfma_i32_16x16x64_i8 v[86:89], v[172:175], v[194:197], v[86:89]
	v_mfma_i32_16x16x64_i8 v[78:81], v[164:167], v[202:205], v[78:81]
	v_mfma_i32_16x16x64_i8 v[74:77], v[172:175], v[202:205], v[74:77]
	v_mfma_i32_16x16x64_i8 v[70:73], v[164:167], v[210:213], v[70:73]
	v_mfma_i32_16x16x64_i8 v[66:69], v[172:175], v[210:213], v[66:69]
	v_mfma_i32_16x16x64_i8 v[110:113], v[168:171], v[190:193], v[110:113]
	v_mfma_i32_16x16x64_i8 v[102:105], v[176:179], v[190:193], v[102:105]
	v_mfma_i32_16x16x64_i8 v[94:97], v[168:171], v[198:201], v[94:97]
	v_mfma_i32_16x16x64_i8 v[86:89], v[176:179], v[198:201], v[86:89]
	v_mfma_i32_16x16x64_i8 v[78:81], v[168:171], v[206:209], v[78:81]
	v_mfma_i32_16x16x64_i8 v[74:77], v[176:179], v[206:209], v[74:77]
	v_mfma_i32_16x16x64_i8 v[70:73], v[168:171], v[214:217], v[70:73]
	v_mfma_i32_16x16x64_i8 v[66:69], v[176:179], v[214:217], v[66:69]
	s_setprio 0
	s_barrier
	s_add_i32 s28, s67, s43
	v_lshl_add_u64 v[184:185], v[184:185], 0, s[18:19]
	s_mov_b32 m0, s28
	ds_read_b128 v[180:183], v189 offset:49152
	ds_read_b128 v[190:193], v189 offset:50176
	ds_read_b128 v[194:197], v189 offset:51200
	ds_read_b128 v[198:201], v189 offset:52224
	ds_read_b128 v[202:205], v189 offset:53248
	ds_read_b128 v[206:209], v189 offset:54272
	ds_read_b128 v[210:213], v189 offset:55296
	ds_read_b128 v[214:217], v189 offset:56320
	global_load_lds_dwordx4 v[184:185], off
	v_lshl_add_u64 v[184:185], v[218:219], 0, s[18:19]
	s_add_i32 m0, s28, 0x2000
	s_add_i32 s28, s68, s43
	global_load_lds_dwordx4 v[184:185], off
	v_lshl_add_u64 v[184:185], v[220:221], 0, s[18:19]
	s_mov_b32 m0, s28
	s_nop 0
	global_load_lds_dwordx4 v[184:185], off
	v_lshl_add_u64 v[184:185], v[222:223], 0, s[18:19]
	s_add_i32 m0, s28, 0x2000
	s_nop 0
	global_load_lds_dwordx4 v[184:185], off
	v_lshl_add_u64 v[184:185], v[224:225], 0, s[18:19]
	s_mov_b32 m0, s55
	s_nop 0
	global_load_lds_dwordx4 v[184:185], off
	v_lshl_add_u64 v[184:185], v[226:227], 0, s[18:19]
	s_mov_b32 m0, s56
	s_nop 0
	global_load_lds_dwordx4 v[184:185], off
	s_waitcnt vmcnt(8)
	s_waitcnt lgkmcnt(0)
	s_setprio 1
	s_waitcnt lgkmcnt(0)
	v_mfma_i32_16x16x64_i8 v[62:65], v[148:151], v[180:183], v[62:65]
	v_mfma_i32_16x16x64_i8 v[58:61], v[156:159], v[180:183], v[58:61]
	s_barrier
	v_mfma_i32_16x16x64_i8 v[54:57], v[148:151], v[194:197], v[54:57]
	v_mfma_i32_16x16x64_i8 v[50:53], v[156:159], v[194:197], v[50:53]
	v_mfma_i32_16x16x64_i8 v[42:45], v[148:151], v[202:205], v[42:45]
	v_mfma_i32_16x16x64_i8 v[34:37], v[156:159], v[202:205], v[34:37]
	v_mfma_i32_16x16x64_i8 v[26:29], v[148:151], v[210:213], v[26:29]
	v_mfma_i32_16x16x64_i8 v[18:21], v[156:159], v[210:213], v[18:21]
	v_mfma_i32_16x16x64_i8 v[62:65], v[152:155], v[190:193], v[62:65]
	v_mfma_i32_16x16x64_i8 v[58:61], v[160:163], v[190:193], v[58:61]
	v_mfma_i32_16x16x64_i8 v[54:57], v[152:155], v[198:201], v[54:57]
	v_mfma_i32_16x16x64_i8 v[50:53], v[160:163], v[198:201], v[50:53]
	v_mfma_i32_16x16x64_i8 v[42:45], v[152:155], v[206:209], v[42:45]
	v_mfma_i32_16x16x64_i8 v[34:37], v[160:163], v[206:209], v[34:37]
	v_mfma_i32_16x16x64_i8 v[26:29], v[152:155], v[214:217], v[26:29]
	v_mfma_i32_16x16x64_i8 v[18:21], v[160:163], v[214:217], v[18:21]
	s_setprio 0
	s_setprio 1
	v_mfma_i32_16x16x64_i8 v[46:49], v[164:167], v[180:183], v[46:49]
	v_mfma_i32_16x16x64_i8 v[38:41], v[172:175], v[180:183], v[38:41]
	v_mfma_i32_16x16x64_i8 v[30:33], v[164:167], v[194:197], v[30:33]
	v_mfma_i32_16x16x64_i8 v[22:25], v[172:175], v[194:197], v[22:25]
	v_mfma_i32_16x16x64_i8 v[14:17], v[164:167], v[202:205], v[14:17]
	v_mfma_i32_16x16x64_i8 v[10:13], v[172:175], v[202:205], v[10:13]
	v_mfma_i32_16x16x64_i8 v[6:9], v[164:167], v[210:213], v[6:9]
	v_mfma_i32_16x16x64_i8 v[2:5], v[172:175], v[210:213], v[2:5]
	v_mfma_i32_16x16x64_i8 v[46:49], v[168:171], v[190:193], v[46:49]
	v_mfma_i32_16x16x64_i8 v[38:41], v[176:179], v[190:193], v[38:41]
	v_mfma_i32_16x16x64_i8 v[30:33], v[168:171], v[198:201], v[30:33]
	v_mfma_i32_16x16x64_i8 v[22:25], v[176:179], v[198:201], v[22:25]
	v_mfma_i32_16x16x64_i8 v[14:17], v[168:171], v[206:209], v[14:17]
	v_mfma_i32_16x16x64_i8 v[10:13], v[176:179], v[206:209], v[10:13]
	v_mfma_i32_16x16x64_i8 v[6:9], v[168:171], v[214:217], v[6:9]
	v_mfma_i32_16x16x64_i8 v[2:5], v[176:179], v[214:217], v[2:5]
	s_setprio 0
	s_add_u32 s26, s26, 0x100
	s_addc_u32 s27, s27, 0
	s_add_u32 s34, s34, 0x100
	s_addc_u32 s35, s35, 0
	s_cmp_ge_i32 s66, s57
	s_mov_b32 s28, s66
	s_barrier
	s_cbranch_scc0 .LBB0_1939
	v_cvt_f32_i32_e32 v172, v126
	v_cvt_f32_i32_e32 v173, v127
	v_cvt_f32_i32_e32 v170, v128
	v_cvt_f32_i32_e32 v171, v129
	v_cvt_f32_i32_e32 v174, v122
	v_cvt_f32_i32_e32 v175, v123
	v_cvt_f32_i32_e32 v176, v124
	v_cvt_f32_i32_e32 v177, v125
	v_cvt_f32_i32_e32 v180, v110
	v_cvt_f32_i32_e32 v181, v111
	v_cvt_f32_i32_e32 v182, v112
	v_cvt_f32_i32_e32 v183, v113
	v_cvt_f32_i32_e32 v178, v102
	v_cvt_f32_i32_e32 v179, v103
	v_cvt_f32_i32_e32 v184, v104
	v_cvt_f32_i32_e32 v185, v105
	v_cvt_f32_i32_e32 v152, v118
	v_cvt_f32_i32_e32 v153, v119
	v_cvt_f32_i32_e32 v154, v120
	v_cvt_f32_i32_e32 v155, v121
	v_cvt_f32_i32_e32 v156, v114
	v_cvt_f32_i32_e32 v157, v115
	v_cvt_f32_i32_e32 v158, v116
	v_cvt_f32_i32_e32 v159, v117
	v_cvt_f32_i32_e32 v160, v94
	v_cvt_f32_i32_e32 v161, v95
	v_cvt_f32_i32_e32 v162, v96
	v_cvt_f32_i32_e32 v163, v97
	v_cvt_f32_i32_e32 v164, v86
	v_cvt_f32_i32_e32 v165, v87
	v_cvt_f32_i32_e32 v166, v88
	v_cvt_f32_i32_e32 v167, v89
	v_cvt_f32_i32_e32 v118, v106
	v_cvt_f32_i32_e32 v119, v107
	v_cvt_f32_i32_e32 v120, v108
	v_cvt_f32_i32_e32 v121, v109
	v_cvt_f32_i32_e32 v122, v98
	v_cvt_f32_i32_e32 v123, v99
	v_cvt_f32_i32_e32 v124, v100
	v_cvt_f32_i32_e32 v125, v101
	v_cvt_f32_i32_e32 v126, v78
	v_cvt_f32_i32_e32 v127, v79
	v_cvt_f32_i32_e32 v128, v80
	v_cvt_f32_i32_e32 v129, v81
	v_cvt_f32_i32_e32 v148, v74
	v_cvt_f32_i32_e32 v149, v75
	v_cvt_f32_i32_e32 v150, v76
	v_cvt_f32_i32_e32 v151, v77
	v_cvt_f32_i32_e32 v102, v90
	v_cvt_f32_i32_e32 v103, v91
	v_cvt_f32_i32_e32 v104, v92
	v_cvt_f32_i32_e32 v105, v93
	v_cvt_f32_i32_e32 v106, v82
	v_cvt_f32_i32_e32 v107, v83
	v_cvt_f32_i32_e32 v108, v84
	v_cvt_f32_i32_e32 v109, v85
	v_cvt_f32_i32_e32 v110, v70
	v_cvt_f32_i32_e32 v111, v71
	v_cvt_f32_i32_e32 v112, v72
	v_cvt_f32_i32_e32 v113, v73
	v_cvt_f32_i32_e32 v114, v66
	v_cvt_f32_i32_e32 v115, v67
	v_cvt_f32_i32_e32 v116, v68
	v_cvt_f32_i32_e32 v117, v69
	v_cvt_f32_i32_e32 v82, v62
	v_cvt_f32_i32_e32 v83, v63
	v_cvt_f32_i32_e32 v84, v64
	v_cvt_f32_i32_e32 v85, v65
	v_cvt_f32_i32_e32 v86, v58
	v_cvt_f32_i32_e32 v87, v59
	v_cvt_f32_i32_e32 v88, v60
	v_cvt_f32_i32_e32 v89, v61
	v_cvt_f32_i32_e32 v92, v46
	v_cvt_f32_i32_e32 v93, v47
	v_cvt_f32_i32_e32 v94, v48
	v_cvt_f32_i32_e32 v95, v49
	v_cvt_f32_i32_e32 v96, v38
	v_cvt_f32_i32_e32 v97, v39
	v_cvt_f32_i32_e32 v98, v40
	v_cvt_f32_i32_e32 v99, v41
	v_cvt_f32_i32_e32 v66, v54
	v_cvt_f32_i32_e32 v67, v55
	v_cvt_f32_i32_e32 v68, v56
	v_cvt_f32_i32_e32 v69, v57
	v_cvt_f32_i32_e32 v70, v50
	v_cvt_f32_i32_e32 v71, v51
	v_cvt_f32_i32_e32 v72, v52
	v_cvt_f32_i32_e32 v73, v53
	v_cvt_f32_i32_e32 v74, v30
	v_cvt_f32_i32_e32 v75, v31
	v_cvt_f32_i32_e32 v76, v32
	v_cvt_f32_i32_e32 v77, v33
	v_cvt_f32_i32_e32 v78, v22
	v_cvt_f32_i32_e32 v79, v23
	v_cvt_f32_i32_e32 v80, v24
	v_cvt_f32_i32_e32 v81, v25
	v_cvt_f32_i32_e32 v50, v42
	v_cvt_f32_i32_e32 v51, v43
	v_cvt_f32_i32_e32 v52, v44
	v_cvt_f32_i32_e32 v53, v45
	v_cvt_f32_i32_e32 v54, v34
	v_cvt_f32_i32_e32 v55, v35
	v_cvt_f32_i32_e32 v56, v36
	v_cvt_f32_i32_e32 v57, v37
	v_cvt_f32_i32_e32 v58, v14
	v_cvt_f32_i32_e32 v59, v15
	v_cvt_f32_i32_e32 v60, v16
	v_cvt_f32_i32_e32 v61, v17
	v_cvt_f32_i32_e32 v62, v10
	v_cvt_f32_i32_e32 v63, v11
	v_cvt_f32_i32_e32 v64, v12
	v_cvt_f32_i32_e32 v65, v13
	v_cvt_f32_i32_e32 v34, v26
	v_cvt_f32_i32_e32 v35, v27
	v_cvt_f32_i32_e32 v36, v28
	v_cvt_f32_i32_e32 v37, v29
	v_cvt_f32_i32_e32 v38, v18
	v_cvt_f32_i32_e32 v39, v19
	v_cvt_f32_i32_e32 v40, v20
	v_cvt_f32_i32_e32 v41, v21
	v_cvt_f32_i32_e32 v42, v6
	v_cvt_f32_i32_e32 v43, v7
	v_cvt_f32_i32_e32 v44, v8
	v_cvt_f32_i32_e32 v45, v9
	v_cvt_f32_i32_e32 v46, v2
	v_cvt_f32_i32_e32 v47, v3
	v_cvt_f32_i32_e32 v48, v4
	v_cvt_f32_i32_e32 v49, v5

.LBB0_2022:
	ds_read_b128 v[114:117], v209
	ds_read_b128 v[118:121], v209 offset:1024
	ds_read_b128 v[122:125], v209 offset:2048
	ds_read_b128 v[126:129], v209 offset:3072
	ds_read_b128 v[146:149], v210
	ds_read_b128 v[150:153], v210 offset:1024
	ds_read_b128 v[154:157], v210 offset:2048
	ds_read_b128 v[158:161], v210 offset:3072
	s_add_i32 s84, s36, 2
	s_add_u32 s37, s34, 0x4000
	s_addc_u32 s38, s35, 0
	s_cmp_eq_u32 s63, s36
	s_cselect_b32 s39, s5, s38
	s_cselect_b32 s38, s4, s37
	s_cselect_b32 s86, s30, s82
	s_cselect_b32 s87, s31, s83
	s_add_u32 s36, s38, 0x8000
	s_addc_u32 s37, s39, 0
	v_lshl_add_u64 v[218:219], s[34:35], 0, v[170:171]
	s_add_i32 m0, s47, 0xc000
	ds_read_b128 v[178:181], v211
	ds_read_b128 v[182:185], v211 offset:1024
	ds_read_b128 v[186:189], v211 offset:2048
	ds_read_b128 v[190:193], v211 offset:3072
	ds_read_b128 v[194:197], v211 offset:4096
	ds_read_b128 v[198:201], v211 offset:5120
	ds_read_b128 v[202:205], v211 offset:6144
	ds_read_b128 v[214:217], v211 offset:7168
	global_load_lds_dwordx4 v[218:219], off
	v_lshl_add_u64 v[218:219], s[34:35], 0, v[172:173]
	s_add_i32 m0, s47, 0xe000
	s_nop 0
	global_load_lds_dwordx4 v[218:219], off
	s_waitcnt vmcnt(8)
	s_waitcnt lgkmcnt(0)
	s_setprio 1
	s_waitcnt lgkmcnt(0)
	v_mfma_f32_16x16x32_bf16 v[142:145], v[114:117], v[178:181], v[142:145]
	v_mfma_f32_16x16x32_bf16 v[138:141], v[122:125], v[178:181], v[138:141]
	s_barrier
	v_mfma_f32_16x16x32_bf16 v[110:113], v[114:117], v[186:189], v[110:113]
	v_mfma_f32_16x16x32_bf16 v[106:109], v[122:125], v[186:189], v[106:109]
	v_mfma_f32_16x16x32_bf16 v[94:97], v[114:117], v[194:197], v[94:97]
	v_mfma_f32_16x16x32_bf16 v[90:93], v[122:125], v[194:197], v[90:93]
	v_mfma_f32_16x16x32_bf16 v[78:81], v[114:117], v[202:205], v[78:81]
	v_mfma_f32_16x16x32_bf16 v[74:77], v[122:125], v[202:205], v[74:77]
	v_mfma_f32_16x16x32_bf16 v[142:145], v[118:121], v[182:185], v[142:145]
	v_mfma_f32_16x16x32_bf16 v[138:141], v[126:129], v[182:185], v[138:141]
	v_mfma_f32_16x16x32_bf16 v[110:113], v[118:121], v[190:193], v[110:113]
	v_mfma_f32_16x16x32_bf16 v[106:109], v[126:129], v[190:193], v[106:109]
	v_mfma_f32_16x16x32_bf16 v[94:97], v[118:121], v[198:201], v[94:97]
	v_mfma_f32_16x16x32_bf16 v[90:93], v[126:129], v[198:201], v[90:93]
	v_mfma_f32_16x16x32_bf16 v[78:81], v[118:121], v[214:217], v[78:81]
	v_mfma_f32_16x16x32_bf16 v[74:77], v[126:129], v[214:217], v[74:77]
	s_setprio 0
	s_setprio 1
	v_mfma_f32_16x16x32_bf16 v[134:137], v[146:149], v[178:181], v[134:137]
	v_mfma_f32_16x16x32_bf16 v[130:133], v[154:157], v[178:181], v[130:133]
	v_mfma_f32_16x16x32_bf16 v[102:105], v[146:149], v[186:189], v[102:105]
	v_mfma_f32_16x16x32_bf16 v[98:101], v[154:157], v[186:189], v[98:101]
	v_mfma_f32_16x16x32_bf16 v[86:89], v[146:149], v[194:197], v[86:89]
	v_mfma_f32_16x16x32_bf16 v[82:85], v[154:157], v[194:197], v[82:85]
	v_mfma_f32_16x16x32_bf16 v[70:73], v[146:149], v[202:205], v[70:73]
	v_mfma_f32_16x16x32_bf16 v[66:69], v[154:157], v[202:205], v[66:69]
	v_mfma_f32_16x16x32_bf16 v[134:137], v[150:153], v[182:185], v[134:137]
	v_mfma_f32_16x16x32_bf16 v[130:133], v[158:161], v[182:185], v[130:133]
	v_mfma_f32_16x16x32_bf16 v[102:105], v[150:153], v[190:193], v[102:105]
	v_mfma_f32_16x16x32_bf16 v[98:101], v[158:161], v[190:193], v[98:101]
	v_mfma_f32_16x16x32_bf16 v[86:89], v[150:153], v[198:201], v[86:89]
	v_mfma_f32_16x16x32_bf16 v[82:85], v[158:161], v[198:201], v[82:85]
	v_mfma_f32_16x16x32_bf16 v[70:73], v[150:153], v[214:217], v[70:73]
	v_mfma_f32_16x16x32_bf16 v[66:69], v[158:161], v[214:217], v[66:69]
	s_setprio 0
	s_barrier
	s_add_i32 s85, s66, s46
	v_lshl_add_u64 v[218:219], s[86:87], 0, v[164:165]
	s_mov_b32 m0, s85
	ds_read_b128 v[178:181], v211 offset:16384
	ds_read_b128 v[182:185], v211 offset:17408
	ds_read_b128 v[186:189], v211 offset:18432
	ds_read_b128 v[190:193], v211 offset:19456
	ds_read_b128 v[194:197], v211 offset:20480
	ds_read_b128 v[198:201], v211 offset:21504
	ds_read_b128 v[202:205], v211 offset:22528
	ds_read_b128 v[214:217], v211 offset:23552
	global_load_lds_dwordx4 v[218:219], off
	s_add_i32 m0, s85, 0x2000
	v_lshl_add_u64 v[220:221], s[86:87], 0, v[168:169]
	s_add_u32 s86, s86, s8
	s_addc_u32 s87, s87, s9
	s_add_i32 s85, s67, s46
	global_load_lds_dwordx4 v[220:221], off
	v_lshl_add_u64 v[222:223], s[86:87], 0, v[164:165]
	s_mov_b32 m0, s85
	v_lshl_add_u64 v[224:225], s[86:87], 0, v[168:169]
	global_load_lds_dwordx4 v[222:223], off
	s_add_i32 m0, s85, 0x2000
	v_lshl_add_u64 v[226:227], s[38:39], 0, v[162:163]
	global_load_lds_dwordx4 v[224:225], off
	s_mov_b32 m0, s47
	s_nop 0
	global_load_lds_dwordx4 v[226:227], off
	v_lshl_add_u64 v[226:227], s[38:39], 0, v[166:167]
	s_mov_b32 m0, s50
	s_nop 0
	global_load_lds_dwordx4 v[226:227], off
	s_waitcnt vmcnt(8)
	s_waitcnt lgkmcnt(0)
	s_setprio 1
	s_waitcnt lgkmcnt(0)
	v_mfma_f32_16x16x32_bf16 v[62:65], v[114:117], v[178:181], v[62:65]
	v_mfma_f32_16x16x32_bf16 v[58:61], v[122:125], v[178:181], v[58:61]
	s_barrier
	v_mfma_f32_16x16x32_bf16 v[46:49], v[114:117], v[186:189], v[46:49]
	v_mfma_f32_16x16x32_bf16 v[42:45], v[122:125], v[186:189], v[42:45]
	v_mfma_f32_16x16x32_bf16 v[30:33], v[114:117], v[194:197], v[30:33]
	v_mfma_f32_16x16x32_bf16 v[26:29], v[122:125], v[194:197], v[26:29]
	v_mfma_f32_16x16x32_bf16 v[14:17], v[114:117], v[202:205], v[14:17]
	v_mfma_f32_16x16x32_bf16 v[10:13], v[122:125], v[202:205], v[10:13]
	v_mfma_f32_16x16x32_bf16 v[62:65], v[118:121], v[182:185], v[62:65]
	v_mfma_f32_16x16x32_bf16 v[58:61], v[126:129], v[182:185], v[58:61]
	v_mfma_f32_16x16x32_bf16 v[46:49], v[118:121], v[190:193], v[46:49]
	v_mfma_f32_16x16x32_bf16 v[42:45], v[126:129], v[190:193], v[42:45]
	v_mfma_f32_16x16x32_bf16 v[30:33], v[118:121], v[198:201], v[30:33]
	v_mfma_f32_16x16x32_bf16 v[26:29], v[126:129], v[198:201], v[26:29]
	v_mfma_f32_16x16x32_bf16 v[14:17], v[118:121], v[214:217], v[14:17]
	v_mfma_f32_16x16x32_bf16 v[10:13], v[126:129], v[214:217], v[10:13]
	s_setprio 0
	s_setprio 1
	v_mfma_f32_16x16x32_bf16 v[54:57], v[146:149], v[178:181], v[54:57]
	v_mfma_f32_16x16x32_bf16 v[50:53], v[154:157], v[178:181], v[50:53]
	v_mfma_f32_16x16x32_bf16 v[38:41], v[146:149], v[186:189], v[38:41]
	v_mfma_f32_16x16x32_bf16 v[34:37], v[154:157], v[186:189], v[34:37]
	v_mfma_f32_16x16x32_bf16 v[22:25], v[146:149], v[194:197], v[22:25]
	v_mfma_f32_16x16x32_bf16 v[18:21], v[154:157], v[194:197], v[18:21]
	v_mfma_f32_16x16x32_bf16 v[6:9], v[146:149], v[202:205], v[6:9]
	v_mfma_f32_16x16x32_bf16 v[2:5], v[154:157], v[202:205], v[2:5]
	v_mfma_f32_16x16x32_bf16 v[54:57], v[150:153], v[182:185], v[54:57]
	v_mfma_f32_16x16x32_bf16 v[50:53], v[158:161], v[182:185], v[50:53]
	v_mfma_f32_16x16x32_bf16 v[38:41], v[150:153], v[190:193], v[38:41]
	v_mfma_f32_16x16x32_bf16 v[34:37], v[158:161], v[190:193], v[34:37]
	v_mfma_f32_16x16x32_bf16 v[22:25], v[150:153], v[198:201], v[22:25]
	v_mfma_f32_16x16x32_bf16 v[18:21], v[158:161], v[198:201], v[18:21]
	v_mfma_f32_16x16x32_bf16 v[6:9], v[150:153], v[214:217], v[6:9]
	v_mfma_f32_16x16x32_bf16 v[2:5], v[158:161], v[214:217], v[2:5]
	s_setprio 0
	s_barrier
	s_add_i32 s85, 0, 0x18000
	s_add_i32 s86, 0, 0x1c000
	v_add_u32_e32 v126, s85, v207
	v_add_u32_e32 v158, s86, v207
	ds_read_b128 v[114:117], v126
	ds_read_b128 v[118:121], v126 offset:1024
	ds_read_b128 v[122:125], v126 offset:2048
	ds_read_b128 v[126:129], v126 offset:3072
	ds_read_b128 v[146:149], v158
	ds_read_b128 v[150:153], v158 offset:1024
	ds_read_b128 v[154:157], v158 offset:2048
	ds_read_b128 v[158:161], v158 offset:3072
	s_add_u32 s38, s38, 0x4000
	s_addc_u32 s39, s39, 0
	s_mov_b32 m0, s51
	v_lshl_add_u64 v[226:227], s[38:39], 0, v[162:163]
	ds_read_b128 v[178:181], v211 offset:32768
	ds_read_b128 v[182:185], v211 offset:33792
	ds_read_b128 v[186:189], v211 offset:34816
	ds_read_b128 v[190:193], v211 offset:35840
	ds_read_b128 v[194:197], v211 offset:36864
	ds_read_b128 v[198:201], v211 offset:37888
	ds_read_b128 v[202:205], v211 offset:38912
	ds_read_b128 v[214:217], v211 offset:39936
	global_load_lds_dwordx4 v[226:227], off
	v_lshl_add_u64 v[226:227], s[38:39], 0, v[166:167]
	s_mov_b32 m0, s54
	s_nop 0
	global_load_lds_dwordx4 v[226:227], off
	s_waitcnt vmcnt(8)
	s_waitcnt lgkmcnt(0)
	s_setprio 1
	s_waitcnt lgkmcnt(0)
	v_mfma_f32_16x16x32_bf16 v[142:145], v[114:117], v[178:181], v[142:145]
	v_mfma_f32_16x16x32_bf16 v[138:141], v[122:125], v[178:181], v[138:141]
	s_barrier
	v_mfma_f32_16x16x32_bf16 v[110:113], v[114:117], v[186:189], v[110:113]
	v_mfma_f32_16x16x32_bf16 v[106:109], v[122:125], v[186:189], v[106:109]
	v_mfma_f32_16x16x32_bf16 v[94:97], v[114:117], v[194:197], v[94:97]
	v_mfma_f32_16x16x32_bf16 v[90:93], v[122:125], v[194:197], v[90:93]
	v_mfma_f32_16x16x32_bf16 v[78:81], v[114:117], v[202:205], v[78:81]
	v_mfma_f32_16x16x32_bf16 v[74:77], v[122:125], v[202:205], v[74:77]
	v_mfma_f32_16x16x32_bf16 v[142:145], v[118:121], v[182:185], v[142:145]
	v_mfma_f32_16x16x32_bf16 v[138:141], v[126:129], v[182:185], v[138:141]
	v_mfma_f32_16x16x32_bf16 v[110:113], v[118:121], v[190:193], v[110:113]
	v_mfma_f32_16x16x32_bf16 v[106:109], v[126:129], v[190:193], v[106:109]
	v_mfma_f32_16x16x32_bf16 v[94:97], v[118:121], v[198:201], v[94:97]
	v_mfma_f32_16x16x32_bf16 v[90:93], v[126:129], v[198:201], v[90:93]
	v_mfma_f32_16x16x32_bf16 v[78:81], v[118:121], v[214:217], v[78:81]
	v_mfma_f32_16x16x32_bf16 v[74:77], v[126:129], v[214:217], v[74:77]
	s_setprio 0
	s_setprio 1
	v_mfma_f32_16x16x32_bf16 v[134:137], v[146:149], v[178:181], v[134:137]
	v_mfma_f32_16x16x32_bf16 v[130:133], v[154:157], v[178:181], v[130:133]
	v_mfma_f32_16x16x32_bf16 v[102:105], v[146:149], v[186:189], v[102:105]
	v_mfma_f32_16x16x32_bf16 v[98:101], v[154:157], v[186:189], v[98:101]
	v_mfma_f32_16x16x32_bf16 v[86:89], v[146:149], v[194:197], v[86:89]
	v_mfma_f32_16x16x32_bf16 v[82:85], v[154:157], v[194:197], v[82:85]
	v_mfma_f32_16x16x32_bf16 v[70:73], v[146:149], v[202:205], v[70:73]
	v_mfma_f32_16x16x32_bf16 v[66:69], v[154:157], v[202:205], v[66:69]
	v_mfma_f32_16x16x32_bf16 v[134:137], v[150:153], v[182:185], v[134:137]
	v_mfma_f32_16x16x32_bf16 v[130:133], v[158:161], v[182:185], v[130:133]
	v_mfma_f32_16x16x32_bf16 v[102:105], v[150:153], v[190:193], v[102:105]
	v_mfma_f32_16x16x32_bf16 v[98:101], v[158:161], v[190:193], v[98:101]
	v_mfma_f32_16x16x32_bf16 v[86:89], v[150:153], v[198:201], v[86:89]
	v_mfma_f32_16x16x32_bf16 v[82:85], v[158:161], v[198:201], v[82:85]
	v_mfma_f32_16x16x32_bf16 v[70:73], v[150:153], v[214:217], v[70:73]
	v_mfma_f32_16x16x32_bf16 v[66:69], v[158:161], v[214:217], v[66:69]
	s_setprio 0
	s_barrier
	s_add_i32 s38, s85, s46
	v_lshl_add_u64 v[218:219], v[218:219], 0, s[24:25]
	s_mov_b32 m0, s38
	ds_read_b128 v[178:181], v211 offset:49152
	ds_read_b128 v[182:185], v211 offset:50176
	ds_read_b128 v[186:189], v211 offset:51200
	ds_read_b128 v[190:193], v211 offset:52224
	ds_read_b128 v[194:197], v211 offset:53248
	ds_read_b128 v[198:201], v211 offset:54272
	ds_read_b128 v[202:205], v211 offset:55296
	ds_read_b128 v[214:217], v211 offset:56320
	global_load_lds_dwordx4 v[218:219], off
	v_lshl_add_u64 v[218:219], v[220:221], 0, s[24:25]
	s_add_i32 m0, s38, 0x2000
	s_add_i32 s38, s86, s46
	global_load_lds_dwordx4 v[218:219], off
	v_lshl_add_u64 v[218:219], v[222:223], 0, s[24:25]
	s_mov_b32 m0, s38
	s_nop 0
	global_load_lds_dwordx4 v[218:219], off
	v_lshl_add_u64 v[218:219], v[224:225], 0, s[24:25]
	s_add_i32 m0, s38, 0x2000
	s_nop 0
	global_load_lds_dwordx4 v[218:219], off
	v_lshl_add_u64 v[218:219], s[36:37], 0, v[162:163]
	s_mov_b32 m0, s61
	s_nop 0
	global_load_lds_dwordx4 v[218:219], off
	v_lshl_add_u64 v[218:219], s[36:37], 0, v[166:167]
	s_mov_b32 m0, s62
	s_nop 0
	global_load_lds_dwordx4 v[218:219], off
	s_waitcnt vmcnt(8)
	s_waitcnt lgkmcnt(0)
	s_setprio 1
	s_waitcnt lgkmcnt(0)
	v_mfma_f32_16x16x32_bf16 v[62:65], v[114:117], v[178:181], v[62:65]
	v_mfma_f32_16x16x32_bf16 v[58:61], v[122:125], v[178:181], v[58:61]
	s_barrier
	v_mfma_f32_16x16x32_bf16 v[46:49], v[114:117], v[186:189], v[46:49]
	v_mfma_f32_16x16x32_bf16 v[42:45], v[122:125], v[186:189], v[42:45]
	v_mfma_f32_16x16x32_bf16 v[30:33], v[114:117], v[194:197], v[30:33]
	v_mfma_f32_16x16x32_bf16 v[26:29], v[122:125], v[194:197], v[26:29]
	v_mfma_f32_16x16x32_bf16 v[14:17], v[114:117], v[202:205], v[14:17]
	v_mfma_f32_16x16x32_bf16 v[10:13], v[122:125], v[202:205], v[10:13]
	v_mfma_f32_16x16x32_bf16 v[62:65], v[118:121], v[182:185], v[62:65]
	v_mfma_f32_16x16x32_bf16 v[58:61], v[126:129], v[182:185], v[58:61]
	v_mfma_f32_16x16x32_bf16 v[46:49], v[118:121], v[190:193], v[46:49]
	v_mfma_f32_16x16x32_bf16 v[42:45], v[126:129], v[190:193], v[42:45]
	v_mfma_f32_16x16x32_bf16 v[30:33], v[118:121], v[198:201], v[30:33]
	v_mfma_f32_16x16x32_bf16 v[26:29], v[126:129], v[198:201], v[26:29]
	v_mfma_f32_16x16x32_bf16 v[14:17], v[118:121], v[214:217], v[14:17]
	v_mfma_f32_16x16x32_bf16 v[10:13], v[126:129], v[214:217], v[10:13]
	s_setprio 0
	s_setprio 1
	v_mfma_f32_16x16x32_bf16 v[54:57], v[146:149], v[178:181], v[54:57]
	v_mfma_f32_16x16x32_bf16 v[50:53], v[154:157], v[178:181], v[50:53]
	v_mfma_f32_16x16x32_bf16 v[38:41], v[146:149], v[186:189], v[38:41]
	v_mfma_f32_16x16x32_bf16 v[34:37], v[154:157], v[186:189], v[34:37]
	v_mfma_f32_16x16x32_bf16 v[22:25], v[146:149], v[194:197], v[22:25]
	v_mfma_f32_16x16x32_bf16 v[18:21], v[154:157], v[194:197], v[18:21]
	v_mfma_f32_16x16x32_bf16 v[6:9], v[146:149], v[202:205], v[6:9]
	v_mfma_f32_16x16x32_bf16 v[2:5], v[154:157], v[202:205], v[2:5]
	v_mfma_f32_16x16x32_bf16 v[54:57], v[150:153], v[182:185], v[54:57]
	v_mfma_f32_16x16x32_bf16 v[50:53], v[158:161], v[182:185], v[50:53]
	v_mfma_f32_16x16x32_bf16 v[38:41], v[150:153], v[190:193], v[38:41]
	v_mfma_f32_16x16x32_bf16 v[34:37], v[158:161], v[190:193], v[34:37]
	v_mfma_f32_16x16x32_bf16 v[22:25], v[150:153], v[198:201], v[22:25]
	v_mfma_f32_16x16x32_bf16 v[18:21], v[158:161], v[198:201], v[18:21]
	v_mfma_f32_16x16x32_bf16 v[6:9], v[150:153], v[214:217], v[6:9]
	v_mfma_f32_16x16x32_bf16 v[2:5], v[158:161], v[214:217], v[2:5]
	s_setprio 0
	s_add_u32 s82, s82, 0x100
	s_addc_u32 s83, s83, 0
	s_add_u32 s34, s34, 0x10000
	s_addc_u32 s35, s35, 0
	s_cmp_ge_i32 s84, s60
	s_mov_b32 s36, s84
	s_barrier
	s_cbranch_scc0 .LBB0_2022

.LBB0_2116:
	ds_read_b128 v[34:37], v186
	ds_read_b128 v[38:41], v186 offset:1024
	ds_read_b128 v[50:53], v186 offset:2048
	ds_read_b128 v[54:57], v186 offset:3072
	ds_read_b128 v[168:171], v187
	ds_read_b128 v[172:175], v187 offset:1024
	ds_read_b128 v[176:179], v187 offset:2048
	ds_read_b128 v[192:195], v187 offset:3072
	s_add_i32 s47, s4, 2
	s_add_u32 s50, s2, 0x80
	s_addc_u32 s5, s3, 0
	s_cmp_eq_u32 s85, s4
	s_cselect_b32 s4, s42, s50
	s_cselect_b32 s5, s43, s5
	s_cselect_b32 s51, s45, s7
	s_cselect_b32 s50, s44, s6
	v_lshl_add_u64 v[228:229], s[2:3], 0, v[160:161]
	s_add_i32 m0, s65, 0xc000
	ds_read_b128 v[196:199], v188
	ds_read_b128 v[200:203], v188 offset:1024
	ds_read_b128 v[204:207], v188 offset:2048
	ds_read_b128 v[208:211], v188 offset:3072
	ds_read_b128 v[212:215], v188 offset:4096
	ds_read_b128 v[216:219], v188 offset:5120
	ds_read_b128 v[220:223], v188 offset:6144
	ds_read_b128 v[224:227], v188 offset:7168
	global_load_lds_dwordx4 v[228:229], off
	v_lshl_add_u64 v[228:229], s[2:3], 0, v[162:163]
	s_add_i32 m0, s65, 0xe000
	s_nop 0
	global_load_lds_dwordx4 v[228:229], off
	s_waitcnt vmcnt(8)
	s_waitcnt lgkmcnt(0)
	s_setprio 1
	s_waitcnt lgkmcnt(0)
	v_mfma_f32_16x16x32_bf16 v[142:145], v[34:37], v[196:199], v[142:145]
	v_mfma_f32_16x16x32_bf16 v[138:141], v[50:53], v[196:199], v[138:141]
	s_barrier
	v_mfma_f32_16x16x32_bf16 v[126:129], v[34:37], v[204:207], v[126:129]
	v_mfma_f32_16x16x32_bf16 v[122:125], v[50:53], v[204:207], v[122:125]
	v_mfma_f32_16x16x32_bf16 v[110:113], v[34:37], v[212:215], v[110:113]
	v_mfma_f32_16x16x32_bf16 v[106:109], v[50:53], v[212:215], v[106:109]
	v_mfma_f32_16x16x32_bf16 v[94:97], v[34:37], v[220:223], v[94:97]
	v_mfma_f32_16x16x32_bf16 v[90:93], v[50:53], v[220:223], v[90:93]
	v_mfma_f32_16x16x32_bf16 v[142:145], v[38:41], v[200:203], v[142:145]
	v_mfma_f32_16x16x32_bf16 v[138:141], v[54:57], v[200:203], v[138:141]
	v_mfma_f32_16x16x32_bf16 v[126:129], v[38:41], v[208:211], v[126:129]
	v_mfma_f32_16x16x32_bf16 v[122:125], v[54:57], v[208:211], v[122:125]
	v_mfma_f32_16x16x32_bf16 v[110:113], v[38:41], v[216:219], v[110:113]
	v_mfma_f32_16x16x32_bf16 v[106:109], v[54:57], v[216:219], v[106:109]
	v_mfma_f32_16x16x32_bf16 v[94:97], v[38:41], v[224:227], v[94:97]
	v_mfma_f32_16x16x32_bf16 v[90:93], v[54:57], v[224:227], v[90:93]
	s_setprio 0
	s_setprio 1
	v_mfma_f32_16x16x32_bf16 v[134:137], v[168:171], v[196:199], v[134:137]
	v_mfma_f32_16x16x32_bf16 v[130:133], v[176:179], v[196:199], v[130:133]
	v_mfma_f32_16x16x32_bf16 v[118:121], v[168:171], v[204:207], v[118:121]
	v_mfma_f32_16x16x32_bf16 v[114:117], v[176:179], v[204:207], v[114:117]
	v_mfma_f32_16x16x32_bf16 v[102:105], v[168:171], v[212:215], v[102:105]
	v_mfma_f32_16x16x32_bf16 v[98:101], v[176:179], v[212:215], v[98:101]
	v_mfma_f32_16x16x32_bf16 v[86:89], v[168:171], v[220:223], v[86:89]
	v_mfma_f32_16x16x32_bf16 v[82:85], v[176:179], v[220:223], v[82:85]
	v_mfma_f32_16x16x32_bf16 v[134:137], v[172:175], v[200:203], v[134:137]
	v_mfma_f32_16x16x32_bf16 v[130:133], v[192:195], v[200:203], v[130:133]
	v_mfma_f32_16x16x32_bf16 v[118:121], v[172:175], v[208:211], v[118:121]
	v_mfma_f32_16x16x32_bf16 v[114:117], v[192:195], v[208:211], v[114:117]
	v_mfma_f32_16x16x32_bf16 v[102:105], v[172:175], v[216:219], v[102:105]
	v_mfma_f32_16x16x32_bf16 v[98:101], v[192:195], v[216:219], v[98:101]
	v_mfma_f32_16x16x32_bf16 v[86:89], v[172:175], v[224:227], v[86:89]
	v_mfma_f32_16x16x32_bf16 v[82:85], v[192:195], v[224:227], v[82:85]
	s_setprio 0
	s_barrier
	s_add_i32 s55, s88, s62
	v_lshl_add_u64 v[228:229], s[50:51], 0, v[148:149]
	s_mov_b32 m0, s55
	ds_read_b128 v[196:199], v188 offset:16384
	ds_read_b128 v[200:203], v188 offset:17408
	ds_read_b128 v[204:207], v188 offset:18432
	ds_read_b128 v[208:211], v188 offset:19456
	ds_read_b128 v[212:215], v188 offset:20480
	ds_read_b128 v[216:219], v188 offset:21504
	ds_read_b128 v[220:223], v188 offset:22528
	ds_read_b128 v[224:227], v188 offset:23552
	global_load_lds_dwordx4 v[228:229], off
	s_add_i32 m0, s55, 0x2000
	v_lshl_add_u64 v[230:231], s[50:51], 0, v[152:153]
	s_add_u32 s50, s50, s14
	s_addc_u32 s51, s51, s15
	s_add_i32 s55, s89, s62
	global_load_lds_dwordx4 v[230:231], off
	v_lshl_add_u64 v[232:233], s[50:51], 0, v[148:149]
	s_mov_b32 m0, s55
	v_lshl_add_u64 v[234:235], s[50:51], 0, v[152:153]
	global_load_lds_dwordx4 v[232:233], off
	s_add_i32 m0, s55, 0x2000
	v_lshl_add_u64 v[236:237], s[4:5], 0, v[146:147]
	global_load_lds_dwordx4 v[234:235], off
	s_mov_b32 m0, s65
	v_lshl_add_u64 v[238:239], s[4:5], 0, v[150:151]
	global_load_lds_dwordx4 v[236:237], off
	s_mov_b32 m0, s66
	s_nop 0
	global_load_lds_dwordx4 v[238:239], off
	s_waitcnt vmcnt(8)
	s_waitcnt lgkmcnt(0)
	s_setprio 1
	s_waitcnt lgkmcnt(0)
	v_mfma_f32_16x16x32_bf16 v[78:81], v[34:37], v[196:199], v[78:81]
	v_mfma_f32_16x16x32_bf16 v[74:77], v[50:53], v[196:199], v[74:77]
	s_barrier
	v_mfma_f32_16x16x32_bf16 v[62:65], v[34:37], v[204:207], v[62:65]
	v_mfma_f32_16x16x32_bf16 v[58:61], v[50:53], v[204:207], v[58:61]
	v_mfma_f32_16x16x32_bf16 v[30:33], v[34:37], v[212:215], v[30:33]
	v_mfma_f32_16x16x32_bf16 v[26:29], v[50:53], v[212:215], v[26:29]
	v_mfma_f32_16x16x32_bf16 v[14:17], v[34:37], v[220:223], v[14:17]
	v_mfma_f32_16x16x32_bf16 v[10:13], v[50:53], v[220:223], v[10:13]
	v_mfma_f32_16x16x32_bf16 v[78:81], v[38:41], v[200:203], v[78:81]
	v_mfma_f32_16x16x32_bf16 v[74:77], v[54:57], v[200:203], v[74:77]
	v_mfma_f32_16x16x32_bf16 v[62:65], v[38:41], v[208:211], v[62:65]
	v_mfma_f32_16x16x32_bf16 v[58:61], v[54:57], v[208:211], v[58:61]
	v_mfma_f32_16x16x32_bf16 v[30:33], v[38:41], v[216:219], v[30:33]
	v_mfma_f32_16x16x32_bf16 v[26:29], v[54:57], v[216:219], v[26:29]
	v_mfma_f32_16x16x32_bf16 v[14:17], v[38:41], v[224:227], v[14:17]
	v_mfma_f32_16x16x32_bf16 v[10:13], v[54:57], v[224:227], v[10:13]
	s_setprio 0
	s_setprio 1
	v_mfma_f32_16x16x32_bf16 v[46:49], v[168:171], v[204:207], v[46:49]
	v_mfma_f32_16x16x32_bf16 v[42:45], v[176:179], v[204:207], v[42:45]
	v_mfma_f32_16x16x32_bf16 v[22:25], v[168:171], v[212:215], v[22:25]
	v_mfma_f32_16x16x32_bf16 v[18:21], v[176:179], v[212:215], v[18:21]
	v_mfma_f32_16x16x32_bf16 v[6:9], v[168:171], v[220:223], v[6:9]
	v_mfma_f32_16x16x32_bf16 v[2:5], v[176:179], v[220:223], v[2:5]
	v_mfma_f32_16x16x32_bf16 v[34:37], v[168:171], v[196:199], v[70:73]
	v_mfma_f32_16x16x32_bf16 v[38:41], v[176:179], v[196:199], v[66:69]
	v_mfma_f32_16x16x32_bf16 v[46:49], v[172:175], v[208:211], v[46:49]
	v_mfma_f32_16x16x32_bf16 v[42:45], v[192:195], v[208:211], v[42:45]
	v_mfma_f32_16x16x32_bf16 v[22:25], v[172:175], v[216:219], v[22:25]
	v_mfma_f32_16x16x32_bf16 v[18:21], v[192:195], v[216:219], v[18:21]
	v_mfma_f32_16x16x32_bf16 v[6:9], v[172:175], v[224:227], v[6:9]
	v_mfma_f32_16x16x32_bf16 v[2:5], v[192:195], v[224:227], v[2:5]
	v_mfma_f32_16x16x32_bf16 v[34:37], v[172:175], v[200:203], v[34:37]
	v_mfma_f32_16x16x32_bf16 v[38:41], v[192:195], v[200:203], v[38:41]
	s_setprio 0
	s_barrier
	s_add_i32 s50, 0, 0x18000
	s_add_i32 s51, 0, 0x1c000
	v_add_u32_e32 v70, s50, v184
	v_add_u32_e32 v154, s51, v184
	ds_read_b128 v[50:53], v70
	ds_read_b128 v[54:57], v70 offset:1024
	ds_read_b128 v[66:69], v70 offset:2048
	ds_read_b128 v[70:73], v70 offset:3072
	ds_read_b128 v[168:171], v154
	ds_read_b128 v[172:175], v154 offset:1024
	ds_read_b128 v[176:179], v154 offset:2048
	ds_read_b128 v[192:195], v154 offset:3072
	s_add_u32 s4, s4, s14
	s_addc_u32 s5, s5, s15
	s_mov_b32 m0, s67
	v_lshl_add_u64 v[240:241], s[4:5], 0, v[146:147]
	ds_read_b128 v[196:199], v188 offset:32768
	ds_read_b128 v[200:203], v188 offset:33792
	ds_read_b128 v[204:207], v188 offset:34816
	ds_read_b128 v[208:211], v188 offset:35840
	ds_read_b128 v[212:215], v188 offset:36864
	ds_read_b128 v[216:219], v188 offset:37888
	ds_read_b128 v[220:223], v188 offset:38912
	ds_read_b128 v[224:227], v188 offset:39936
	global_load_lds_dwordx4 v[240:241], off
	v_lshl_add_u64 v[240:241], s[4:5], 0, v[150:151]
	s_mov_b32 m0, s68
	s_nop 0
	global_load_lds_dwordx4 v[240:241], off
	s_waitcnt vmcnt(8)
	s_waitcnt lgkmcnt(0)
	s_setprio 1
	s_waitcnt lgkmcnt(0)
	v_mfma_f32_16x16x32_bf16 v[142:145], v[50:53], v[196:199], v[142:145]
	v_mfma_f32_16x16x32_bf16 v[138:141], v[66:69], v[196:199], v[138:141]
	s_barrier
	v_mfma_f32_16x16x32_bf16 v[126:129], v[50:53], v[204:207], v[126:129]
	v_mfma_f32_16x16x32_bf16 v[122:125], v[66:69], v[204:207], v[122:125]
	v_mfma_f32_16x16x32_bf16 v[110:113], v[50:53], v[212:215], v[110:113]
	v_mfma_f32_16x16x32_bf16 v[106:109], v[66:69], v[212:215], v[106:109]
	v_mfma_f32_16x16x32_bf16 v[94:97], v[50:53], v[220:223], v[94:97]
	v_mfma_f32_16x16x32_bf16 v[90:93], v[66:69], v[220:223], v[90:93]
	v_mfma_f32_16x16x32_bf16 v[142:145], v[54:57], v[200:203], v[142:145]
	v_mfma_f32_16x16x32_bf16 v[138:141], v[70:73], v[200:203], v[138:141]
	v_mfma_f32_16x16x32_bf16 v[126:129], v[54:57], v[208:211], v[126:129]
	v_mfma_f32_16x16x32_bf16 v[122:125], v[70:73], v[208:211], v[122:125]
	v_mfma_f32_16x16x32_bf16 v[110:113], v[54:57], v[216:219], v[110:113]
	v_mfma_f32_16x16x32_bf16 v[106:109], v[70:73], v[216:219], v[106:109]
	v_mfma_f32_16x16x32_bf16 v[94:97], v[54:57], v[224:227], v[94:97]
	v_mfma_f32_16x16x32_bf16 v[90:93], v[70:73], v[224:227], v[90:93]
	s_setprio 0
	s_setprio 1
	v_mfma_f32_16x16x32_bf16 v[134:137], v[168:171], v[196:199], v[134:137]
	v_mfma_f32_16x16x32_bf16 v[130:133], v[176:179], v[196:199], v[130:133]
	v_mfma_f32_16x16x32_bf16 v[118:121], v[168:171], v[204:207], v[118:121]
	v_mfma_f32_16x16x32_bf16 v[114:117], v[176:179], v[204:207], v[114:117]
	v_mfma_f32_16x16x32_bf16 v[102:105], v[168:171], v[212:215], v[102:105]
	v_mfma_f32_16x16x32_bf16 v[98:101], v[176:179], v[212:215], v[98:101]
	v_mfma_f32_16x16x32_bf16 v[86:89], v[168:171], v[220:223], v[86:89]
	v_mfma_f32_16x16x32_bf16 v[82:85], v[176:179], v[220:223], v[82:85]
	v_mfma_f32_16x16x32_bf16 v[134:137], v[172:175], v[200:203], v[134:137]
	v_mfma_f32_16x16x32_bf16 v[130:133], v[192:195], v[200:203], v[130:133]
	v_mfma_f32_16x16x32_bf16 v[118:121], v[172:175], v[208:211], v[118:121]
	v_mfma_f32_16x16x32_bf16 v[114:117], v[192:195], v[208:211], v[114:117]
	v_mfma_f32_16x16x32_bf16 v[102:105], v[172:175], v[216:219], v[102:105]
	v_mfma_f32_16x16x32_bf16 v[98:101], v[192:195], v[216:219], v[98:101]
	v_mfma_f32_16x16x32_bf16 v[86:89], v[172:175], v[224:227], v[86:89]
	v_mfma_f32_16x16x32_bf16 v[82:85], v[192:195], v[224:227], v[82:85]
	s_setprio 0
	s_barrier
	s_add_i32 s4, s50, s62
	v_lshl_add_u64 v[228:229], v[228:229], 0, s[28:29]
	s_mov_b32 m0, s4
	ds_read_b128 v[196:199], v188 offset:49152
	ds_read_b128 v[200:203], v188 offset:50176
	ds_read_b128 v[204:207], v188 offset:51200
	ds_read_b128 v[208:211], v188 offset:52224
	ds_read_b128 v[212:215], v188 offset:53248
	ds_read_b128 v[216:219], v188 offset:54272
	ds_read_b128 v[220:223], v188 offset:55296
	ds_read_b128 v[224:227], v188 offset:56320
	global_load_lds_dwordx4 v[228:229], off
	v_lshl_add_u64 v[228:229], v[230:231], 0, s[28:29]
	s_add_i32 m0, s4, 0x2000
	s_add_i32 s4, s51, s62
	global_load_lds_dwordx4 v[228:229], off
	v_lshl_add_u64 v[228:229], v[232:233], 0, s[28:29]
	s_mov_b32 m0, s4
	s_nop 0
	global_load_lds_dwordx4 v[228:229], off
	v_lshl_add_u64 v[228:229], v[234:235], 0, s[28:29]
	s_add_i32 m0, s4, 0x2000
	s_nop 0
	global_load_lds_dwordx4 v[228:229], off
	v_lshl_add_u64 v[228:229], v[236:237], 0, s[28:29]
	s_mov_b32 m0, s82
	s_nop 0
	global_load_lds_dwordx4 v[228:229], off
	v_lshl_add_u64 v[228:229], v[238:239], 0, s[28:29]
	s_mov_b32 m0, s83
	s_nop 0
	global_load_lds_dwordx4 v[228:229], off
	s_waitcnt vmcnt(8)
	s_waitcnt lgkmcnt(0)
	s_setprio 1
	s_waitcnt lgkmcnt(0)
	v_mfma_f32_16x16x32_bf16 v[78:81], v[50:53], v[196:199], v[78:81]
	v_mfma_f32_16x16x32_bf16 v[74:77], v[66:69], v[196:199], v[74:77]
	s_barrier
	v_mfma_f32_16x16x32_bf16 v[62:65], v[50:53], v[204:207], v[62:65]
	v_mfma_f32_16x16x32_bf16 v[58:61], v[66:69], v[204:207], v[58:61]
	v_mfma_f32_16x16x32_bf16 v[30:33], v[50:53], v[212:215], v[30:33]
	v_mfma_f32_16x16x32_bf16 v[26:29], v[66:69], v[212:215], v[26:29]
	v_mfma_f32_16x16x32_bf16 v[14:17], v[50:53], v[220:223], v[14:17]
	v_mfma_f32_16x16x32_bf16 v[10:13], v[66:69], v[220:223], v[10:13]
	v_mfma_f32_16x16x32_bf16 v[78:81], v[54:57], v[200:203], v[78:81]
	v_mfma_f32_16x16x32_bf16 v[74:77], v[70:73], v[200:203], v[74:77]
	v_mfma_f32_16x16x32_bf16 v[62:65], v[54:57], v[208:211], v[62:65]
	v_mfma_f32_16x16x32_bf16 v[58:61], v[70:73], v[208:211], v[58:61]
	v_mfma_f32_16x16x32_bf16 v[30:33], v[54:57], v[216:219], v[30:33]
	v_mfma_f32_16x16x32_bf16 v[26:29], v[70:73], v[216:219], v[26:29]
	v_mfma_f32_16x16x32_bf16 v[14:17], v[54:57], v[224:227], v[14:17]
	v_mfma_f32_16x16x32_bf16 v[10:13], v[70:73], v[224:227], v[10:13]
	s_setprio 0
	s_setprio 1
	v_mfma_f32_16x16x32_bf16 v[34:37], v[168:171], v[196:199], v[34:37]
	v_mfma_f32_16x16x32_bf16 v[70:73], v[172:175], v[200:203], v[34:37]
	v_mfma_f32_16x16x32_bf16 v[34:37], v[176:179], v[196:199], v[38:41]
	v_mfma_f32_16x16x32_bf16 v[66:69], v[192:195], v[200:203], v[34:37]
	v_mfma_f32_16x16x32_bf16 v[34:37], v[168:171], v[204:207], v[46:49]
	v_mfma_f32_16x16x32_bf16 v[46:49], v[172:175], v[208:211], v[34:37]
	v_mfma_f32_16x16x32_bf16 v[34:37], v[176:179], v[204:207], v[42:45]
	v_mfma_f32_16x16x32_bf16 v[22:25], v[168:171], v[212:215], v[22:25]
	v_mfma_f32_16x16x32_bf16 v[18:21], v[176:179], v[212:215], v[18:21]
	v_mfma_f32_16x16x32_bf16 v[6:9], v[168:171], v[220:223], v[6:9]
	v_mfma_f32_16x16x32_bf16 v[2:5], v[176:179], v[220:223], v[2:5]
	v_mfma_f32_16x16x32_bf16 v[42:45], v[192:195], v[208:211], v[34:37]
	v_mfma_f32_16x16x32_bf16 v[22:25], v[172:175], v[216:219], v[22:25]
	v_mfma_f32_16x16x32_bf16 v[18:21], v[192:195], v[216:219], v[18:21]
	v_mfma_f32_16x16x32_bf16 v[6:9], v[172:175], v[224:227], v[6:9]
	v_mfma_f32_16x16x32_bf16 v[2:5], v[192:195], v[224:227], v[2:5]
	s_setprio 0
	s_add_u32 s2, s2, 0x100
	s_addc_u32 s3, s3, 0
	s_add_u32 s6, s6, 0x100
	s_addc_u32 s7, s7, 0
	s_cmp_ge_i32 s47, s84
	s_mov_b32 s4, s47
	s_barrier
	s_cbranch_scc0 .LBB0_2116

.LBB0_2764:
	v_add_u32_e32 v158, s68, v229
	v_add_u32_e32 v174, s69, v229
	ds_read_b128 v[146:149], v158
	ds_read_b128 v[150:153], v158 offset:1024
	ds_read_b128 v[154:157], v158 offset:2048
	ds_read_b128 v[158:161], v158 offset:3072
	ds_read_b128 v[162:165], v174
	ds_read_b128 v[166:169], v174 offset:1024
	ds_read_b128 v[170:173], v174 offset:2048
	ds_read_b128 v[174:177], v174 offset:3072
	s_add_i32 s84, s42, 2
	s_add_u32 s85, s40, 0x80
	s_addc_u32 s43, s41, 0
	s_cmp_eq_u32 s65, s42
	s_cselect_b32 s42, s4, s85
	s_cselect_b32 s43, s5, s43
	s_cselect_b32 s87, s39, s83
	s_cselect_b32 s86, s38, s82
	v_lshl_add_u64 v[210:211], s[40:41], 0, v[138:139]
	s_add_i32 m0, s51, 0xc000
	ds_read_b128 v[178:181], v231
	ds_read_b128 v[182:185], v231 offset:1024
	ds_read_b128 v[186:189], v231 offset:2048
	ds_read_b128 v[190:193], v231 offset:3072
	ds_read_b128 v[194:197], v231 offset:4096
	ds_read_b128 v[198:201], v231 offset:5120
	ds_read_b128 v[202:205], v231 offset:6144
	ds_read_b128 v[206:209], v231 offset:7168
	global_load_lds_dwordx4 v[210:211], off
	v_lshl_add_u64 v[210:211], s[40:41], 0, v[140:141]
	s_add_i32 m0, s51, 0xe000
	s_nop 0
	global_load_lds_dwordx4 v[210:211], off
	s_waitcnt vmcnt(8)
	s_waitcnt lgkmcnt(0)
	s_setprio 1
	s_waitcnt lgkmcnt(0)
	v_mfma_i32_16x16x64_i8 v[126:129], v[146:149], v[178:181], v[126:129]
	v_mfma_i32_16x16x64_i8 v[122:125], v[154:157], v[178:181], v[122:125]
	s_barrier
	v_mfma_i32_16x16x64_i8 v[118:121], v[146:149], v[186:189], v[118:121]
	v_mfma_i32_16x16x64_i8 v[114:117], v[154:157], v[186:189], v[114:117]
	v_mfma_i32_16x16x64_i8 v[106:109], v[146:149], v[194:197], v[106:109]
	v_mfma_i32_16x16x64_i8 v[98:101], v[154:157], v[194:197], v[98:101]
	v_mfma_i32_16x16x64_i8 v[90:93], v[146:149], v[202:205], v[90:93]
	v_mfma_i32_16x16x64_i8 v[82:85], v[154:157], v[202:205], v[82:85]
	v_mfma_i32_16x16x64_i8 v[126:129], v[150:153], v[182:185], v[126:129]
	v_mfma_i32_16x16x64_i8 v[122:125], v[158:161], v[182:185], v[122:125]
	v_mfma_i32_16x16x64_i8 v[118:121], v[150:153], v[190:193], v[118:121]
	v_mfma_i32_16x16x64_i8 v[114:117], v[158:161], v[190:193], v[114:117]
	v_mfma_i32_16x16x64_i8 v[106:109], v[150:153], v[198:201], v[106:109]
	v_mfma_i32_16x16x64_i8 v[98:101], v[158:161], v[198:201], v[98:101]
	v_mfma_i32_16x16x64_i8 v[90:93], v[150:153], v[206:209], v[90:93]
	v_mfma_i32_16x16x64_i8 v[82:85], v[158:161], v[206:209], v[82:85]
	s_setprio 0
	s_setprio 1
	v_mfma_i32_16x16x64_i8 v[110:113], v[162:165], v[178:181], v[110:113]
	v_mfma_i32_16x16x64_i8 v[102:105], v[170:173], v[178:181], v[102:105]
	v_mfma_i32_16x16x64_i8 v[94:97], v[162:165], v[186:189], v[94:97]
	v_mfma_i32_16x16x64_i8 v[86:89], v[170:173], v[186:189], v[86:89]
	v_mfma_i32_16x16x64_i8 v[78:81], v[162:165], v[194:197], v[78:81]
	v_mfma_i32_16x16x64_i8 v[74:77], v[170:173], v[194:197], v[74:77]
	v_mfma_i32_16x16x64_i8 v[70:73], v[162:165], v[202:205], v[70:73]
	v_mfma_i32_16x16x64_i8 v[66:69], v[170:173], v[202:205], v[66:69]
	v_mfma_i32_16x16x64_i8 v[110:113], v[166:169], v[182:185], v[110:113]
	v_mfma_i32_16x16x64_i8 v[102:105], v[174:177], v[182:185], v[102:105]
	v_mfma_i32_16x16x64_i8 v[94:97], v[166:169], v[190:193], v[94:97]
	v_mfma_i32_16x16x64_i8 v[86:89], v[174:177], v[190:193], v[86:89]
	v_mfma_i32_16x16x64_i8 v[78:81], v[166:169], v[198:201], v[78:81]
	v_mfma_i32_16x16x64_i8 v[74:77], v[174:177], v[198:201], v[74:77]
	v_mfma_i32_16x16x64_i8 v[70:73], v[166:169], v[206:209], v[70:73]
	v_mfma_i32_16x16x64_i8 v[66:69], v[174:177], v[206:209], v[66:69]
	s_setprio 0
	s_barrier
	s_add_i32 s85, s68, s50
	v_lshl_add_u64 v[210:211], s[86:87], 0, v[132:133]
	s_mov_b32 m0, s85
	ds_read_b128 v[178:181], v231 offset:16384
	ds_read_b128 v[182:185], v231 offset:17408
	ds_read_b128 v[186:189], v231 offset:18432
	ds_read_b128 v[190:193], v231 offset:19456
	ds_read_b128 v[194:197], v231 offset:20480
	ds_read_b128 v[198:201], v231 offset:21504
	ds_read_b128 v[202:205], v231 offset:22528
	ds_read_b128 v[206:209], v231 offset:23552
	global_load_lds_dwordx4 v[210:211], off
	s_add_i32 m0, s85, 0x2000
	v_lshl_add_u64 v[212:213], s[86:87], 0, v[136:137]
	s_add_u32 s86, s86, s8
	s_addc_u32 s87, s87, s9
	s_add_i32 s85, s69, s50
	global_load_lds_dwordx4 v[212:213], off
	v_lshl_add_u64 v[214:215], s[86:87], 0, v[132:133]
	s_mov_b32 m0, s85
	v_lshl_add_u64 v[216:217], s[86:87], 0, v[136:137]
	global_load_lds_dwordx4 v[214:215], off
	s_add_i32 m0, s85, 0x2000
	v_lshl_add_u64 v[218:219], s[42:43], 0, v[130:131]
	global_load_lds_dwordx4 v[216:217], off
	s_mov_b32 m0, s51
	v_lshl_add_u64 v[220:221], s[42:43], 0, v[134:135]
	global_load_lds_dwordx4 v[218:219], off
	s_mov_b32 m0, s54
	s_nop 0
	global_load_lds_dwordx4 v[220:221], off
	s_waitcnt vmcnt(8)
	s_waitcnt lgkmcnt(0)
	s_setprio 1
	s_waitcnt lgkmcnt(0)
	v_mfma_i32_16x16x64_i8 v[62:65], v[146:149], v[178:181], v[62:65]
	v_mfma_i32_16x16x64_i8 v[58:61], v[154:157], v[178:181], v[58:61]
	s_barrier
	v_mfma_i32_16x16x64_i8 v[54:57], v[146:149], v[186:189], v[54:57]
	v_mfma_i32_16x16x64_i8 v[50:53], v[154:157], v[186:189], v[50:53]
	v_mfma_i32_16x16x64_i8 v[42:45], v[146:149], v[194:197], v[42:45]
	v_mfma_i32_16x16x64_i8 v[34:37], v[154:157], v[194:197], v[34:37]
	v_mfma_i32_16x16x64_i8 v[26:29], v[146:149], v[202:205], v[26:29]
	v_mfma_i32_16x16x64_i8 v[18:21], v[154:157], v[202:205], v[18:21]
	v_mfma_i32_16x16x64_i8 v[62:65], v[150:153], v[182:185], v[62:65]
	v_mfma_i32_16x16x64_i8 v[58:61], v[158:161], v[182:185], v[58:61]
	v_mfma_i32_16x16x64_i8 v[54:57], v[150:153], v[190:193], v[54:57]
	v_mfma_i32_16x16x64_i8 v[50:53], v[158:161], v[190:193], v[50:53]
	v_mfma_i32_16x16x64_i8 v[42:45], v[150:153], v[198:201], v[42:45]
	v_mfma_i32_16x16x64_i8 v[34:37], v[158:161], v[198:201], v[34:37]
	v_mfma_i32_16x16x64_i8 v[26:29], v[150:153], v[206:209], v[26:29]
	v_mfma_i32_16x16x64_i8 v[18:21], v[158:161], v[206:209], v[18:21]
	s_setprio 0
	s_setprio 1
	v_mfma_i32_16x16x64_i8 v[46:49], v[162:165], v[178:181], v[46:49]
	v_mfma_i32_16x16x64_i8 v[38:41], v[170:173], v[178:181], v[38:41]
	v_mfma_i32_16x16x64_i8 v[30:33], v[162:165], v[186:189], v[30:33]
	v_mfma_i32_16x16x64_i8 v[22:25], v[170:173], v[186:189], v[22:25]
	v_mfma_i32_16x16x64_i8 v[14:17], v[162:165], v[194:197], v[14:17]
	v_mfma_i32_16x16x64_i8 v[10:13], v[170:173], v[194:197], v[10:13]
	v_mfma_i32_16x16x64_i8 v[6:9], v[162:165], v[202:205], v[6:9]
	v_mfma_i32_16x16x64_i8 v[2:5], v[170:173], v[202:205], v[2:5]
	v_mfma_i32_16x16x64_i8 v[46:49], v[166:169], v[182:185], v[46:49]
	v_mfma_i32_16x16x64_i8 v[38:41], v[174:177], v[182:185], v[38:41]
	v_mfma_i32_16x16x64_i8 v[30:33], v[166:169], v[190:193], v[30:33]
	v_mfma_i32_16x16x64_i8 v[22:25], v[174:177], v[190:193], v[22:25]
	v_mfma_i32_16x16x64_i8 v[14:17], v[166:169], v[198:201], v[14:17]
	v_mfma_i32_16x16x64_i8 v[10:13], v[174:177], v[198:201], v[10:13]
	v_mfma_i32_16x16x64_i8 v[6:9], v[166:169], v[206:209], v[6:9]
	v_mfma_i32_16x16x64_i8 v[2:5], v[174:177], v[206:209], v[2:5]
	s_setprio 0
	s_barrier
	s_add_i32 s85, 0, 0x18000
	s_add_i32 s86, 0, 0x1c000
	v_add_u32_e32 v158, s85, v229
	v_add_u32_e32 v174, s86, v229
	ds_read_b128 v[146:149], v158
	ds_read_b128 v[150:153], v158 offset:1024
	ds_read_b128 v[154:157], v158 offset:2048
	ds_read_b128 v[158:161], v158 offset:3072
	ds_read_b128 v[162:165], v174
	ds_read_b128 v[166:169], v174 offset:1024
	ds_read_b128 v[170:173], v174 offset:2048
	ds_read_b128 v[174:177], v174 offset:3072
	s_add_u32 s42, s42, s8
	s_addc_u32 s43, s43, s9
	s_mov_b32 m0, s55
	v_lshl_add_u64 v[222:223], s[42:43], 0, v[130:131]
	ds_read_b128 v[178:181], v231 offset:32768
	ds_read_b128 v[182:185], v231 offset:33792
	ds_read_b128 v[186:189], v231 offset:34816
	ds_read_b128 v[190:193], v231 offset:35840
	ds_read_b128 v[194:197], v231 offset:36864
	ds_read_b128 v[198:201], v231 offset:37888
	ds_read_b128 v[202:205], v231 offset:38912
	ds_read_b128 v[206:209], v231 offset:39936
	global_load_lds_dwordx4 v[222:223], off
	v_lshl_add_u64 v[222:223], s[42:43], 0, v[134:135]
	s_mov_b32 m0, s56
	s_nop 0
	global_load_lds_dwordx4 v[222:223], off
	s_waitcnt vmcnt(8)
	s_waitcnt lgkmcnt(0)
	s_setprio 1
	s_waitcnt lgkmcnt(0)
	v_mfma_i32_16x16x64_i8 v[126:129], v[146:149], v[178:181], v[126:129]
	v_mfma_i32_16x16x64_i8 v[122:125], v[154:157], v[178:181], v[122:125]
	s_barrier
	v_mfma_i32_16x16x64_i8 v[118:121], v[146:149], v[186:189], v[118:121]
	v_mfma_i32_16x16x64_i8 v[114:117], v[154:157], v[186:189], v[114:117]
	v_mfma_i32_16x16x64_i8 v[106:109], v[146:149], v[194:197], v[106:109]
	v_mfma_i32_16x16x64_i8 v[98:101], v[154:157], v[194:197], v[98:101]
	v_mfma_i32_16x16x64_i8 v[90:93], v[146:149], v[202:205], v[90:93]
	v_mfma_i32_16x16x64_i8 v[82:85], v[154:157], v[202:205], v[82:85]
	v_mfma_i32_16x16x64_i8 v[126:129], v[150:153], v[182:185], v[126:129]
	v_mfma_i32_16x16x64_i8 v[122:125], v[158:161], v[182:185], v[122:125]
	v_mfma_i32_16x16x64_i8 v[118:121], v[150:153], v[190:193], v[118:121]
	v_mfma_i32_16x16x64_i8 v[114:117], v[158:161], v[190:193], v[114:117]
	v_mfma_i32_16x16x64_i8 v[106:109], v[150:153], v[198:201], v[106:109]
	v_mfma_i32_16x16x64_i8 v[98:101], v[158:161], v[198:201], v[98:101]
	v_mfma_i32_16x16x64_i8 v[90:93], v[150:153], v[206:209], v[90:93]
	v_mfma_i32_16x16x64_i8 v[82:85], v[158:161], v[206:209], v[82:85]
	s_setprio 0
	s_setprio 1
	v_mfma_i32_16x16x64_i8 v[110:113], v[162:165], v[178:181], v[110:113]
	v_mfma_i32_16x16x64_i8 v[102:105], v[170:173], v[178:181], v[102:105]
	v_mfma_i32_16x16x64_i8 v[94:97], v[162:165], v[186:189], v[94:97]
	v_mfma_i32_16x16x64_i8 v[86:89], v[170:173], v[186:189], v[86:89]
	v_mfma_i32_16x16x64_i8 v[78:81], v[162:165], v[194:197], v[78:81]
	v_mfma_i32_16x16x64_i8 v[74:77], v[170:173], v[194:197], v[74:77]
	v_mfma_i32_16x16x64_i8 v[70:73], v[162:165], v[202:205], v[70:73]
	v_mfma_i32_16x16x64_i8 v[66:69], v[170:173], v[202:205], v[66:69]
	v_mfma_i32_16x16x64_i8 v[110:113], v[166:169], v[182:185], v[110:113]
	v_mfma_i32_16x16x64_i8 v[102:105], v[174:177], v[182:185], v[102:105]
	v_mfma_i32_16x16x64_i8 v[94:97], v[166:169], v[190:193], v[94:97]
	v_mfma_i32_16x16x64_i8 v[86:89], v[174:177], v[190:193], v[86:89]
	v_mfma_i32_16x16x64_i8 v[78:81], v[166:169], v[198:201], v[78:81]
	v_mfma_i32_16x16x64_i8 v[74:77], v[174:177], v[198:201], v[74:77]
	v_mfma_i32_16x16x64_i8 v[70:73], v[166:169], v[206:209], v[70:73]
	v_mfma_i32_16x16x64_i8 v[66:69], v[174:177], v[206:209], v[66:69]
	s_setprio 0
	s_barrier
	s_add_i32 s42, s85, s50
	v_lshl_add_u64 v[210:211], v[210:211], 0, s[30:31]
	s_mov_b32 m0, s42
	ds_read_b128 v[178:181], v231 offset:49152
	ds_read_b128 v[182:185], v231 offset:50176
	ds_read_b128 v[186:189], v231 offset:51200
	ds_read_b128 v[190:193], v231 offset:52224
	ds_read_b128 v[194:197], v231 offset:53248
	ds_read_b128 v[198:201], v231 offset:54272
	ds_read_b128 v[202:205], v231 offset:55296
	ds_read_b128 v[206:209], v231 offset:56320
	global_load_lds_dwordx4 v[210:211], off
	v_lshl_add_u64 v[210:211], v[212:213], 0, s[30:31]
	s_add_i32 m0, s42, 0x2000
	s_add_i32 s42, s86, s50
	global_load_lds_dwordx4 v[210:211], off
	v_lshl_add_u64 v[210:211], v[214:215], 0, s[30:31]
	s_mov_b32 m0, s42
	s_nop 0
	global_load_lds_dwordx4 v[210:211], off
	v_lshl_add_u64 v[210:211], v[216:217], 0, s[30:31]
	s_add_i32 m0, s42, 0x2000
	s_nop 0
	global_load_lds_dwordx4 v[210:211], off
	v_lshl_add_u64 v[210:211], v[218:219], 0, s[30:31]
	s_mov_b32 m0, s61
	s_nop 0
	global_load_lds_dwordx4 v[210:211], off
	v_lshl_add_u64 v[210:211], v[220:221], 0, s[30:31]
	s_mov_b32 m0, s62
	s_nop 0
	global_load_lds_dwordx4 v[210:211], off
	s_waitcnt vmcnt(8)
	s_waitcnt lgkmcnt(0)
	s_setprio 1
	s_waitcnt lgkmcnt(0)
	v_mfma_i32_16x16x64_i8 v[62:65], v[146:149], v[178:181], v[62:65]
	v_mfma_i32_16x16x64_i8 v[58:61], v[154:157], v[178:181], v[58:61]
	s_barrier
	v_mfma_i32_16x16x64_i8 v[54:57], v[146:149], v[186:189], v[54:57]
	v_mfma_i32_16x16x64_i8 v[50:53], v[154:157], v[186:189], v[50:53]
	v_mfma_i32_16x16x64_i8 v[42:45], v[146:149], v[194:197], v[42:45]
	v_mfma_i32_16x16x64_i8 v[34:37], v[154:157], v[194:197], v[34:37]
	v_mfma_i32_16x16x64_i8 v[26:29], v[146:149], v[202:205], v[26:29]
	v_mfma_i32_16x16x64_i8 v[18:21], v[154:157], v[202:205], v[18:21]
	v_mfma_i32_16x16x64_i8 v[62:65], v[150:153], v[182:185], v[62:65]
	v_mfma_i32_16x16x64_i8 v[58:61], v[158:161], v[182:185], v[58:61]
	v_mfma_i32_16x16x64_i8 v[54:57], v[150:153], v[190:193], v[54:57]
	v_mfma_i32_16x16x64_i8 v[50:53], v[158:161], v[190:193], v[50:53]
	v_mfma_i32_16x16x64_i8 v[42:45], v[150:153], v[198:201], v[42:45]
	v_mfma_i32_16x16x64_i8 v[34:37], v[158:161], v[198:201], v[34:37]
	v_mfma_i32_16x16x64_i8 v[26:29], v[150:153], v[206:209], v[26:29]
	v_mfma_i32_16x16x64_i8 v[18:21], v[158:161], v[206:209], v[18:21]
	s_setprio 0
	s_setprio 1
	v_mfma_i32_16x16x64_i8 v[46:49], v[162:165], v[178:181], v[46:49]
	v_mfma_i32_16x16x64_i8 v[38:41], v[170:173], v[178:181], v[38:41]
	v_mfma_i32_16x16x64_i8 v[30:33], v[162:165], v[186:189], v[30:33]
	v_mfma_i32_16x16x64_i8 v[22:25], v[170:173], v[186:189], v[22:25]
	v_mfma_i32_16x16x64_i8 v[14:17], v[162:165], v[194:197], v[14:17]
	v_mfma_i32_16x16x64_i8 v[10:13], v[170:173], v[194:197], v[10:13]
	v_mfma_i32_16x16x64_i8 v[6:9], v[162:165], v[202:205], v[6:9]
	v_mfma_i32_16x16x64_i8 v[2:5], v[170:173], v[202:205], v[2:5]
	v_mfma_i32_16x16x64_i8 v[46:49], v[166:169], v[182:185], v[46:49]
	v_mfma_i32_16x16x64_i8 v[38:41], v[174:177], v[182:185], v[38:41]
	v_mfma_i32_16x16x64_i8 v[30:33], v[166:169], v[190:193], v[30:33]
	v_mfma_i32_16x16x64_i8 v[22:25], v[174:177], v[190:193], v[22:25]
	v_mfma_i32_16x16x64_i8 v[14:17], v[166:169], v[198:201], v[14:17]
	v_mfma_i32_16x16x64_i8 v[10:13], v[174:177], v[198:201], v[10:13]
	v_mfma_i32_16x16x64_i8 v[6:9], v[166:169], v[206:209], v[6:9]
	v_mfma_i32_16x16x64_i8 v[2:5], v[174:177], v[206:209], v[2:5]
	s_setprio 0
	s_add_u32 s40, s40, 0x100
	s_addc_u32 s41, s41, 0
	s_add_u32 s82, s82, 0x100
	s_addc_u32 s83, s83, 0
	s_cmp_ge_i32 s84, s64
	s_mov_b32 s42, s84
	s_barrier
	s_cbranch_scc0 .LBB0_2764
	v_cvt_f32_i32_e32 v214, v126
	v_cvt_f32_i32_e32 v215, v127
	v_cvt_f32_i32_e32 v212, v128
	v_cvt_f32_i32_e32 v213, v129
	v_cvt_f32_i32_e32 v218, v122
	v_cvt_f32_i32_e32 v219, v123
	v_cvt_f32_i32_e32 v216, v124
	v_cvt_f32_i32_e32 v217, v125
	v_cvt_f32_i32_e32 v222, v110
	v_cvt_f32_i32_e32 v223, v111
	v_cvt_f32_i32_e32 v220, v112
	v_cvt_f32_i32_e32 v221, v113
	v_cvt_f32_i32_e32 v226, v102
	v_cvt_f32_i32_e32 v227, v103
	v_cvt_f32_i32_e32 v224, v104
	v_cvt_f32_i32_e32 v225, v105
	v_cvt_f32_i32_e32 v194, v118
	v_cvt_f32_i32_e32 v195, v119
	v_cvt_f32_i32_e32 v192, v120
	v_cvt_f32_i32_e32 v193, v121
	v_cvt_f32_i32_e32 v200, v114
	v_cvt_f32_i32_e32 v201, v115
	v_cvt_f32_i32_e32 v198, v116
	v_cvt_f32_i32_e32 v199, v117
	v_cvt_f32_i32_e32 v206, v94
	v_cvt_f32_i32_e32 v207, v95
	v_cvt_f32_i32_e32 v202, v96
	v_cvt_f32_i32_e32 v203, v97
	v_cvt_f32_i32_e32 v208, v86
	v_cvt_f32_i32_e32 v209, v87
	v_cvt_f32_i32_e32 v204, v88
	v_cvt_f32_i32_e32 v205, v89
	v_cvt_f32_i32_e32 v178, v106
	v_cvt_f32_i32_e32 v179, v107
	v_cvt_f32_i32_e32 v176, v108
	v_cvt_f32_i32_e32 v177, v109
	v_cvt_f32_i32_e32 v182, v98
	v_cvt_f32_i32_e32 v183, v99
	v_cvt_f32_i32_e32 v180, v100
	v_cvt_f32_i32_e32 v181, v101
	v_cvt_f32_i32_e32 v188, v78
	v_cvt_f32_i32_e32 v189, v79
	v_cvt_f32_i32_e32 v184, v80
	v_cvt_f32_i32_e32 v185, v81
	v_cvt_f32_i32_e32 v190, v74
	v_cvt_f32_i32_e32 v191, v75
	v_cvt_f32_i32_e32 v186, v76
	v_cvt_f32_i32_e32 v187, v77
	v_cvt_f32_i32_e32 v162, v90
	v_cvt_f32_i32_e32 v163, v91
	v_cvt_f32_i32_e32 v160, v92
	v_cvt_f32_i32_e32 v161, v93
	v_cvt_f32_i32_e32 v166, v82
	v_cvt_f32_i32_e32 v167, v83
	v_cvt_f32_i32_e32 v164, v84
	v_cvt_f32_i32_e32 v165, v85
	v_cvt_f32_i32_e32 v172, v70
	v_cvt_f32_i32_e32 v173, v71
	v_cvt_f32_i32_e32 v168, v72
	v_cvt_f32_i32_e32 v169, v73
	v_cvt_f32_i32_e32 v174, v66
	v_cvt_f32_i32_e32 v175, v67
	v_cvt_f32_i32_e32 v170, v68
	v_cvt_f32_i32_e32 v171, v69
	v_cvt_f32_i32_e32 v146, v62
	v_cvt_f32_i32_e32 v147, v63
	v_cvt_f32_i32_e32 v128, v64
	v_cvt_f32_i32_e32 v129, v65
	v_cvt_f32_i32_e32 v150, v58
	v_cvt_f32_i32_e32 v151, v59
	v_cvt_f32_i32_e32 v148, v60
	v_cvt_f32_i32_e32 v149, v61
	v_cvt_f32_i32_e32 v156, v46
	v_cvt_f32_i32_e32 v157, v47
	v_cvt_f32_i32_e32 v152, v48
	v_cvt_f32_i32_e32 v153, v49
	v_cvt_f32_i32_e32 v158, v38
	v_cvt_f32_i32_e32 v159, v39
	v_cvt_f32_i32_e32 v154, v40
	v_cvt_f32_i32_e32 v155, v41
	v_cvt_f32_i32_e32 v114, v54
	v_cvt_f32_i32_e32 v115, v55
	v_cvt_f32_i32_e32 v112, v56
	v_cvt_f32_i32_e32 v113, v57
	v_cvt_f32_i32_e32 v118, v50
	v_cvt_f32_i32_e32 v119, v51
	v_cvt_f32_i32_e32 v116, v52
	v_cvt_f32_i32_e32 v117, v53
	v_cvt_f32_i32_e32 v124, v30
	v_cvt_f32_i32_e32 v125, v31
	v_cvt_f32_i32_e32 v120, v32
	v_cvt_f32_i32_e32 v121, v33
	v_cvt_f32_i32_e32 v126, v22
	v_cvt_f32_i32_e32 v127, v23
	v_cvt_f32_i32_e32 v122, v24
	v_cvt_f32_i32_e32 v123, v25
	v_cvt_f32_i32_e32 v64, v42
	v_cvt_f32_i32_e32 v65, v43
	v_cvt_f32_i32_e32 v62, v44
	v_cvt_f32_i32_e32 v63, v45
	v_cvt_f32_i32_e32 v68, v34
	v_cvt_f32_i32_e32 v69, v35
	v_cvt_f32_i32_e32 v66, v36
	v_cvt_f32_i32_e32 v67, v37
	v_cvt_f32_i32_e32 v74, v14
	v_cvt_f32_i32_e32 v75, v15
	v_cvt_f32_i32_e32 v70, v16
	v_cvt_f32_i32_e32 v71, v17
	v_cvt_f32_i32_e32 v76, v10
	v_cvt_f32_i32_e32 v77, v11
	v_cvt_f32_i32_e32 v72, v12
	v_cvt_f32_i32_e32 v73, v13
	v_cvt_f32_i32_e32 v48, v26
	v_cvt_f32_i32_e32 v49, v27
	v_cvt_f32_i32_e32 v46, v28
	v_cvt_f32_i32_e32 v47, v29
	v_cvt_f32_i32_e32 v52, v18
	v_cvt_f32_i32_e32 v53, v19
	v_cvt_f32_i32_e32 v50, v20
	v_cvt_f32_i32_e32 v51, v21
	v_cvt_f32_i32_e32 v58, v6
	v_cvt_f32_i32_e32 v59, v7
	v_cvt_f32_i32_e32 v54, v8
	v_cvt_f32_i32_e32 v55, v9
	v_cvt_f32_i32_e32 v60, v2
	v_cvt_f32_i32_e32 v61, v3
	v_cvt_f32_i32_e32 v56, v4
	v_cvt_f32_i32_e32 v57, v5

.LBB0_2949:
	v_add_u32_e32 v138, s60, v188
	ds_read_b128 v[148:151], v138
	ds_read_b128 v[152:155], v138 offset:1024
	ds_read_b128 v[156:159], v138 offset:2048
	ds_read_b128 v[160:163], v138 offset:3072
	v_add_u32_e32 v138, s61, v188
	ds_read_b128 v[164:167], v138
	ds_read_b128 v[168:171], v138 offset:1024
	ds_read_b128 v[172:175], v138 offset:2048
	ds_read_b128 v[176:179], v138 offset:3072
	s_add_i32 s64, s28, 2
	s_add_u32 s65, s26, 0x80
	s_addc_u32 s29, s27, 0
	s_cmp_eq_u32 s58, s28
	s_cselect_b32 s28, s2, s65
	s_cselect_b32 s29, s3, s29
	s_cselect_b32 s67, s25, s35
	s_cselect_b32 s66, s24, s34
	v_lshl_add_u64 v[184:185], s[26:27], 0, v[140:141]
	s_add_i32 m0, s42, 0xc000
	ds_read_b128 v[180:183], v189
	ds_read_b128 v[190:193], v189 offset:1024
	ds_read_b128 v[194:197], v189 offset:2048
	ds_read_b128 v[198:201], v189 offset:3072
	ds_read_b128 v[202:205], v189 offset:4096
	ds_read_b128 v[206:209], v189 offset:5120
	ds_read_b128 v[210:213], v189 offset:6144
	ds_read_b128 v[214:217], v189 offset:7168
	global_load_lds_dwordx4 v[184:185], off
	v_lshl_add_u64 v[184:185], s[26:27], 0, v[142:143]
	s_add_i32 m0, s42, 0xe000
	s_nop 0
	global_load_lds_dwordx4 v[184:185], off
	s_waitcnt vmcnt(8)
	s_waitcnt lgkmcnt(0)
	s_setprio 1
	s_waitcnt lgkmcnt(0)
	v_mfma_i32_16x16x64_i8 v[126:129], v[148:151], v[180:183], v[126:129]
	v_mfma_i32_16x16x64_i8 v[122:125], v[156:159], v[180:183], v[122:125]
	s_barrier
	v_mfma_i32_16x16x64_i8 v[118:121], v[148:151], v[194:197], v[118:121]
	v_mfma_i32_16x16x64_i8 v[114:117], v[156:159], v[194:197], v[114:117]
	v_mfma_i32_16x16x64_i8 v[106:109], v[148:151], v[202:205], v[106:109]
	v_mfma_i32_16x16x64_i8 v[98:101], v[156:159], v[202:205], v[98:101]
	v_mfma_i32_16x16x64_i8 v[90:93], v[148:151], v[210:213], v[90:93]
	v_mfma_i32_16x16x64_i8 v[82:85], v[156:159], v[210:213], v[82:85]
	v_mfma_i32_16x16x64_i8 v[126:129], v[152:155], v[190:193], v[126:129]
	v_mfma_i32_16x16x64_i8 v[122:125], v[160:163], v[190:193], v[122:125]
	v_mfma_i32_16x16x64_i8 v[118:121], v[152:155], v[198:201], v[118:121]
	v_mfma_i32_16x16x64_i8 v[114:117], v[160:163], v[198:201], v[114:117]
	v_mfma_i32_16x16x64_i8 v[106:109], v[152:155], v[206:209], v[106:109]
	v_mfma_i32_16x16x64_i8 v[98:101], v[160:163], v[206:209], v[98:101]
	v_mfma_i32_16x16x64_i8 v[90:93], v[152:155], v[214:217], v[90:93]
	v_mfma_i32_16x16x64_i8 v[82:85], v[160:163], v[214:217], v[82:85]
	s_setprio 0
	s_setprio 1
	v_mfma_i32_16x16x64_i8 v[110:113], v[164:167], v[180:183], v[110:113]
	v_mfma_i32_16x16x64_i8 v[102:105], v[172:175], v[180:183], v[102:105]
	v_mfma_i32_16x16x64_i8 v[94:97], v[164:167], v[194:197], v[94:97]
	v_mfma_i32_16x16x64_i8 v[86:89], v[172:175], v[194:197], v[86:89]
	v_mfma_i32_16x16x64_i8 v[78:81], v[164:167], v[202:205], v[78:81]
	v_mfma_i32_16x16x64_i8 v[74:77], v[172:175], v[202:205], v[74:77]
	v_mfma_i32_16x16x64_i8 v[70:73], v[164:167], v[210:213], v[70:73]
	v_mfma_i32_16x16x64_i8 v[66:69], v[172:175], v[210:213], v[66:69]
	v_mfma_i32_16x16x64_i8 v[110:113], v[168:171], v[190:193], v[110:113]
	v_mfma_i32_16x16x64_i8 v[102:105], v[176:179], v[190:193], v[102:105]
	v_mfma_i32_16x16x64_i8 v[94:97], v[168:171], v[198:201], v[94:97]
	v_mfma_i32_16x16x64_i8 v[86:89], v[176:179], v[198:201], v[86:89]
	v_mfma_i32_16x16x64_i8 v[78:81], v[168:171], v[206:209], v[78:81]
	v_mfma_i32_16x16x64_i8 v[74:77], v[176:179], v[206:209], v[74:77]
	v_mfma_i32_16x16x64_i8 v[70:73], v[168:171], v[214:217], v[70:73]
	v_mfma_i32_16x16x64_i8 v[66:69], v[176:179], v[214:217], v[66:69]
	s_setprio 0
	s_barrier
	s_add_i32 s65, s60, s41
	v_lshl_add_u64 v[184:185], s[66:67], 0, v[132:133]
	s_mov_b32 m0, s65
	ds_read_b128 v[180:183], v189 offset:16384
	ds_read_b128 v[190:193], v189 offset:17408
	ds_read_b128 v[194:197], v189 offset:18432
	ds_read_b128 v[198:201], v189 offset:19456
	ds_read_b128 v[202:205], v189 offset:20480
	ds_read_b128 v[206:209], v189 offset:21504
	ds_read_b128 v[210:213], v189 offset:22528
	ds_read_b128 v[214:217], v189 offset:23552
	global_load_lds_dwordx4 v[184:185], off
	s_add_i32 m0, s65, 0x2000
	v_lshl_add_u64 v[218:219], s[66:67], 0, v[136:137]
	s_add_u32 s66, s66, s6
	s_addc_u32 s67, s67, s7
	s_add_i32 s65, s61, s41
	global_load_lds_dwordx4 v[218:219], off
	v_lshl_add_u64 v[220:221], s[66:67], 0, v[132:133]
	s_mov_b32 m0, s65
	v_lshl_add_u64 v[222:223], s[66:67], 0, v[136:137]
	global_load_lds_dwordx4 v[220:221], off
	s_add_i32 m0, s65, 0x2000
	v_lshl_add_u64 v[224:225], s[28:29], 0, v[130:131]
	global_load_lds_dwordx4 v[222:223], off
	s_mov_b32 m0, s42
	v_lshl_add_u64 v[226:227], s[28:29], 0, v[134:135]
	global_load_lds_dwordx4 v[224:225], off
	s_mov_b32 m0, s43
	s_nop 0
	global_load_lds_dwordx4 v[226:227], off
	s_waitcnt vmcnt(8)
	s_waitcnt lgkmcnt(0)
	s_setprio 1
	s_waitcnt lgkmcnt(0)
	v_mfma_i32_16x16x64_i8 v[62:65], v[148:151], v[180:183], v[62:65]
	v_mfma_i32_16x16x64_i8 v[58:61], v[156:159], v[180:183], v[58:61]
	s_barrier
	v_mfma_i32_16x16x64_i8 v[54:57], v[148:151], v[194:197], v[54:57]
	v_mfma_i32_16x16x64_i8 v[50:53], v[156:159], v[194:197], v[50:53]
	v_mfma_i32_16x16x64_i8 v[42:45], v[148:151], v[202:205], v[42:45]
	v_mfma_i32_16x16x64_i8 v[34:37], v[156:159], v[202:205], v[34:37]
	v_mfma_i32_16x16x64_i8 v[26:29], v[148:151], v[210:213], v[26:29]
	v_mfma_i32_16x16x64_i8 v[18:21], v[156:159], v[210:213], v[18:21]
	v_mfma_i32_16x16x64_i8 v[62:65], v[152:155], v[190:193], v[62:65]
	v_mfma_i32_16x16x64_i8 v[58:61], v[160:163], v[190:193], v[58:61]
	v_mfma_i32_16x16x64_i8 v[54:57], v[152:155], v[198:201], v[54:57]
	v_mfma_i32_16x16x64_i8 v[50:53], v[160:163], v[198:201], v[50:53]
	v_mfma_i32_16x16x64_i8 v[42:45], v[152:155], v[206:209], v[42:45]
	v_mfma_i32_16x16x64_i8 v[34:37], v[160:163], v[206:209], v[34:37]
	v_mfma_i32_16x16x64_i8 v[26:29], v[152:155], v[214:217], v[26:29]
	v_mfma_i32_16x16x64_i8 v[18:21], v[160:163], v[214:217], v[18:21]
	s_setprio 0
	s_setprio 1
	v_mfma_i32_16x16x64_i8 v[46:49], v[164:167], v[180:183], v[46:49]
	v_mfma_i32_16x16x64_i8 v[38:41], v[172:175], v[180:183], v[38:41]
	v_mfma_i32_16x16x64_i8 v[30:33], v[164:167], v[194:197], v[30:33]
	v_mfma_i32_16x16x64_i8 v[22:25], v[172:175], v[194:197], v[22:25]
	v_mfma_i32_16x16x64_i8 v[14:17], v[164:167], v[202:205], v[14:17]
	v_mfma_i32_16x16x64_i8 v[10:13], v[172:175], v[202:205], v[10:13]
	v_mfma_i32_16x16x64_i8 v[6:9], v[164:167], v[210:213], v[6:9]
	v_mfma_i32_16x16x64_i8 v[2:5], v[172:175], v[210:213], v[2:5]
	v_mfma_i32_16x16x64_i8 v[46:49], v[168:171], v[190:193], v[46:49]
	v_mfma_i32_16x16x64_i8 v[38:41], v[176:179], v[190:193], v[38:41]
	v_mfma_i32_16x16x64_i8 v[30:33], v[168:171], v[198:201], v[30:33]
	v_mfma_i32_16x16x64_i8 v[22:25], v[176:179], v[198:201], v[22:25]
	v_mfma_i32_16x16x64_i8 v[14:17], v[168:171], v[206:209], v[14:17]
	v_mfma_i32_16x16x64_i8 v[10:13], v[176:179], v[206:209], v[10:13]
	v_mfma_i32_16x16x64_i8 v[6:9], v[168:171], v[214:217], v[6:9]
	v_mfma_i32_16x16x64_i8 v[2:5], v[176:179], v[214:217], v[2:5]
	s_setprio 0
	s_barrier
	s_add_i32 s65, 0, 0x18000
	v_add_u32_e32 v138, s65, v188
	s_add_i32 s66, 0, 0x1c000
	ds_read_b128 v[148:151], v138
	ds_read_b128 v[152:155], v138 offset:1024
	ds_read_b128 v[156:159], v138 offset:2048
	ds_read_b128 v[160:163], v138 offset:3072
	v_add_u32_e32 v138, s66, v188
	ds_read_b128 v[164:167], v138
	ds_read_b128 v[168:171], v138 offset:1024
	ds_read_b128 v[172:175], v138 offset:2048
	ds_read_b128 v[176:179], v138 offset:3072
	s_add_u32 s28, s28, s6
	s_addc_u32 s29, s29, s7
	s_mov_b32 m0, s44
	v_lshl_add_u64 v[228:229], s[28:29], 0, v[130:131]
	ds_read_b128 v[180:183], v189 offset:32768
	ds_read_b128 v[190:193], v189 offset:33792
	ds_read_b128 v[194:197], v189 offset:34816
	ds_read_b128 v[198:201], v189 offset:35840
	ds_read_b128 v[202:205], v189 offset:36864
	ds_read_b128 v[206:209], v189 offset:37888
	ds_read_b128 v[210:213], v189 offset:38912
	ds_read_b128 v[214:217], v189 offset:39936
	global_load_lds_dwordx4 v[228:229], off
	v_lshl_add_u64 v[228:229], s[28:29], 0, v[134:135]
	s_mov_b32 m0, s45
	s_nop 0
	global_load_lds_dwordx4 v[228:229], off
	s_waitcnt vmcnt(8)
	s_waitcnt lgkmcnt(0)
	s_setprio 1
	s_waitcnt lgkmcnt(0)
	v_mfma_i32_16x16x64_i8 v[126:129], v[148:151], v[180:183], v[126:129]
	v_mfma_i32_16x16x64_i8 v[122:125], v[156:159], v[180:183], v[122:125]
	s_barrier
	v_mfma_i32_16x16x64_i8 v[118:121], v[148:151], v[194:197], v[118:121]
	v_mfma_i32_16x16x64_i8 v[114:117], v[156:159], v[194:197], v[114:117]
	v_mfma_i32_16x16x64_i8 v[106:109], v[148:151], v[202:205], v[106:109]
	v_mfma_i32_16x16x64_i8 v[98:101], v[156:159], v[202:205], v[98:101]
	v_mfma_i32_16x16x64_i8 v[90:93], v[148:151], v[210:213], v[90:93]
	v_mfma_i32_16x16x64_i8 v[82:85], v[156:159], v[210:213], v[82:85]
	v_mfma_i32_16x16x64_i8 v[126:129], v[152:155], v[190:193], v[126:129]
	v_mfma_i32_16x16x64_i8 v[122:125], v[160:163], v[190:193], v[122:125]
	v_mfma_i32_16x16x64_i8 v[118:121], v[152:155], v[198:201], v[118:121]
	v_mfma_i32_16x16x64_i8 v[114:117], v[160:163], v[198:201], v[114:117]
	v_mfma_i32_16x16x64_i8 v[106:109], v[152:155], v[206:209], v[106:109]
	v_mfma_i32_16x16x64_i8 v[98:101], v[160:163], v[206:209], v[98:101]
	v_mfma_i32_16x16x64_i8 v[90:93], v[152:155], v[214:217], v[90:93]
	v_mfma_i32_16x16x64_i8 v[82:85], v[160:163], v[214:217], v[82:85]
	s_setprio 0
	s_setprio 1
	v_mfma_i32_16x16x64_i8 v[110:113], v[164:167], v[180:183], v[110:113]
	v_mfma_i32_16x16x64_i8 v[102:105], v[172:175], v[180:183], v[102:105]
	v_mfma_i32_16x16x64_i8 v[94:97], v[164:167], v[194:197], v[94:97]
	v_mfma_i32_16x16x64_i8 v[86:89], v[172:175], v[194:197], v[86:89]
	v_mfma_i32_16x16x64_i8 v[78:81], v[164:167], v[202:205], v[78:81]
	v_mfma_i32_16x16x64_i8 v[74:77], v[172:175], v[202:205], v[74:77]
	v_mfma_i32_16x16x64_i8 v[70:73], v[164:167], v[210:213], v[70:73]
	v_mfma_i32_16x16x64_i8 v[66:69], v[172:175], v[210:213], v[66:69]
	v_mfma_i32_16x16x64_i8 v[110:113], v[168:171], v[190:193], v[110:113]
	v_mfma_i32_16x16x64_i8 v[102:105], v[176:179], v[190:193], v[102:105]
	v_mfma_i32_16x16x64_i8 v[94:97], v[168:171], v[198:201], v[94:97]
	v_mfma_i32_16x16x64_i8 v[86:89], v[176:179], v[198:201], v[86:89]
	v_mfma_i32_16x16x64_i8 v[78:81], v[168:171], v[206:209], v[78:81]
	v_mfma_i32_16x16x64_i8 v[74:77], v[176:179], v[206:209], v[74:77]
	v_mfma_i32_16x16x64_i8 v[70:73], v[168:171], v[214:217], v[70:73]
	v_mfma_i32_16x16x64_i8 v[66:69], v[176:179], v[214:217], v[66:69]
	s_setprio 0
	s_barrier
	s_add_i32 s28, s65, s41
	v_lshl_add_u64 v[184:185], v[184:185], 0, s[18:19]
	s_mov_b32 m0, s28
	ds_read_b128 v[180:183], v189 offset:49152
	ds_read_b128 v[190:193], v189 offset:50176
	ds_read_b128 v[194:197], v189 offset:51200
	ds_read_b128 v[198:201], v189 offset:52224
	ds_read_b128 v[202:205], v189 offset:53248
	ds_read_b128 v[206:209], v189 offset:54272
	ds_read_b128 v[210:213], v189 offset:55296
	ds_read_b128 v[214:217], v189 offset:56320
	global_load_lds_dwordx4 v[184:185], off
	v_lshl_add_u64 v[184:185], v[218:219], 0, s[18:19]
	s_add_i32 m0, s28, 0x2000
	s_add_i32 s28, s66, s41
	global_load_lds_dwordx4 v[184:185], off
	v_lshl_add_u64 v[184:185], v[220:221], 0, s[18:19]
	s_mov_b32 m0, s28
	s_nop 0
	global_load_lds_dwordx4 v[184:185], off
	v_lshl_add_u64 v[184:185], v[222:223], 0, s[18:19]
	s_add_i32 m0, s28, 0x2000
	s_nop 0
	global_load_lds_dwordx4 v[184:185], off
	v_lshl_add_u64 v[184:185], v[224:225], 0, s[18:19]
	s_mov_b32 m0, s51
	s_nop 0
	global_load_lds_dwordx4 v[184:185], off
	v_lshl_add_u64 v[184:185], v[226:227], 0, s[18:19]
	s_mov_b32 m0, s54
	s_nop 0
	global_load_lds_dwordx4 v[184:185], off
	s_waitcnt vmcnt(8)
	s_waitcnt lgkmcnt(0)
	s_setprio 1
	s_waitcnt lgkmcnt(0)
	v_mfma_i32_16x16x64_i8 v[62:65], v[148:151], v[180:183], v[62:65]
	v_mfma_i32_16x16x64_i8 v[58:61], v[156:159], v[180:183], v[58:61]
	s_barrier
	v_mfma_i32_16x16x64_i8 v[54:57], v[148:151], v[194:197], v[54:57]
	v_mfma_i32_16x16x64_i8 v[50:53], v[156:159], v[194:197], v[50:53]
	v_mfma_i32_16x16x64_i8 v[42:45], v[148:151], v[202:205], v[42:45]
	v_mfma_i32_16x16x64_i8 v[34:37], v[156:159], v[202:205], v[34:37]
	v_mfma_i32_16x16x64_i8 v[26:29], v[148:151], v[210:213], v[26:29]
	v_mfma_i32_16x16x64_i8 v[18:21], v[156:159], v[210:213], v[18:21]
	v_mfma_i32_16x16x64_i8 v[62:65], v[152:155], v[190:193], v[62:65]
	v_mfma_i32_16x16x64_i8 v[58:61], v[160:163], v[190:193], v[58:61]
	v_mfma_i32_16x16x64_i8 v[54:57], v[152:155], v[198:201], v[54:57]
	v_mfma_i32_16x16x64_i8 v[50:53], v[160:163], v[198:201], v[50:53]
	v_mfma_i32_16x16x64_i8 v[42:45], v[152:155], v[206:209], v[42:45]
	v_mfma_i32_16x16x64_i8 v[34:37], v[160:163], v[206:209], v[34:37]
	v_mfma_i32_16x16x64_i8 v[26:29], v[152:155], v[214:217], v[26:29]
	v_mfma_i32_16x16x64_i8 v[18:21], v[160:163], v[214:217], v[18:21]
	s_setprio 0
	s_setprio 1
	v_mfma_i32_16x16x64_i8 v[46:49], v[164:167], v[180:183], v[46:49]
	v_mfma_i32_16x16x64_i8 v[38:41], v[172:175], v[180:183], v[38:41]
	v_mfma_i32_16x16x64_i8 v[30:33], v[164:167], v[194:197], v[30:33]
	v_mfma_i32_16x16x64_i8 v[22:25], v[172:175], v[194:197], v[22:25]
	v_mfma_i32_16x16x64_i8 v[14:17], v[164:167], v[202:205], v[14:17]
	v_mfma_i32_16x16x64_i8 v[10:13], v[172:175], v[202:205], v[10:13]
	v_mfma_i32_16x16x64_i8 v[6:9], v[164:167], v[210:213], v[6:9]
	v_mfma_i32_16x16x64_i8 v[2:5], v[172:175], v[210:213], v[2:5]
	v_mfma_i32_16x16x64_i8 v[46:49], v[168:171], v[190:193], v[46:49]
	v_mfma_i32_16x16x64_i8 v[38:41], v[176:179], v[190:193], v[38:41]
	v_mfma_i32_16x16x64_i8 v[30:33], v[168:171], v[198:201], v[30:33]
	v_mfma_i32_16x16x64_i8 v[22:25], v[176:179], v[198:201], v[22:25]
	v_mfma_i32_16x16x64_i8 v[14:17], v[168:171], v[206:209], v[14:17]
	v_mfma_i32_16x16x64_i8 v[10:13], v[176:179], v[206:209], v[10:13]
	v_mfma_i32_16x16x64_i8 v[6:9], v[168:171], v[214:217], v[6:9]
	v_mfma_i32_16x16x64_i8 v[2:5], v[176:179], v[214:217], v[2:5]
	s_setprio 0
	s_add_u32 s26, s26, 0x100
	s_addc_u32 s27, s27, 0
	s_add_u32 s34, s34, 0x100
	s_addc_u32 s35, s35, 0
	s_cmp_ge_i32 s64, s55
	s_mov_b32 s28, s64
	s_barrier
	s_cbranch_scc0 .LBB0_2949
	v_cvt_f32_i32_e32 v172, v126
	v_cvt_f32_i32_e32 v173, v127
	v_cvt_f32_i32_e32 v170, v128
	v_cvt_f32_i32_e32 v171, v129
	v_cvt_f32_i32_e32 v174, v122
	v_cvt_f32_i32_e32 v175, v123
	v_cvt_f32_i32_e32 v176, v124
	v_cvt_f32_i32_e32 v177, v125
	v_cvt_f32_i32_e32 v180, v110
	v_cvt_f32_i32_e32 v181, v111
	v_cvt_f32_i32_e32 v182, v112
	v_cvt_f32_i32_e32 v183, v113
	v_cvt_f32_i32_e32 v178, v102
	v_cvt_f32_i32_e32 v179, v103
	v_cvt_f32_i32_e32 v184, v104
	v_cvt_f32_i32_e32 v185, v105
	v_cvt_f32_i32_e32 v152, v118
	v_cvt_f32_i32_e32 v153, v119
	v_cvt_f32_i32_e32 v154, v120
	v_cvt_f32_i32_e32 v155, v121
	v_cvt_f32_i32_e32 v156, v114
	v_cvt_f32_i32_e32 v157, v115
	v_cvt_f32_i32_e32 v158, v116
	v_cvt_f32_i32_e32 v159, v117
	v_cvt_f32_i32_e32 v160, v94
	v_cvt_f32_i32_e32 v161, v95
	v_cvt_f32_i32_e32 v162, v96
	v_cvt_f32_i32_e32 v163, v97
	v_cvt_f32_i32_e32 v164, v86
	v_cvt_f32_i32_e32 v165, v87
	v_cvt_f32_i32_e32 v166, v88
	v_cvt_f32_i32_e32 v167, v89
	v_cvt_f32_i32_e32 v118, v106
	v_cvt_f32_i32_e32 v119, v107
	v_cvt_f32_i32_e32 v120, v108
	v_cvt_f32_i32_e32 v121, v109
	v_cvt_f32_i32_e32 v122, v98
	v_cvt_f32_i32_e32 v123, v99
	v_cvt_f32_i32_e32 v124, v100
	v_cvt_f32_i32_e32 v125, v101
	v_cvt_f32_i32_e32 v126, v78
	v_cvt_f32_i32_e32 v127, v79
	v_cvt_f32_i32_e32 v128, v80
	v_cvt_f32_i32_e32 v129, v81
	v_cvt_f32_i32_e32 v148, v74
	v_cvt_f32_i32_e32 v149, v75
	v_cvt_f32_i32_e32 v150, v76
	v_cvt_f32_i32_e32 v151, v77
	v_cvt_f32_i32_e32 v102, v90
	v_cvt_f32_i32_e32 v103, v91
	v_cvt_f32_i32_e32 v104, v92
	v_cvt_f32_i32_e32 v105, v93
	v_cvt_f32_i32_e32 v106, v82
	v_cvt_f32_i32_e32 v107, v83
	v_cvt_f32_i32_e32 v108, v84
	v_cvt_f32_i32_e32 v109, v85
	v_cvt_f32_i32_e32 v110, v70
	v_cvt_f32_i32_e32 v111, v71
	v_cvt_f32_i32_e32 v112, v72
	v_cvt_f32_i32_e32 v113, v73
	v_cvt_f32_i32_e32 v114, v66
	v_cvt_f32_i32_e32 v115, v67
	v_cvt_f32_i32_e32 v116, v68
	v_cvt_f32_i32_e32 v117, v69
	v_cvt_f32_i32_e32 v82, v62
	v_cvt_f32_i32_e32 v83, v63
	v_cvt_f32_i32_e32 v84, v64
	v_cvt_f32_i32_e32 v85, v65
	v_cvt_f32_i32_e32 v86, v58
	v_cvt_f32_i32_e32 v87, v59
	v_cvt_f32_i32_e32 v88, v60
	v_cvt_f32_i32_e32 v89, v61
	v_cvt_f32_i32_e32 v92, v46
	v_cvt_f32_i32_e32 v93, v47
	v_cvt_f32_i32_e32 v94, v48
	v_cvt_f32_i32_e32 v95, v49
	v_cvt_f32_i32_e32 v96, v38
	v_cvt_f32_i32_e32 v97, v39
	v_cvt_f32_i32_e32 v98, v40
	v_cvt_f32_i32_e32 v99, v41
	v_cvt_f32_i32_e32 v66, v54
	v_cvt_f32_i32_e32 v67, v55
	v_cvt_f32_i32_e32 v68, v56
	v_cvt_f32_i32_e32 v69, v57
	v_cvt_f32_i32_e32 v70, v50
	v_cvt_f32_i32_e32 v71, v51
	v_cvt_f32_i32_e32 v72, v52
	v_cvt_f32_i32_e32 v73, v53
	v_cvt_f32_i32_e32 v74, v30
	v_cvt_f32_i32_e32 v75, v31
	v_cvt_f32_i32_e32 v76, v32
	v_cvt_f32_i32_e32 v77, v33
	v_cvt_f32_i32_e32 v78, v22
	v_cvt_f32_i32_e32 v79, v23
	v_cvt_f32_i32_e32 v80, v24
	v_cvt_f32_i32_e32 v81, v25
	v_cvt_f32_i32_e32 v50, v42
	v_cvt_f32_i32_e32 v51, v43
	v_cvt_f32_i32_e32 v52, v44
	v_cvt_f32_i32_e32 v53, v45
	v_cvt_f32_i32_e32 v54, v34
	v_cvt_f32_i32_e32 v55, v35
	v_cvt_f32_i32_e32 v56, v36
	v_cvt_f32_i32_e32 v57, v37
	v_cvt_f32_i32_e32 v58, v14
	v_cvt_f32_i32_e32 v59, v15
	v_cvt_f32_i32_e32 v60, v16
	v_cvt_f32_i32_e32 v61, v17
	v_cvt_f32_i32_e32 v62, v10
	v_cvt_f32_i32_e32 v63, v11
	v_cvt_f32_i32_e32 v64, v12
	v_cvt_f32_i32_e32 v65, v13
	v_cvt_f32_i32_e32 v34, v26
	v_cvt_f32_i32_e32 v35, v27
	v_cvt_f32_i32_e32 v36, v28
	v_cvt_f32_i32_e32 v37, v29
	v_cvt_f32_i32_e32 v38, v18
	v_cvt_f32_i32_e32 v39, v19
	v_cvt_f32_i32_e32 v40, v20
	v_cvt_f32_i32_e32 v41, v21
	v_cvt_f32_i32_e32 v42, v6
	v_cvt_f32_i32_e32 v43, v7
	v_cvt_f32_i32_e32 v44, v8
	v_cvt_f32_i32_e32 v45, v9
	v_cvt_f32_i32_e32 v46, v2
	v_cvt_f32_i32_e32 v47, v3
	v_cvt_f32_i32_e32 v48, v4
	v_cvt_f32_i32_e32 v49, v5

.LBB0_3032:
	ds_read_b128 v[114:117], v209
	ds_read_b128 v[118:121], v209 offset:1024
	ds_read_b128 v[122:125], v209 offset:2048
	ds_read_b128 v[126:129], v209 offset:3072
	ds_read_b128 v[146:149], v210
	ds_read_b128 v[150:153], v210 offset:1024
	ds_read_b128 v[154:157], v210 offset:2048
	ds_read_b128 v[158:161], v210 offset:3072
	s_add_i32 s80, s36, 2
	s_add_u32 s37, s34, 0x4000
	s_addc_u32 s38, s35, 0
	s_cmp_eq_u32 s61, s36
	s_cselect_b32 s39, s5, s38
	s_cselect_b32 s38, s4, s37
	s_cselect_b32 s82, s30, s70
	s_cselect_b32 s83, s31, s71
	s_add_u32 s36, s38, 0x8000
	s_addc_u32 s37, s39, 0
	v_lshl_add_u64 v[218:219], s[34:35], 0, v[170:171]
	s_add_i32 m0, s45, 0xc000
	ds_read_b128 v[178:181], v211
	ds_read_b128 v[182:185], v211 offset:1024
	ds_read_b128 v[186:189], v211 offset:2048
	ds_read_b128 v[190:193], v211 offset:3072
	ds_read_b128 v[194:197], v211 offset:4096
	ds_read_b128 v[198:201], v211 offset:5120
	ds_read_b128 v[202:205], v211 offset:6144
	ds_read_b128 v[214:217], v211 offset:7168
	global_load_lds_dwordx4 v[218:219], off
	v_lshl_add_u64 v[218:219], s[34:35], 0, v[172:173]
	s_add_i32 m0, s45, 0xe000
	s_nop 0
	global_load_lds_dwordx4 v[218:219], off
	s_waitcnt vmcnt(8)
	s_waitcnt lgkmcnt(0)
	s_setprio 1
	s_waitcnt lgkmcnt(0)
	v_mfma_f32_16x16x32_bf16 v[142:145], v[114:117], v[178:181], v[142:145]
	v_mfma_f32_16x16x32_bf16 v[138:141], v[122:125], v[178:181], v[138:141]
	s_barrier
	v_mfma_f32_16x16x32_bf16 v[110:113], v[114:117], v[186:189], v[110:113]
	v_mfma_f32_16x16x32_bf16 v[106:109], v[122:125], v[186:189], v[106:109]
	v_mfma_f32_16x16x32_bf16 v[94:97], v[114:117], v[194:197], v[94:97]
	v_mfma_f32_16x16x32_bf16 v[90:93], v[122:125], v[194:197], v[90:93]
	v_mfma_f32_16x16x32_bf16 v[78:81], v[114:117], v[202:205], v[78:81]
	v_mfma_f32_16x16x32_bf16 v[74:77], v[122:125], v[202:205], v[74:77]
	v_mfma_f32_16x16x32_bf16 v[142:145], v[118:121], v[182:185], v[142:145]
	v_mfma_f32_16x16x32_bf16 v[138:141], v[126:129], v[182:185], v[138:141]
	v_mfma_f32_16x16x32_bf16 v[110:113], v[118:121], v[190:193], v[110:113]
	v_mfma_f32_16x16x32_bf16 v[106:109], v[126:129], v[190:193], v[106:109]
	v_mfma_f32_16x16x32_bf16 v[94:97], v[118:121], v[198:201], v[94:97]
	v_mfma_f32_16x16x32_bf16 v[90:93], v[126:129], v[198:201], v[90:93]
	v_mfma_f32_16x16x32_bf16 v[78:81], v[118:121], v[214:217], v[78:81]
	v_mfma_f32_16x16x32_bf16 v[74:77], v[126:129], v[214:217], v[74:77]
	s_setprio 0
	s_setprio 1
	v_mfma_f32_16x16x32_bf16 v[134:137], v[146:149], v[178:181], v[134:137]
	v_mfma_f32_16x16x32_bf16 v[130:133], v[154:157], v[178:181], v[130:133]
	v_mfma_f32_16x16x32_bf16 v[102:105], v[146:149], v[186:189], v[102:105]
	v_mfma_f32_16x16x32_bf16 v[98:101], v[154:157], v[186:189], v[98:101]
	v_mfma_f32_16x16x32_bf16 v[86:89], v[146:149], v[194:197], v[86:89]
	v_mfma_f32_16x16x32_bf16 v[82:85], v[154:157], v[194:197], v[82:85]
	v_mfma_f32_16x16x32_bf16 v[70:73], v[146:149], v[202:205], v[70:73]
	v_mfma_f32_16x16x32_bf16 v[66:69], v[154:157], v[202:205], v[66:69]
	v_mfma_f32_16x16x32_bf16 v[134:137], v[150:153], v[182:185], v[134:137]
	v_mfma_f32_16x16x32_bf16 v[130:133], v[158:161], v[182:185], v[130:133]
	v_mfma_f32_16x16x32_bf16 v[102:105], v[150:153], v[190:193], v[102:105]
	v_mfma_f32_16x16x32_bf16 v[98:101], v[158:161], v[190:193], v[98:101]
	v_mfma_f32_16x16x32_bf16 v[86:89], v[150:153], v[198:201], v[86:89]
	v_mfma_f32_16x16x32_bf16 v[82:85], v[158:161], v[198:201], v[82:85]
	v_mfma_f32_16x16x32_bf16 v[70:73], v[150:153], v[214:217], v[70:73]
	v_mfma_f32_16x16x32_bf16 v[66:69], v[158:161], v[214:217], v[66:69]
	s_setprio 0
	s_barrier
	s_add_i32 s81, s64, s44
	v_lshl_add_u64 v[218:219], s[82:83], 0, v[164:165]
	s_mov_b32 m0, s81
	ds_read_b128 v[178:181], v211 offset:16384
	ds_read_b128 v[182:185], v211 offset:17408
	ds_read_b128 v[186:189], v211 offset:18432
	ds_read_b128 v[190:193], v211 offset:19456
	ds_read_b128 v[194:197], v211 offset:20480
	ds_read_b128 v[198:201], v211 offset:21504
	ds_read_b128 v[202:205], v211 offset:22528
	ds_read_b128 v[214:217], v211 offset:23552
	global_load_lds_dwordx4 v[218:219], off
	s_add_i32 m0, s81, 0x2000
	v_lshl_add_u64 v[220:221], s[82:83], 0, v[168:169]
	s_add_u32 s82, s82, s8
	s_addc_u32 s83, s83, s9
	s_add_i32 s81, s65, s44
	global_load_lds_dwordx4 v[220:221], off
	v_lshl_add_u64 v[222:223], s[82:83], 0, v[164:165]
	s_mov_b32 m0, s81
	v_lshl_add_u64 v[224:225], s[82:83], 0, v[168:169]
	global_load_lds_dwordx4 v[222:223], off
	s_add_i32 m0, s81, 0x2000
	v_lshl_add_u64 v[226:227], s[38:39], 0, v[162:163]
	global_load_lds_dwordx4 v[224:225], off
	s_mov_b32 m0, s45
	s_nop 0
	global_load_lds_dwordx4 v[226:227], off
	v_lshl_add_u64 v[226:227], s[38:39], 0, v[166:167]
	s_mov_b32 m0, s46
	s_nop 0
	global_load_lds_dwordx4 v[226:227], off
	s_waitcnt vmcnt(8)
	s_waitcnt lgkmcnt(0)
	s_setprio 1
	s_waitcnt lgkmcnt(0)
	v_mfma_f32_16x16x32_bf16 v[62:65], v[114:117], v[178:181], v[62:65]
	v_mfma_f32_16x16x32_bf16 v[58:61], v[122:125], v[178:181], v[58:61]
	s_barrier
	v_mfma_f32_16x16x32_bf16 v[46:49], v[114:117], v[186:189], v[46:49]
	v_mfma_f32_16x16x32_bf16 v[42:45], v[122:125], v[186:189], v[42:45]
	v_mfma_f32_16x16x32_bf16 v[30:33], v[114:117], v[194:197], v[30:33]
	v_mfma_f32_16x16x32_bf16 v[26:29], v[122:125], v[194:197], v[26:29]
	v_mfma_f32_16x16x32_bf16 v[14:17], v[114:117], v[202:205], v[14:17]
	v_mfma_f32_16x16x32_bf16 v[10:13], v[122:125], v[202:205], v[10:13]
	v_mfma_f32_16x16x32_bf16 v[62:65], v[118:121], v[182:185], v[62:65]
	v_mfma_f32_16x16x32_bf16 v[58:61], v[126:129], v[182:185], v[58:61]
	v_mfma_f32_16x16x32_bf16 v[46:49], v[118:121], v[190:193], v[46:49]
	v_mfma_f32_16x16x32_bf16 v[42:45], v[126:129], v[190:193], v[42:45]
	v_mfma_f32_16x16x32_bf16 v[30:33], v[118:121], v[198:201], v[30:33]
	v_mfma_f32_16x16x32_bf16 v[26:29], v[126:129], v[198:201], v[26:29]
	v_mfma_f32_16x16x32_bf16 v[14:17], v[118:121], v[214:217], v[14:17]
	v_mfma_f32_16x16x32_bf16 v[10:13], v[126:129], v[214:217], v[10:13]
	s_setprio 0
	s_setprio 1
	v_mfma_f32_16x16x32_bf16 v[54:57], v[146:149], v[178:181], v[54:57]
	v_mfma_f32_16x16x32_bf16 v[50:53], v[154:157], v[178:181], v[50:53]
	v_mfma_f32_16x16x32_bf16 v[38:41], v[146:149], v[186:189], v[38:41]
	v_mfma_f32_16x16x32_bf16 v[34:37], v[154:157], v[186:189], v[34:37]
	v_mfma_f32_16x16x32_bf16 v[22:25], v[146:149], v[194:197], v[22:25]
	v_mfma_f32_16x16x32_bf16 v[18:21], v[154:157], v[194:197], v[18:21]
	v_mfma_f32_16x16x32_bf16 v[6:9], v[146:149], v[202:205], v[6:9]
	v_mfma_f32_16x16x32_bf16 v[2:5], v[154:157], v[202:205], v[2:5]
	v_mfma_f32_16x16x32_bf16 v[54:57], v[150:153], v[182:185], v[54:57]
	v_mfma_f32_16x16x32_bf16 v[50:53], v[158:161], v[182:185], v[50:53]
	v_mfma_f32_16x16x32_bf16 v[38:41], v[150:153], v[190:193], v[38:41]
	v_mfma_f32_16x16x32_bf16 v[34:37], v[158:161], v[190:193], v[34:37]
	v_mfma_f32_16x16x32_bf16 v[22:25], v[150:153], v[198:201], v[22:25]
	v_mfma_f32_16x16x32_bf16 v[18:21], v[158:161], v[198:201], v[18:21]
	v_mfma_f32_16x16x32_bf16 v[6:9], v[150:153], v[214:217], v[6:9]
	v_mfma_f32_16x16x32_bf16 v[2:5], v[158:161], v[214:217], v[2:5]
	s_setprio 0
	s_barrier
	s_add_i32 s81, 0, 0x18000
	s_add_i32 s82, 0, 0x1c000
	v_add_u32_e32 v126, s81, v207
	v_add_u32_e32 v158, s82, v207
	ds_read_b128 v[114:117], v126
	ds_read_b128 v[118:121], v126 offset:1024
	ds_read_b128 v[122:125], v126 offset:2048
	ds_read_b128 v[126:129], v126 offset:3072
	ds_read_b128 v[146:149], v158
	ds_read_b128 v[150:153], v158 offset:1024
	ds_read_b128 v[154:157], v158 offset:2048
	ds_read_b128 v[158:161], v158 offset:3072
	s_add_u32 s38, s38, 0x4000
	s_addc_u32 s39, s39, 0
	s_mov_b32 m0, s47
	v_lshl_add_u64 v[226:227], s[38:39], 0, v[162:163]
	ds_read_b128 v[178:181], v211 offset:32768
	ds_read_b128 v[182:185], v211 offset:33792
	ds_read_b128 v[186:189], v211 offset:34816
	ds_read_b128 v[190:193], v211 offset:35840
	ds_read_b128 v[194:197], v211 offset:36864
	ds_read_b128 v[198:201], v211 offset:37888
	ds_read_b128 v[202:205], v211 offset:38912
	ds_read_b128 v[214:217], v211 offset:39936
	global_load_lds_dwordx4 v[226:227], off
	v_lshl_add_u64 v[226:227], s[38:39], 0, v[166:167]
	s_mov_b32 m0, s50
	s_nop 0
	global_load_lds_dwordx4 v[226:227], off
	s_waitcnt vmcnt(8)
	s_waitcnt lgkmcnt(0)
	s_setprio 1
	s_waitcnt lgkmcnt(0)
	v_mfma_f32_16x16x32_bf16 v[142:145], v[114:117], v[178:181], v[142:145]
	v_mfma_f32_16x16x32_bf16 v[138:141], v[122:125], v[178:181], v[138:141]
	s_barrier
	v_mfma_f32_16x16x32_bf16 v[110:113], v[114:117], v[186:189], v[110:113]
	v_mfma_f32_16x16x32_bf16 v[106:109], v[122:125], v[186:189], v[106:109]
	v_mfma_f32_16x16x32_bf16 v[94:97], v[114:117], v[194:197], v[94:97]
	v_mfma_f32_16x16x32_bf16 v[90:93], v[122:125], v[194:197], v[90:93]
	v_mfma_f32_16x16x32_bf16 v[78:81], v[114:117], v[202:205], v[78:81]
	v_mfma_f32_16x16x32_bf16 v[74:77], v[122:125], v[202:205], v[74:77]
	v_mfma_f32_16x16x32_bf16 v[142:145], v[118:121], v[182:185], v[142:145]
	v_mfma_f32_16x16x32_bf16 v[138:141], v[126:129], v[182:185], v[138:141]
	v_mfma_f32_16x16x32_bf16 v[110:113], v[118:121], v[190:193], v[110:113]
	v_mfma_f32_16x16x32_bf16 v[106:109], v[126:129], v[190:193], v[106:109]
	v_mfma_f32_16x16x32_bf16 v[94:97], v[118:121], v[198:201], v[94:97]
	v_mfma_f32_16x16x32_bf16 v[90:93], v[126:129], v[198:201], v[90:93]
	v_mfma_f32_16x16x32_bf16 v[78:81], v[118:121], v[214:217], v[78:81]
	v_mfma_f32_16x16x32_bf16 v[74:77], v[126:129], v[214:217], v[74:77]
	s_setprio 0
	s_setprio 1
	v_mfma_f32_16x16x32_bf16 v[134:137], v[146:149], v[178:181], v[134:137]
	v_mfma_f32_16x16x32_bf16 v[130:133], v[154:157], v[178:181], v[130:133]
	v_mfma_f32_16x16x32_bf16 v[102:105], v[146:149], v[186:189], v[102:105]
	v_mfma_f32_16x16x32_bf16 v[98:101], v[154:157], v[186:189], v[98:101]
	v_mfma_f32_16x16x32_bf16 v[86:89], v[146:149], v[194:197], v[86:89]
	v_mfma_f32_16x16x32_bf16 v[82:85], v[154:157], v[194:197], v[82:85]
	v_mfma_f32_16x16x32_bf16 v[70:73], v[146:149], v[202:205], v[70:73]
	v_mfma_f32_16x16x32_bf16 v[66:69], v[154:157], v[202:205], v[66:69]
	v_mfma_f32_16x16x32_bf16 v[134:137], v[150:153], v[182:185], v[134:137]
	v_mfma_f32_16x16x32_bf16 v[130:133], v[158:161], v[182:185], v[130:133]
	v_mfma_f32_16x16x32_bf16 v[102:105], v[150:153], v[190:193], v[102:105]
	v_mfma_f32_16x16x32_bf16 v[98:101], v[158:161], v[190:193], v[98:101]
	v_mfma_f32_16x16x32_bf16 v[86:89], v[150:153], v[198:201], v[86:89]
	v_mfma_f32_16x16x32_bf16 v[82:85], v[158:161], v[198:201], v[82:85]
	v_mfma_f32_16x16x32_bf16 v[70:73], v[150:153], v[214:217], v[70:73]
	v_mfma_f32_16x16x32_bf16 v[66:69], v[158:161], v[214:217], v[66:69]
	s_setprio 0
	s_barrier
	s_add_i32 s38, s81, s44
	v_lshl_add_u64 v[218:219], v[218:219], 0, s[24:25]
	s_mov_b32 m0, s38
	ds_read_b128 v[178:181], v211 offset:49152
	ds_read_b128 v[182:185], v211 offset:50176
	ds_read_b128 v[186:189], v211 offset:51200
	ds_read_b128 v[190:193], v211 offset:52224
	ds_read_b128 v[194:197], v211 offset:53248
	ds_read_b128 v[198:201], v211 offset:54272
	ds_read_b128 v[202:205], v211 offset:55296
	ds_read_b128 v[214:217], v211 offset:56320
	global_load_lds_dwordx4 v[218:219], off
	v_lshl_add_u64 v[218:219], v[220:221], 0, s[24:25]
	s_add_i32 m0, s38, 0x2000
	s_add_i32 s38, s82, s44
	global_load_lds_dwordx4 v[218:219], off
	v_lshl_add_u64 v[218:219], v[222:223], 0, s[24:25]
	s_mov_b32 m0, s38
	s_nop 0
	global_load_lds_dwordx4 v[218:219], off
	v_lshl_add_u64 v[218:219], v[224:225], 0, s[24:25]
	s_add_i32 m0, s38, 0x2000
	s_nop 0
	global_load_lds_dwordx4 v[218:219], off
	v_lshl_add_u64 v[218:219], s[36:37], 0, v[162:163]
	s_mov_b32 m0, s59
	s_nop 0
	global_load_lds_dwordx4 v[218:219], off
	v_lshl_add_u64 v[218:219], s[36:37], 0, v[166:167]
	s_mov_b32 m0, s60
	s_nop 0
	global_load_lds_dwordx4 v[218:219], off
	s_waitcnt vmcnt(8)
	s_waitcnt lgkmcnt(0)
	s_setprio 1
	s_waitcnt lgkmcnt(0)
	v_mfma_f32_16x16x32_bf16 v[62:65], v[114:117], v[178:181], v[62:65]
	v_mfma_f32_16x16x32_bf16 v[58:61], v[122:125], v[178:181], v[58:61]
	s_barrier
	v_mfma_f32_16x16x32_bf16 v[46:49], v[114:117], v[186:189], v[46:49]
	v_mfma_f32_16x16x32_bf16 v[42:45], v[122:125], v[186:189], v[42:45]
	v_mfma_f32_16x16x32_bf16 v[30:33], v[114:117], v[194:197], v[30:33]
	v_mfma_f32_16x16x32_bf16 v[26:29], v[122:125], v[194:197], v[26:29]
	v_mfma_f32_16x16x32_bf16 v[14:17], v[114:117], v[202:205], v[14:17]
	v_mfma_f32_16x16x32_bf16 v[10:13], v[122:125], v[202:205], v[10:13]
	v_mfma_f32_16x16x32_bf16 v[62:65], v[118:121], v[182:185], v[62:65]
	v_mfma_f32_16x16x32_bf16 v[58:61], v[126:129], v[182:185], v[58:61]
	v_mfma_f32_16x16x32_bf16 v[46:49], v[118:121], v[190:193], v[46:49]
	v_mfma_f32_16x16x32_bf16 v[42:45], v[126:129], v[190:193], v[42:45]
	v_mfma_f32_16x16x32_bf16 v[30:33], v[118:121], v[198:201], v[30:33]
	v_mfma_f32_16x16x32_bf16 v[26:29], v[126:129], v[198:201], v[26:29]
	v_mfma_f32_16x16x32_bf16 v[14:17], v[118:121], v[214:217], v[14:17]
	v_mfma_f32_16x16x32_bf16 v[10:13], v[126:129], v[214:217], v[10:13]
	s_setprio 0
	s_setprio 1
	v_mfma_f32_16x16x32_bf16 v[54:57], v[146:149], v[178:181], v[54:57]
	v_mfma_f32_16x16x32_bf16 v[50:53], v[154:157], v[178:181], v[50:53]
	v_mfma_f32_16x16x32_bf16 v[38:41], v[146:149], v[186:189], v[38:41]
	v_mfma_f32_16x16x32_bf16 v[34:37], v[154:157], v[186:189], v[34:37]
	v_mfma_f32_16x16x32_bf16 v[22:25], v[146:149], v[194:197], v[22:25]
	v_mfma_f32_16x16x32_bf16 v[18:21], v[154:157], v[194:197], v[18:21]
	v_mfma_f32_16x16x32_bf16 v[6:9], v[146:149], v[202:205], v[6:9]
	v_mfma_f32_16x16x32_bf16 v[2:5], v[154:157], v[202:205], v[2:5]
	v_mfma_f32_16x16x32_bf16 v[54:57], v[150:153], v[182:185], v[54:57]
	v_mfma_f32_16x16x32_bf16 v[50:53], v[158:161], v[182:185], v[50:53]
	v_mfma_f32_16x16x32_bf16 v[38:41], v[150:153], v[190:193], v[38:41]
	v_mfma_f32_16x16x32_bf16 v[34:37], v[158:161], v[190:193], v[34:37]
	v_mfma_f32_16x16x32_bf16 v[22:25], v[150:153], v[198:201], v[22:25]
	v_mfma_f32_16x16x32_bf16 v[18:21], v[158:161], v[198:201], v[18:21]
	v_mfma_f32_16x16x32_bf16 v[6:9], v[150:153], v[214:217], v[6:9]
	v_mfma_f32_16x16x32_bf16 v[2:5], v[158:161], v[214:217], v[2:5]
	s_setprio 0
	s_add_u32 s70, s70, 0x100
	s_addc_u32 s71, s71, 0
	s_add_u32 s34, s34, 0x10000
	s_addc_u32 s35, s35, 0
	s_cmp_ge_i32 s80, s58
	s_mov_b32 s36, s80
	s_barrier
	s_cbranch_scc0 .LBB0_3032

.LBB0_3126:
	ds_read_b128 v[34:37], v196
	ds_read_b128 v[38:41], v196 offset:1024
	ds_read_b128 v[50:53], v196 offset:2048
	ds_read_b128 v[54:57], v196 offset:3072
	ds_read_b128 v[146:149], v197
	ds_read_b128 v[150:153], v197 offset:1024
	ds_read_b128 v[184:187], v197 offset:2048
	ds_read_b128 v[188:191], v197 offset:3072
	s_add_i32 s11, s6, 2
	s_add_u32 s12, s4, 0x80
	s_addc_u32 s7, s5, 0
	s_cmp_eq_u32 s84, s6
	s_cselect_b32 s6, s44, s12
	s_cselect_b32 s7, s45, s7
	s_cselect_b32 s13, s47, s9
	s_cselect_b32 s12, s46, s8
	v_lshl_add_u64 v[192:193], s[4:5], 0, v[174:175]
	s_add_i32 m0, s66, 0xc000
	ds_read_b128 v[200:203], v198
	ds_read_b128 v[204:207], v198 offset:1024
	ds_read_b128 v[208:211], v198 offset:2048
	ds_read_b128 v[212:215], v198 offset:3072
	ds_read_b128 v[216:219], v198 offset:4096
	ds_read_b128 v[220:223], v198 offset:5120
	ds_read_b128 v[224:227], v198 offset:6144
	ds_read_b128 v[228:231], v198 offset:7168
	global_load_lds_dwordx4 v[192:193], off
	v_lshl_add_u64 v[192:193], s[4:5], 0, v[176:177]
	s_add_i32 m0, s66, 0xe000
	s_nop 0
	global_load_lds_dwordx4 v[192:193], off
	s_waitcnt vmcnt(8)
	s_waitcnt lgkmcnt(0)
	s_setprio 1
	s_waitcnt lgkmcnt(0)
	v_mfma_f32_16x16x32_bf16 v[142:145], v[34:37], v[200:203], v[142:145]
	v_mfma_f32_16x16x32_bf16 v[138:141], v[50:53], v[200:203], v[138:141]
	s_barrier
	v_mfma_f32_16x16x32_bf16 v[126:129], v[34:37], v[208:211], v[126:129]
	v_mfma_f32_16x16x32_bf16 v[122:125], v[50:53], v[208:211], v[122:125]
	v_mfma_f32_16x16x32_bf16 v[110:113], v[34:37], v[216:219], v[110:113]
	v_mfma_f32_16x16x32_bf16 v[106:109], v[50:53], v[216:219], v[106:109]
	v_mfma_f32_16x16x32_bf16 v[94:97], v[34:37], v[224:227], v[94:97]
	v_mfma_f32_16x16x32_bf16 v[90:93], v[50:53], v[224:227], v[90:93]
	v_mfma_f32_16x16x32_bf16 v[142:145], v[38:41], v[204:207], v[142:145]
	v_mfma_f32_16x16x32_bf16 v[138:141], v[54:57], v[204:207], v[138:141]
	v_mfma_f32_16x16x32_bf16 v[126:129], v[38:41], v[212:215], v[126:129]
	v_mfma_f32_16x16x32_bf16 v[122:125], v[54:57], v[212:215], v[122:125]
	v_mfma_f32_16x16x32_bf16 v[110:113], v[38:41], v[220:223], v[110:113]
	v_mfma_f32_16x16x32_bf16 v[106:109], v[54:57], v[220:223], v[106:109]
	v_mfma_f32_16x16x32_bf16 v[94:97], v[38:41], v[228:231], v[94:97]
	v_mfma_f32_16x16x32_bf16 v[90:93], v[54:57], v[228:231], v[90:93]
	s_setprio 0
	s_setprio 1
	v_mfma_f32_16x16x32_bf16 v[134:137], v[146:149], v[200:203], v[134:137]
	v_mfma_f32_16x16x32_bf16 v[130:133], v[184:187], v[200:203], v[130:133]
	v_mfma_f32_16x16x32_bf16 v[118:121], v[146:149], v[208:211], v[118:121]
	v_mfma_f32_16x16x32_bf16 v[114:117], v[184:187], v[208:211], v[114:117]
	v_mfma_f32_16x16x32_bf16 v[102:105], v[146:149], v[216:219], v[102:105]
	v_mfma_f32_16x16x32_bf16 v[98:101], v[184:187], v[216:219], v[98:101]
	v_mfma_f32_16x16x32_bf16 v[86:89], v[146:149], v[224:227], v[86:89]
	v_mfma_f32_16x16x32_bf16 v[82:85], v[184:187], v[224:227], v[82:85]
	v_mfma_f32_16x16x32_bf16 v[134:137], v[150:153], v[204:207], v[134:137]
	v_mfma_f32_16x16x32_bf16 v[130:133], v[188:191], v[204:207], v[130:133]
	v_mfma_f32_16x16x32_bf16 v[118:121], v[150:153], v[212:215], v[118:121]
	v_mfma_f32_16x16x32_bf16 v[114:117], v[188:191], v[212:215], v[114:117]
	v_mfma_f32_16x16x32_bf16 v[102:105], v[150:153], v[220:223], v[102:105]
	v_mfma_f32_16x16x32_bf16 v[98:101], v[188:191], v[220:223], v[98:101]
	v_mfma_f32_16x16x32_bf16 v[86:89], v[150:153], v[228:231], v[86:89]
	v_mfma_f32_16x16x32_bf16 v[82:85], v[188:191], v[228:231], v[82:85]
	s_setprio 0
	s_barrier
	s_add_i32 s20, s88, s61
	v_lshl_add_u64 v[192:193], s[12:13], 0, v[156:157]
	s_mov_b32 m0, s20
	ds_read_b128 v[200:203], v198 offset:16384
	ds_read_b128 v[204:207], v198 offset:17408
	ds_read_b128 v[208:211], v198 offset:18432
	ds_read_b128 v[212:215], v198 offset:19456
	ds_read_b128 v[216:219], v198 offset:20480
	ds_read_b128 v[220:223], v198 offset:21504
	ds_read_b128 v[224:227], v198 offset:22528
	ds_read_b128 v[228:231], v198 offset:23552
	global_load_lds_dwordx4 v[192:193], off
	s_add_i32 m0, s20, 0x2000
	v_lshl_add_u64 v[232:233], s[12:13], 0, v[160:161]
	s_add_u32 s12, s12, s16
	s_addc_u32 s13, s13, s17
	s_add_i32 s20, s89, s61
	global_load_lds_dwordx4 v[232:233], off
	v_lshl_add_u64 v[234:235], s[12:13], 0, v[156:157]
	s_mov_b32 m0, s20
	v_lshl_add_u64 v[236:237], s[12:13], 0, v[160:161]
	global_load_lds_dwordx4 v[234:235], off
	s_add_i32 m0, s20, 0x2000
	v_lshl_add_u64 v[238:239], s[6:7], 0, v[154:155]
	global_load_lds_dwordx4 v[236:237], off
	s_mov_b32 m0, s66
	v_lshl_add_u64 v[240:241], s[6:7], 0, v[158:159]
	global_load_lds_dwordx4 v[238:239], off
	s_mov_b32 m0, s68
	s_nop 0
	global_load_lds_dwordx4 v[240:241], off
	s_waitcnt vmcnt(8)
	s_waitcnt lgkmcnt(0)
	s_setprio 1
	s_waitcnt lgkmcnt(0)
	v_mfma_f32_16x16x32_bf16 v[78:81], v[34:37], v[200:203], v[78:81]
	v_mfma_f32_16x16x32_bf16 v[74:77], v[50:53], v[200:203], v[74:77]
	s_barrier
	v_mfma_f32_16x16x32_bf16 v[62:65], v[34:37], v[208:211], v[62:65]
	v_mfma_f32_16x16x32_bf16 v[58:61], v[50:53], v[208:211], v[58:61]
	v_mfma_f32_16x16x32_bf16 v[30:33], v[34:37], v[216:219], v[30:33]
	v_mfma_f32_16x16x32_bf16 v[26:29], v[50:53], v[216:219], v[26:29]
	v_mfma_f32_16x16x32_bf16 v[14:17], v[34:37], v[224:227], v[14:17]
	v_mfma_f32_16x16x32_bf16 v[10:13], v[50:53], v[224:227], v[10:13]
	v_mfma_f32_16x16x32_bf16 v[78:81], v[38:41], v[204:207], v[78:81]
	v_mfma_f32_16x16x32_bf16 v[74:77], v[54:57], v[204:207], v[74:77]
	v_mfma_f32_16x16x32_bf16 v[62:65], v[38:41], v[212:215], v[62:65]
	v_mfma_f32_16x16x32_bf16 v[58:61], v[54:57], v[212:215], v[58:61]
	v_mfma_f32_16x16x32_bf16 v[30:33], v[38:41], v[220:223], v[30:33]
	v_mfma_f32_16x16x32_bf16 v[26:29], v[54:57], v[220:223], v[26:29]
	v_mfma_f32_16x16x32_bf16 v[14:17], v[38:41], v[228:231], v[14:17]
	v_mfma_f32_16x16x32_bf16 v[10:13], v[54:57], v[228:231], v[10:13]
	s_setprio 0
	s_setprio 1
	v_mfma_f32_16x16x32_bf16 v[46:49], v[146:149], v[208:211], v[46:49]
	v_mfma_f32_16x16x32_bf16 v[42:45], v[184:187], v[208:211], v[42:45]
	v_mfma_f32_16x16x32_bf16 v[22:25], v[146:149], v[216:219], v[22:25]
	v_mfma_f32_16x16x32_bf16 v[18:21], v[184:187], v[216:219], v[18:21]
	v_mfma_f32_16x16x32_bf16 v[6:9], v[146:149], v[224:227], v[6:9]
	v_mfma_f32_16x16x32_bf16 v[2:5], v[184:187], v[224:227], v[2:5]
	v_mfma_f32_16x16x32_bf16 v[34:37], v[146:149], v[200:203], v[70:73]
	v_mfma_f32_16x16x32_bf16 v[38:41], v[184:187], v[200:203], v[66:69]
	v_mfma_f32_16x16x32_bf16 v[46:49], v[150:153], v[212:215], v[46:49]
	v_mfma_f32_16x16x32_bf16 v[42:45], v[188:191], v[212:215], v[42:45]
	v_mfma_f32_16x16x32_bf16 v[22:25], v[150:153], v[220:223], v[22:25]
	v_mfma_f32_16x16x32_bf16 v[18:21], v[188:191], v[220:223], v[18:21]
	v_mfma_f32_16x16x32_bf16 v[6:9], v[150:153], v[228:231], v[6:9]
	v_mfma_f32_16x16x32_bf16 v[2:5], v[188:191], v[228:231], v[2:5]
	v_mfma_f32_16x16x32_bf16 v[34:37], v[150:153], v[204:207], v[34:37]
	v_mfma_f32_16x16x32_bf16 v[38:41], v[188:191], v[204:207], v[38:41]
	s_setprio 0
	s_barrier
	s_add_i32 s12, 0, 0x18000
	s_add_i32 s13, 0, 0x1c000
	v_add_u32_e32 v70, s12, v194
	v_add_u32_e32 v162, s13, v194
	ds_read_b128 v[50:53], v70
	ds_read_b128 v[54:57], v70 offset:1024
	ds_read_b128 v[66:69], v70 offset:2048
	ds_read_b128 v[70:73], v70 offset:3072
	ds_read_b128 v[146:149], v162
	ds_read_b128 v[150:153], v162 offset:1024
	ds_read_b128 v[184:187], v162 offset:2048
	ds_read_b128 v[188:191], v162 offset:3072
	s_add_u32 s6, s6, s16
	s_addc_u32 s7, s7, s17
	s_mov_b32 m0, s69
	v_lshl_add_u64 v[242:243], s[6:7], 0, v[154:155]
	ds_read_b128 v[200:203], v198 offset:32768
	ds_read_b128 v[204:207], v198 offset:33792
	ds_read_b128 v[208:211], v198 offset:34816
	ds_read_b128 v[212:215], v198 offset:35840
	ds_read_b128 v[216:219], v198 offset:36864
	ds_read_b128 v[220:223], v198 offset:37888
	ds_read_b128 v[224:227], v198 offset:38912
	ds_read_b128 v[228:231], v198 offset:39936
	global_load_lds_dwordx4 v[242:243], off
	v_lshl_add_u64 v[242:243], s[6:7], 0, v[158:159]
	s_mov_b32 m0, s70
	s_nop 0
	global_load_lds_dwordx4 v[242:243], off
	s_waitcnt vmcnt(8)
	s_waitcnt lgkmcnt(0)
	s_setprio 1
	s_waitcnt lgkmcnt(0)
	v_mfma_f32_16x16x32_bf16 v[142:145], v[50:53], v[200:203], v[142:145]
	v_mfma_f32_16x16x32_bf16 v[138:141], v[66:69], v[200:203], v[138:141]
	s_barrier
	v_mfma_f32_16x16x32_bf16 v[126:129], v[50:53], v[208:211], v[126:129]
	v_mfma_f32_16x16x32_bf16 v[122:125], v[66:69], v[208:211], v[122:125]
	v_mfma_f32_16x16x32_bf16 v[110:113], v[50:53], v[216:219], v[110:113]
	v_mfma_f32_16x16x32_bf16 v[106:109], v[66:69], v[216:219], v[106:109]
	v_mfma_f32_16x16x32_bf16 v[94:97], v[50:53], v[224:227], v[94:97]
	v_mfma_f32_16x16x32_bf16 v[90:93], v[66:69], v[224:227], v[90:93]
	v_mfma_f32_16x16x32_bf16 v[142:145], v[54:57], v[204:207], v[142:145]
	v_mfma_f32_16x16x32_bf16 v[138:141], v[70:73], v[204:207], v[138:141]
	v_mfma_f32_16x16x32_bf16 v[126:129], v[54:57], v[212:215], v[126:129]
	v_mfma_f32_16x16x32_bf16 v[122:125], v[70:73], v[212:215], v[122:125]
	v_mfma_f32_16x16x32_bf16 v[110:113], v[54:57], v[220:223], v[110:113]
	v_mfma_f32_16x16x32_bf16 v[106:109], v[70:73], v[220:223], v[106:109]
	v_mfma_f32_16x16x32_bf16 v[94:97], v[54:57], v[228:231], v[94:97]
	v_mfma_f32_16x16x32_bf16 v[90:93], v[70:73], v[228:231], v[90:93]
	s_setprio 0
	s_setprio 1
	v_mfma_f32_16x16x32_bf16 v[134:137], v[146:149], v[200:203], v[134:137]
	v_mfma_f32_16x16x32_bf16 v[130:133], v[184:187], v[200:203], v[130:133]
	v_mfma_f32_16x16x32_bf16 v[118:121], v[146:149], v[208:211], v[118:121]
	v_mfma_f32_16x16x32_bf16 v[114:117], v[184:187], v[208:211], v[114:117]
	v_mfma_f32_16x16x32_bf16 v[102:105], v[146:149], v[216:219], v[102:105]
	v_mfma_f32_16x16x32_bf16 v[98:101], v[184:187], v[216:219], v[98:101]
	v_mfma_f32_16x16x32_bf16 v[86:89], v[146:149], v[224:227], v[86:89]
	v_mfma_f32_16x16x32_bf16 v[82:85], v[184:187], v[224:227], v[82:85]
	v_mfma_f32_16x16x32_bf16 v[134:137], v[150:153], v[204:207], v[134:137]
	v_mfma_f32_16x16x32_bf16 v[130:133], v[188:191], v[204:207], v[130:133]
	v_mfma_f32_16x16x32_bf16 v[118:121], v[150:153], v[212:215], v[118:121]
	v_mfma_f32_16x16x32_bf16 v[114:117], v[188:191], v[212:215], v[114:117]
	v_mfma_f32_16x16x32_bf16 v[102:105], v[150:153], v[220:223], v[102:105]
	v_mfma_f32_16x16x32_bf16 v[98:101], v[188:191], v[220:223], v[98:101]
	v_mfma_f32_16x16x32_bf16 v[86:89], v[150:153], v[228:231], v[86:89]
	v_mfma_f32_16x16x32_bf16 v[82:85], v[188:191], v[228:231], v[82:85]
	s_setprio 0
	s_barrier
	s_add_i32 s6, s12, s61
	v_lshl_add_u64 v[192:193], v[192:193], 0, s[38:39]
	s_mov_b32 m0, s6
	ds_read_b128 v[200:203], v198 offset:49152
	ds_read_b128 v[204:207], v198 offset:50176
	ds_read_b128 v[208:211], v198 offset:51200
	ds_read_b128 v[212:215], v198 offset:52224
	ds_read_b128 v[216:219], v198 offset:53248
	ds_read_b128 v[220:223], v198 offset:54272
	ds_read_b128 v[224:227], v198 offset:55296
	ds_read_b128 v[228:231], v198 offset:56320
	global_load_lds_dwordx4 v[192:193], off
	v_lshl_add_u64 v[192:193], v[232:233], 0, s[38:39]
	s_add_i32 m0, s6, 0x2000
	s_add_i32 s6, s13, s61
	global_load_lds_dwordx4 v[192:193], off
	v_lshl_add_u64 v[192:193], v[234:235], 0, s[38:39]
	s_mov_b32 m0, s6
	s_nop 0
	global_load_lds_dwordx4 v[192:193], off
	v_lshl_add_u64 v[192:193], v[236:237], 0, s[38:39]
	s_add_i32 m0, s6, 0x2000
	s_nop 0
	global_load_lds_dwordx4 v[192:193], off
	v_lshl_add_u64 v[192:193], v[238:239], 0, s[38:39]
	s_mov_b32 m0, s81
	s_nop 0
	global_load_lds_dwordx4 v[192:193], off
	v_lshl_add_u64 v[192:193], v[240:241], 0, s[38:39]
	s_mov_b32 m0, s82
	s_nop 0
	global_load_lds_dwordx4 v[192:193], off
	s_waitcnt vmcnt(8)
	s_waitcnt lgkmcnt(0)
	s_setprio 1
	s_waitcnt lgkmcnt(0)
	v_mfma_f32_16x16x32_bf16 v[78:81], v[50:53], v[200:203], v[78:81]
	v_mfma_f32_16x16x32_bf16 v[74:77], v[66:69], v[200:203], v[74:77]
	s_barrier
	v_mfma_f32_16x16x32_bf16 v[62:65], v[50:53], v[208:211], v[62:65]
	v_mfma_f32_16x16x32_bf16 v[58:61], v[66:69], v[208:211], v[58:61]
	v_mfma_f32_16x16x32_bf16 v[30:33], v[50:53], v[216:219], v[30:33]
	v_mfma_f32_16x16x32_bf16 v[26:29], v[66:69], v[216:219], v[26:29]
	v_mfma_f32_16x16x32_bf16 v[14:17], v[50:53], v[224:227], v[14:17]
	v_mfma_f32_16x16x32_bf16 v[10:13], v[66:69], v[224:227], v[10:13]
	v_mfma_f32_16x16x32_bf16 v[78:81], v[54:57], v[204:207], v[78:81]
	v_mfma_f32_16x16x32_bf16 v[74:77], v[70:73], v[204:207], v[74:77]
	v_mfma_f32_16x16x32_bf16 v[62:65], v[54:57], v[212:215], v[62:65]
	v_mfma_f32_16x16x32_bf16 v[58:61], v[70:73], v[212:215], v[58:61]
	v_mfma_f32_16x16x32_bf16 v[30:33], v[54:57], v[220:223], v[30:33]
	v_mfma_f32_16x16x32_bf16 v[26:29], v[70:73], v[220:223], v[26:29]
	v_mfma_f32_16x16x32_bf16 v[14:17], v[54:57], v[228:231], v[14:17]
	v_mfma_f32_16x16x32_bf16 v[10:13], v[70:73], v[228:231], v[10:13]
	s_setprio 0
	s_setprio 1
	v_mfma_f32_16x16x32_bf16 v[34:37], v[146:149], v[200:203], v[34:37]
	v_mfma_f32_16x16x32_bf16 v[70:73], v[150:153], v[204:207], v[34:37]
	v_mfma_f32_16x16x32_bf16 v[34:37], v[184:187], v[200:203], v[38:41]
	v_mfma_f32_16x16x32_bf16 v[66:69], v[188:191], v[204:207], v[34:37]
	v_mfma_f32_16x16x32_bf16 v[34:37], v[146:149], v[208:211], v[46:49]
	v_mfma_f32_16x16x32_bf16 v[46:49], v[150:153], v[212:215], v[34:37]
	v_mfma_f32_16x16x32_bf16 v[34:37], v[184:187], v[208:211], v[42:45]
	v_mfma_f32_16x16x32_bf16 v[22:25], v[146:149], v[216:219], v[22:25]
	v_mfma_f32_16x16x32_bf16 v[18:21], v[184:187], v[216:219], v[18:21]
	v_mfma_f32_16x16x32_bf16 v[6:9], v[146:149], v[224:227], v[6:9]
	v_mfma_f32_16x16x32_bf16 v[2:5], v[184:187], v[224:227], v[2:5]
	v_mfma_f32_16x16x32_bf16 v[42:45], v[188:191], v[212:215], v[34:37]
	v_mfma_f32_16x16x32_bf16 v[22:25], v[150:153], v[220:223], v[22:25]
	v_mfma_f32_16x16x32_bf16 v[18:21], v[188:191], v[220:223], v[18:21]
	v_mfma_f32_16x16x32_bf16 v[6:9], v[150:153], v[228:231], v[6:9]
	v_mfma_f32_16x16x32_bf16 v[2:5], v[188:191], v[228:231], v[2:5]
	s_setprio 0
	s_add_u32 s4, s4, 0x100
	s_addc_u32 s5, s5, 0
	s_add_u32 s8, s8, 0x100
	s_addc_u32 s9, s9, 0
	s_cmp_ge_i32 s11, s83
	s_mov_b32 s6, s11
	s_barrier
	s_cbranch_scc0 .LBB0_3126

.LBB0_3613:
	v_add_u32_e32 v158, s64, v229
	v_add_u32_e32 v174, s65, v229
	ds_read_b128 v[146:149], v158
	ds_read_b128 v[150:153], v158 offset:1024
	ds_read_b128 v[154:157], v158 offset:2048
	ds_read_b128 v[158:161], v158 offset:3072
	ds_read_b128 v[162:165], v174
	ds_read_b128 v[166:169], v174 offset:1024
	ds_read_b128 v[170:173], v174 offset:2048
	ds_read_b128 v[174:177], v174 offset:3072
	s_add_i32 s80, s42, 2
	s_add_u32 s81, s40, 0x80
	s_addc_u32 s43, s41, 0
	s_cmp_eq_u32 s61, s42
	s_cselect_b32 s42, s4, s81
	s_cselect_b32 s43, s5, s43
	s_cselect_b32 s83, s39, s71
	s_cselect_b32 s82, s38, s70
	v_lshl_add_u64 v[210:211], s[40:41], 0, v[138:139]
	s_add_i32 m0, s51, 0xc000
	ds_read_b128 v[178:181], v231
	ds_read_b128 v[182:185], v231 offset:1024
	ds_read_b128 v[186:189], v231 offset:2048
	ds_read_b128 v[190:193], v231 offset:3072
	ds_read_b128 v[194:197], v231 offset:4096
	ds_read_b128 v[198:201], v231 offset:5120
	ds_read_b128 v[202:205], v231 offset:6144
	ds_read_b128 v[206:209], v231 offset:7168
	global_load_lds_dwordx4 v[210:211], off
	v_lshl_add_u64 v[210:211], s[40:41], 0, v[140:141]
	s_add_i32 m0, s51, 0xe000
	s_nop 0
	global_load_lds_dwordx4 v[210:211], off
	s_waitcnt vmcnt(8)
	s_waitcnt lgkmcnt(0)
	s_setprio 1
	s_waitcnt lgkmcnt(0)
	v_mfma_i32_16x16x64_i8 v[126:129], v[146:149], v[178:181], v[126:129]
	v_mfma_i32_16x16x64_i8 v[122:125], v[154:157], v[178:181], v[122:125]
	s_barrier
	v_mfma_i32_16x16x64_i8 v[118:121], v[146:149], v[186:189], v[118:121]
	v_mfma_i32_16x16x64_i8 v[114:117], v[154:157], v[186:189], v[114:117]
	v_mfma_i32_16x16x64_i8 v[106:109], v[146:149], v[194:197], v[106:109]
	v_mfma_i32_16x16x64_i8 v[98:101], v[154:157], v[194:197], v[98:101]
	v_mfma_i32_16x16x64_i8 v[90:93], v[146:149], v[202:205], v[90:93]
	v_mfma_i32_16x16x64_i8 v[82:85], v[154:157], v[202:205], v[82:85]
	v_mfma_i32_16x16x64_i8 v[126:129], v[150:153], v[182:185], v[126:129]
	v_mfma_i32_16x16x64_i8 v[122:125], v[158:161], v[182:185], v[122:125]
	v_mfma_i32_16x16x64_i8 v[118:121], v[150:153], v[190:193], v[118:121]
	v_mfma_i32_16x16x64_i8 v[114:117], v[158:161], v[190:193], v[114:117]
	v_mfma_i32_16x16x64_i8 v[106:109], v[150:153], v[198:201], v[106:109]
	v_mfma_i32_16x16x64_i8 v[98:101], v[158:161], v[198:201], v[98:101]
	v_mfma_i32_16x16x64_i8 v[90:93], v[150:153], v[206:209], v[90:93]
	v_mfma_i32_16x16x64_i8 v[82:85], v[158:161], v[206:209], v[82:85]
	s_setprio 0
	s_setprio 1
	v_mfma_i32_16x16x64_i8 v[110:113], v[162:165], v[178:181], v[110:113]
	v_mfma_i32_16x16x64_i8 v[102:105], v[170:173], v[178:181], v[102:105]
	v_mfma_i32_16x16x64_i8 v[94:97], v[162:165], v[186:189], v[94:97]
	v_mfma_i32_16x16x64_i8 v[86:89], v[170:173], v[186:189], v[86:89]
	v_mfma_i32_16x16x64_i8 v[78:81], v[162:165], v[194:197], v[78:81]
	v_mfma_i32_16x16x64_i8 v[74:77], v[170:173], v[194:197], v[74:77]
	v_mfma_i32_16x16x64_i8 v[70:73], v[162:165], v[202:205], v[70:73]
	v_mfma_i32_16x16x64_i8 v[66:69], v[170:173], v[202:205], v[66:69]
	v_mfma_i32_16x16x64_i8 v[110:113], v[166:169], v[182:185], v[110:113]
	v_mfma_i32_16x16x64_i8 v[102:105], v[174:177], v[182:185], v[102:105]
	v_mfma_i32_16x16x64_i8 v[94:97], v[166:169], v[190:193], v[94:97]
	v_mfma_i32_16x16x64_i8 v[86:89], v[174:177], v[190:193], v[86:89]
	v_mfma_i32_16x16x64_i8 v[78:81], v[166:169], v[198:201], v[78:81]
	v_mfma_i32_16x16x64_i8 v[74:77], v[174:177], v[198:201], v[74:77]
	v_mfma_i32_16x16x64_i8 v[70:73], v[166:169], v[206:209], v[70:73]
	v_mfma_i32_16x16x64_i8 v[66:69], v[174:177], v[206:209], v[66:69]
	s_setprio 0
	s_barrier
	s_add_i32 s81, s64, s50
	v_lshl_add_u64 v[210:211], s[82:83], 0, v[132:133]
	s_mov_b32 m0, s81
	ds_read_b128 v[178:181], v231 offset:16384
	ds_read_b128 v[182:185], v231 offset:17408
	ds_read_b128 v[186:189], v231 offset:18432
	ds_read_b128 v[190:193], v231 offset:19456
	ds_read_b128 v[194:197], v231 offset:20480
	ds_read_b128 v[198:201], v231 offset:21504
	ds_read_b128 v[202:205], v231 offset:22528
	ds_read_b128 v[206:209], v231 offset:23552
	global_load_lds_dwordx4 v[210:211], off
	s_add_i32 m0, s81, 0x2000
	v_lshl_add_u64 v[212:213], s[82:83], 0, v[136:137]
	s_add_u32 s82, s82, s8
	s_addc_u32 s83, s83, s9
	s_add_i32 s81, s65, s50
	global_load_lds_dwordx4 v[212:213], off
	v_lshl_add_u64 v[214:215], s[82:83], 0, v[132:133]
	s_mov_b32 m0, s81
	v_lshl_add_u64 v[216:217], s[82:83], 0, v[136:137]
	global_load_lds_dwordx4 v[214:215], off
	s_add_i32 m0, s81, 0x2000
	v_lshl_add_u64 v[218:219], s[42:43], 0, v[130:131]
	global_load_lds_dwordx4 v[216:217], off
	s_mov_b32 m0, s51
	v_lshl_add_u64 v[220:221], s[42:43], 0, v[134:135]
	global_load_lds_dwordx4 v[218:219], off
	s_mov_b32 m0, s52
	s_nop 0
	global_load_lds_dwordx4 v[220:221], off
	s_waitcnt vmcnt(8)
	s_waitcnt lgkmcnt(0)
	s_setprio 1
	s_waitcnt lgkmcnt(0)
	v_mfma_i32_16x16x64_i8 v[62:65], v[146:149], v[178:181], v[62:65]
	v_mfma_i32_16x16x64_i8 v[58:61], v[154:157], v[178:181], v[58:61]
	s_barrier
	v_mfma_i32_16x16x64_i8 v[54:57], v[146:149], v[186:189], v[54:57]
	v_mfma_i32_16x16x64_i8 v[50:53], v[154:157], v[186:189], v[50:53]
	v_mfma_i32_16x16x64_i8 v[42:45], v[146:149], v[194:197], v[42:45]
	v_mfma_i32_16x16x64_i8 v[34:37], v[154:157], v[194:197], v[34:37]
	v_mfma_i32_16x16x64_i8 v[26:29], v[146:149], v[202:205], v[26:29]
	v_mfma_i32_16x16x64_i8 v[18:21], v[154:157], v[202:205], v[18:21]
	v_mfma_i32_16x16x64_i8 v[62:65], v[150:153], v[182:185], v[62:65]
	v_mfma_i32_16x16x64_i8 v[58:61], v[158:161], v[182:185], v[58:61]
	v_mfma_i32_16x16x64_i8 v[54:57], v[150:153], v[190:193], v[54:57]
	v_mfma_i32_16x16x64_i8 v[50:53], v[158:161], v[190:193], v[50:53]
	v_mfma_i32_16x16x64_i8 v[42:45], v[150:153], v[198:201], v[42:45]
	v_mfma_i32_16x16x64_i8 v[34:37], v[158:161], v[198:201], v[34:37]
	v_mfma_i32_16x16x64_i8 v[26:29], v[150:153], v[206:209], v[26:29]
	v_mfma_i32_16x16x64_i8 v[18:21], v[158:161], v[206:209], v[18:21]
	s_setprio 0
	s_setprio 1
	v_mfma_i32_16x16x64_i8 v[46:49], v[162:165], v[178:181], v[46:49]
	v_mfma_i32_16x16x64_i8 v[38:41], v[170:173], v[178:181], v[38:41]
	v_mfma_i32_16x16x64_i8 v[30:33], v[162:165], v[186:189], v[30:33]
	v_mfma_i32_16x16x64_i8 v[22:25], v[170:173], v[186:189], v[22:25]
	v_mfma_i32_16x16x64_i8 v[14:17], v[162:165], v[194:197], v[14:17]
	v_mfma_i32_16x16x64_i8 v[10:13], v[170:173], v[194:197], v[10:13]
	v_mfma_i32_16x16x64_i8 v[6:9], v[162:165], v[202:205], v[6:9]
	v_mfma_i32_16x16x64_i8 v[2:5], v[170:173], v[202:205], v[2:5]
	v_mfma_i32_16x16x64_i8 v[46:49], v[166:169], v[182:185], v[46:49]
	v_mfma_i32_16x16x64_i8 v[38:41], v[174:177], v[182:185], v[38:41]
	v_mfma_i32_16x16x64_i8 v[30:33], v[166:169], v[190:193], v[30:33]
	v_mfma_i32_16x16x64_i8 v[22:25], v[174:177], v[190:193], v[22:25]
	v_mfma_i32_16x16x64_i8 v[14:17], v[166:169], v[198:201], v[14:17]
	v_mfma_i32_16x16x64_i8 v[10:13], v[174:177], v[198:201], v[10:13]
	v_mfma_i32_16x16x64_i8 v[6:9], v[166:169], v[206:209], v[6:9]
	v_mfma_i32_16x16x64_i8 v[2:5], v[174:177], v[206:209], v[2:5]
	s_setprio 0
	s_barrier
	s_add_i32 s81, 0, 0x18000
	s_add_i32 s82, 0, 0x1c000
	v_add_u32_e32 v158, s81, v229
	v_add_u32_e32 v174, s82, v229
	ds_read_b128 v[146:149], v158
	ds_read_b128 v[150:153], v158 offset:1024
	ds_read_b128 v[154:157], v158 offset:2048
	ds_read_b128 v[158:161], v158 offset:3072
	ds_read_b128 v[162:165], v174
	ds_read_b128 v[166:169], v174 offset:1024
	ds_read_b128 v[170:173], v174 offset:2048
	ds_read_b128 v[174:177], v174 offset:3072
	s_add_u32 s42, s42, s8
	s_addc_u32 s43, s43, s9
	s_mov_b32 m0, s53
	v_lshl_add_u64 v[222:223], s[42:43], 0, v[130:131]
	ds_read_b128 v[178:181], v231 offset:32768
	ds_read_b128 v[182:185], v231 offset:33792
	ds_read_b128 v[186:189], v231 offset:34816
	ds_read_b128 v[190:193], v231 offset:35840
	ds_read_b128 v[194:197], v231 offset:36864
	ds_read_b128 v[198:201], v231 offset:37888
	ds_read_b128 v[202:205], v231 offset:38912
	ds_read_b128 v[206:209], v231 offset:39936
	global_load_lds_dwordx4 v[222:223], off
	v_lshl_add_u64 v[222:223], s[42:43], 0, v[134:135]
	s_mov_b32 m0, s54
	s_nop 0
	global_load_lds_dwordx4 v[222:223], off
	s_waitcnt vmcnt(8)
	s_waitcnt lgkmcnt(0)
	s_setprio 1
	s_waitcnt lgkmcnt(0)
	v_mfma_i32_16x16x64_i8 v[126:129], v[146:149], v[178:181], v[126:129]
	v_mfma_i32_16x16x64_i8 v[122:125], v[154:157], v[178:181], v[122:125]
	s_barrier
	v_mfma_i32_16x16x64_i8 v[118:121], v[146:149], v[186:189], v[118:121]
	v_mfma_i32_16x16x64_i8 v[114:117], v[154:157], v[186:189], v[114:117]
	v_mfma_i32_16x16x64_i8 v[106:109], v[146:149], v[194:197], v[106:109]
	v_mfma_i32_16x16x64_i8 v[98:101], v[154:157], v[194:197], v[98:101]
	v_mfma_i32_16x16x64_i8 v[90:93], v[146:149], v[202:205], v[90:93]
	v_mfma_i32_16x16x64_i8 v[82:85], v[154:157], v[202:205], v[82:85]
	v_mfma_i32_16x16x64_i8 v[126:129], v[150:153], v[182:185], v[126:129]
	v_mfma_i32_16x16x64_i8 v[122:125], v[158:161], v[182:185], v[122:125]
	v_mfma_i32_16x16x64_i8 v[118:121], v[150:153], v[190:193], v[118:121]
	v_mfma_i32_16x16x64_i8 v[114:117], v[158:161], v[190:193], v[114:117]
	v_mfma_i32_16x16x64_i8 v[106:109], v[150:153], v[198:201], v[106:109]
	v_mfma_i32_16x16x64_i8 v[98:101], v[158:161], v[198:201], v[98:101]
	v_mfma_i32_16x16x64_i8 v[90:93], v[150:153], v[206:209], v[90:93]
	v_mfma_i32_16x16x64_i8 v[82:85], v[158:161], v[206:209], v[82:85]
	s_setprio 0
	s_setprio 1
	v_mfma_i32_16x16x64_i8 v[110:113], v[162:165], v[178:181], v[110:113]
	v_mfma_i32_16x16x64_i8 v[102:105], v[170:173], v[178:181], v[102:105]
	v_mfma_i32_16x16x64_i8 v[94:97], v[162:165], v[186:189], v[94:97]
	v_mfma_i32_16x16x64_i8 v[86:89], v[170:173], v[186:189], v[86:89]
	v_mfma_i32_16x16x64_i8 v[78:81], v[162:165], v[194:197], v[78:81]
	v_mfma_i32_16x16x64_i8 v[74:77], v[170:173], v[194:197], v[74:77]
	v_mfma_i32_16x16x64_i8 v[70:73], v[162:165], v[202:205], v[70:73]
	v_mfma_i32_16x16x64_i8 v[66:69], v[170:173], v[202:205], v[66:69]
	v_mfma_i32_16x16x64_i8 v[110:113], v[166:169], v[182:185], v[110:113]
	v_mfma_i32_16x16x64_i8 v[102:105], v[174:177], v[182:185], v[102:105]
	v_mfma_i32_16x16x64_i8 v[94:97], v[166:169], v[190:193], v[94:97]
	v_mfma_i32_16x16x64_i8 v[86:89], v[174:177], v[190:193], v[86:89]
	v_mfma_i32_16x16x64_i8 v[78:81], v[166:169], v[198:201], v[78:81]
	v_mfma_i32_16x16x64_i8 v[74:77], v[174:177], v[198:201], v[74:77]
	v_mfma_i32_16x16x64_i8 v[70:73], v[166:169], v[206:209], v[70:73]
	v_mfma_i32_16x16x64_i8 v[66:69], v[174:177], v[206:209], v[66:69]
	s_setprio 0
	s_barrier
	s_add_i32 s42, s81, s50
	v_lshl_add_u64 v[210:211], v[210:211], 0, s[30:31]
	s_mov_b32 m0, s42
	ds_read_b128 v[178:181], v231 offset:49152
	ds_read_b128 v[182:185], v231 offset:50176
	ds_read_b128 v[186:189], v231 offset:51200
	ds_read_b128 v[190:193], v231 offset:52224
	ds_read_b128 v[194:197], v231 offset:53248
	ds_read_b128 v[198:201], v231 offset:54272
	ds_read_b128 v[202:205], v231 offset:55296
	ds_read_b128 v[206:209], v231 offset:56320
	global_load_lds_dwordx4 v[210:211], off
	v_lshl_add_u64 v[210:211], v[212:213], 0, s[30:31]
	s_add_i32 m0, s42, 0x2000
	s_add_i32 s42, s82, s50
	global_load_lds_dwordx4 v[210:211], off
	v_lshl_add_u64 v[210:211], v[214:215], 0, s[30:31]
	s_mov_b32 m0, s42
	s_nop 0
	global_load_lds_dwordx4 v[210:211], off
	v_lshl_add_u64 v[210:211], v[216:217], 0, s[30:31]
	s_add_i32 m0, s42, 0x2000
	s_nop 0
	global_load_lds_dwordx4 v[210:211], off
	v_lshl_add_u64 v[210:211], v[218:219], 0, s[30:31]
	s_mov_b32 m0, s57
	s_nop 0
	global_load_lds_dwordx4 v[210:211], off
	v_lshl_add_u64 v[210:211], v[220:221], 0, s[30:31]
	s_mov_b32 m0, s58
	s_nop 0
	global_load_lds_dwordx4 v[210:211], off
	s_waitcnt vmcnt(8)
	s_waitcnt lgkmcnt(0)
	s_setprio 1
	s_waitcnt lgkmcnt(0)
	v_mfma_i32_16x16x64_i8 v[62:65], v[146:149], v[178:181], v[62:65]
	v_mfma_i32_16x16x64_i8 v[58:61], v[154:157], v[178:181], v[58:61]
	s_barrier
	v_mfma_i32_16x16x64_i8 v[54:57], v[146:149], v[186:189], v[54:57]
	v_mfma_i32_16x16x64_i8 v[50:53], v[154:157], v[186:189], v[50:53]
	v_mfma_i32_16x16x64_i8 v[42:45], v[146:149], v[194:197], v[42:45]
	v_mfma_i32_16x16x64_i8 v[34:37], v[154:157], v[194:197], v[34:37]
	v_mfma_i32_16x16x64_i8 v[26:29], v[146:149], v[202:205], v[26:29]
	v_mfma_i32_16x16x64_i8 v[18:21], v[154:157], v[202:205], v[18:21]
	v_mfma_i32_16x16x64_i8 v[62:65], v[150:153], v[182:185], v[62:65]
	v_mfma_i32_16x16x64_i8 v[58:61], v[158:161], v[182:185], v[58:61]
	v_mfma_i32_16x16x64_i8 v[54:57], v[150:153], v[190:193], v[54:57]
	v_mfma_i32_16x16x64_i8 v[50:53], v[158:161], v[190:193], v[50:53]
	v_mfma_i32_16x16x64_i8 v[42:45], v[150:153], v[198:201], v[42:45]
	v_mfma_i32_16x16x64_i8 v[34:37], v[158:161], v[198:201], v[34:37]
	v_mfma_i32_16x16x64_i8 v[26:29], v[150:153], v[206:209], v[26:29]
	v_mfma_i32_16x16x64_i8 v[18:21], v[158:161], v[206:209], v[18:21]
	s_setprio 0
	s_setprio 1
	v_mfma_i32_16x16x64_i8 v[46:49], v[162:165], v[178:181], v[46:49]
	v_mfma_i32_16x16x64_i8 v[38:41], v[170:173], v[178:181], v[38:41]
	v_mfma_i32_16x16x64_i8 v[30:33], v[162:165], v[186:189], v[30:33]
	v_mfma_i32_16x16x64_i8 v[22:25], v[170:173], v[186:189], v[22:25]
	v_mfma_i32_16x16x64_i8 v[14:17], v[162:165], v[194:197], v[14:17]
	v_mfma_i32_16x16x64_i8 v[10:13], v[170:173], v[194:197], v[10:13]
	v_mfma_i32_16x16x64_i8 v[6:9], v[162:165], v[202:205], v[6:9]
	v_mfma_i32_16x16x64_i8 v[2:5], v[170:173], v[202:205], v[2:5]
	v_mfma_i32_16x16x64_i8 v[46:49], v[166:169], v[182:185], v[46:49]
	v_mfma_i32_16x16x64_i8 v[38:41], v[174:177], v[182:185], v[38:41]
	v_mfma_i32_16x16x64_i8 v[30:33], v[166:169], v[190:193], v[30:33]
	v_mfma_i32_16x16x64_i8 v[22:25], v[174:177], v[190:193], v[22:25]
	v_mfma_i32_16x16x64_i8 v[14:17], v[166:169], v[198:201], v[14:17]
	v_mfma_i32_16x16x64_i8 v[10:13], v[174:177], v[198:201], v[10:13]
	v_mfma_i32_16x16x64_i8 v[6:9], v[166:169], v[206:209], v[6:9]
	v_mfma_i32_16x16x64_i8 v[2:5], v[174:177], v[206:209], v[2:5]
	s_setprio 0
	s_add_u32 s40, s40, 0x100
	s_addc_u32 s41, s41, 0
	s_add_u32 s70, s70, 0x100
	s_addc_u32 s71, s71, 0
	s_cmp_ge_i32 s80, s60
	s_mov_b32 s42, s80
	s_barrier
	s_cbranch_scc0 .LBB0_3613
	v_cvt_f32_i32_e32 v214, v126
	v_cvt_f32_i32_e32 v215, v127
	v_cvt_f32_i32_e32 v212, v128
	v_cvt_f32_i32_e32 v213, v129
	v_cvt_f32_i32_e32 v218, v122
	v_cvt_f32_i32_e32 v219, v123
	v_cvt_f32_i32_e32 v216, v124
	v_cvt_f32_i32_e32 v217, v125
	v_cvt_f32_i32_e32 v222, v110
	v_cvt_f32_i32_e32 v223, v111
	v_cvt_f32_i32_e32 v220, v112
	v_cvt_f32_i32_e32 v221, v113
	v_cvt_f32_i32_e32 v226, v102
	v_cvt_f32_i32_e32 v227, v103
	v_cvt_f32_i32_e32 v224, v104
	v_cvt_f32_i32_e32 v225, v105
	v_cvt_f32_i32_e32 v194, v118
	v_cvt_f32_i32_e32 v195, v119
	v_cvt_f32_i32_e32 v192, v120
	v_cvt_f32_i32_e32 v193, v121
	v_cvt_f32_i32_e32 v200, v114
	v_cvt_f32_i32_e32 v201, v115
	v_cvt_f32_i32_e32 v198, v116
	v_cvt_f32_i32_e32 v199, v117
	v_cvt_f32_i32_e32 v206, v94
	v_cvt_f32_i32_e32 v207, v95
	v_cvt_f32_i32_e32 v202, v96
	v_cvt_f32_i32_e32 v203, v97
	v_cvt_f32_i32_e32 v208, v86
	v_cvt_f32_i32_e32 v209, v87
	v_cvt_f32_i32_e32 v204, v88
	v_cvt_f32_i32_e32 v205, v89
	v_cvt_f32_i32_e32 v178, v106
	v_cvt_f32_i32_e32 v179, v107
	v_cvt_f32_i32_e32 v176, v108
	v_cvt_f32_i32_e32 v177, v109
	v_cvt_f32_i32_e32 v182, v98
	v_cvt_f32_i32_e32 v183, v99
	v_cvt_f32_i32_e32 v180, v100
	v_cvt_f32_i32_e32 v181, v101
	v_cvt_f32_i32_e32 v188, v78
	v_cvt_f32_i32_e32 v189, v79
	v_cvt_f32_i32_e32 v184, v80
	v_cvt_f32_i32_e32 v185, v81
	v_cvt_f32_i32_e32 v190, v74
	v_cvt_f32_i32_e32 v191, v75
	v_cvt_f32_i32_e32 v186, v76
	v_cvt_f32_i32_e32 v187, v77
	v_cvt_f32_i32_e32 v162, v90
	v_cvt_f32_i32_e32 v163, v91
	v_cvt_f32_i32_e32 v160, v92
	v_cvt_f32_i32_e32 v161, v93
	v_cvt_f32_i32_e32 v166, v82
	v_cvt_f32_i32_e32 v167, v83
	v_cvt_f32_i32_e32 v164, v84
	v_cvt_f32_i32_e32 v165, v85
	v_cvt_f32_i32_e32 v172, v70
	v_cvt_f32_i32_e32 v173, v71
	v_cvt_f32_i32_e32 v168, v72
	v_cvt_f32_i32_e32 v169, v73
	v_cvt_f32_i32_e32 v174, v66
	v_cvt_f32_i32_e32 v175, v67
	v_cvt_f32_i32_e32 v170, v68
	v_cvt_f32_i32_e32 v171, v69
	v_cvt_f32_i32_e32 v146, v62
	v_cvt_f32_i32_e32 v147, v63
	v_cvt_f32_i32_e32 v128, v64
	v_cvt_f32_i32_e32 v129, v65
	v_cvt_f32_i32_e32 v150, v58
	v_cvt_f32_i32_e32 v151, v59
	v_cvt_f32_i32_e32 v148, v60
	v_cvt_f32_i32_e32 v149, v61
	v_cvt_f32_i32_e32 v156, v46
	v_cvt_f32_i32_e32 v157, v47
	v_cvt_f32_i32_e32 v152, v48
	v_cvt_f32_i32_e32 v153, v49
	v_cvt_f32_i32_e32 v158, v38
	v_cvt_f32_i32_e32 v159, v39
	v_cvt_f32_i32_e32 v154, v40
	v_cvt_f32_i32_e32 v155, v41
	v_cvt_f32_i32_e32 v114, v54
	v_cvt_f32_i32_e32 v115, v55
	v_cvt_f32_i32_e32 v112, v56
	v_cvt_f32_i32_e32 v113, v57
	v_cvt_f32_i32_e32 v118, v50
	v_cvt_f32_i32_e32 v119, v51
	v_cvt_f32_i32_e32 v116, v52
	v_cvt_f32_i32_e32 v117, v53
	v_cvt_f32_i32_e32 v124, v30
	v_cvt_f32_i32_e32 v125, v31
	v_cvt_f32_i32_e32 v120, v32
	v_cvt_f32_i32_e32 v121, v33
	v_cvt_f32_i32_e32 v126, v22
	v_cvt_f32_i32_e32 v127, v23
	v_cvt_f32_i32_e32 v122, v24
	v_cvt_f32_i32_e32 v123, v25
	v_cvt_f32_i32_e32 v64, v42
	v_cvt_f32_i32_e32 v65, v43
	v_cvt_f32_i32_e32 v62, v44
	v_cvt_f32_i32_e32 v63, v45
	v_cvt_f32_i32_e32 v68, v34
	v_cvt_f32_i32_e32 v69, v35
	v_cvt_f32_i32_e32 v66, v36
	v_cvt_f32_i32_e32 v67, v37
	v_cvt_f32_i32_e32 v74, v14
	v_cvt_f32_i32_e32 v75, v15
	v_cvt_f32_i32_e32 v70, v16
	v_cvt_f32_i32_e32 v71, v17
	v_cvt_f32_i32_e32 v76, v10
	v_cvt_f32_i32_e32 v77, v11
	v_cvt_f32_i32_e32 v72, v12
	v_cvt_f32_i32_e32 v73, v13
	v_cvt_f32_i32_e32 v48, v26
	v_cvt_f32_i32_e32 v49, v27
	v_cvt_f32_i32_e32 v46, v28
	v_cvt_f32_i32_e32 v47, v29
	v_cvt_f32_i32_e32 v52, v18
	v_cvt_f32_i32_e32 v53, v19
	v_cvt_f32_i32_e32 v50, v20
	v_cvt_f32_i32_e32 v51, v21
	v_cvt_f32_i32_e32 v58, v6
	v_cvt_f32_i32_e32 v59, v7
	v_cvt_f32_i32_e32 v54, v8
	v_cvt_f32_i32_e32 v55, v9
	v_cvt_f32_i32_e32 v60, v2
	v_cvt_f32_i32_e32 v61, v3
	v_cvt_f32_i32_e32 v56, v4
	v_cvt_f32_i32_e32 v57, v5

.LBB0_3798:
	v_add_u32_e32 v138, s56, v188
	ds_read_b128 v[148:151], v138
	ds_read_b128 v[152:155], v138 offset:1024
	ds_read_b128 v[156:159], v138 offset:2048
	ds_read_b128 v[160:163], v138 offset:3072
	v_add_u32_e32 v138, s57, v188
	ds_read_b128 v[164:167], v138
	ds_read_b128 v[168:171], v138 offset:1024
	ds_read_b128 v[172:175], v138 offset:2048
	ds_read_b128 v[176:179], v138 offset:3072
	s_add_i32 s60, s28, 2
	s_add_u32 s61, s26, 0x80
	s_addc_u32 s29, s27, 0
	s_cmp_eq_u32 s54, s28
	s_cselect_b32 s28, s2, s61
	s_cselect_b32 s29, s3, s29
	s_cselect_b32 s63, s25, s35
	s_cselect_b32 s62, s24, s34
	v_lshl_add_u64 v[184:185], s[26:27], 0, v[140:141]
	s_add_i32 m0, s42, 0xc000
	ds_read_b128 v[180:183], v189
	ds_read_b128 v[190:193], v189 offset:1024
	ds_read_b128 v[194:197], v189 offset:2048
	ds_read_b128 v[198:201], v189 offset:3072
	ds_read_b128 v[202:205], v189 offset:4096
	ds_read_b128 v[206:209], v189 offset:5120
	ds_read_b128 v[210:213], v189 offset:6144
	ds_read_b128 v[214:217], v189 offset:7168
	global_load_lds_dwordx4 v[184:185], off
	v_lshl_add_u64 v[184:185], s[26:27], 0, v[142:143]
	s_add_i32 m0, s42, 0xe000
	s_nop 0
	global_load_lds_dwordx4 v[184:185], off
	s_waitcnt vmcnt(8)
	s_waitcnt lgkmcnt(0)
	s_setprio 1
	s_waitcnt lgkmcnt(0)
	v_mfma_i32_16x16x64_i8 v[126:129], v[148:151], v[180:183], v[126:129]
	v_mfma_i32_16x16x64_i8 v[122:125], v[156:159], v[180:183], v[122:125]
	s_barrier
	v_mfma_i32_16x16x64_i8 v[118:121], v[148:151], v[194:197], v[118:121]
	v_mfma_i32_16x16x64_i8 v[114:117], v[156:159], v[194:197], v[114:117]
	v_mfma_i32_16x16x64_i8 v[106:109], v[148:151], v[202:205], v[106:109]
	v_mfma_i32_16x16x64_i8 v[98:101], v[156:159], v[202:205], v[98:101]
	v_mfma_i32_16x16x64_i8 v[90:93], v[148:151], v[210:213], v[90:93]
	v_mfma_i32_16x16x64_i8 v[82:85], v[156:159], v[210:213], v[82:85]
	v_mfma_i32_16x16x64_i8 v[126:129], v[152:155], v[190:193], v[126:129]
	v_mfma_i32_16x16x64_i8 v[122:125], v[160:163], v[190:193], v[122:125]
	v_mfma_i32_16x16x64_i8 v[118:121], v[152:155], v[198:201], v[118:121]
	v_mfma_i32_16x16x64_i8 v[114:117], v[160:163], v[198:201], v[114:117]
	v_mfma_i32_16x16x64_i8 v[106:109], v[152:155], v[206:209], v[106:109]
	v_mfma_i32_16x16x64_i8 v[98:101], v[160:163], v[206:209], v[98:101]
	v_mfma_i32_16x16x64_i8 v[90:93], v[152:155], v[214:217], v[90:93]
	v_mfma_i32_16x16x64_i8 v[82:85], v[160:163], v[214:217], v[82:85]
	s_setprio 0
	s_setprio 1
	v_mfma_i32_16x16x64_i8 v[110:113], v[164:167], v[180:183], v[110:113]
	v_mfma_i32_16x16x64_i8 v[102:105], v[172:175], v[180:183], v[102:105]
	v_mfma_i32_16x16x64_i8 v[94:97], v[164:167], v[194:197], v[94:97]
	v_mfma_i32_16x16x64_i8 v[86:89], v[172:175], v[194:197], v[86:89]
	v_mfma_i32_16x16x64_i8 v[78:81], v[164:167], v[202:205], v[78:81]
	v_mfma_i32_16x16x64_i8 v[74:77], v[172:175], v[202:205], v[74:77]
	v_mfma_i32_16x16x64_i8 v[70:73], v[164:167], v[210:213], v[70:73]
	v_mfma_i32_16x16x64_i8 v[66:69], v[172:175], v[210:213], v[66:69]
	v_mfma_i32_16x16x64_i8 v[110:113], v[168:171], v[190:193], v[110:113]
	v_mfma_i32_16x16x64_i8 v[102:105], v[176:179], v[190:193], v[102:105]
	v_mfma_i32_16x16x64_i8 v[94:97], v[168:171], v[198:201], v[94:97]
	v_mfma_i32_16x16x64_i8 v[86:89], v[176:179], v[198:201], v[86:89]
	v_mfma_i32_16x16x64_i8 v[78:81], v[168:171], v[206:209], v[78:81]
	v_mfma_i32_16x16x64_i8 v[74:77], v[176:179], v[206:209], v[74:77]
	v_mfma_i32_16x16x64_i8 v[70:73], v[168:171], v[214:217], v[70:73]
	v_mfma_i32_16x16x64_i8 v[66:69], v[176:179], v[214:217], v[66:69]
	s_setprio 0
	s_barrier
	s_add_i32 s61, s56, s41
	v_lshl_add_u64 v[184:185], s[62:63], 0, v[132:133]
	s_mov_b32 m0, s61
	ds_read_b128 v[180:183], v189 offset:16384
	ds_read_b128 v[190:193], v189 offset:17408
	ds_read_b128 v[194:197], v189 offset:18432
	ds_read_b128 v[198:201], v189 offset:19456
	ds_read_b128 v[202:205], v189 offset:20480
	ds_read_b128 v[206:209], v189 offset:21504
	ds_read_b128 v[210:213], v189 offset:22528
	ds_read_b128 v[214:217], v189 offset:23552
	global_load_lds_dwordx4 v[184:185], off
	s_add_i32 m0, s61, 0x2000
	v_lshl_add_u64 v[218:219], s[62:63], 0, v[136:137]
	s_add_u32 s62, s62, s6
	s_addc_u32 s63, s63, s7
	s_add_i32 s61, s57, s41
	global_load_lds_dwordx4 v[218:219], off
	v_lshl_add_u64 v[220:221], s[62:63], 0, v[132:133]
	s_mov_b32 m0, s61
	v_lshl_add_u64 v[222:223], s[62:63], 0, v[136:137]
	global_load_lds_dwordx4 v[220:221], off
	s_add_i32 m0, s61, 0x2000
	v_lshl_add_u64 v[224:225], s[28:29], 0, v[130:131]
	global_load_lds_dwordx4 v[222:223], off
	s_mov_b32 m0, s42
	v_lshl_add_u64 v[226:227], s[28:29], 0, v[134:135]
	global_load_lds_dwordx4 v[224:225], off
	s_mov_b32 m0, s43
	s_nop 0
	global_load_lds_dwordx4 v[226:227], off
	s_waitcnt vmcnt(8)
	s_waitcnt lgkmcnt(0)
	s_setprio 1
	s_waitcnt lgkmcnt(0)
	v_mfma_i32_16x16x64_i8 v[62:65], v[148:151], v[180:183], v[62:65]
	v_mfma_i32_16x16x64_i8 v[58:61], v[156:159], v[180:183], v[58:61]
	s_barrier
	v_mfma_i32_16x16x64_i8 v[54:57], v[148:151], v[194:197], v[54:57]
	v_mfma_i32_16x16x64_i8 v[50:53], v[156:159], v[194:197], v[50:53]
	v_mfma_i32_16x16x64_i8 v[42:45], v[148:151], v[202:205], v[42:45]
	v_mfma_i32_16x16x64_i8 v[34:37], v[156:159], v[202:205], v[34:37]
	v_mfma_i32_16x16x64_i8 v[26:29], v[148:151], v[210:213], v[26:29]
	v_mfma_i32_16x16x64_i8 v[18:21], v[156:159], v[210:213], v[18:21]
	v_mfma_i32_16x16x64_i8 v[62:65], v[152:155], v[190:193], v[62:65]
	v_mfma_i32_16x16x64_i8 v[58:61], v[160:163], v[190:193], v[58:61]
	v_mfma_i32_16x16x64_i8 v[54:57], v[152:155], v[198:201], v[54:57]
	v_mfma_i32_16x16x64_i8 v[50:53], v[160:163], v[198:201], v[50:53]
	v_mfma_i32_16x16x64_i8 v[42:45], v[152:155], v[206:209], v[42:45]
	v_mfma_i32_16x16x64_i8 v[34:37], v[160:163], v[206:209], v[34:37]
	v_mfma_i32_16x16x64_i8 v[26:29], v[152:155], v[214:217], v[26:29]
	v_mfma_i32_16x16x64_i8 v[18:21], v[160:163], v[214:217], v[18:21]
	s_setprio 0
	s_setprio 1
	v_mfma_i32_16x16x64_i8 v[46:49], v[164:167], v[180:183], v[46:49]
	v_mfma_i32_16x16x64_i8 v[38:41], v[172:175], v[180:183], v[38:41]
	v_mfma_i32_16x16x64_i8 v[30:33], v[164:167], v[194:197], v[30:33]
	v_mfma_i32_16x16x64_i8 v[22:25], v[172:175], v[194:197], v[22:25]
	v_mfma_i32_16x16x64_i8 v[14:17], v[164:167], v[202:205], v[14:17]
	v_mfma_i32_16x16x64_i8 v[10:13], v[172:175], v[202:205], v[10:13]
	v_mfma_i32_16x16x64_i8 v[6:9], v[164:167], v[210:213], v[6:9]
	v_mfma_i32_16x16x64_i8 v[2:5], v[172:175], v[210:213], v[2:5]
	v_mfma_i32_16x16x64_i8 v[46:49], v[168:171], v[190:193], v[46:49]
	v_mfma_i32_16x16x64_i8 v[38:41], v[176:179], v[190:193], v[38:41]
	v_mfma_i32_16x16x64_i8 v[30:33], v[168:171], v[198:201], v[30:33]
	v_mfma_i32_16x16x64_i8 v[22:25], v[176:179], v[198:201], v[22:25]
	v_mfma_i32_16x16x64_i8 v[14:17], v[168:171], v[206:209], v[14:17]
	v_mfma_i32_16x16x64_i8 v[10:13], v[176:179], v[206:209], v[10:13]
	v_mfma_i32_16x16x64_i8 v[6:9], v[168:171], v[214:217], v[6:9]
	v_mfma_i32_16x16x64_i8 v[2:5], v[176:179], v[214:217], v[2:5]
	s_setprio 0
	s_barrier
	s_add_i32 s61, 0, 0x18000
	v_add_u32_e32 v138, s61, v188
	s_add_i32 s62, 0, 0x1c000
	ds_read_b128 v[148:151], v138
	ds_read_b128 v[152:155], v138 offset:1024
	ds_read_b128 v[156:159], v138 offset:2048
	ds_read_b128 v[160:163], v138 offset:3072
	v_add_u32_e32 v138, s62, v188
	ds_read_b128 v[164:167], v138
	ds_read_b128 v[168:171], v138 offset:1024
	ds_read_b128 v[172:175], v138 offset:2048
	ds_read_b128 v[176:179], v138 offset:3072
	s_add_u32 s28, s28, s6
	s_addc_u32 s29, s29, s7
	s_mov_b32 m0, s44
	v_lshl_add_u64 v[228:229], s[28:29], 0, v[130:131]
	ds_read_b128 v[180:183], v189 offset:32768
	ds_read_b128 v[190:193], v189 offset:33792
	ds_read_b128 v[194:197], v189 offset:34816
	ds_read_b128 v[198:201], v189 offset:35840
	ds_read_b128 v[202:205], v189 offset:36864
	ds_read_b128 v[206:209], v189 offset:37888
	ds_read_b128 v[210:213], v189 offset:38912
	ds_read_b128 v[214:217], v189 offset:39936
	global_load_lds_dwordx4 v[228:229], off
	v_lshl_add_u64 v[228:229], s[28:29], 0, v[134:135]
	s_mov_b32 m0, s45
	s_nop 0
	global_load_lds_dwordx4 v[228:229], off
	s_waitcnt vmcnt(8)
	s_waitcnt lgkmcnt(0)
	s_setprio 1
	s_waitcnt lgkmcnt(0)
	v_mfma_i32_16x16x64_i8 v[126:129], v[148:151], v[180:183], v[126:129]
	v_mfma_i32_16x16x64_i8 v[122:125], v[156:159], v[180:183], v[122:125]
	s_barrier
	v_mfma_i32_16x16x64_i8 v[118:121], v[148:151], v[194:197], v[118:121]
	v_mfma_i32_16x16x64_i8 v[114:117], v[156:159], v[194:197], v[114:117]
	v_mfma_i32_16x16x64_i8 v[106:109], v[148:151], v[202:205], v[106:109]
	v_mfma_i32_16x16x64_i8 v[98:101], v[156:159], v[202:205], v[98:101]
	v_mfma_i32_16x16x64_i8 v[90:93], v[148:151], v[210:213], v[90:93]
	v_mfma_i32_16x16x64_i8 v[82:85], v[156:159], v[210:213], v[82:85]
	v_mfma_i32_16x16x64_i8 v[126:129], v[152:155], v[190:193], v[126:129]
	v_mfma_i32_16x16x64_i8 v[122:125], v[160:163], v[190:193], v[122:125]
	v_mfma_i32_16x16x64_i8 v[118:121], v[152:155], v[198:201], v[118:121]
	v_mfma_i32_16x16x64_i8 v[114:117], v[160:163], v[198:201], v[114:117]
	v_mfma_i32_16x16x64_i8 v[106:109], v[152:155], v[206:209], v[106:109]
	v_mfma_i32_16x16x64_i8 v[98:101], v[160:163], v[206:209], v[98:101]
	v_mfma_i32_16x16x64_i8 v[90:93], v[152:155], v[214:217], v[90:93]
	v_mfma_i32_16x16x64_i8 v[82:85], v[160:163], v[214:217], v[82:85]
	s_setprio 0
	s_setprio 1
	v_mfma_i32_16x16x64_i8 v[110:113], v[164:167], v[180:183], v[110:113]
	v_mfma_i32_16x16x64_i8 v[102:105], v[172:175], v[180:183], v[102:105]
	v_mfma_i32_16x16x64_i8 v[94:97], v[164:167], v[194:197], v[94:97]
	v_mfma_i32_16x16x64_i8 v[86:89], v[172:175], v[194:197], v[86:89]
	v_mfma_i32_16x16x64_i8 v[78:81], v[164:167], v[202:205], v[78:81]
	v_mfma_i32_16x16x64_i8 v[74:77], v[172:175], v[202:205], v[74:77]
	v_mfma_i32_16x16x64_i8 v[70:73], v[164:167], v[210:213], v[70:73]
	v_mfma_i32_16x16x64_i8 v[66:69], v[172:175], v[210:213], v[66:69]
	v_mfma_i32_16x16x64_i8 v[110:113], v[168:171], v[190:193], v[110:113]
	v_mfma_i32_16x16x64_i8 v[102:105], v[176:179], v[190:193], v[102:105]
	v_mfma_i32_16x16x64_i8 v[94:97], v[168:171], v[198:201], v[94:97]
	v_mfma_i32_16x16x64_i8 v[86:89], v[176:179], v[198:201], v[86:89]
	v_mfma_i32_16x16x64_i8 v[78:81], v[168:171], v[206:209], v[78:81]
	v_mfma_i32_16x16x64_i8 v[74:77], v[176:179], v[206:209], v[74:77]
	v_mfma_i32_16x16x64_i8 v[70:73], v[168:171], v[214:217], v[70:73]
	v_mfma_i32_16x16x64_i8 v[66:69], v[176:179], v[214:217], v[66:69]
	s_setprio 0
	s_barrier
	s_add_i32 s28, s61, s41
	v_lshl_add_u64 v[184:185], v[184:185], 0, s[18:19]
	s_mov_b32 m0, s28
	ds_read_b128 v[180:183], v189 offset:49152
	ds_read_b128 v[190:193], v189 offset:50176
	ds_read_b128 v[194:197], v189 offset:51200
	ds_read_b128 v[198:201], v189 offset:52224
	ds_read_b128 v[202:205], v189 offset:53248
	ds_read_b128 v[206:209], v189 offset:54272
	ds_read_b128 v[210:213], v189 offset:55296
	ds_read_b128 v[214:217], v189 offset:56320
	global_load_lds_dwordx4 v[184:185], off
	v_lshl_add_u64 v[184:185], v[218:219], 0, s[18:19]
	s_add_i32 m0, s28, 0x2000
	s_add_i32 s28, s62, s41
	global_load_lds_dwordx4 v[184:185], off
	v_lshl_add_u64 v[184:185], v[220:221], 0, s[18:19]
	s_mov_b32 m0, s28
	s_nop 0
	global_load_lds_dwordx4 v[184:185], off
	v_lshl_add_u64 v[184:185], v[222:223], 0, s[18:19]
	s_add_i32 m0, s28, 0x2000
	s_nop 0
	global_load_lds_dwordx4 v[184:185], off
	v_lshl_add_u64 v[184:185], v[224:225], 0, s[18:19]
	s_mov_b32 m0, s49
	s_nop 0
	global_load_lds_dwordx4 v[184:185], off
	v_lshl_add_u64 v[184:185], v[226:227], 0, s[18:19]
	s_mov_b32 m0, s50
	s_nop 0
	global_load_lds_dwordx4 v[184:185], off
	s_waitcnt vmcnt(8)
	s_waitcnt lgkmcnt(0)
	s_setprio 1
	s_waitcnt lgkmcnt(0)
	v_mfma_i32_16x16x64_i8 v[62:65], v[148:151], v[180:183], v[62:65]
	v_mfma_i32_16x16x64_i8 v[58:61], v[156:159], v[180:183], v[58:61]
	s_barrier
	v_mfma_i32_16x16x64_i8 v[54:57], v[148:151], v[194:197], v[54:57]
	v_mfma_i32_16x16x64_i8 v[50:53], v[156:159], v[194:197], v[50:53]
	v_mfma_i32_16x16x64_i8 v[42:45], v[148:151], v[202:205], v[42:45]
	v_mfma_i32_16x16x64_i8 v[34:37], v[156:159], v[202:205], v[34:37]
	v_mfma_i32_16x16x64_i8 v[26:29], v[148:151], v[210:213], v[26:29]
	v_mfma_i32_16x16x64_i8 v[18:21], v[156:159], v[210:213], v[18:21]
	v_mfma_i32_16x16x64_i8 v[62:65], v[152:155], v[190:193], v[62:65]
	v_mfma_i32_16x16x64_i8 v[58:61], v[160:163], v[190:193], v[58:61]
	v_mfma_i32_16x16x64_i8 v[54:57], v[152:155], v[198:201], v[54:57]
	v_mfma_i32_16x16x64_i8 v[50:53], v[160:163], v[198:201], v[50:53]
	v_mfma_i32_16x16x64_i8 v[42:45], v[152:155], v[206:209], v[42:45]
	v_mfma_i32_16x16x64_i8 v[34:37], v[160:163], v[206:209], v[34:37]
	v_mfma_i32_16x16x64_i8 v[26:29], v[152:155], v[214:217], v[26:29]
	v_mfma_i32_16x16x64_i8 v[18:21], v[160:163], v[214:217], v[18:21]
	s_setprio 0
	s_setprio 1
	v_mfma_i32_16x16x64_i8 v[46:49], v[164:167], v[180:183], v[46:49]
	v_mfma_i32_16x16x64_i8 v[38:41], v[172:175], v[180:183], v[38:41]
	v_mfma_i32_16x16x64_i8 v[30:33], v[164:167], v[194:197], v[30:33]
	v_mfma_i32_16x16x64_i8 v[22:25], v[172:175], v[194:197], v[22:25]
	v_mfma_i32_16x16x64_i8 v[14:17], v[164:167], v[202:205], v[14:17]
	v_mfma_i32_16x16x64_i8 v[10:13], v[172:175], v[202:205], v[10:13]
	v_mfma_i32_16x16x64_i8 v[6:9], v[164:167], v[210:213], v[6:9]
	v_mfma_i32_16x16x64_i8 v[2:5], v[172:175], v[210:213], v[2:5]
	v_mfma_i32_16x16x64_i8 v[46:49], v[168:171], v[190:193], v[46:49]
	v_mfma_i32_16x16x64_i8 v[38:41], v[176:179], v[190:193], v[38:41]
	v_mfma_i32_16x16x64_i8 v[30:33], v[168:171], v[198:201], v[30:33]
	v_mfma_i32_16x16x64_i8 v[22:25], v[176:179], v[198:201], v[22:25]
	v_mfma_i32_16x16x64_i8 v[14:17], v[168:171], v[206:209], v[14:17]
	v_mfma_i32_16x16x64_i8 v[10:13], v[176:179], v[206:209], v[10:13]
	v_mfma_i32_16x16x64_i8 v[6:9], v[168:171], v[214:217], v[6:9]
	v_mfma_i32_16x16x64_i8 v[2:5], v[176:179], v[214:217], v[2:5]
	s_setprio 0
	s_add_u32 s26, s26, 0x100
	s_addc_u32 s27, s27, 0
	s_add_u32 s34, s34, 0x100
	s_addc_u32 s35, s35, 0
	s_cmp_ge_i32 s60, s51
	s_mov_b32 s28, s60
	s_barrier
	s_cbranch_scc0 .LBB0_3798
	v_cvt_f32_i32_e32 v172, v126
	v_cvt_f32_i32_e32 v173, v127
	v_cvt_f32_i32_e32 v170, v128
	v_cvt_f32_i32_e32 v171, v129
	v_cvt_f32_i32_e32 v174, v122
	v_cvt_f32_i32_e32 v175, v123
	v_cvt_f32_i32_e32 v176, v124
	v_cvt_f32_i32_e32 v177, v125
	v_cvt_f32_i32_e32 v180, v110
	v_cvt_f32_i32_e32 v181, v111
	v_cvt_f32_i32_e32 v182, v112
	v_cvt_f32_i32_e32 v183, v113
	v_cvt_f32_i32_e32 v178, v102
	v_cvt_f32_i32_e32 v179, v103
	v_cvt_f32_i32_e32 v184, v104
	v_cvt_f32_i32_e32 v185, v105
	v_cvt_f32_i32_e32 v152, v118
	v_cvt_f32_i32_e32 v153, v119
	v_cvt_f32_i32_e32 v154, v120
	v_cvt_f32_i32_e32 v155, v121
	v_cvt_f32_i32_e32 v156, v114
	v_cvt_f32_i32_e32 v157, v115
	v_cvt_f32_i32_e32 v158, v116
	v_cvt_f32_i32_e32 v159, v117
	v_cvt_f32_i32_e32 v160, v94
	v_cvt_f32_i32_e32 v161, v95
	v_cvt_f32_i32_e32 v162, v96
	v_cvt_f32_i32_e32 v163, v97
	v_cvt_f32_i32_e32 v164, v86
	v_cvt_f32_i32_e32 v165, v87
	v_cvt_f32_i32_e32 v166, v88
	v_cvt_f32_i32_e32 v167, v89
	v_cvt_f32_i32_e32 v118, v106
	v_cvt_f32_i32_e32 v119, v107
	v_cvt_f32_i32_e32 v120, v108
	v_cvt_f32_i32_e32 v121, v109
	v_cvt_f32_i32_e32 v122, v98
	v_cvt_f32_i32_e32 v123, v99
	v_cvt_f32_i32_e32 v124, v100
	v_cvt_f32_i32_e32 v125, v101
	v_cvt_f32_i32_e32 v126, v78
	v_cvt_f32_i32_e32 v127, v79
	v_cvt_f32_i32_e32 v128, v80
	v_cvt_f32_i32_e32 v129, v81
	v_cvt_f32_i32_e32 v148, v74
	v_cvt_f32_i32_e32 v149, v75
	v_cvt_f32_i32_e32 v150, v76
	v_cvt_f32_i32_e32 v151, v77
	v_cvt_f32_i32_e32 v102, v90
	v_cvt_f32_i32_e32 v103, v91
	v_cvt_f32_i32_e32 v104, v92
	v_cvt_f32_i32_e32 v105, v93
	v_cvt_f32_i32_e32 v106, v82
	v_cvt_f32_i32_e32 v107, v83
	v_cvt_f32_i32_e32 v108, v84
	v_cvt_f32_i32_e32 v109, v85
	v_cvt_f32_i32_e32 v110, v70
	v_cvt_f32_i32_e32 v111, v71
	v_cvt_f32_i32_e32 v112, v72
	v_cvt_f32_i32_e32 v113, v73
	v_cvt_f32_i32_e32 v114, v66
	v_cvt_f32_i32_e32 v115, v67
	v_cvt_f32_i32_e32 v116, v68
	v_cvt_f32_i32_e32 v117, v69
	v_cvt_f32_i32_e32 v82, v62
	v_cvt_f32_i32_e32 v83, v63
	v_cvt_f32_i32_e32 v84, v64
	v_cvt_f32_i32_e32 v85, v65
	v_cvt_f32_i32_e32 v86, v58
	v_cvt_f32_i32_e32 v87, v59
	v_cvt_f32_i32_e32 v88, v60
	v_cvt_f32_i32_e32 v89, v61
	v_cvt_f32_i32_e32 v92, v46
	v_cvt_f32_i32_e32 v93, v47
	v_cvt_f32_i32_e32 v94, v48
	v_cvt_f32_i32_e32 v95, v49
	v_cvt_f32_i32_e32 v96, v38
	v_cvt_f32_i32_e32 v97, v39
	v_cvt_f32_i32_e32 v98, v40
	v_cvt_f32_i32_e32 v99, v41
	v_cvt_f32_i32_e32 v66, v54
	v_cvt_f32_i32_e32 v67, v55
	v_cvt_f32_i32_e32 v68, v56
	v_cvt_f32_i32_e32 v69, v57
	v_cvt_f32_i32_e32 v70, v50
	v_cvt_f32_i32_e32 v71, v51
	v_cvt_f32_i32_e32 v72, v52
	v_cvt_f32_i32_e32 v73, v53
	v_cvt_f32_i32_e32 v74, v30
	v_cvt_f32_i32_e32 v75, v31
	v_cvt_f32_i32_e32 v76, v32
	v_cvt_f32_i32_e32 v77, v33
	v_cvt_f32_i32_e32 v78, v22
	v_cvt_f32_i32_e32 v79, v23
	v_cvt_f32_i32_e32 v80, v24
	v_cvt_f32_i32_e32 v81, v25
	v_cvt_f32_i32_e32 v50, v42
	v_cvt_f32_i32_e32 v51, v43
	v_cvt_f32_i32_e32 v52, v44
	v_cvt_f32_i32_e32 v53, v45
	v_cvt_f32_i32_e32 v54, v34
	v_cvt_f32_i32_e32 v55, v35
	v_cvt_f32_i32_e32 v56, v36
	v_cvt_f32_i32_e32 v57, v37
	v_cvt_f32_i32_e32 v58, v14
	v_cvt_f32_i32_e32 v59, v15
	v_cvt_f32_i32_e32 v60, v16
	v_cvt_f32_i32_e32 v61, v17
	v_cvt_f32_i32_e32 v62, v10
	v_cvt_f32_i32_e32 v63, v11
	v_cvt_f32_i32_e32 v64, v12
	v_cvt_f32_i32_e32 v65, v13
	v_cvt_f32_i32_e32 v34, v26
	v_cvt_f32_i32_e32 v35, v27
	v_cvt_f32_i32_e32 v36, v28
	v_cvt_f32_i32_e32 v37, v29
	v_cvt_f32_i32_e32 v38, v18
	v_cvt_f32_i32_e32 v39, v19
	v_cvt_f32_i32_e32 v40, v20
	v_cvt_f32_i32_e32 v41, v21
	v_cvt_f32_i32_e32 v42, v6
	v_cvt_f32_i32_e32 v43, v7
	v_cvt_f32_i32_e32 v44, v8
	v_cvt_f32_i32_e32 v45, v9
	v_cvt_f32_i32_e32 v46, v2
	v_cvt_f32_i32_e32 v47, v3
	v_cvt_f32_i32_e32 v48, v4
	v_cvt_f32_i32_e32 v49, v5

.LBB0_3879:
	ds_read_b128 v[130:133], v169
	ds_read_b128 v[134:137], v169 offset:1024
	ds_read_b128 v[138:141], v169 offset:2048
	ds_read_b128 v[142:145], v169 offset:3072
	ds_read_b128 v[162:165], v170
	ds_read_b128 v[172:175], v170 offset:1024
	ds_read_b128 v[176:179], v170 offset:2048
	ds_read_b128 v[180:183], v170 offset:3072
	s_add_i32 s59, s26, 2
	s_add_u32 s27, s24, 0x4000
	s_addc_u32 s28, s25, 0
	s_cmp_eq_u32 s48, s26
	s_cselect_b32 s29, s3, s28
	s_cselect_b32 s28, s2, s27
	s_cselect_b32 s60, s22, s57
	s_cselect_b32 s61, s23, s58
	s_add_u32 s26, s28, 0x8000
	s_addc_u32 s27, s29, 0
	v_lshl_add_u64 v[216:217], s[24:25], 0, v[154:155]
	s_add_i32 m0, s38, 0xc000
	ds_read_b128 v[184:187], v171
	ds_read_b128 v[188:191], v171 offset:1024
	ds_read_b128 v[192:195], v171 offset:2048
	ds_read_b128 v[196:199], v171 offset:3072
	ds_read_b128 v[200:203], v171 offset:4096
	ds_read_b128 v[204:207], v171 offset:5120
	ds_read_b128 v[208:211], v171 offset:6144
	ds_read_b128 v[212:215], v171 offset:7168
	global_load_lds_dwordx4 v[216:217], off
	v_lshl_add_u64 v[216:217], s[24:25], 0, v[156:157]
	s_add_i32 m0, s38, 0xe000
	s_nop 0
	global_load_lds_dwordx4 v[216:217], off
	s_waitcnt vmcnt(8)
	s_waitcnt lgkmcnt(0)
	s_setprio 1
	s_waitcnt lgkmcnt(0)
	v_mfma_f32_16x16x32_bf16 v[126:129], v[130:133], v[184:187], v[126:129]
	v_mfma_f32_16x16x32_bf16 v[122:125], v[138:141], v[184:187], v[122:125]
	s_barrier
	v_mfma_f32_16x16x32_bf16 v[110:113], v[130:133], v[192:195], v[110:113]
	v_mfma_f32_16x16x32_bf16 v[106:109], v[138:141], v[192:195], v[106:109]
	v_mfma_f32_16x16x32_bf16 v[94:97], v[130:133], v[200:203], v[94:97]
	v_mfma_f32_16x16x32_bf16 v[90:93], v[138:141], v[200:203], v[90:93]
	v_mfma_f32_16x16x32_bf16 v[78:81], v[130:133], v[208:211], v[78:81]
	v_mfma_f32_16x16x32_bf16 v[74:77], v[138:141], v[208:211], v[74:77]
	v_mfma_f32_16x16x32_bf16 v[126:129], v[134:137], v[188:191], v[126:129]
	v_mfma_f32_16x16x32_bf16 v[122:125], v[142:145], v[188:191], v[122:125]
	v_mfma_f32_16x16x32_bf16 v[110:113], v[134:137], v[196:199], v[110:113]
	v_mfma_f32_16x16x32_bf16 v[106:109], v[142:145], v[196:199], v[106:109]
	v_mfma_f32_16x16x32_bf16 v[94:97], v[134:137], v[204:207], v[94:97]
	v_mfma_f32_16x16x32_bf16 v[90:93], v[142:145], v[204:207], v[90:93]
	v_mfma_f32_16x16x32_bf16 v[78:81], v[134:137], v[212:215], v[78:81]
	v_mfma_f32_16x16x32_bf16 v[74:77], v[142:145], v[212:215], v[74:77]
	s_setprio 0
	s_setprio 1
	v_mfma_f32_16x16x32_bf16 v[118:121], v[162:165], v[184:187], v[118:121]
	v_mfma_f32_16x16x32_bf16 v[114:117], v[176:179], v[184:187], v[114:117]
	v_mfma_f32_16x16x32_bf16 v[102:105], v[162:165], v[192:195], v[102:105]
	v_mfma_f32_16x16x32_bf16 v[98:101], v[176:179], v[192:195], v[98:101]
	v_mfma_f32_16x16x32_bf16 v[86:89], v[162:165], v[200:203], v[86:89]
	v_mfma_f32_16x16x32_bf16 v[82:85], v[176:179], v[200:203], v[82:85]
	v_mfma_f32_16x16x32_bf16 v[70:73], v[162:165], v[208:211], v[70:73]
	v_mfma_f32_16x16x32_bf16 v[66:69], v[176:179], v[208:211], v[66:69]
	v_mfma_f32_16x16x32_bf16 v[118:121], v[172:175], v[188:191], v[118:121]
	v_mfma_f32_16x16x32_bf16 v[114:117], v[180:183], v[188:191], v[114:117]
	v_mfma_f32_16x16x32_bf16 v[102:105], v[172:175], v[196:199], v[102:105]
	v_mfma_f32_16x16x32_bf16 v[98:101], v[180:183], v[196:199], v[98:101]
	v_mfma_f32_16x16x32_bf16 v[86:89], v[172:175], v[204:207], v[86:89]
	v_mfma_f32_16x16x32_bf16 v[82:85], v[180:183], v[204:207], v[82:85]
	v_mfma_f32_16x16x32_bf16 v[70:73], v[172:175], v[212:215], v[70:73]
	v_mfma_f32_16x16x32_bf16 v[66:69], v[180:183], v[212:215], v[66:69]
	s_setprio 0
	s_barrier
	s_add_i32 s62, s50, s37
	v_lshl_add_u64 v[216:217], s[60:61], 0, v[148:149]
	s_mov_b32 m0, s62
	ds_read_b128 v[184:187], v171 offset:16384
	ds_read_b128 v[188:191], v171 offset:17408
	ds_read_b128 v[192:195], v171 offset:18432
	ds_read_b128 v[196:199], v171 offset:19456
	ds_read_b128 v[200:203], v171 offset:20480
	ds_read_b128 v[204:207], v171 offset:21504
	ds_read_b128 v[208:211], v171 offset:22528
	ds_read_b128 v[212:215], v171 offset:23552
	global_load_lds_dwordx4 v[216:217], off
	s_add_i32 m0, s62, 0x2000
	v_lshl_add_u64 v[218:219], s[60:61], 0, v[152:153]
	s_add_u32 s60, s60, s6
	s_addc_u32 s61, s61, s7
	s_add_i32 s62, s51, s37
	global_load_lds_dwordx4 v[218:219], off
	v_lshl_add_u64 v[220:221], s[60:61], 0, v[148:149]
	s_mov_b32 m0, s62
	v_lshl_add_u64 v[222:223], s[60:61], 0, v[152:153]
	global_load_lds_dwordx4 v[220:221], off
	s_add_i32 m0, s62, 0x2000
	v_lshl_add_u64 v[224:225], s[28:29], 0, v[146:147]
	global_load_lds_dwordx4 v[222:223], off
	s_mov_b32 m0, s38
	s_nop 0
	global_load_lds_dwordx4 v[224:225], off
	v_lshl_add_u64 v[224:225], s[28:29], 0, v[150:151]
	s_mov_b32 m0, s39
	s_nop 0
	global_load_lds_dwordx4 v[224:225], off
	s_waitcnt vmcnt(8)
	s_waitcnt lgkmcnt(0)
	s_setprio 1
	s_waitcnt lgkmcnt(0)
	v_mfma_f32_16x16x32_bf16 v[62:65], v[130:133], v[184:187], v[62:65]
	v_mfma_f32_16x16x32_bf16 v[58:61], v[138:141], v[184:187], v[58:61]
	s_barrier
	v_mfma_f32_16x16x32_bf16 v[46:49], v[130:133], v[192:195], v[46:49]
	v_mfma_f32_16x16x32_bf16 v[42:45], v[138:141], v[192:195], v[42:45]
	v_mfma_f32_16x16x32_bf16 v[30:33], v[130:133], v[200:203], v[30:33]
	v_mfma_f32_16x16x32_bf16 v[26:29], v[138:141], v[200:203], v[26:29]
	v_mfma_f32_16x16x32_bf16 v[14:17], v[130:133], v[208:211], v[14:17]
	v_mfma_f32_16x16x32_bf16 v[10:13], v[138:141], v[208:211], v[10:13]
	v_mfma_f32_16x16x32_bf16 v[62:65], v[134:137], v[188:191], v[62:65]
	v_mfma_f32_16x16x32_bf16 v[58:61], v[142:145], v[188:191], v[58:61]
	v_mfma_f32_16x16x32_bf16 v[46:49], v[134:137], v[196:199], v[46:49]
	v_mfma_f32_16x16x32_bf16 v[42:45], v[142:145], v[196:199], v[42:45]
	v_mfma_f32_16x16x32_bf16 v[30:33], v[134:137], v[204:207], v[30:33]
	v_mfma_f32_16x16x32_bf16 v[26:29], v[142:145], v[204:207], v[26:29]
	v_mfma_f32_16x16x32_bf16 v[14:17], v[134:137], v[212:215], v[14:17]
	v_mfma_f32_16x16x32_bf16 v[10:13], v[142:145], v[212:215], v[10:13]
	s_setprio 0
	s_setprio 1
	v_mfma_f32_16x16x32_bf16 v[54:57], v[162:165], v[184:187], v[54:57]
	v_mfma_f32_16x16x32_bf16 v[50:53], v[176:179], v[184:187], v[50:53]
	v_mfma_f32_16x16x32_bf16 v[38:41], v[162:165], v[192:195], v[38:41]
	v_mfma_f32_16x16x32_bf16 v[34:37], v[176:179], v[192:195], v[34:37]
	v_mfma_f32_16x16x32_bf16 v[22:25], v[162:165], v[200:203], v[22:25]
	v_mfma_f32_16x16x32_bf16 v[18:21], v[176:179], v[200:203], v[18:21]
	v_mfma_f32_16x16x32_bf16 v[6:9], v[162:165], v[208:211], v[6:9]
	v_mfma_f32_16x16x32_bf16 v[2:5], v[176:179], v[208:211], v[2:5]
	v_mfma_f32_16x16x32_bf16 v[54:57], v[172:175], v[188:191], v[54:57]
	v_mfma_f32_16x16x32_bf16 v[50:53], v[180:183], v[188:191], v[50:53]
	v_mfma_f32_16x16x32_bf16 v[38:41], v[172:175], v[196:199], v[38:41]
	v_mfma_f32_16x16x32_bf16 v[34:37], v[180:183], v[196:199], v[34:37]
	v_mfma_f32_16x16x32_bf16 v[22:25], v[172:175], v[204:207], v[22:25]
	v_mfma_f32_16x16x32_bf16 v[18:21], v[180:183], v[204:207], v[18:21]
	v_mfma_f32_16x16x32_bf16 v[6:9], v[172:175], v[212:215], v[6:9]
	v_mfma_f32_16x16x32_bf16 v[2:5], v[180:183], v[212:215], v[2:5]
	s_setprio 0
	s_barrier
	s_add_i32 s60, 0, 0x18000
	s_add_i32 s61, 0, 0x1c000
	v_add_u32_e32 v142, s60, v167
	v_add_u32_e32 v180, s61, v167
	ds_read_b128 v[130:133], v142
	ds_read_b128 v[134:137], v142 offset:1024
	ds_read_b128 v[138:141], v142 offset:2048
	ds_read_b128 v[142:145], v142 offset:3072
	ds_read_b128 v[162:165], v180
	ds_read_b128 v[172:175], v180 offset:1024
	ds_read_b128 v[176:179], v180 offset:2048
	ds_read_b128 v[180:183], v180 offset:3072
	s_add_u32 s28, s28, 0x4000
	s_addc_u32 s29, s29, 0
	s_mov_b32 m0, s40
	v_lshl_add_u64 v[224:225], s[28:29], 0, v[146:147]
	ds_read_b128 v[184:187], v171 offset:32768
	ds_read_b128 v[188:191], v171 offset:33792
	ds_read_b128 v[192:195], v171 offset:34816
	ds_read_b128 v[196:199], v171 offset:35840
	ds_read_b128 v[200:203], v171 offset:36864
	ds_read_b128 v[204:207], v171 offset:37888
	ds_read_b128 v[208:211], v171 offset:38912
	ds_read_b128 v[212:215], v171 offset:39936
	global_load_lds_dwordx4 v[224:225], off
	v_lshl_add_u64 v[224:225], s[28:29], 0, v[150:151]
	s_mov_b32 m0, s41
	s_nop 0
	global_load_lds_dwordx4 v[224:225], off
	s_waitcnt vmcnt(8)
	s_waitcnt lgkmcnt(0)
	s_setprio 1
	s_waitcnt lgkmcnt(0)
	v_mfma_f32_16x16x32_bf16 v[126:129], v[130:133], v[184:187], v[126:129]
	v_mfma_f32_16x16x32_bf16 v[122:125], v[138:141], v[184:187], v[122:125]
	s_barrier
	v_mfma_f32_16x16x32_bf16 v[110:113], v[130:133], v[192:195], v[110:113]
	v_mfma_f32_16x16x32_bf16 v[106:109], v[138:141], v[192:195], v[106:109]
	v_mfma_f32_16x16x32_bf16 v[94:97], v[130:133], v[200:203], v[94:97]
	v_mfma_f32_16x16x32_bf16 v[90:93], v[138:141], v[200:203], v[90:93]
	v_mfma_f32_16x16x32_bf16 v[78:81], v[130:133], v[208:211], v[78:81]
	v_mfma_f32_16x16x32_bf16 v[74:77], v[138:141], v[208:211], v[74:77]
	v_mfma_f32_16x16x32_bf16 v[126:129], v[134:137], v[188:191], v[126:129]
	v_mfma_f32_16x16x32_bf16 v[122:125], v[142:145], v[188:191], v[122:125]
	v_mfma_f32_16x16x32_bf16 v[110:113], v[134:137], v[196:199], v[110:113]
	v_mfma_f32_16x16x32_bf16 v[106:109], v[142:145], v[196:199], v[106:109]
	v_mfma_f32_16x16x32_bf16 v[94:97], v[134:137], v[204:207], v[94:97]
	v_mfma_f32_16x16x32_bf16 v[90:93], v[142:145], v[204:207], v[90:93]
	v_mfma_f32_16x16x32_bf16 v[78:81], v[134:137], v[212:215], v[78:81]
	v_mfma_f32_16x16x32_bf16 v[74:77], v[142:145], v[212:215], v[74:77]
	s_setprio 0
	s_setprio 1
	v_mfma_f32_16x16x32_bf16 v[118:121], v[162:165], v[184:187], v[118:121]
	v_mfma_f32_16x16x32_bf16 v[114:117], v[176:179], v[184:187], v[114:117]
	v_mfma_f32_16x16x32_bf16 v[102:105], v[162:165], v[192:195], v[102:105]
	v_mfma_f32_16x16x32_bf16 v[98:101], v[176:179], v[192:195], v[98:101]
	v_mfma_f32_16x16x32_bf16 v[86:89], v[162:165], v[200:203], v[86:89]
	v_mfma_f32_16x16x32_bf16 v[82:85], v[176:179], v[200:203], v[82:85]
	v_mfma_f32_16x16x32_bf16 v[70:73], v[162:165], v[208:211], v[70:73]
	v_mfma_f32_16x16x32_bf16 v[66:69], v[176:179], v[208:211], v[66:69]
	v_mfma_f32_16x16x32_bf16 v[118:121], v[172:175], v[188:191], v[118:121]
	v_mfma_f32_16x16x32_bf16 v[114:117], v[180:183], v[188:191], v[114:117]
	v_mfma_f32_16x16x32_bf16 v[102:105], v[172:175], v[196:199], v[102:105]
	v_mfma_f32_16x16x32_bf16 v[98:101], v[180:183], v[196:199], v[98:101]
	v_mfma_f32_16x16x32_bf16 v[86:89], v[172:175], v[204:207], v[86:89]
	v_mfma_f32_16x16x32_bf16 v[82:85], v[180:183], v[204:207], v[82:85]
	v_mfma_f32_16x16x32_bf16 v[70:73], v[172:175], v[212:215], v[70:73]
	v_mfma_f32_16x16x32_bf16 v[66:69], v[180:183], v[212:215], v[66:69]
	s_setprio 0
	s_barrier
	s_add_i32 s28, s60, s37
	v_lshl_add_u64 v[216:217], v[216:217], 0, s[14:15]
	s_mov_b32 m0, s28
	ds_read_b128 v[184:187], v171 offset:49152
	ds_read_b128 v[188:191], v171 offset:50176
	ds_read_b128 v[192:195], v171 offset:51200
	ds_read_b128 v[196:199], v171 offset:52224
	ds_read_b128 v[200:203], v171 offset:53248
	ds_read_b128 v[204:207], v171 offset:54272
	ds_read_b128 v[208:211], v171 offset:55296
	ds_read_b128 v[212:215], v171 offset:56320
	global_load_lds_dwordx4 v[216:217], off
	v_lshl_add_u64 v[216:217], v[218:219], 0, s[14:15]
	s_add_i32 m0, s28, 0x2000
	s_add_i32 s28, s61, s37
	global_load_lds_dwordx4 v[216:217], off
	v_lshl_add_u64 v[216:217], v[220:221], 0, s[14:15]
	s_mov_b32 m0, s28
	s_nop 0
	global_load_lds_dwordx4 v[216:217], off
	v_lshl_add_u64 v[216:217], v[222:223], 0, s[14:15]
	s_add_i32 m0, s28, 0x2000
	s_nop 0
	global_load_lds_dwordx4 v[216:217], off
	v_lshl_add_u64 v[216:217], s[26:27], 0, v[146:147]
	s_mov_b32 m0, s46
	s_nop 0
	global_load_lds_dwordx4 v[216:217], off
	v_lshl_add_u64 v[216:217], s[26:27], 0, v[150:151]
	s_mov_b32 m0, s47
	s_nop 0
	global_load_lds_dwordx4 v[216:217], off
	s_waitcnt vmcnt(8)
	s_waitcnt lgkmcnt(0)
	s_setprio 1
	s_waitcnt lgkmcnt(0)
	v_mfma_f32_16x16x32_bf16 v[62:65], v[130:133], v[184:187], v[62:65]
	v_mfma_f32_16x16x32_bf16 v[58:61], v[138:141], v[184:187], v[58:61]
	s_barrier
	v_mfma_f32_16x16x32_bf16 v[46:49], v[130:133], v[192:195], v[46:49]
	v_mfma_f32_16x16x32_bf16 v[42:45], v[138:141], v[192:195], v[42:45]
	v_mfma_f32_16x16x32_bf16 v[30:33], v[130:133], v[200:203], v[30:33]
	v_mfma_f32_16x16x32_bf16 v[26:29], v[138:141], v[200:203], v[26:29]
	v_mfma_f32_16x16x32_bf16 v[14:17], v[130:133], v[208:211], v[14:17]
	v_mfma_f32_16x16x32_bf16 v[10:13], v[138:141], v[208:211], v[10:13]
	v_mfma_f32_16x16x32_bf16 v[62:65], v[134:137], v[188:191], v[62:65]
	v_mfma_f32_16x16x32_bf16 v[58:61], v[142:145], v[188:191], v[58:61]
	v_mfma_f32_16x16x32_bf16 v[46:49], v[134:137], v[196:199], v[46:49]
	v_mfma_f32_16x16x32_bf16 v[42:45], v[142:145], v[196:199], v[42:45]
	v_mfma_f32_16x16x32_bf16 v[30:33], v[134:137], v[204:207], v[30:33]
	v_mfma_f32_16x16x32_bf16 v[26:29], v[142:145], v[204:207], v[26:29]
	v_mfma_f32_16x16x32_bf16 v[14:17], v[134:137], v[212:215], v[14:17]
	v_mfma_f32_16x16x32_bf16 v[10:13], v[142:145], v[212:215], v[10:13]
	s_setprio 0
	s_setprio 1
	v_mfma_f32_16x16x32_bf16 v[54:57], v[162:165], v[184:187], v[54:57]
	v_mfma_f32_16x16x32_bf16 v[50:53], v[176:179], v[184:187], v[50:53]
	v_mfma_f32_16x16x32_bf16 v[38:41], v[162:165], v[192:195], v[38:41]
	v_mfma_f32_16x16x32_bf16 v[34:37], v[176:179], v[192:195], v[34:37]
	v_mfma_f32_16x16x32_bf16 v[22:25], v[162:165], v[200:203], v[22:25]
	v_mfma_f32_16x16x32_bf16 v[18:21], v[176:179], v[200:203], v[18:21]
	v_mfma_f32_16x16x32_bf16 v[6:9], v[162:165], v[208:211], v[6:9]
	v_mfma_f32_16x16x32_bf16 v[2:5], v[176:179], v[208:211], v[2:5]
	v_mfma_f32_16x16x32_bf16 v[54:57], v[172:175], v[188:191], v[54:57]
	v_mfma_f32_16x16x32_bf16 v[50:53], v[180:183], v[188:191], v[50:53]
	v_mfma_f32_16x16x32_bf16 v[38:41], v[172:175], v[196:199], v[38:41]
	v_mfma_f32_16x16x32_bf16 v[34:37], v[180:183], v[196:199], v[34:37]
	v_mfma_f32_16x16x32_bf16 v[22:25], v[172:175], v[204:207], v[22:25]
	v_mfma_f32_16x16x32_bf16 v[18:21], v[180:183], v[204:207], v[18:21]
	v_mfma_f32_16x16x32_bf16 v[6:9], v[172:175], v[212:215], v[6:9]
	v_mfma_f32_16x16x32_bf16 v[2:5], v[180:183], v[212:215], v[2:5]
	s_setprio 0
	s_add_u32 s57, s57, 0x100
	s_addc_u32 s58, s58, 0
	s_add_u32 s24, s24, 0x10000
	s_addc_u32 s25, s25, 0
	s_cmp_ge_i32 s59, s45
	s_mov_b32 s26, s59
	s_barrier
	s_cbranch_scc0 .LBB0_3879
